# K-loop back edge rotated: loop-back barrier is the loop head, branch issued before the barrier wait (8 GEMM loops); on top of v48
# baseline (speedup 1.0000x reference)
; #define LDA8(dst, b, h) _Pragma("unroll") for (int m = 0; m < 4; ++m) _Pragma("unroll") for (int k = 0; k < 2; ++k) \
;     dst[m][k] = *(const bf16x8*)((const char*)SA8(b, h) + lds_byte8(wr * 64 + m * 16 + fr, k * 32 + fq * 8))
; #define LDB8(dst, b, h) _Pragma("unroll") for (int n = 0; n < 2; ++n) _Pragma("unroll") for (int k = 0; k < 2; ++k) \
;     dst[n][k] = *(const bf16x8*)((const char*)SB8(b, h) + lds_byte8(wc * 32 + n * 16 + fr, k * 32 + fq * 8))
; #define WAIT_V8(n) asm volatile("s_waitcnt vmcnt(" #n ")" ::: "memory")
; #define WAIT_L8(n) asm volatile("s_waitcnt lgkmcnt(" #n ")" ::: "memory")
; #define BAR8 __builtin_amdgcn_s_barrier()
; #define SCHED8 __builtin_amdgcn_sched_barrier(0)
;     ...
;   if (wr == 1) BAR8;
;   WAIT_V8(4); BAR8;
;   STAGE8(SB8(1, 0), Bt, K, bcol, 1); STAGE8(SA8(1, 0), A, lda, brow, 1); STAGE8(SB8(1, 1), Bt, K, bcol + 128, 1);
;   WAIT_V8(6); BAR8;
;   for (int tt = 0; tt < nt - 2; tt += 2) {
;     LDB8(B0, 0, 0); SCHED8; LDA8(At, 0, 0); STAGE8(SA8(1, 1), A, lda, brow + 128, tt + 1);
;     WAIT_L8(8); BAR8; WAIT_L8(0); MMA8(0, 0, At, B0); BAR8; SCHED8;
;     LDB8(B1, 0, 1); STAGE8(SB8(0, 0), Bt, K, bcol, tt + 2);
.LBB0_191:
	s_or_b64 exec, exec, s[14:15]
	s_mov_b64 s[60:61], 0x80
	v_lshl_add_u64 v[10:11], v[10:11], 0, s[60:61]
	s_or_b32 m0, s100, 0x18000
	s_waitcnt vmcnt(4)
	s_barrier
	global_load_lds_dwordx4 v[10:11], off
	v_lshl_add_u64 v[10:11], v[12:13], 0, s[60:61]
	s_or_b32 m0, s100, 0x1a000
	global_load_lds_dwordx4 v[10:11], off
	v_lshl_add_u64 v[10:11], v[14:15], 0, s[60:61]
	s_or_b32 m0, s100, 0x8000
	global_load_lds_dwordx4 v[10:11], off
	v_lshl_add_u64 v[10:11], v[16:17], 0, s[60:61]
	s_or_b32 m0, s100, 0xa000
	global_load_lds_dwordx4 v[10:11], off
	s_or_b32 m0, s100, 0x1c000
	v_lshl_add_u64 v[10:11], v[18:19], 0, s[60:61]
	global_load_lds_dwordx4 v[10:11], off
	v_lshl_add_u64 v[10:11], v[20:21], 0, s[60:61]
	s_or_b32 m0, s100, 0x1e000
	v_and_b32_e32 v147, 15, v3
	global_load_lds_dwordx4 v[10:11], off
	v_bfe_u32 v148, v3, 4, 2
	v_lshlrev_b32_e32 v10, 4, v148
	v_lshlrev_b32_e32 v11, 6, v147
	v_lshlrev_b32_e32 v14, 2, v3
	v_or_b32_e32 v13, v10, v11
	v_and_b32_e32 v14, 32, v14
	s_mov_b32 s14, 0x10000
	v_bitop3_b32 v16, v13, s14, v14 bitop3:0xde
	s_mov_b32 s14, 0x14000
	v_bitop3_b32 v15, v10, v14, v11 bitop3:0x36
	v_bitop3_b32 v17, v13, s14, v14 bitop3:0xde
	s_mov_b32 s14, 0x18000
	v_lshlrev_b32_e32 v11, 6, v3
	v_bitop3_b32 v18, v13, s14, v14 bitop3:0xde
	s_mov_b32 s14, 0x1c000
	v_and_b32_e32 v11, 0x3c0, v11
	v_bitop3_b32 v13, v13, s14, v14 bitop3:0xde
	v_bitop3_b32 v14, v11, v14, v10 bitop3:0x36
	v_lshl_add_u64 v[10:11], s[30:31], 0, v[136:137]
	v_lshl_add_u64 v[10:11], v[10:11], 0, v[8:9]
	v_lshl_add_u64 v[138:139], s[12:13], 0, v[10:11]
	v_lshl_add_u64 v[10:11], s[30:31], 0, v[132:133]
	v_lshl_add_u64 v[10:11], v[10:11], 0, v[6:7]
	v_lshl_add_u64 v[140:141], s[12:13], 0, v[10:11]
	v_lshl_add_u64 v[10:11], s[56:57], 0, v[132:133]
	v_lshl_add_u64 v[6:7], v[10:11], 0, v[6:7]
	v_bfe_u32 v146, v3, 6, 2
	s_waitcnt vmcnt(6)
	v_lshlrev_b32_e32 v149, 6, v5
	v_lshlrev_b32_e32 v5, 13, v5
	v_lshl_add_u64 v[142:143], s[46:47], 0, v[6:7]
	v_lshl_add_u64 v[6:7], s[56:57], 0, v[136:137]
	v_lshlrev_b32_e32 v12, 12, v146
	v_or_b32_e32 v19, 0x800, v5
	v_or_b32_e32 v20, 0x1000, v5
	v_or_b32_e32 v21, 0x1800, v5
	v_lshl_add_u64 v[6:7], v[6:7], 0, v[8:9]
	v_lshl_add_u64 v[144:145], s[46:47], 0, v[6:7]
	s_mov_b32 s14, -2
	s_mov_b64 s[12:13], 0
	v_add_u32_e32 v173, v16, v12
	v_add_u32_e32 v156, v15, v5
	v_add_u32_e32 v154, v14, v19
	v_add_u32_e32 v153, v14, v20
	v_add_u32_e32 v152, v14, v21
	v_add_u32_e32 v169, v17, v12
	v_add_u32_e32 v159, v18, v12
	v_add_u32_e32 v158, v13, v12
	s_mov_b64 s[60:61], 0xc000100
	s_mov_b64 s[62:63], 0xc040100
	s_mov_b64 s[64:65], 0xc000180
	s_mov_b64 s[66:67], 0xc040180
	s_barrier
	ds_read_b128 v[174:177], v173
	ds_read_b128 v[178:181], v173 offset:1024
	ds_read_b128 v[182:185], v173 offset:2048
	ds_read_b128 v[186:189], v173 offset:3072
	v_lshl_add_u64 v[222:223], v[140:141], 0, s[12:13]
	v_lshl_add_u64 v[226:227], v[222:223], 0, s[34:35]
	s_or_b32 m0, s100, 0xc000
	ds_read_b128 v[190:193], v156
	ds_read_b128 v[194:197], v156 offset:1024
	ds_read_b128 v[198:201], v154
	ds_read_b128 v[202:205], v154 offset:1024
	ds_read_b128 v[206:209], v153
	ds_read_b128 v[210:213], v153 offset:1024
	ds_read_b128 v[214:217], v152
	ds_read_b128 v[218:221], v152 offset:1024
	global_load_lds_dwordx4 v[226:227], off
	v_lshl_add_u64 v[226:227], v[138:139], 0, s[12:13]
	s_or_b32 m0, s100, 0xe000
	v_lshl_add_u64 v[228:229], v[226:227], 0, s[34:35]
	global_load_lds_dwordx4 v[228:229], off
	s_waitcnt lgkmcnt(8)
	s_barrier
	s_waitcnt lgkmcnt(0)
	v_mfma_f32_16x16x32_f16 v[128:131], v[190:193], v[174:177], 0
	v_mfma_f32_16x16x32_f16 v[124:127], v[190:193], v[182:185], 0
	v_mfma_f32_16x16x32_f16 v[120:123], v[198:201], v[174:177], 0
	v_mfma_f32_16x16x32_f16 v[116:119], v[198:201], v[182:185], 0
	v_mfma_f32_16x16x32_f16 v[112:115], v[206:209], v[174:177], 0
	v_mfma_f32_16x16x32_f16 v[108:111], v[206:209], v[182:185], 0
	v_mfma_f32_16x16x32_f16 v[104:107], v[214:217], v[174:177], 0
	v_mfma_f32_16x16x32_f16 v[100:103], v[214:217], v[182:185], 0
	v_mfma_f32_16x16x32_f16 v[128:131], v[194:197], v[178:181], v[128:131]
	v_mfma_f32_16x16x32_f16 v[124:127], v[194:197], v[186:189], v[124:127]
	v_mfma_f32_16x16x32_f16 v[120:123], v[202:205], v[178:181], v[120:123]
	v_mfma_f32_16x16x32_f16 v[116:119], v[202:205], v[186:189], v[116:119]
	v_mfma_f32_16x16x32_f16 v[112:115], v[210:213], v[178:181], v[112:115]
	v_mfma_f32_16x16x32_f16 v[108:111], v[210:213], v[186:189], v[108:111]
	v_mfma_f32_16x16x32_f16 v[104:107], v[218:221], v[178:181], v[104:107]
	v_mfma_f32_16x16x32_f16 v[100:103], v[218:221], v[186:189], v[100:103]
	s_barrier
	v_lshl_add_u64 v[228:229], v[142:143], 0, s[12:13]
	v_lshl_add_u64 v[236:237], v[228:229], 0, s[60:61]
	s_or_b32 m0, s100, 0x10000
	ds_read_b128 v[238:241], v169
	ds_read_b128 v[242:245], v169 offset:1024
	ds_read_b128 v[246:249], v169 offset:2048
	ds_read_b128 v[230:233], v169 offset:3072
	global_load_lds_dwordx4 v[236:237], off
	v_lshl_add_u64 v[236:237], v[144:145], 0, s[12:13]
	s_or_b32 m0, s100, 0x12000
	v_lshl_add_u64 v[250:251], v[236:237], 0, s[60:61]
	global_load_lds_dwordx4 v[250:251], off
	s_barrier
; #define LDA8(dst, b, h) _Pragma("unroll") for (int m = 0; m < 4; ++m) _Pragma("unroll") for (int k = 0; k < 2; ++k) \
;     dst[m][k] = *(const bf16x8*)((const char*)SA8(b, h) + lds_byte8(wr * 64 + m * 16 + fr, k * 32 + fq * 8))
; #define LDB8(dst, b, h) _Pragma("unroll") for (int n = 0; n < 2; ++n) _Pragma("unroll") for (int k = 0; k < 2; ++k) \
;     dst[n][k] = *(const bf16x8*)((const char*)SB8(b, h) + lds_byte8(wc * 32 + n * 16 + fr, k * 32 + fq * 8))
; #define WAIT_V8(n) asm volatile("s_waitcnt vmcnt(" #n ")" ::: "memory")
; #define WAIT_L8(n) asm volatile("s_waitcnt lgkmcnt(" #n ")" ::: "memory")
; #define BAR8 __builtin_amdgcn_s_barrier()
; #define SCHED8 __builtin_amdgcn_sched_barrier(0)
;     ...
;     WAIT_L8(8); BAR8; WAIT_L8(0); MMA8(0, 0, At, B0); BAR8; SCHED8;
;     LDB8(B1, 0, 1); STAGE8(SB8(0, 0), Bt, K, bcol, tt + 2);
;     BAR8; WAIT_L8(0); MMA8(0, 1, At, B1); BAR8;
;     LDA8(At, 0, 1); STAGE8(SA8(0, 0), A, lda, brow, tt + 2);
;     BAR8; WAIT_L8(0); MMA8(1, 0, At, B0); BAR8; SCHED8;
;     STAGE8(SB8(0, 1), Bt, K, bcol + 128, tt + 2);
;     WAIT_V8(6); BAR8; MMA8(1, 1, At, B1); BAR8;
;     LDB8(B0, 1, 0); SCHED8; LDA8(At, 1, 0); STAGE8(SA8(0, 1), A, lda, brow + 128, tt + 2);
;     WAIT_L8(8); BAR8; WAIT_L8(0); MMA8(0, 0, At, B0); BAR8; SCHED8;
	s_waitcnt lgkmcnt(0)
	v_mfma_f32_16x16x32_f16 v[96:99], v[190:193], v[238:241], 0
	v_mfma_f32_16x16x32_f16 v[92:95], v[190:193], v[246:249], 0
	v_mfma_f32_16x16x32_f16 v[88:91], v[198:201], v[238:241], 0
	v_mfma_f32_16x16x32_f16 v[84:87], v[198:201], v[246:249], 0
	v_mfma_f32_16x16x32_f16 v[80:83], v[206:209], v[238:241], 0
	v_mfma_f32_16x16x32_f16 v[76:79], v[206:209], v[246:249], 0
	v_mfma_f32_16x16x32_f16 v[72:75], v[214:217], v[238:241], 0
	v_mfma_f32_16x16x32_f16 v[68:71], v[214:217], v[246:249], 0
	v_mfma_f32_16x16x32_f16 v[96:99], v[194:197], v[242:245], v[96:99]
	v_mfma_f32_16x16x32_f16 v[92:95], v[194:197], v[230:233], v[92:95]
	v_mfma_f32_16x16x32_f16 v[88:91], v[202:205], v[242:245], v[88:91]
	v_mfma_f32_16x16x32_f16 v[84:87], v[202:205], v[230:233], v[84:87]
	v_mfma_f32_16x16x32_f16 v[80:83], v[210:213], v[242:245], v[80:83]
	v_mfma_f32_16x16x32_f16 v[76:79], v[210:213], v[230:233], v[76:79]
	v_mfma_f32_16x16x32_f16 v[72:75], v[218:221], v[242:245], v[72:75]
	v_mfma_f32_16x16x32_f16 v[68:71], v[218:221], v[230:233], v[68:71]
	v_lshl_add_u64 v[250:251], v[222:223], 0, s[10:11]
	s_mov_b32 m0, s100
	s_barrier
	ds_read_b128 v[190:193], v156 offset:16384
	ds_read_b128 v[194:197], v156 offset:17408
	ds_read_b128 v[198:201], v154 offset:16384
	ds_read_b128 v[202:205], v154 offset:17408
	ds_read_b128 v[206:209], v153 offset:16384
	ds_read_b128 v[210:213], v153 offset:17408
	ds_read_b128 v[214:217], v152 offset:16384
	ds_read_b128 v[218:221], v152 offset:17408
	global_load_lds_dwordx4 v[250:251], off
	s_or_b32 m0, s100, 0x2000
	v_lshl_add_u64 v[250:251], v[226:227], 0, s[10:11]
	global_load_lds_dwordx4 v[250:251], off
	s_barrier
	s_waitcnt lgkmcnt(0)
	v_mfma_f32_16x16x32_f16 v[64:67], v[190:193], v[174:177], 0
	v_mfma_f32_16x16x32_f16 v[60:63], v[190:193], v[182:185], 0
	v_mfma_f32_16x16x32_f16 v[56:59], v[198:201], v[174:177], 0
	v_mfma_f32_16x16x32_f16 v[52:55], v[198:201], v[182:185], 0
	v_mfma_f32_16x16x32_f16 v[48:51], v[206:209], v[174:177], 0
	v_mfma_f32_16x16x32_f16 v[44:47], v[206:209], v[182:185], 0
	v_mfma_f32_16x16x32_f16 v[40:43], v[214:217], v[174:177], 0
	v_mfma_f32_16x16x32_f16 v[36:39], v[214:217], v[182:185], 0
	v_mfma_f32_16x16x32_f16 v[64:67], v[194:197], v[178:181], v[64:67]
	v_mfma_f32_16x16x32_f16 v[60:63], v[194:197], v[186:189], v[60:63]
	v_mfma_f32_16x16x32_f16 v[56:59], v[202:205], v[178:181], v[56:59]
	v_mfma_f32_16x16x32_f16 v[52:55], v[202:205], v[186:189], v[52:55]
	v_mfma_f32_16x16x32_f16 v[48:51], v[210:213], v[178:181], v[48:51]
	v_mfma_f32_16x16x32_f16 v[44:47], v[210:213], v[186:189], v[44:47]
	v_mfma_f32_16x16x32_f16 v[40:43], v[218:221], v[178:181], v[40:43]
	v_mfma_f32_16x16x32_f16 v[36:39], v[218:221], v[186:189], v[36:39]
	s_barrier
	s_or_b32 m0, s100, 0x14000
	v_lshl_add_u64 v[174:175], v[228:229], 0, s[62:63]
	global_load_lds_dwordx4 v[174:175], off
	s_or_b32 m0, s100, 0x16000
	v_lshl_add_u64 v[174:175], v[236:237], 0, s[62:63]
	global_load_lds_dwordx4 v[174:175], off
	s_waitcnt vmcnt(6)
	s_barrier
	v_mfma_f32_16x16x32_f16 v[32:35], v[190:193], v[238:241], 0
	v_mfma_f32_16x16x32_f16 v[28:31], v[190:193], v[246:249], 0
	v_mfma_f32_16x16x32_f16 v[24:27], v[198:201], v[238:241], 0
	v_mfma_f32_16x16x32_f16 v[20:23], v[198:201], v[246:249], 0
	v_mfma_f32_16x16x32_f16 v[16:19], v[206:209], v[238:241], 0
	v_mfma_f32_16x16x32_f16 v[12:15], v[206:209], v[246:249], 0
	v_mfma_f32_16x16x32_f16 v[8:11], v[214:217], v[238:241], 0
	v_mfma_f32_16x16x32_f16 v[4:7], v[214:217], v[246:249], 0
	v_mfma_f32_16x16x32_f16 v[32:35], v[194:197], v[242:245], v[32:35]
	v_mfma_f32_16x16x32_f16 v[28:31], v[194:197], v[230:233], v[28:31]
	v_mfma_f32_16x16x32_f16 v[24:27], v[202:205], v[242:245], v[24:27]
	v_mfma_f32_16x16x32_f16 v[20:23], v[202:205], v[230:233], v[20:23]
	v_mfma_f32_16x16x32_f16 v[16:19], v[210:213], v[242:245], v[16:19]
	v_mfma_f32_16x16x32_f16 v[12:15], v[210:213], v[230:233], v[12:15]
	v_mfma_f32_16x16x32_f16 v[8:11], v[218:221], v[242:245], v[8:11]
	v_mfma_f32_16x16x32_f16 v[4:7], v[218:221], v[230:233], v[4:7]
	s_barrier
	ds_read_b128 v[174:177], v159
	ds_read_b128 v[178:181], v159 offset:1024
	ds_read_b128 v[182:185], v159 offset:2048
	ds_read_b128 v[186:189], v159 offset:3072
	v_lshl_add_u64 v[230:231], v[222:223], 0, s[18:19]
	s_or_b32 m0, s100, 0x4000
	ds_read_b128 v[190:193], v156 offset:32768
	ds_read_b128 v[194:197], v156 offset:33792
	ds_read_b128 v[198:201], v154 offset:32768
	ds_read_b128 v[202:205], v154 offset:33792
	ds_read_b128 v[206:209], v153 offset:32768
	ds_read_b128 v[210:213], v153 offset:33792
	ds_read_b128 v[214:217], v152 offset:32768
	ds_read_b128 v[218:221], v152 offset:33792
	global_load_lds_dwordx4 v[230:231], off
	s_or_b32 m0, s100, 0x6000
	v_lshl_add_u64 v[230:231], v[226:227], 0, s[18:19]
	global_load_lds_dwordx4 v[230:231], off
	s_waitcnt lgkmcnt(8)
	s_barrier
	s_waitcnt lgkmcnt(0)
	v_mfma_f32_16x16x32_f16 v[128:131], v[190:193], v[174:177], v[128:131]
	v_mfma_f32_16x16x32_f16 v[124:127], v[190:193], v[182:185], v[124:127]
	v_mfma_f32_16x16x32_f16 v[120:123], v[198:201], v[174:177], v[120:123]
	v_mfma_f32_16x16x32_f16 v[116:119], v[198:201], v[182:185], v[116:119]
	v_mfma_f32_16x16x32_f16 v[112:115], v[206:209], v[174:177], v[112:115]
	v_mfma_f32_16x16x32_f16 v[108:111], v[206:209], v[182:185], v[108:111]
	v_mfma_f32_16x16x32_f16 v[104:107], v[214:217], v[174:177], v[104:107]
	v_mfma_f32_16x16x32_f16 v[100:103], v[214:217], v[182:185], v[100:103]
	v_mfma_f32_16x16x32_f16 v[128:131], v[194:197], v[178:181], v[128:131]
	v_mfma_f32_16x16x32_f16 v[124:127], v[194:197], v[186:189], v[124:127]
	v_mfma_f32_16x16x32_f16 v[120:123], v[202:205], v[178:181], v[120:123]
	v_mfma_f32_16x16x32_f16 v[116:119], v[202:205], v[186:189], v[116:119]
	v_mfma_f32_16x16x32_f16 v[112:115], v[210:213], v[178:181], v[112:115]
	v_mfma_f32_16x16x32_f16 v[108:111], v[210:213], v[186:189], v[108:111]
	v_mfma_f32_16x16x32_f16 v[104:107], v[218:221], v[178:181], v[104:107]
	v_mfma_f32_16x16x32_f16 v[100:103], v[218:221], v[186:189], v[100:103]
	s_barrier
; #define LDA8(dst, b, h) _Pragma("unroll") for (int m = 0; m < 4; ++m) _Pragma("unroll") for (int k = 0; k < 2; ++k) \
;     dst[m][k] = *(const bf16x8*)((const char*)SA8(b, h) + lds_byte8(wr * 64 + m * 16 + fr, k * 32 + fq * 8))
; #define LDB8(dst, b, h) _Pragma("unroll") for (int n = 0; n < 2; ++n) _Pragma("unroll") for (int k = 0; k < 2; ++k) \
;     dst[n][k] = *(const bf16x8*)((const char*)SB8(b, h) + lds_byte8(wc * 32 + n * 16 + fr, k * 32 + fq * 8))
; #define WAIT_V8(n) asm volatile("s_waitcnt vmcnt(" #n ")" ::: "memory")
; #define WAIT_L8(n) asm volatile("s_waitcnt lgkmcnt(" #n ")" ::: "memory")
; #define BAR8 __builtin_amdgcn_s_barrier()
; #define SCHED8 __builtin_amdgcn_sched_barrier(0)
;     ...
;     WAIT_L8(8); BAR8; WAIT_L8(0); MMA8(0, 0, At, B0); BAR8; SCHED8;
;     LDB8(B1, 1, 1); STAGE8(SB8(1, 0), Bt, K, bcol, tt + 3);
;     BAR8; WAIT_L8(0); MMA8(0, 1, At, B1); BAR8;
;     LDA8(At, 1, 1); STAGE8(SA8(1, 0), A, lda, brow, tt + 3);
;     BAR8; WAIT_L8(0); MMA8(1, 0, At, B0); BAR8; SCHED8;
;     STAGE8(SB8(1, 1), Bt, K, bcol + 128, tt + 3);
;     WAIT_V8(6); BAR8; MMA8(1, 1, At, B1); BAR8;
;   }
	v_lshl_add_u64 v[250:251], v[228:229], 0, s[64:65]
	s_or_b32 m0, s100, 0x18000
	ds_read_b128 v[230:233], v158
	ds_read_b128 v[238:241], v158 offset:1024
	ds_read_b128 v[242:245], v158 offset:2048
	ds_read_b128 v[246:249], v158 offset:3072
	global_load_lds_dwordx4 v[250:251], off
	s_or_b32 m0, s100, 0x1a000
	v_lshl_add_u64 v[250:251], v[236:237], 0, s[64:65]
	global_load_lds_dwordx4 v[250:251], off
	s_barrier
	s_waitcnt lgkmcnt(0)
	v_mfma_f32_16x16x32_f16 v[96:99], v[190:193], v[230:233], v[96:99]
	v_mfma_f32_16x16x32_f16 v[92:95], v[190:193], v[242:245], v[92:95]
	v_mfma_f32_16x16x32_f16 v[88:91], v[198:201], v[230:233], v[88:91]
	v_mfma_f32_16x16x32_f16 v[84:87], v[198:201], v[242:245], v[84:87]
	v_mfma_f32_16x16x32_f16 v[80:83], v[206:209], v[230:233], v[80:83]
	v_mfma_f32_16x16x32_f16 v[76:79], v[206:209], v[242:245], v[76:79]
	v_mfma_f32_16x16x32_f16 v[72:75], v[214:217], v[230:233], v[72:75]
	v_mfma_f32_16x16x32_f16 v[68:71], v[214:217], v[242:245], v[68:71]
	v_mfma_f32_16x16x32_f16 v[96:99], v[194:197], v[238:241], v[96:99]
	v_mfma_f32_16x16x32_f16 v[92:95], v[194:197], v[246:249], v[92:95]
	v_mfma_f32_16x16x32_f16 v[88:91], v[202:205], v[238:241], v[88:91]
	v_mfma_f32_16x16x32_f16 v[84:87], v[202:205], v[246:249], v[84:87]
	v_mfma_f32_16x16x32_f16 v[80:83], v[210:213], v[238:241], v[80:83]
	v_mfma_f32_16x16x32_f16 v[76:79], v[210:213], v[246:249], v[76:79]
	v_mfma_f32_16x16x32_f16 v[72:75], v[218:221], v[238:241], v[72:75]
	v_mfma_f32_16x16x32_f16 v[68:71], v[218:221], v[246:249], v[68:71]
	v_lshl_add_u64 v[222:223], v[222:223], 0, s[22:23]
	s_or_b32 m0, s100, 0x8000
	s_barrier
	ds_read_b128 v[190:193], v156 offset:49152
	ds_read_b128 v[194:197], v156 offset:50176
	ds_read_b128 v[198:201], v154 offset:49152
	ds_read_b128 v[202:205], v154 offset:50176
	ds_read_b128 v[206:209], v153 offset:49152
	ds_read_b128 v[210:213], v153 offset:50176
	ds_read_b128 v[214:217], v152 offset:49152
	ds_read_b128 v[218:221], v152 offset:50176
	global_load_lds_dwordx4 v[222:223], off
	s_or_b32 m0, s100, 0xa000
	v_lshl_add_u64 v[222:223], v[226:227], 0, s[22:23]
	global_load_lds_dwordx4 v[222:223], off
	s_barrier
	s_waitcnt lgkmcnt(0)
	v_mfma_f32_16x16x32_f16 v[64:67], v[190:193], v[174:177], v[64:67]
	v_mfma_f32_16x16x32_f16 v[60:63], v[190:193], v[182:185], v[60:63]
	v_mfma_f32_16x16x32_f16 v[56:59], v[198:201], v[174:177], v[56:59]
	v_mfma_f32_16x16x32_f16 v[52:55], v[198:201], v[182:185], v[52:55]
	v_mfma_f32_16x16x32_f16 v[48:51], v[206:209], v[174:177], v[48:51]
	v_mfma_f32_16x16x32_f16 v[44:47], v[206:209], v[182:185], v[44:47]
	v_mfma_f32_16x16x32_f16 v[40:43], v[214:217], v[174:177], v[40:43]
	v_mfma_f32_16x16x32_f16 v[36:39], v[214:217], v[182:185], v[36:39]
	v_mfma_f32_16x16x32_f16 v[64:67], v[194:197], v[178:181], v[64:67]
	v_mfma_f32_16x16x32_f16 v[60:63], v[194:197], v[186:189], v[60:63]
	v_mfma_f32_16x16x32_f16 v[56:59], v[202:205], v[178:181], v[56:59]
	v_mfma_f32_16x16x32_f16 v[52:55], v[202:205], v[186:189], v[52:55]
	v_mfma_f32_16x16x32_f16 v[48:51], v[210:213], v[178:181], v[48:51]
	v_mfma_f32_16x16x32_f16 v[44:47], v[210:213], v[186:189], v[44:47]
	v_mfma_f32_16x16x32_f16 v[40:43], v[218:221], v[178:181], v[40:43]
	v_mfma_f32_16x16x32_f16 v[36:39], v[218:221], v[186:189], v[36:39]
	s_barrier
	s_or_b32 m0, s100, 0x1c000
	v_lshl_add_u64 v[174:175], v[228:229], 0, s[66:67]
	global_load_lds_dwordx4 v[174:175], off
	s_or_b32 m0, s100, 0x1e000
	v_lshl_add_u64 v[174:175], v[236:237], 0, s[66:67]
	global_load_lds_dwordx4 v[174:175], off
	s_waitcnt vmcnt(6)
	s_barrier
	v_mfma_f32_16x16x32_f16 v[32:35], v[190:193], v[230:233], v[32:35]
	v_mfma_f32_16x16x32_f16 v[28:31], v[190:193], v[242:245], v[28:31]
	v_mfma_f32_16x16x32_f16 v[24:27], v[198:201], v[230:233], v[24:27]
	v_mfma_f32_16x16x32_f16 v[20:23], v[198:201], v[242:245], v[20:23]
	v_mfma_f32_16x16x32_f16 v[16:19], v[206:209], v[230:233], v[16:19]
	v_mfma_f32_16x16x32_f16 v[12:15], v[206:209], v[242:245], v[12:15]
	v_mfma_f32_16x16x32_f16 v[8:11], v[214:217], v[230:233], v[8:11]
	v_mfma_f32_16x16x32_f16 v[4:7], v[214:217], v[242:245], v[4:7]
	v_mfma_f32_16x16x32_f16 v[32:35], v[194:197], v[238:241], v[32:35]
	v_mfma_f32_16x16x32_f16 v[28:31], v[194:197], v[246:249], v[28:31]
	v_mfma_f32_16x16x32_f16 v[24:27], v[202:205], v[238:241], v[24:27]
	v_mfma_f32_16x16x32_f16 v[20:23], v[202:205], v[246:249], v[20:23]
	v_mfma_f32_16x16x32_f16 v[16:19], v[210:213], v[238:241], v[16:19]
	v_mfma_f32_16x16x32_f16 v[12:15], v[210:213], v[246:249], v[12:15]
	v_mfma_f32_16x16x32_f16 v[8:11], v[218:221], v[238:241], v[8:11]
	v_mfma_f32_16x16x32_f16 v[4:7], v[218:221], v[246:249], v[4:7]
	s_add_i32 s14, s14, 2
	s_add_u32 s12, s12, 0x100
	s_addc_u32 s13, s13, 0
	s_cmp_lt_u32 s14, 12
	s_cbranch_scc0 .Lpk_exitb_0
; #define LDA8(dst, b, h) _Pragma("unroll") for (int m = 0; m < 4; ++m) _Pragma("unroll") for (int k = 0; k < 2; ++k) \
;     dst[m][k] = *(const bf16x8*)((const char*)SA8(b, h) + lds_byte8(wr * 64 + m * 16 + fr, k * 32 + fq * 8))
; #define LDB8(dst, b, h) _Pragma("unroll") for (int n = 0; n < 2; ++n) _Pragma("unroll") for (int k = 0; k < 2; ++k) \
;     dst[n][k] = *(const bf16x8*)((const char*)SB8(b, h) + lds_byte8(wc * 32 + n * 16 + fr, k * 32 + fq * 8))
; #define WAIT_V8(n) asm volatile("s_waitcnt vmcnt(" #n ")" ::: "memory")
; #define WAIT_L8(n) asm volatile("s_waitcnt lgkmcnt(" #n ")" ::: "memory")
; #define BAR8 __builtin_amdgcn_s_barrier()
; #define SCHED8 __builtin_amdgcn_sched_barrier(0)
;     ...
;   for (int tt = 0; tt < nt - 2; tt += 2) {
;     LDB8(B0, 0, 0); SCHED8; LDA8(At, 0, 0); STAGE8(SA8(1, 1), A, lda, brow + 128, tt + 1);
;     WAIT_L8(8); BAR8; WAIT_L8(0); MMA8(0, 0, At, B0); BAR8; SCHED8;
;     LDB8(B1, 0, 1); STAGE8(SB8(0, 0), Bt, K, bcol, tt + 2);
;     BAR8; WAIT_L8(0); MMA8(0, 1, At, B1); BAR8;
;     LDA8(At, 0, 1); STAGE8(SA8(0, 0), A, lda, brow, tt + 2);
;     BAR8; WAIT_L8(0); MMA8(1, 0, At, B0); BAR8; SCHED8;
;     STAGE8(SB8(0, 1), Bt, K, bcol + 128, tt + 2);
;     WAIT_V8(6); BAR8; MMA8(1, 1, At, B1); BAR8;
.LBB0_192:
	s_barrier
	ds_read_b128 v[174:177], v173
	ds_read_b128 v[178:181], v173 offset:1024
	ds_read_b128 v[182:185], v173 offset:2048
	ds_read_b128 v[186:189], v173 offset:3072
	v_lshl_add_u64 v[222:223], v[140:141], 0, s[12:13]
	v_lshl_add_u64 v[226:227], v[222:223], 0, s[34:35]
	s_or_b32 m0, s100, 0xc000
	ds_read_b128 v[190:193], v156
	ds_read_b128 v[194:197], v156 offset:1024
	ds_read_b128 v[198:201], v154
	ds_read_b128 v[202:205], v154 offset:1024
	ds_read_b128 v[206:209], v153
	ds_read_b128 v[210:213], v153 offset:1024
	ds_read_b128 v[214:217], v152
	ds_read_b128 v[218:221], v152 offset:1024
	global_load_lds_dwordx4 v[226:227], off
	v_lshl_add_u64 v[226:227], v[138:139], 0, s[12:13]
	s_or_b32 m0, s100, 0xe000
	v_lshl_add_u64 v[228:229], v[226:227], 0, s[34:35]
	global_load_lds_dwordx4 v[228:229], off
	s_waitcnt lgkmcnt(8)
	s_barrier
	s_waitcnt lgkmcnt(0)
	v_mfma_f32_16x16x32_f16 v[128:131], v[190:193], v[174:177], v[128:131]
	v_mfma_f32_16x16x32_f16 v[124:127], v[190:193], v[182:185], v[124:127]
	v_mfma_f32_16x16x32_f16 v[120:123], v[198:201], v[174:177], v[120:123]
	v_mfma_f32_16x16x32_f16 v[116:119], v[198:201], v[182:185], v[116:119]
	v_mfma_f32_16x16x32_f16 v[112:115], v[206:209], v[174:177], v[112:115]
	v_mfma_f32_16x16x32_f16 v[108:111], v[206:209], v[182:185], v[108:111]
	v_mfma_f32_16x16x32_f16 v[104:107], v[214:217], v[174:177], v[104:107]
	v_mfma_f32_16x16x32_f16 v[100:103], v[214:217], v[182:185], v[100:103]
	v_mfma_f32_16x16x32_f16 v[128:131], v[194:197], v[178:181], v[128:131]
	v_mfma_f32_16x16x32_f16 v[124:127], v[194:197], v[186:189], v[124:127]
	v_mfma_f32_16x16x32_f16 v[120:123], v[202:205], v[178:181], v[120:123]
	v_mfma_f32_16x16x32_f16 v[116:119], v[202:205], v[186:189], v[116:119]
	v_mfma_f32_16x16x32_f16 v[112:115], v[210:213], v[178:181], v[112:115]
	v_mfma_f32_16x16x32_f16 v[108:111], v[210:213], v[186:189], v[108:111]
	v_mfma_f32_16x16x32_f16 v[104:107], v[218:221], v[178:181], v[104:107]
	v_mfma_f32_16x16x32_f16 v[100:103], v[218:221], v[186:189], v[100:103]
	s_barrier
	v_lshl_add_u64 v[228:229], v[142:143], 0, s[12:13]
	v_lshl_add_u64 v[236:237], v[228:229], 0, s[60:61]
	s_or_b32 m0, s100, 0x10000
	ds_read_b128 v[238:241], v169
	ds_read_b128 v[242:245], v169 offset:1024
	ds_read_b128 v[246:249], v169 offset:2048
	ds_read_b128 v[230:233], v169 offset:3072
	global_load_lds_dwordx4 v[236:237], off
	v_lshl_add_u64 v[236:237], v[144:145], 0, s[12:13]
	s_or_b32 m0, s100, 0x12000
	v_lshl_add_u64 v[250:251], v[236:237], 0, s[60:61]
	global_load_lds_dwordx4 v[250:251], off
	s_barrier
	s_waitcnt lgkmcnt(0)
	v_mfma_f32_16x16x32_f16 v[96:99], v[190:193], v[238:241], v[96:99]
	v_mfma_f32_16x16x32_f16 v[92:95], v[190:193], v[246:249], v[92:95]
	v_mfma_f32_16x16x32_f16 v[88:91], v[198:201], v[238:241], v[88:91]
	v_mfma_f32_16x16x32_f16 v[84:87], v[198:201], v[246:249], v[84:87]
	v_mfma_f32_16x16x32_f16 v[80:83], v[206:209], v[238:241], v[80:83]
	v_mfma_f32_16x16x32_f16 v[76:79], v[206:209], v[246:249], v[76:79]
	v_mfma_f32_16x16x32_f16 v[72:75], v[214:217], v[238:241], v[72:75]
	v_mfma_f32_16x16x32_f16 v[68:71], v[214:217], v[246:249], v[68:71]
	v_mfma_f32_16x16x32_f16 v[96:99], v[194:197], v[242:245], v[96:99]
	v_mfma_f32_16x16x32_f16 v[92:95], v[194:197], v[230:233], v[92:95]
	v_mfma_f32_16x16x32_f16 v[88:91], v[202:205], v[242:245], v[88:91]
	v_mfma_f32_16x16x32_f16 v[84:87], v[202:205], v[230:233], v[84:87]
	v_mfma_f32_16x16x32_f16 v[80:83], v[210:213], v[242:245], v[80:83]
	v_mfma_f32_16x16x32_f16 v[76:79], v[210:213], v[230:233], v[76:79]
	v_mfma_f32_16x16x32_f16 v[72:75], v[218:221], v[242:245], v[72:75]
	v_mfma_f32_16x16x32_f16 v[68:71], v[218:221], v[230:233], v[68:71]
	v_lshl_add_u64 v[250:251], v[222:223], 0, s[10:11]
	s_mov_b32 m0, s100
	s_barrier
	ds_read_b128 v[190:193], v156 offset:16384
	ds_read_b128 v[194:197], v156 offset:17408
	ds_read_b128 v[198:201], v154 offset:16384
	ds_read_b128 v[202:205], v154 offset:17408
	ds_read_b128 v[206:209], v153 offset:16384
	ds_read_b128 v[210:213], v153 offset:17408
	ds_read_b128 v[214:217], v152 offset:16384
	ds_read_b128 v[218:221], v152 offset:17408
	global_load_lds_dwordx4 v[250:251], off
	s_or_b32 m0, s100, 0x2000
	v_lshl_add_u64 v[250:251], v[226:227], 0, s[10:11]
	global_load_lds_dwordx4 v[250:251], off
	s_barrier
	s_waitcnt lgkmcnt(0)
	v_mfma_f32_16x16x32_f16 v[64:67], v[190:193], v[174:177], v[64:67]
	v_mfma_f32_16x16x32_f16 v[60:63], v[190:193], v[182:185], v[60:63]
	v_mfma_f32_16x16x32_f16 v[56:59], v[198:201], v[174:177], v[56:59]
	v_mfma_f32_16x16x32_f16 v[52:55], v[198:201], v[182:185], v[52:55]
	v_mfma_f32_16x16x32_f16 v[48:51], v[206:209], v[174:177], v[48:51]
	v_mfma_f32_16x16x32_f16 v[44:47], v[206:209], v[182:185], v[44:47]
	v_mfma_f32_16x16x32_f16 v[40:43], v[214:217], v[174:177], v[40:43]
	v_mfma_f32_16x16x32_f16 v[36:39], v[214:217], v[182:185], v[36:39]
	v_mfma_f32_16x16x32_f16 v[64:67], v[194:197], v[178:181], v[64:67]
	v_mfma_f32_16x16x32_f16 v[60:63], v[194:197], v[186:189], v[60:63]
	v_mfma_f32_16x16x32_f16 v[56:59], v[202:205], v[178:181], v[56:59]
	v_mfma_f32_16x16x32_f16 v[52:55], v[202:205], v[186:189], v[52:55]
	v_mfma_f32_16x16x32_f16 v[48:51], v[210:213], v[178:181], v[48:51]
	v_mfma_f32_16x16x32_f16 v[44:47], v[210:213], v[186:189], v[44:47]
	v_mfma_f32_16x16x32_f16 v[40:43], v[218:221], v[178:181], v[40:43]
	v_mfma_f32_16x16x32_f16 v[36:39], v[218:221], v[186:189], v[36:39]
	s_barrier
	s_or_b32 m0, s100, 0x14000
	v_lshl_add_u64 v[174:175], v[228:229], 0, s[62:63]
	global_load_lds_dwordx4 v[174:175], off
	s_or_b32 m0, s100, 0x16000
	v_lshl_add_u64 v[174:175], v[236:237], 0, s[62:63]
	global_load_lds_dwordx4 v[174:175], off
	s_waitcnt vmcnt(6)
	s_barrier
; #define LDA8(dst, b, h) _Pragma("unroll") for (int m = 0; m < 4; ++m) _Pragma("unroll") for (int k = 0; k < 2; ++k) \
;     dst[m][k] = *(const bf16x8*)((const char*)SA8(b, h) + lds_byte8(wr * 64 + m * 16 + fr, k * 32 + fq * 8))
; #define LDB8(dst, b, h) _Pragma("unroll") for (int n = 0; n < 2; ++n) _Pragma("unroll") for (int k = 0; k < 2; ++k) \
;     dst[n][k] = *(const bf16x8*)((const char*)SB8(b, h) + lds_byte8(wc * 32 + n * 16 + fr, k * 32 + fq * 8))
; #define WAIT_V8(n) asm volatile("s_waitcnt vmcnt(" #n ")" ::: "memory")
; #define WAIT_L8(n) asm volatile("s_waitcnt lgkmcnt(" #n ")" ::: "memory")
; #define BAR8 __builtin_amdgcn_s_barrier()
; #define SCHED8 __builtin_amdgcn_sched_barrier(0)
;     ...
;     WAIT_V8(6); BAR8; MMA8(1, 1, At, B1); BAR8;
;     LDB8(B0, 1, 0); SCHED8; LDA8(At, 1, 0); STAGE8(SA8(0, 1), A, lda, brow + 128, tt + 2);
;     WAIT_L8(8); BAR8; WAIT_L8(0); MMA8(0, 0, At, B0); BAR8; SCHED8;
;     LDB8(B1, 1, 1); STAGE8(SB8(1, 0), Bt, K, bcol, tt + 3);
;     BAR8; WAIT_L8(0); MMA8(0, 1, At, B1); BAR8;
;     LDA8(At, 1, 1); STAGE8(SA8(1, 0), A, lda, brow, tt + 3);
	v_mfma_f32_16x16x32_f16 v[32:35], v[190:193], v[238:241], v[32:35]
	v_mfma_f32_16x16x32_f16 v[28:31], v[190:193], v[246:249], v[28:31]
	v_mfma_f32_16x16x32_f16 v[24:27], v[198:201], v[238:241], v[24:27]
	v_mfma_f32_16x16x32_f16 v[20:23], v[198:201], v[246:249], v[20:23]
	v_mfma_f32_16x16x32_f16 v[16:19], v[206:209], v[238:241], v[16:19]
	v_mfma_f32_16x16x32_f16 v[12:15], v[206:209], v[246:249], v[12:15]
	v_mfma_f32_16x16x32_f16 v[8:11], v[214:217], v[238:241], v[8:11]
	v_mfma_f32_16x16x32_f16 v[4:7], v[214:217], v[246:249], v[4:7]
	v_mfma_f32_16x16x32_f16 v[32:35], v[194:197], v[242:245], v[32:35]
	v_mfma_f32_16x16x32_f16 v[28:31], v[194:197], v[230:233], v[28:31]
	v_mfma_f32_16x16x32_f16 v[24:27], v[202:205], v[242:245], v[24:27]
	v_mfma_f32_16x16x32_f16 v[20:23], v[202:205], v[230:233], v[20:23]
	v_mfma_f32_16x16x32_f16 v[16:19], v[210:213], v[242:245], v[16:19]
	v_mfma_f32_16x16x32_f16 v[12:15], v[210:213], v[230:233], v[12:15]
	v_mfma_f32_16x16x32_f16 v[8:11], v[218:221], v[242:245], v[8:11]
	v_mfma_f32_16x16x32_f16 v[4:7], v[218:221], v[230:233], v[4:7]
	s_barrier
	ds_read_b128 v[174:177], v159
	ds_read_b128 v[178:181], v159 offset:1024
	ds_read_b128 v[182:185], v159 offset:2048
	ds_read_b128 v[186:189], v159 offset:3072
	v_lshl_add_u64 v[230:231], v[222:223], 0, s[18:19]
	s_or_b32 m0, s100, 0x4000
	ds_read_b128 v[190:193], v156 offset:32768
	ds_read_b128 v[194:197], v156 offset:33792
	ds_read_b128 v[198:201], v154 offset:32768
	ds_read_b128 v[202:205], v154 offset:33792
	ds_read_b128 v[206:209], v153 offset:32768
	ds_read_b128 v[210:213], v153 offset:33792
	ds_read_b128 v[214:217], v152 offset:32768
	ds_read_b128 v[218:221], v152 offset:33792
	global_load_lds_dwordx4 v[230:231], off
	s_or_b32 m0, s100, 0x6000
	v_lshl_add_u64 v[230:231], v[226:227], 0, s[18:19]
	global_load_lds_dwordx4 v[230:231], off
	s_waitcnt lgkmcnt(8)
	s_barrier
	s_waitcnt lgkmcnt(0)
	v_mfma_f32_16x16x32_f16 v[128:131], v[190:193], v[174:177], v[128:131]
	v_mfma_f32_16x16x32_f16 v[124:127], v[190:193], v[182:185], v[124:127]
	v_mfma_f32_16x16x32_f16 v[120:123], v[198:201], v[174:177], v[120:123]
	v_mfma_f32_16x16x32_f16 v[116:119], v[198:201], v[182:185], v[116:119]
	v_mfma_f32_16x16x32_f16 v[112:115], v[206:209], v[174:177], v[112:115]
	v_mfma_f32_16x16x32_f16 v[108:111], v[206:209], v[182:185], v[108:111]
	v_mfma_f32_16x16x32_f16 v[104:107], v[214:217], v[174:177], v[104:107]
	v_mfma_f32_16x16x32_f16 v[100:103], v[214:217], v[182:185], v[100:103]
	v_mfma_f32_16x16x32_f16 v[128:131], v[194:197], v[178:181], v[128:131]
	v_mfma_f32_16x16x32_f16 v[124:127], v[194:197], v[186:189], v[124:127]
	v_mfma_f32_16x16x32_f16 v[120:123], v[202:205], v[178:181], v[120:123]
	v_mfma_f32_16x16x32_f16 v[116:119], v[202:205], v[186:189], v[116:119]
	v_mfma_f32_16x16x32_f16 v[112:115], v[210:213], v[178:181], v[112:115]
	v_mfma_f32_16x16x32_f16 v[108:111], v[210:213], v[186:189], v[108:111]
	v_mfma_f32_16x16x32_f16 v[104:107], v[218:221], v[178:181], v[104:107]
	v_mfma_f32_16x16x32_f16 v[100:103], v[218:221], v[186:189], v[100:103]
	s_barrier
	v_lshl_add_u64 v[250:251], v[228:229], 0, s[64:65]
	s_or_b32 m0, s100, 0x18000
	ds_read_b128 v[230:233], v158
	ds_read_b128 v[238:241], v158 offset:1024
	ds_read_b128 v[242:245], v158 offset:2048
	ds_read_b128 v[246:249], v158 offset:3072
	global_load_lds_dwordx4 v[250:251], off
	s_or_b32 m0, s100, 0x1a000
	v_lshl_add_u64 v[250:251], v[236:237], 0, s[64:65]
	global_load_lds_dwordx4 v[250:251], off
	s_barrier
; #define LDA8(dst, b, h) _Pragma("unroll") for (int m = 0; m < 4; ++m) _Pragma("unroll") for (int k = 0; k < 2; ++k) \
;     dst[m][k] = *(const bf16x8*)((const char*)SA8(b, h) + lds_byte8(wr * 64 + m * 16 + fr, k * 32 + fq * 8))
; #define WAIT_V8(n) asm volatile("s_waitcnt vmcnt(" #n ")" ::: "memory")
; #define WAIT_L8(n) asm volatile("s_waitcnt lgkmcnt(" #n ")" ::: "memory")
; #define BAR8 __builtin_amdgcn_s_barrier()
; #define SCHED8 __builtin_amdgcn_sched_barrier(0)
;     ...
;     LDA8(At, 1, 1); STAGE8(SA8(1, 0), A, lda, brow, tt + 3);
;     BAR8; WAIT_L8(0); MMA8(1, 0, At, B0); BAR8; SCHED8;
;     STAGE8(SB8(1, 1), Bt, K, bcol + 128, tt + 3);
;     WAIT_V8(6); BAR8; MMA8(1, 1, At, B1); BAR8;
;   }
	s_waitcnt lgkmcnt(0)
	v_mfma_f32_16x16x32_f16 v[96:99], v[190:193], v[230:233], v[96:99]
	v_mfma_f32_16x16x32_f16 v[92:95], v[190:193], v[242:245], v[92:95]
	v_mfma_f32_16x16x32_f16 v[88:91], v[198:201], v[230:233], v[88:91]
	v_mfma_f32_16x16x32_f16 v[84:87], v[198:201], v[242:245], v[84:87]
	v_mfma_f32_16x16x32_f16 v[80:83], v[206:209], v[230:233], v[80:83]
	v_mfma_f32_16x16x32_f16 v[76:79], v[206:209], v[242:245], v[76:79]
	v_mfma_f32_16x16x32_f16 v[72:75], v[214:217], v[230:233], v[72:75]
	v_mfma_f32_16x16x32_f16 v[68:71], v[214:217], v[242:245], v[68:71]
	v_mfma_f32_16x16x32_f16 v[96:99], v[194:197], v[238:241], v[96:99]
	v_mfma_f32_16x16x32_f16 v[92:95], v[194:197], v[246:249], v[92:95]
	v_mfma_f32_16x16x32_f16 v[88:91], v[202:205], v[238:241], v[88:91]
	v_mfma_f32_16x16x32_f16 v[84:87], v[202:205], v[246:249], v[84:87]
	v_mfma_f32_16x16x32_f16 v[80:83], v[210:213], v[238:241], v[80:83]
	v_mfma_f32_16x16x32_f16 v[76:79], v[210:213], v[246:249], v[76:79]
	v_mfma_f32_16x16x32_f16 v[72:75], v[218:221], v[238:241], v[72:75]
	v_mfma_f32_16x16x32_f16 v[68:71], v[218:221], v[246:249], v[68:71]
	v_lshl_add_u64 v[222:223], v[222:223], 0, s[22:23]
	s_or_b32 m0, s100, 0x8000
	s_barrier
	ds_read_b128 v[190:193], v156 offset:49152
	ds_read_b128 v[194:197], v156 offset:50176
	ds_read_b128 v[198:201], v154 offset:49152
	ds_read_b128 v[202:205], v154 offset:50176
	ds_read_b128 v[206:209], v153 offset:49152
	ds_read_b128 v[210:213], v153 offset:50176
	ds_read_b128 v[214:217], v152 offset:49152
	ds_read_b128 v[218:221], v152 offset:50176
	global_load_lds_dwordx4 v[222:223], off
	s_or_b32 m0, s100, 0xa000
	v_lshl_add_u64 v[222:223], v[226:227], 0, s[22:23]
	global_load_lds_dwordx4 v[222:223], off
	s_barrier
	s_waitcnt lgkmcnt(0)
	v_mfma_f32_16x16x32_f16 v[64:67], v[190:193], v[174:177], v[64:67]
	v_mfma_f32_16x16x32_f16 v[60:63], v[190:193], v[182:185], v[60:63]
	v_mfma_f32_16x16x32_f16 v[56:59], v[198:201], v[174:177], v[56:59]
	v_mfma_f32_16x16x32_f16 v[52:55], v[198:201], v[182:185], v[52:55]
	v_mfma_f32_16x16x32_f16 v[48:51], v[206:209], v[174:177], v[48:51]
	v_mfma_f32_16x16x32_f16 v[44:47], v[206:209], v[182:185], v[44:47]
	v_mfma_f32_16x16x32_f16 v[40:43], v[214:217], v[174:177], v[40:43]
	v_mfma_f32_16x16x32_f16 v[36:39], v[214:217], v[182:185], v[36:39]
	v_mfma_f32_16x16x32_f16 v[64:67], v[194:197], v[178:181], v[64:67]
	v_mfma_f32_16x16x32_f16 v[60:63], v[194:197], v[186:189], v[60:63]
	v_mfma_f32_16x16x32_f16 v[56:59], v[202:205], v[178:181], v[56:59]
	v_mfma_f32_16x16x32_f16 v[52:55], v[202:205], v[186:189], v[52:55]
	v_mfma_f32_16x16x32_f16 v[48:51], v[210:213], v[178:181], v[48:51]
	v_mfma_f32_16x16x32_f16 v[44:47], v[210:213], v[186:189], v[44:47]
	v_mfma_f32_16x16x32_f16 v[40:43], v[218:221], v[178:181], v[40:43]
	v_mfma_f32_16x16x32_f16 v[36:39], v[218:221], v[186:189], v[36:39]
	s_barrier
	s_or_b32 m0, s100, 0x1c000
	v_lshl_add_u64 v[174:175], v[228:229], 0, s[66:67]
	global_load_lds_dwordx4 v[174:175], off
	s_or_b32 m0, s100, 0x1e000
	v_lshl_add_u64 v[174:175], v[236:237], 0, s[66:67]
	global_load_lds_dwordx4 v[174:175], off
	s_waitcnt vmcnt(6)
	s_barrier
	v_mfma_f32_16x16x32_f16 v[32:35], v[190:193], v[230:233], v[32:35]
	v_mfma_f32_16x16x32_f16 v[28:31], v[190:193], v[242:245], v[28:31]
	v_mfma_f32_16x16x32_f16 v[24:27], v[198:201], v[230:233], v[24:27]
	v_mfma_f32_16x16x32_f16 v[20:23], v[198:201], v[242:245], v[20:23]
	v_mfma_f32_16x16x32_f16 v[16:19], v[206:209], v[230:233], v[16:19]
	v_mfma_f32_16x16x32_f16 v[12:15], v[206:209], v[242:245], v[12:15]
	v_mfma_f32_16x16x32_f16 v[8:11], v[214:217], v[230:233], v[8:11]
	v_mfma_f32_16x16x32_f16 v[4:7], v[214:217], v[242:245], v[4:7]
	v_mfma_f32_16x16x32_f16 v[32:35], v[194:197], v[238:241], v[32:35]
	v_mfma_f32_16x16x32_f16 v[28:31], v[194:197], v[246:249], v[28:31]
	v_mfma_f32_16x16x32_f16 v[24:27], v[202:205], v[238:241], v[24:27]
	v_mfma_f32_16x16x32_f16 v[20:23], v[202:205], v[246:249], v[20:23]
	v_mfma_f32_16x16x32_f16 v[16:19], v[210:213], v[238:241], v[16:19]
	v_mfma_f32_16x16x32_f16 v[12:15], v[210:213], v[246:249], v[12:15]
	v_mfma_f32_16x16x32_f16 v[8:11], v[218:221], v[238:241], v[8:11]
	v_mfma_f32_16x16x32_f16 v[4:7], v[218:221], v[246:249], v[4:7]
	s_add_i32 s14, s14, 2
	s_add_u32 s12, s12, 0x100
	s_addc_u32 s13, s13, 0
	s_cmp_lt_u32 s14, 12
	s_cbranch_scc1 .LBB0_192
.Lpk_exitb_0:
	s_barrier

; #define LDA8(dst, b, h) _Pragma("unroll") for (int m = 0; m < 4; ++m) _Pragma("unroll") for (int k = 0; k < 2; ++k) \
;     dst[m][k] = *(const bf16x8*)((const char*)SA8(b, h) + lds_byte8(wr * 64 + m * 16 + fr, k * 32 + fq * 8))
; #define LDB8(dst, b, h) _Pragma("unroll") for (int n = 0; n < 2; ++n) _Pragma("unroll") for (int k = 0; k < 2; ++k) \
;     dst[n][k] = *(const bf16x8*)((const char*)SB8(b, h) + lds_byte8(wc * 32 + n * 16 + fr, k * 32 + fq * 8))
; #define WAIT_V8(n) asm volatile("s_waitcnt vmcnt(" #n ")" ::: "memory")
; #define WAIT_L8(n) asm volatile("s_waitcnt lgkmcnt(" #n ")" ::: "memory")
; #define BAR8 __builtin_amdgcn_s_barrier()
; #define SCHED8 __builtin_amdgcn_sched_barrier(0)
;     ...
;   if (wr == 1) BAR8;
;   WAIT_V8(4); BAR8;
;   STAGE8(SB8(1, 0), Bt, K, bcol, 1); STAGE8(SA8(1, 0), A, lda, brow, 1); STAGE8(SB8(1, 1), Bt, K, bcol + 128, 1);
;   WAIT_V8(6); BAR8;
;   for (int tt = 0; tt < nt - 2; tt += 2) {
;     LDB8(B0, 0, 0); SCHED8; LDA8(At, 0, 0); STAGE8(SA8(1, 1), A, lda, brow + 128, tt + 1);
;     WAIT_L8(8); BAR8; WAIT_L8(0); MMA8(0, 0, At, B0); BAR8; SCHED8;
;     LDB8(B1, 0, 1); STAGE8(SB8(0, 0), Bt, K, bcol, tt + 2);
.LBB0_241:
	s_or_b64 exec, exec, s[20:21]
	s_mov_b64 s[20:21], 0x80
	v_lshl_add_u64 v[10:11], v[10:11], 0, s[20:21]
	s_or_b32 m0, s100, 0x18000
	s_waitcnt vmcnt(4)
	s_barrier
	global_load_lds_dwordx4 v[10:11], off
	v_lshl_add_u64 v[10:11], v[12:13], 0, s[20:21]
	s_or_b32 m0, s100, 0x1a000
	global_load_lds_dwordx4 v[10:11], off
	v_lshl_add_u64 v[10:11], v[14:15], 0, s[20:21]
	s_or_b32 m0, s100, 0x8000
	global_load_lds_dwordx4 v[10:11], off
	v_lshl_add_u64 v[10:11], v[16:17], 0, s[20:21]
	s_or_b32 m0, s100, 0xa000
	global_load_lds_dwordx4 v[10:11], off
	s_or_b32 m0, s100, 0x1c000
	v_lshl_add_u64 v[10:11], v[18:19], 0, s[20:21]
	global_load_lds_dwordx4 v[10:11], off
	v_lshl_add_u64 v[10:11], v[20:21], 0, s[20:21]
	s_or_b32 m0, s100, 0x1e000
	v_and_b32_e32 v147, 15, v3
	global_load_lds_dwordx4 v[10:11], off
	v_bfe_u32 v148, v3, 4, 2
	v_lshlrev_b32_e32 v10, 4, v148
	v_lshlrev_b32_e32 v11, 6, v147
	v_lshlrev_b32_e32 v14, 2, v3
	v_or_b32_e32 v13, v10, v11
	v_and_b32_e32 v14, 32, v14
	s_mov_b32 s1, 0x10000
	v_bitop3_b32 v16, v13, s1, v14 bitop3:0xde
	s_mov_b32 s1, 0x14000
	v_bitop3_b32 v15, v10, v14, v11 bitop3:0x36
	v_bitop3_b32 v17, v13, s1, v14 bitop3:0xde
	s_mov_b32 s1, 0x18000
	v_lshlrev_b32_e32 v11, 6, v3
	v_bitop3_b32 v18, v13, s1, v14 bitop3:0xde
	s_mov_b32 s1, 0x1c000
	v_and_b32_e32 v11, 0x3c0, v11
	v_bitop3_b32 v13, v13, s1, v14 bitop3:0xde
	v_bitop3_b32 v14, v11, v14, v10 bitop3:0x36
	v_lshl_add_u64 v[10:11], s[30:31], 0, v[136:137]
	v_lshl_add_u64 v[10:11], v[10:11], 0, v[8:9]
	v_lshl_add_u64 v[138:139], s[14:15], 0, v[10:11]
	v_lshl_add_u64 v[10:11], s[30:31], 0, v[132:133]
	v_lshl_add_u64 v[10:11], v[10:11], 0, v[6:7]
	v_lshl_add_u64 v[140:141], s[14:15], 0, v[10:11]
	v_lshl_add_u64 v[10:11], s[56:57], 0, v[132:133]
	v_lshl_add_u64 v[6:7], v[10:11], 0, v[6:7]
	v_bfe_u32 v146, v3, 6, 2
	s_waitcnt vmcnt(6)
	v_lshlrev_b32_e32 v149, 6, v5
	v_lshlrev_b32_e32 v5, 13, v5
	v_lshl_add_u64 v[142:143], s[46:47], 0, v[6:7]
	v_lshl_add_u64 v[6:7], s[56:57], 0, v[136:137]
	v_lshlrev_b32_e32 v12, 12, v146
	v_or_b32_e32 v19, 0x800, v5
	v_or_b32_e32 v20, 0x1000, v5
	v_or_b32_e32 v21, 0x1800, v5
	v_lshl_add_u64 v[6:7], v[6:7], 0, v[8:9]
	v_lshl_add_u64 v[144:145], s[46:47], 0, v[6:7]
	s_mov_b32 s1, -2
	s_mov_b64 s[14:15], 0
	v_add_u32_e32 v171, v16, v12
	v_add_u32_e32 v156, v15, v5
	v_add_u32_e32 v154, v14, v19
	v_add_u32_e32 v153, v14, v20
	v_add_u32_e32 v152, v14, v21
	v_add_u32_e32 v168, v17, v12
	v_add_u32_e32 v159, v18, v12
	v_add_u32_e32 v157, v13, v12
	s_mov_b64 s[30:31], 0xc000100
	s_mov_b64 s[56:57], 0xc040100
	s_mov_b64 s[58:59], 0xc000180
	s_mov_b64 s[60:61], 0xc040180
	s_barrier
	ds_read_b128 v[174:177], v171
	ds_read_b128 v[178:181], v171 offset:1024
	ds_read_b128 v[182:185], v171 offset:2048
	ds_read_b128 v[186:189], v171 offset:3072
	v_lshl_add_u64 v[222:223], v[140:141], 0, s[14:15]
	v_lshl_add_u64 v[226:227], v[222:223], 0, s[34:35]
	s_or_b32 m0, s100, 0xc000
	ds_read_b128 v[190:193], v156
	ds_read_b128 v[194:197], v156 offset:1024
	ds_read_b128 v[198:201], v154
	ds_read_b128 v[202:205], v154 offset:1024
	ds_read_b128 v[206:209], v153
	ds_read_b128 v[210:213], v153 offset:1024
	ds_read_b128 v[214:217], v152
	ds_read_b128 v[218:221], v152 offset:1024
	global_load_lds_dwordx4 v[226:227], off
	v_lshl_add_u64 v[226:227], v[138:139], 0, s[14:15]
	s_or_b32 m0, s100, 0xe000
	v_lshl_add_u64 v[228:229], v[226:227], 0, s[34:35]
	global_load_lds_dwordx4 v[228:229], off
	s_waitcnt lgkmcnt(8)
	s_barrier
	s_waitcnt lgkmcnt(0)
	v_mfma_f32_16x16x32_f16 v[128:131], v[190:193], v[174:177], 0
	v_mfma_f32_16x16x32_f16 v[124:127], v[190:193], v[182:185], 0
	v_mfma_f32_16x16x32_f16 v[120:123], v[198:201], v[174:177], 0
	v_mfma_f32_16x16x32_f16 v[116:119], v[198:201], v[182:185], 0
	v_mfma_f32_16x16x32_f16 v[112:115], v[206:209], v[174:177], 0
	v_mfma_f32_16x16x32_f16 v[108:111], v[206:209], v[182:185], 0
	v_mfma_f32_16x16x32_f16 v[104:107], v[214:217], v[174:177], 0
	v_mfma_f32_16x16x32_f16 v[100:103], v[214:217], v[182:185], 0
	v_mfma_f32_16x16x32_f16 v[128:131], v[194:197], v[178:181], v[128:131]
	v_mfma_f32_16x16x32_f16 v[124:127], v[194:197], v[186:189], v[124:127]
	v_mfma_f32_16x16x32_f16 v[120:123], v[202:205], v[178:181], v[120:123]
	v_mfma_f32_16x16x32_f16 v[116:119], v[202:205], v[186:189], v[116:119]
	v_mfma_f32_16x16x32_f16 v[112:115], v[210:213], v[178:181], v[112:115]
	v_mfma_f32_16x16x32_f16 v[108:111], v[210:213], v[186:189], v[108:111]
	v_mfma_f32_16x16x32_f16 v[104:107], v[218:221], v[178:181], v[104:107]
	v_mfma_f32_16x16x32_f16 v[100:103], v[218:221], v[186:189], v[100:103]
	s_barrier
	v_lshl_add_u64 v[228:229], v[142:143], 0, s[14:15]
	v_lshl_add_u64 v[236:237], v[228:229], 0, s[30:31]
	s_or_b32 m0, s100, 0x10000
	ds_read_b128 v[230:233], v168
	ds_read_b128 v[238:241], v168 offset:1024
	ds_read_b128 v[242:245], v168 offset:2048
	ds_read_b128 v[246:249], v168 offset:3072
	global_load_lds_dwordx4 v[236:237], off
	v_lshl_add_u64 v[236:237], v[144:145], 0, s[14:15]
	s_or_b32 m0, s100, 0x12000
	v_lshl_add_u64 v[250:251], v[236:237], 0, s[30:31]
	global_load_lds_dwordx4 v[250:251], off
	s_barrier
; #define LDA8(dst, b, h) _Pragma("unroll") for (int m = 0; m < 4; ++m) _Pragma("unroll") for (int k = 0; k < 2; ++k) \
;     dst[m][k] = *(const bf16x8*)((const char*)SA8(b, h) + lds_byte8(wr * 64 + m * 16 + fr, k * 32 + fq * 8))
; #define LDB8(dst, b, h) _Pragma("unroll") for (int n = 0; n < 2; ++n) _Pragma("unroll") for (int k = 0; k < 2; ++k) \
;     dst[n][k] = *(const bf16x8*)((const char*)SB8(b, h) + lds_byte8(wc * 32 + n * 16 + fr, k * 32 + fq * 8))
; #define WAIT_V8(n) asm volatile("s_waitcnt vmcnt(" #n ")" ::: "memory")
; #define WAIT_L8(n) asm volatile("s_waitcnt lgkmcnt(" #n ")" ::: "memory")
; #define BAR8 __builtin_amdgcn_s_barrier()
; #define SCHED8 __builtin_amdgcn_sched_barrier(0)
;     ...
;     BAR8; WAIT_L8(0); MMA8(0, 1, At, B1); BAR8;
;     LDA8(At, 0, 1); STAGE8(SA8(0, 0), A, lda, brow, tt + 2);
;     BAR8; WAIT_L8(0); MMA8(1, 0, At, B0); BAR8; SCHED8;
;     STAGE8(SB8(0, 1), Bt, K, bcol + 128, tt + 2);
;     WAIT_V8(6); BAR8; MMA8(1, 1, At, B1); BAR8;
;     LDB8(B0, 1, 0); SCHED8; LDA8(At, 1, 0); STAGE8(SA8(0, 1), A, lda, brow + 128, tt + 2);
;     WAIT_L8(8); BAR8; WAIT_L8(0); MMA8(0, 0, At, B0); BAR8; SCHED8;
	s_waitcnt lgkmcnt(0)
	v_mfma_f32_16x16x32_f16 v[96:99], v[190:193], v[230:233], 0
	v_mfma_f32_16x16x32_f16 v[92:95], v[190:193], v[242:245], 0
	v_mfma_f32_16x16x32_f16 v[88:91], v[198:201], v[230:233], 0
	v_mfma_f32_16x16x32_f16 v[84:87], v[198:201], v[242:245], 0
	v_mfma_f32_16x16x32_f16 v[80:83], v[206:209], v[230:233], 0
	v_mfma_f32_16x16x32_f16 v[76:79], v[206:209], v[242:245], 0
	v_mfma_f32_16x16x32_f16 v[72:75], v[214:217], v[230:233], 0
	v_mfma_f32_16x16x32_f16 v[68:71], v[214:217], v[242:245], 0
	v_mfma_f32_16x16x32_f16 v[96:99], v[194:197], v[238:241], v[96:99]
	v_mfma_f32_16x16x32_f16 v[92:95], v[194:197], v[246:249], v[92:95]
	v_mfma_f32_16x16x32_f16 v[88:91], v[202:205], v[238:241], v[88:91]
	v_mfma_f32_16x16x32_f16 v[84:87], v[202:205], v[246:249], v[84:87]
	v_mfma_f32_16x16x32_f16 v[80:83], v[210:213], v[238:241], v[80:83]
	v_mfma_f32_16x16x32_f16 v[76:79], v[210:213], v[246:249], v[76:79]
	v_mfma_f32_16x16x32_f16 v[72:75], v[218:221], v[238:241], v[72:75]
	v_mfma_f32_16x16x32_f16 v[68:71], v[218:221], v[246:249], v[68:71]
	v_lshl_add_u64 v[250:251], v[222:223], 0, s[10:11]
	s_mov_b32 m0, s100
	s_barrier
	ds_read_b128 v[190:193], v156 offset:16384
	ds_read_b128 v[194:197], v156 offset:17408
	ds_read_b128 v[198:201], v154 offset:16384
	ds_read_b128 v[202:205], v154 offset:17408
	ds_read_b128 v[206:209], v153 offset:16384
	ds_read_b128 v[210:213], v153 offset:17408
	ds_read_b128 v[214:217], v152 offset:16384
	ds_read_b128 v[218:221], v152 offset:17408
	global_load_lds_dwordx4 v[250:251], off
	s_or_b32 m0, s100, 0x2000
	v_lshl_add_u64 v[250:251], v[226:227], 0, s[10:11]
	global_load_lds_dwordx4 v[250:251], off
	s_barrier
	s_waitcnt lgkmcnt(0)
	v_mfma_f32_16x16x32_f16 v[64:67], v[190:193], v[174:177], 0
	v_mfma_f32_16x16x32_f16 v[60:63], v[190:193], v[182:185], 0
	v_mfma_f32_16x16x32_f16 v[56:59], v[198:201], v[174:177], 0
	v_mfma_f32_16x16x32_f16 v[52:55], v[198:201], v[182:185], 0
	v_mfma_f32_16x16x32_f16 v[48:51], v[206:209], v[174:177], 0
	v_mfma_f32_16x16x32_f16 v[44:47], v[206:209], v[182:185], 0
	v_mfma_f32_16x16x32_f16 v[40:43], v[214:217], v[174:177], 0
	v_mfma_f32_16x16x32_f16 v[36:39], v[214:217], v[182:185], 0
	v_mfma_f32_16x16x32_f16 v[64:67], v[194:197], v[178:181], v[64:67]
	v_mfma_f32_16x16x32_f16 v[60:63], v[194:197], v[186:189], v[60:63]
	v_mfma_f32_16x16x32_f16 v[56:59], v[202:205], v[178:181], v[56:59]
	v_mfma_f32_16x16x32_f16 v[52:55], v[202:205], v[186:189], v[52:55]
	v_mfma_f32_16x16x32_f16 v[48:51], v[210:213], v[178:181], v[48:51]
	v_mfma_f32_16x16x32_f16 v[44:47], v[210:213], v[186:189], v[44:47]
	v_mfma_f32_16x16x32_f16 v[40:43], v[218:221], v[178:181], v[40:43]
	v_mfma_f32_16x16x32_f16 v[36:39], v[218:221], v[186:189], v[36:39]
	s_barrier
	s_or_b32 m0, s100, 0x14000
	v_lshl_add_u64 v[174:175], v[228:229], 0, s[56:57]
	global_load_lds_dwordx4 v[174:175], off
	s_or_b32 m0, s100, 0x16000
	v_lshl_add_u64 v[174:175], v[236:237], 0, s[56:57]
	global_load_lds_dwordx4 v[174:175], off
	s_waitcnt vmcnt(6)
	s_barrier
	v_mfma_f32_16x16x32_f16 v[32:35], v[190:193], v[230:233], 0
	v_mfma_f32_16x16x32_f16 v[28:31], v[190:193], v[242:245], 0
	v_mfma_f32_16x16x32_f16 v[24:27], v[198:201], v[230:233], 0
	v_mfma_f32_16x16x32_f16 v[20:23], v[198:201], v[242:245], 0
	v_mfma_f32_16x16x32_f16 v[16:19], v[206:209], v[230:233], 0
	v_mfma_f32_16x16x32_f16 v[12:15], v[206:209], v[242:245], 0
	v_mfma_f32_16x16x32_f16 v[8:11], v[214:217], v[230:233], 0
	v_mfma_f32_16x16x32_f16 v[4:7], v[214:217], v[242:245], 0
	v_mfma_f32_16x16x32_f16 v[32:35], v[194:197], v[238:241], v[32:35]
	v_mfma_f32_16x16x32_f16 v[28:31], v[194:197], v[246:249], v[28:31]
	v_mfma_f32_16x16x32_f16 v[24:27], v[202:205], v[238:241], v[24:27]
	v_mfma_f32_16x16x32_f16 v[20:23], v[202:205], v[246:249], v[20:23]
	v_mfma_f32_16x16x32_f16 v[16:19], v[210:213], v[238:241], v[16:19]
	v_mfma_f32_16x16x32_f16 v[12:15], v[210:213], v[246:249], v[12:15]
	v_mfma_f32_16x16x32_f16 v[8:11], v[218:221], v[238:241], v[8:11]
	v_mfma_f32_16x16x32_f16 v[4:7], v[218:221], v[246:249], v[4:7]
	s_barrier
	ds_read_b128 v[174:177], v159
	ds_read_b128 v[178:181], v159 offset:1024
	ds_read_b128 v[182:185], v159 offset:2048
	ds_read_b128 v[186:189], v159 offset:3072
	v_lshl_add_u64 v[230:231], v[222:223], 0, s[18:19]
	s_or_b32 m0, s100, 0x4000
	ds_read_b128 v[190:193], v156 offset:32768
	ds_read_b128 v[194:197], v156 offset:33792
	ds_read_b128 v[198:201], v154 offset:32768
	ds_read_b128 v[202:205], v154 offset:33792
	ds_read_b128 v[206:209], v153 offset:32768
	ds_read_b128 v[210:213], v153 offset:33792
	ds_read_b128 v[214:217], v152 offset:32768
	ds_read_b128 v[218:221], v152 offset:33792
	global_load_lds_dwordx4 v[230:231], off
	s_or_b32 m0, s100, 0x6000
	v_lshl_add_u64 v[230:231], v[226:227], 0, s[18:19]
	global_load_lds_dwordx4 v[230:231], off
	s_waitcnt lgkmcnt(8)
	s_barrier
	s_waitcnt lgkmcnt(0)
	v_mfma_f32_16x16x32_f16 v[128:131], v[190:193], v[174:177], v[128:131]
	v_mfma_f32_16x16x32_f16 v[124:127], v[190:193], v[182:185], v[124:127]
	v_mfma_f32_16x16x32_f16 v[120:123], v[198:201], v[174:177], v[120:123]
	v_mfma_f32_16x16x32_f16 v[116:119], v[198:201], v[182:185], v[116:119]
	v_mfma_f32_16x16x32_f16 v[112:115], v[206:209], v[174:177], v[112:115]
	v_mfma_f32_16x16x32_f16 v[108:111], v[206:209], v[182:185], v[108:111]
	v_mfma_f32_16x16x32_f16 v[104:107], v[214:217], v[174:177], v[104:107]
	v_mfma_f32_16x16x32_f16 v[100:103], v[214:217], v[182:185], v[100:103]
	v_mfma_f32_16x16x32_f16 v[128:131], v[194:197], v[178:181], v[128:131]
	v_mfma_f32_16x16x32_f16 v[124:127], v[194:197], v[186:189], v[124:127]
	v_mfma_f32_16x16x32_f16 v[120:123], v[202:205], v[178:181], v[120:123]
	v_mfma_f32_16x16x32_f16 v[116:119], v[202:205], v[186:189], v[116:119]
	v_mfma_f32_16x16x32_f16 v[112:115], v[210:213], v[178:181], v[112:115]
	v_mfma_f32_16x16x32_f16 v[108:111], v[210:213], v[186:189], v[108:111]
	v_mfma_f32_16x16x32_f16 v[104:107], v[218:221], v[178:181], v[104:107]
	v_mfma_f32_16x16x32_f16 v[100:103], v[218:221], v[186:189], v[100:103]
	s_barrier
; #define LDA8(dst, b, h) _Pragma("unroll") for (int m = 0; m < 4; ++m) _Pragma("unroll") for (int k = 0; k < 2; ++k) \
;     dst[m][k] = *(const bf16x8*)((const char*)SA8(b, h) + lds_byte8(wr * 64 + m * 16 + fr, k * 32 + fq * 8))
; #define LDB8(dst, b, h) _Pragma("unroll") for (int n = 0; n < 2; ++n) _Pragma("unroll") for (int k = 0; k < 2; ++k) \
;     dst[n][k] = *(const bf16x8*)((const char*)SB8(b, h) + lds_byte8(wc * 32 + n * 16 + fr, k * 32 + fq * 8))
; #define WAIT_V8(n) asm volatile("s_waitcnt vmcnt(" #n ")" ::: "memory")
; #define WAIT_L8(n) asm volatile("s_waitcnt lgkmcnt(" #n ")" ::: "memory")
; #define BAR8 __builtin_amdgcn_s_barrier()
; #define SCHED8 __builtin_amdgcn_sched_barrier(0)
;     ...
;   for (int tt = 0; tt < nt - 2; tt += 2) {
;     LDB8(B0, 0, 0); SCHED8; LDA8(At, 0, 0); STAGE8(SA8(1, 1), A, lda, brow + 128, tt + 1);
;     WAIT_L8(8); BAR8; WAIT_L8(0); MMA8(0, 0, At, B0); BAR8; SCHED8;
;     LDB8(B1, 0, 1); STAGE8(SB8(0, 0), Bt, K, bcol, tt + 2);
;     BAR8; WAIT_L8(0); MMA8(0, 1, At, B1); BAR8;
;     LDA8(At, 0, 1); STAGE8(SA8(0, 0), A, lda, brow, tt + 2);
;     BAR8; WAIT_L8(0); MMA8(1, 0, At, B0); BAR8; SCHED8;
;     STAGE8(SB8(0, 1), Bt, K, bcol + 128, tt + 2);
;     WAIT_V8(6); BAR8; MMA8(1, 1, At, B1); BAR8;
;     LDB8(B0, 1, 0); SCHED8; LDA8(At, 1, 0); STAGE8(SA8(0, 1), A, lda, brow + 128, tt + 2);
;     WAIT_L8(8); BAR8; WAIT_L8(0); MMA8(0, 0, At, B0); BAR8; SCHED8;
;     LDB8(B1, 1, 1); STAGE8(SB8(1, 0), Bt, K, bcol, tt + 3);
;     BAR8; WAIT_L8(0); MMA8(0, 1, At, B1); BAR8;
;     LDA8(At, 1, 1); STAGE8(SA8(1, 0), A, lda, brow, tt + 3);
;     BAR8; WAIT_L8(0); MMA8(1, 0, At, B0); BAR8; SCHED8;
;     STAGE8(SB8(1, 1), Bt, K, bcol + 128, tt + 3);
;     WAIT_V8(6); BAR8; MMA8(1, 1, At, B1); BAR8;
;   }
	v_lshl_add_u64 v[250:251], v[228:229], 0, s[58:59]
	s_or_b32 m0, s100, 0x18000
	ds_read_b128 v[230:233], v157
	ds_read_b128 v[238:241], v157 offset:1024
	ds_read_b128 v[242:245], v157 offset:2048
	ds_read_b128 v[246:249], v157 offset:3072
	global_load_lds_dwordx4 v[250:251], off
	s_or_b32 m0, s100, 0x1a000
	v_lshl_add_u64 v[250:251], v[236:237], 0, s[58:59]
	global_load_lds_dwordx4 v[250:251], off
	s_barrier
	s_waitcnt lgkmcnt(0)
	v_mfma_f32_16x16x32_f16 v[96:99], v[190:193], v[230:233], v[96:99]
	v_mfma_f32_16x16x32_f16 v[92:95], v[190:193], v[242:245], v[92:95]
	v_mfma_f32_16x16x32_f16 v[88:91], v[198:201], v[230:233], v[88:91]
	v_mfma_f32_16x16x32_f16 v[84:87], v[198:201], v[242:245], v[84:87]
	v_mfma_f32_16x16x32_f16 v[80:83], v[206:209], v[230:233], v[80:83]
	v_mfma_f32_16x16x32_f16 v[76:79], v[206:209], v[242:245], v[76:79]
	v_mfma_f32_16x16x32_f16 v[72:75], v[214:217], v[230:233], v[72:75]
	v_mfma_f32_16x16x32_f16 v[68:71], v[214:217], v[242:245], v[68:71]
	v_mfma_f32_16x16x32_f16 v[96:99], v[194:197], v[238:241], v[96:99]
	v_mfma_f32_16x16x32_f16 v[92:95], v[194:197], v[246:249], v[92:95]
	v_mfma_f32_16x16x32_f16 v[88:91], v[202:205], v[238:241], v[88:91]
	v_mfma_f32_16x16x32_f16 v[84:87], v[202:205], v[246:249], v[84:87]
	v_mfma_f32_16x16x32_f16 v[80:83], v[210:213], v[238:241], v[80:83]
	v_mfma_f32_16x16x32_f16 v[76:79], v[210:213], v[246:249], v[76:79]
	v_mfma_f32_16x16x32_f16 v[72:75], v[218:221], v[238:241], v[72:75]
	v_mfma_f32_16x16x32_f16 v[68:71], v[218:221], v[246:249], v[68:71]
	v_lshl_add_u64 v[222:223], v[222:223], 0, s[22:23]
	s_or_b32 m0, s100, 0x8000
	s_barrier
	ds_read_b128 v[190:193], v156 offset:49152
	ds_read_b128 v[194:197], v156 offset:50176
	ds_read_b128 v[198:201], v154 offset:49152
	ds_read_b128 v[202:205], v154 offset:50176
	ds_read_b128 v[206:209], v153 offset:49152
	ds_read_b128 v[210:213], v153 offset:50176
	ds_read_b128 v[214:217], v152 offset:49152
	ds_read_b128 v[218:221], v152 offset:50176
	global_load_lds_dwordx4 v[222:223], off
	s_or_b32 m0, s100, 0xa000
	v_lshl_add_u64 v[222:223], v[226:227], 0, s[22:23]
	global_load_lds_dwordx4 v[222:223], off
	s_barrier
	s_waitcnt lgkmcnt(0)
	v_mfma_f32_16x16x32_f16 v[64:67], v[190:193], v[174:177], v[64:67]
	v_mfma_f32_16x16x32_f16 v[60:63], v[190:193], v[182:185], v[60:63]
	v_mfma_f32_16x16x32_f16 v[56:59], v[198:201], v[174:177], v[56:59]
	v_mfma_f32_16x16x32_f16 v[52:55], v[198:201], v[182:185], v[52:55]
	v_mfma_f32_16x16x32_f16 v[48:51], v[206:209], v[174:177], v[48:51]
	v_mfma_f32_16x16x32_f16 v[44:47], v[206:209], v[182:185], v[44:47]
	v_mfma_f32_16x16x32_f16 v[40:43], v[214:217], v[174:177], v[40:43]
	v_mfma_f32_16x16x32_f16 v[36:39], v[214:217], v[182:185], v[36:39]
	v_mfma_f32_16x16x32_f16 v[64:67], v[194:197], v[178:181], v[64:67]
	v_mfma_f32_16x16x32_f16 v[60:63], v[194:197], v[186:189], v[60:63]
	v_mfma_f32_16x16x32_f16 v[56:59], v[202:205], v[178:181], v[56:59]
	v_mfma_f32_16x16x32_f16 v[52:55], v[202:205], v[186:189], v[52:55]
	v_mfma_f32_16x16x32_f16 v[48:51], v[210:213], v[178:181], v[48:51]
	v_mfma_f32_16x16x32_f16 v[44:47], v[210:213], v[186:189], v[44:47]
	v_mfma_f32_16x16x32_f16 v[40:43], v[218:221], v[178:181], v[40:43]
	v_mfma_f32_16x16x32_f16 v[36:39], v[218:221], v[186:189], v[36:39]
	s_barrier
	s_or_b32 m0, s100, 0x1c000
	v_lshl_add_u64 v[174:175], v[228:229], 0, s[60:61]
	global_load_lds_dwordx4 v[174:175], off
	s_or_b32 m0, s100, 0x1e000
	v_lshl_add_u64 v[174:175], v[236:237], 0, s[60:61]
	global_load_lds_dwordx4 v[174:175], off
	s_waitcnt vmcnt(6)
	s_barrier
	v_mfma_f32_16x16x32_f16 v[32:35], v[190:193], v[230:233], v[32:35]
	v_mfma_f32_16x16x32_f16 v[28:31], v[190:193], v[242:245], v[28:31]
	v_mfma_f32_16x16x32_f16 v[24:27], v[198:201], v[230:233], v[24:27]
	v_mfma_f32_16x16x32_f16 v[20:23], v[198:201], v[242:245], v[20:23]
	v_mfma_f32_16x16x32_f16 v[16:19], v[206:209], v[230:233], v[16:19]
	v_mfma_f32_16x16x32_f16 v[12:15], v[206:209], v[242:245], v[12:15]
	v_mfma_f32_16x16x32_f16 v[8:11], v[214:217], v[230:233], v[8:11]
	v_mfma_f32_16x16x32_f16 v[4:7], v[214:217], v[242:245], v[4:7]
	v_mfma_f32_16x16x32_f16 v[32:35], v[194:197], v[238:241], v[32:35]
	v_mfma_f32_16x16x32_f16 v[28:31], v[194:197], v[246:249], v[28:31]
	v_mfma_f32_16x16x32_f16 v[24:27], v[202:205], v[238:241], v[24:27]
	v_mfma_f32_16x16x32_f16 v[20:23], v[202:205], v[246:249], v[20:23]
	v_mfma_f32_16x16x32_f16 v[16:19], v[210:213], v[238:241], v[16:19]
	v_mfma_f32_16x16x32_f16 v[12:15], v[210:213], v[246:249], v[12:15]
	v_mfma_f32_16x16x32_f16 v[8:11], v[218:221], v[238:241], v[8:11]
	v_mfma_f32_16x16x32_f16 v[4:7], v[218:221], v[246:249], v[4:7]
	s_add_i32 s1, s1, 2
	s_add_u32 s14, s14, 0x100
	s_addc_u32 s15, s15, 0
	s_cmp_lt_u32 s1, 12
	s_cbranch_scc0 .Lpk_exitb_1
; #define LDA8(dst, b, h) _Pragma("unroll") for (int m = 0; m < 4; ++m) _Pragma("unroll") for (int k = 0; k < 2; ++k) \
;     dst[m][k] = *(const bf16x8*)((const char*)SA8(b, h) + lds_byte8(wr * 64 + m * 16 + fr, k * 32 + fq * 8))
; #define LDB8(dst, b, h) _Pragma("unroll") for (int n = 0; n < 2; ++n) _Pragma("unroll") for (int k = 0; k < 2; ++k) \
;     dst[n][k] = *(const bf16x8*)((const char*)SB8(b, h) + lds_byte8(wc * 32 + n * 16 + fr, k * 32 + fq * 8))
; #define WAIT_V8(n) asm volatile("s_waitcnt vmcnt(" #n ")" ::: "memory")
; #define WAIT_L8(n) asm volatile("s_waitcnt lgkmcnt(" #n ")" ::: "memory")
; #define BAR8 __builtin_amdgcn_s_barrier()
; #define SCHED8 __builtin_amdgcn_sched_barrier(0)
;     ...
;   for (int tt = 0; tt < nt - 2; tt += 2) {
;     LDB8(B0, 0, 0); SCHED8; LDA8(At, 0, 0); STAGE8(SA8(1, 1), A, lda, brow + 128, tt + 1);
;     WAIT_L8(8); BAR8; WAIT_L8(0); MMA8(0, 0, At, B0); BAR8; SCHED8;
;     LDB8(B1, 0, 1); STAGE8(SB8(0, 0), Bt, K, bcol, tt + 2);
;     BAR8; WAIT_L8(0); MMA8(0, 1, At, B1); BAR8;
;     LDA8(At, 0, 1); STAGE8(SA8(0, 0), A, lda, brow, tt + 2);
;     BAR8; WAIT_L8(0); MMA8(1, 0, At, B0); BAR8; SCHED8;
;     STAGE8(SB8(0, 1), Bt, K, bcol + 128, tt + 2);
;     WAIT_V8(6); BAR8; MMA8(1, 1, At, B1); BAR8;
.LBB0_242:
	s_barrier
	ds_read_b128 v[174:177], v171
	ds_read_b128 v[178:181], v171 offset:1024
	ds_read_b128 v[182:185], v171 offset:2048
	ds_read_b128 v[186:189], v171 offset:3072
	v_lshl_add_u64 v[222:223], v[140:141], 0, s[14:15]
	v_lshl_add_u64 v[226:227], v[222:223], 0, s[34:35]
	s_or_b32 m0, s100, 0xc000
	ds_read_b128 v[190:193], v156
	ds_read_b128 v[194:197], v156 offset:1024
	ds_read_b128 v[198:201], v154
	ds_read_b128 v[202:205], v154 offset:1024
	ds_read_b128 v[206:209], v153
	ds_read_b128 v[210:213], v153 offset:1024
	ds_read_b128 v[214:217], v152
	ds_read_b128 v[218:221], v152 offset:1024
	global_load_lds_dwordx4 v[226:227], off
	v_lshl_add_u64 v[226:227], v[138:139], 0, s[14:15]
	s_or_b32 m0, s100, 0xe000
	v_lshl_add_u64 v[228:229], v[226:227], 0, s[34:35]
	global_load_lds_dwordx4 v[228:229], off
	s_waitcnt lgkmcnt(8)
	s_barrier
	s_waitcnt lgkmcnt(0)
	v_mfma_f32_16x16x32_f16 v[128:131], v[190:193], v[174:177], v[128:131]
	v_mfma_f32_16x16x32_f16 v[124:127], v[190:193], v[182:185], v[124:127]
	v_mfma_f32_16x16x32_f16 v[120:123], v[198:201], v[174:177], v[120:123]
	v_mfma_f32_16x16x32_f16 v[116:119], v[198:201], v[182:185], v[116:119]
	v_mfma_f32_16x16x32_f16 v[112:115], v[206:209], v[174:177], v[112:115]
	v_mfma_f32_16x16x32_f16 v[108:111], v[206:209], v[182:185], v[108:111]
	v_mfma_f32_16x16x32_f16 v[104:107], v[214:217], v[174:177], v[104:107]
	v_mfma_f32_16x16x32_f16 v[100:103], v[214:217], v[182:185], v[100:103]
	v_mfma_f32_16x16x32_f16 v[128:131], v[194:197], v[178:181], v[128:131]
	v_mfma_f32_16x16x32_f16 v[124:127], v[194:197], v[186:189], v[124:127]
	v_mfma_f32_16x16x32_f16 v[120:123], v[202:205], v[178:181], v[120:123]
	v_mfma_f32_16x16x32_f16 v[116:119], v[202:205], v[186:189], v[116:119]
	v_mfma_f32_16x16x32_f16 v[112:115], v[210:213], v[178:181], v[112:115]
	v_mfma_f32_16x16x32_f16 v[108:111], v[210:213], v[186:189], v[108:111]
	v_mfma_f32_16x16x32_f16 v[104:107], v[218:221], v[178:181], v[104:107]
	v_mfma_f32_16x16x32_f16 v[100:103], v[218:221], v[186:189], v[100:103]
	s_barrier
	v_lshl_add_u64 v[228:229], v[142:143], 0, s[14:15]
	v_lshl_add_u64 v[236:237], v[228:229], 0, s[30:31]
	s_or_b32 m0, s100, 0x10000
	ds_read_b128 v[230:233], v168
	ds_read_b128 v[238:241], v168 offset:1024
	ds_read_b128 v[242:245], v168 offset:2048
	ds_read_b128 v[246:249], v168 offset:3072
	global_load_lds_dwordx4 v[236:237], off
	v_lshl_add_u64 v[236:237], v[144:145], 0, s[14:15]
	s_or_b32 m0, s100, 0x12000
	v_lshl_add_u64 v[250:251], v[236:237], 0, s[30:31]
	global_load_lds_dwordx4 v[250:251], off
	s_barrier
	s_waitcnt lgkmcnt(0)
	v_mfma_f32_16x16x32_f16 v[96:99], v[190:193], v[230:233], v[96:99]
	v_mfma_f32_16x16x32_f16 v[92:95], v[190:193], v[242:245], v[92:95]
	v_mfma_f32_16x16x32_f16 v[88:91], v[198:201], v[230:233], v[88:91]
	v_mfma_f32_16x16x32_f16 v[84:87], v[198:201], v[242:245], v[84:87]
	v_mfma_f32_16x16x32_f16 v[80:83], v[206:209], v[230:233], v[80:83]
	v_mfma_f32_16x16x32_f16 v[76:79], v[206:209], v[242:245], v[76:79]
	v_mfma_f32_16x16x32_f16 v[72:75], v[214:217], v[230:233], v[72:75]
	v_mfma_f32_16x16x32_f16 v[68:71], v[214:217], v[242:245], v[68:71]
	v_mfma_f32_16x16x32_f16 v[96:99], v[194:197], v[238:241], v[96:99]
	v_mfma_f32_16x16x32_f16 v[92:95], v[194:197], v[246:249], v[92:95]
	v_mfma_f32_16x16x32_f16 v[88:91], v[202:205], v[238:241], v[88:91]
	v_mfma_f32_16x16x32_f16 v[84:87], v[202:205], v[246:249], v[84:87]
	v_mfma_f32_16x16x32_f16 v[80:83], v[210:213], v[238:241], v[80:83]
	v_mfma_f32_16x16x32_f16 v[76:79], v[210:213], v[246:249], v[76:79]
	v_mfma_f32_16x16x32_f16 v[72:75], v[218:221], v[238:241], v[72:75]
	v_mfma_f32_16x16x32_f16 v[68:71], v[218:221], v[246:249], v[68:71]
	v_lshl_add_u64 v[250:251], v[222:223], 0, s[10:11]
	s_mov_b32 m0, s100
	s_barrier
	ds_read_b128 v[190:193], v156 offset:16384
	ds_read_b128 v[194:197], v156 offset:17408
	ds_read_b128 v[198:201], v154 offset:16384
	ds_read_b128 v[202:205], v154 offset:17408
	ds_read_b128 v[206:209], v153 offset:16384
	ds_read_b128 v[210:213], v153 offset:17408
	ds_read_b128 v[214:217], v152 offset:16384
	ds_read_b128 v[218:221], v152 offset:17408
	global_load_lds_dwordx4 v[250:251], off
	s_or_b32 m0, s100, 0x2000
	v_lshl_add_u64 v[250:251], v[226:227], 0, s[10:11]
	global_load_lds_dwordx4 v[250:251], off
	s_barrier
	s_waitcnt lgkmcnt(0)
	v_mfma_f32_16x16x32_f16 v[64:67], v[190:193], v[174:177], v[64:67]
	v_mfma_f32_16x16x32_f16 v[60:63], v[190:193], v[182:185], v[60:63]
	v_mfma_f32_16x16x32_f16 v[56:59], v[198:201], v[174:177], v[56:59]
	v_mfma_f32_16x16x32_f16 v[52:55], v[198:201], v[182:185], v[52:55]
	v_mfma_f32_16x16x32_f16 v[48:51], v[206:209], v[174:177], v[48:51]
	v_mfma_f32_16x16x32_f16 v[44:47], v[206:209], v[182:185], v[44:47]
	v_mfma_f32_16x16x32_f16 v[40:43], v[214:217], v[174:177], v[40:43]
	v_mfma_f32_16x16x32_f16 v[36:39], v[214:217], v[182:185], v[36:39]
	v_mfma_f32_16x16x32_f16 v[64:67], v[194:197], v[178:181], v[64:67]
	v_mfma_f32_16x16x32_f16 v[60:63], v[194:197], v[186:189], v[60:63]
	v_mfma_f32_16x16x32_f16 v[56:59], v[202:205], v[178:181], v[56:59]
	v_mfma_f32_16x16x32_f16 v[52:55], v[202:205], v[186:189], v[52:55]
	v_mfma_f32_16x16x32_f16 v[48:51], v[210:213], v[178:181], v[48:51]
	v_mfma_f32_16x16x32_f16 v[44:47], v[210:213], v[186:189], v[44:47]
	v_mfma_f32_16x16x32_f16 v[40:43], v[218:221], v[178:181], v[40:43]
	v_mfma_f32_16x16x32_f16 v[36:39], v[218:221], v[186:189], v[36:39]
	s_barrier
	s_or_b32 m0, s100, 0x14000
	v_lshl_add_u64 v[174:175], v[228:229], 0, s[56:57]
	global_load_lds_dwordx4 v[174:175], off
	s_or_b32 m0, s100, 0x16000
	v_lshl_add_u64 v[174:175], v[236:237], 0, s[56:57]
	global_load_lds_dwordx4 v[174:175], off
	s_waitcnt vmcnt(6)
	s_barrier
; #define LDA8(dst, b, h) _Pragma("unroll") for (int m = 0; m < 4; ++m) _Pragma("unroll") for (int k = 0; k < 2; ++k) \
;     dst[m][k] = *(const bf16x8*)((const char*)SA8(b, h) + lds_byte8(wr * 64 + m * 16 + fr, k * 32 + fq * 8))
; #define LDB8(dst, b, h) _Pragma("unroll") for (int n = 0; n < 2; ++n) _Pragma("unroll") for (int k = 0; k < 2; ++k) \
;     dst[n][k] = *(const bf16x8*)((const char*)SB8(b, h) + lds_byte8(wc * 32 + n * 16 + fr, k * 32 + fq * 8))
; #define WAIT_V8(n) asm volatile("s_waitcnt vmcnt(" #n ")" ::: "memory")
; #define WAIT_L8(n) asm volatile("s_waitcnt lgkmcnt(" #n ")" ::: "memory")
; #define BAR8 __builtin_amdgcn_s_barrier()
; #define SCHED8 __builtin_amdgcn_sched_barrier(0)
;     ...
;     WAIT_V8(6); BAR8; MMA8(1, 1, At, B1); BAR8;
;     LDB8(B0, 1, 0); SCHED8; LDA8(At, 1, 0); STAGE8(SA8(0, 1), A, lda, brow + 128, tt + 2);
;     WAIT_L8(8); BAR8; WAIT_L8(0); MMA8(0, 0, At, B0); BAR8; SCHED8;
;     LDB8(B1, 1, 1); STAGE8(SB8(1, 0), Bt, K, bcol, tt + 3);
;     BAR8; WAIT_L8(0); MMA8(0, 1, At, B1); BAR8;
	v_mfma_f32_16x16x32_f16 v[32:35], v[190:193], v[230:233], v[32:35]
	v_mfma_f32_16x16x32_f16 v[28:31], v[190:193], v[242:245], v[28:31]
	v_mfma_f32_16x16x32_f16 v[24:27], v[198:201], v[230:233], v[24:27]
	v_mfma_f32_16x16x32_f16 v[20:23], v[198:201], v[242:245], v[20:23]
	v_mfma_f32_16x16x32_f16 v[16:19], v[206:209], v[230:233], v[16:19]
	v_mfma_f32_16x16x32_f16 v[12:15], v[206:209], v[242:245], v[12:15]
	v_mfma_f32_16x16x32_f16 v[8:11], v[214:217], v[230:233], v[8:11]
	v_mfma_f32_16x16x32_f16 v[4:7], v[214:217], v[242:245], v[4:7]
	v_mfma_f32_16x16x32_f16 v[32:35], v[194:197], v[238:241], v[32:35]
	v_mfma_f32_16x16x32_f16 v[28:31], v[194:197], v[246:249], v[28:31]
	v_mfma_f32_16x16x32_f16 v[24:27], v[202:205], v[238:241], v[24:27]
	v_mfma_f32_16x16x32_f16 v[20:23], v[202:205], v[246:249], v[20:23]
	v_mfma_f32_16x16x32_f16 v[16:19], v[210:213], v[238:241], v[16:19]
	v_mfma_f32_16x16x32_f16 v[12:15], v[210:213], v[246:249], v[12:15]
	v_mfma_f32_16x16x32_f16 v[8:11], v[218:221], v[238:241], v[8:11]
	v_mfma_f32_16x16x32_f16 v[4:7], v[218:221], v[246:249], v[4:7]
	s_barrier
	ds_read_b128 v[174:177], v159
	ds_read_b128 v[178:181], v159 offset:1024
	ds_read_b128 v[182:185], v159 offset:2048
	ds_read_b128 v[186:189], v159 offset:3072
	v_lshl_add_u64 v[230:231], v[222:223], 0, s[18:19]
	s_or_b32 m0, s100, 0x4000
	ds_read_b128 v[190:193], v156 offset:32768
	ds_read_b128 v[194:197], v156 offset:33792
	ds_read_b128 v[198:201], v154 offset:32768
	ds_read_b128 v[202:205], v154 offset:33792
	ds_read_b128 v[206:209], v153 offset:32768
	ds_read_b128 v[210:213], v153 offset:33792
	ds_read_b128 v[214:217], v152 offset:32768
	ds_read_b128 v[218:221], v152 offset:33792
	global_load_lds_dwordx4 v[230:231], off
	s_or_b32 m0, s100, 0x6000
	v_lshl_add_u64 v[230:231], v[226:227], 0, s[18:19]
	global_load_lds_dwordx4 v[230:231], off
	s_waitcnt lgkmcnt(8)
	s_barrier
	s_waitcnt lgkmcnt(0)
	v_mfma_f32_16x16x32_f16 v[128:131], v[190:193], v[174:177], v[128:131]
	v_mfma_f32_16x16x32_f16 v[124:127], v[190:193], v[182:185], v[124:127]
	v_mfma_f32_16x16x32_f16 v[120:123], v[198:201], v[174:177], v[120:123]
	v_mfma_f32_16x16x32_f16 v[116:119], v[198:201], v[182:185], v[116:119]
	v_mfma_f32_16x16x32_f16 v[112:115], v[206:209], v[174:177], v[112:115]
	v_mfma_f32_16x16x32_f16 v[108:111], v[206:209], v[182:185], v[108:111]
	v_mfma_f32_16x16x32_f16 v[104:107], v[214:217], v[174:177], v[104:107]
	v_mfma_f32_16x16x32_f16 v[100:103], v[214:217], v[182:185], v[100:103]
	v_mfma_f32_16x16x32_f16 v[128:131], v[194:197], v[178:181], v[128:131]
	v_mfma_f32_16x16x32_f16 v[124:127], v[194:197], v[186:189], v[124:127]
	v_mfma_f32_16x16x32_f16 v[120:123], v[202:205], v[178:181], v[120:123]
	v_mfma_f32_16x16x32_f16 v[116:119], v[202:205], v[186:189], v[116:119]
	v_mfma_f32_16x16x32_f16 v[112:115], v[210:213], v[178:181], v[112:115]
	v_mfma_f32_16x16x32_f16 v[108:111], v[210:213], v[186:189], v[108:111]
	v_mfma_f32_16x16x32_f16 v[104:107], v[218:221], v[178:181], v[104:107]
	v_mfma_f32_16x16x32_f16 v[100:103], v[218:221], v[186:189], v[100:103]
	s_barrier
	v_lshl_add_u64 v[250:251], v[228:229], 0, s[58:59]
	s_or_b32 m0, s100, 0x18000
	ds_read_b128 v[230:233], v157
	ds_read_b128 v[238:241], v157 offset:1024
	ds_read_b128 v[242:245], v157 offset:2048
	ds_read_b128 v[246:249], v157 offset:3072
	global_load_lds_dwordx4 v[250:251], off
	s_or_b32 m0, s100, 0x1a000
	v_lshl_add_u64 v[250:251], v[236:237], 0, s[58:59]
	global_load_lds_dwordx4 v[250:251], off
	s_barrier
; #define LDA8(dst, b, h) _Pragma("unroll") for (int m = 0; m < 4; ++m) _Pragma("unroll") for (int k = 0; k < 2; ++k) \
;     dst[m][k] = *(const bf16x8*)((const char*)SA8(b, h) + lds_byte8(wr * 64 + m * 16 + fr, k * 32 + fq * 8))
; #define WAIT_V8(n) asm volatile("s_waitcnt vmcnt(" #n ")" ::: "memory")
; #define WAIT_L8(n) asm volatile("s_waitcnt lgkmcnt(" #n ")" ::: "memory")
; #define BAR8 __builtin_amdgcn_s_barrier()
; #define SCHED8 __builtin_amdgcn_sched_barrier(0)
;     ...
;     BAR8; WAIT_L8(0); MMA8(0, 1, At, B1); BAR8;
;     LDA8(At, 1, 1); STAGE8(SA8(1, 0), A, lda, brow, tt + 3);
;     BAR8; WAIT_L8(0); MMA8(1, 0, At, B0); BAR8; SCHED8;
;     STAGE8(SB8(1, 1), Bt, K, bcol + 128, tt + 3);
;     WAIT_V8(6); BAR8; MMA8(1, 1, At, B1); BAR8;
;   }
	s_waitcnt lgkmcnt(0)
	v_mfma_f32_16x16x32_f16 v[96:99], v[190:193], v[230:233], v[96:99]
	v_mfma_f32_16x16x32_f16 v[92:95], v[190:193], v[242:245], v[92:95]
	v_mfma_f32_16x16x32_f16 v[88:91], v[198:201], v[230:233], v[88:91]
	v_mfma_f32_16x16x32_f16 v[84:87], v[198:201], v[242:245], v[84:87]
	v_mfma_f32_16x16x32_f16 v[80:83], v[206:209], v[230:233], v[80:83]
	v_mfma_f32_16x16x32_f16 v[76:79], v[206:209], v[242:245], v[76:79]
	v_mfma_f32_16x16x32_f16 v[72:75], v[214:217], v[230:233], v[72:75]
	v_mfma_f32_16x16x32_f16 v[68:71], v[214:217], v[242:245], v[68:71]
	v_mfma_f32_16x16x32_f16 v[96:99], v[194:197], v[238:241], v[96:99]
	v_mfma_f32_16x16x32_f16 v[92:95], v[194:197], v[246:249], v[92:95]
	v_mfma_f32_16x16x32_f16 v[88:91], v[202:205], v[238:241], v[88:91]
	v_mfma_f32_16x16x32_f16 v[84:87], v[202:205], v[246:249], v[84:87]
	v_mfma_f32_16x16x32_f16 v[80:83], v[210:213], v[238:241], v[80:83]
	v_mfma_f32_16x16x32_f16 v[76:79], v[210:213], v[246:249], v[76:79]
	v_mfma_f32_16x16x32_f16 v[72:75], v[218:221], v[238:241], v[72:75]
	v_mfma_f32_16x16x32_f16 v[68:71], v[218:221], v[246:249], v[68:71]
	v_lshl_add_u64 v[222:223], v[222:223], 0, s[22:23]
	s_or_b32 m0, s100, 0x8000
	s_barrier
	ds_read_b128 v[190:193], v156 offset:49152
	ds_read_b128 v[194:197], v156 offset:50176
	ds_read_b128 v[198:201], v154 offset:49152
	ds_read_b128 v[202:205], v154 offset:50176
	ds_read_b128 v[206:209], v153 offset:49152
	ds_read_b128 v[210:213], v153 offset:50176
	ds_read_b128 v[214:217], v152 offset:49152
	ds_read_b128 v[218:221], v152 offset:50176
	global_load_lds_dwordx4 v[222:223], off
	s_or_b32 m0, s100, 0xa000
	v_lshl_add_u64 v[222:223], v[226:227], 0, s[22:23]
	global_load_lds_dwordx4 v[222:223], off
	s_barrier
	s_waitcnt lgkmcnt(0)
	v_mfma_f32_16x16x32_f16 v[64:67], v[190:193], v[174:177], v[64:67]
	v_mfma_f32_16x16x32_f16 v[60:63], v[190:193], v[182:185], v[60:63]
	v_mfma_f32_16x16x32_f16 v[56:59], v[198:201], v[174:177], v[56:59]
	v_mfma_f32_16x16x32_f16 v[52:55], v[198:201], v[182:185], v[52:55]
	v_mfma_f32_16x16x32_f16 v[48:51], v[206:209], v[174:177], v[48:51]
	v_mfma_f32_16x16x32_f16 v[44:47], v[206:209], v[182:185], v[44:47]
	v_mfma_f32_16x16x32_f16 v[40:43], v[214:217], v[174:177], v[40:43]
	v_mfma_f32_16x16x32_f16 v[36:39], v[214:217], v[182:185], v[36:39]
	v_mfma_f32_16x16x32_f16 v[64:67], v[194:197], v[178:181], v[64:67]
	v_mfma_f32_16x16x32_f16 v[60:63], v[194:197], v[186:189], v[60:63]
	v_mfma_f32_16x16x32_f16 v[56:59], v[202:205], v[178:181], v[56:59]
	v_mfma_f32_16x16x32_f16 v[52:55], v[202:205], v[186:189], v[52:55]
	v_mfma_f32_16x16x32_f16 v[48:51], v[210:213], v[178:181], v[48:51]
	v_mfma_f32_16x16x32_f16 v[44:47], v[210:213], v[186:189], v[44:47]
	v_mfma_f32_16x16x32_f16 v[40:43], v[218:221], v[178:181], v[40:43]
	v_mfma_f32_16x16x32_f16 v[36:39], v[218:221], v[186:189], v[36:39]
	s_barrier
	s_or_b32 m0, s100, 0x1c000
	v_lshl_add_u64 v[174:175], v[228:229], 0, s[60:61]
	global_load_lds_dwordx4 v[174:175], off
	s_or_b32 m0, s100, 0x1e000
	v_lshl_add_u64 v[174:175], v[236:237], 0, s[60:61]
	global_load_lds_dwordx4 v[174:175], off
	s_waitcnt vmcnt(6)
	s_barrier
	v_mfma_f32_16x16x32_f16 v[32:35], v[190:193], v[230:233], v[32:35]
	v_mfma_f32_16x16x32_f16 v[28:31], v[190:193], v[242:245], v[28:31]
	v_mfma_f32_16x16x32_f16 v[24:27], v[198:201], v[230:233], v[24:27]
	v_mfma_f32_16x16x32_f16 v[20:23], v[198:201], v[242:245], v[20:23]
	v_mfma_f32_16x16x32_f16 v[16:19], v[206:209], v[230:233], v[16:19]
	v_mfma_f32_16x16x32_f16 v[12:15], v[206:209], v[242:245], v[12:15]
	v_mfma_f32_16x16x32_f16 v[8:11], v[214:217], v[230:233], v[8:11]
	v_mfma_f32_16x16x32_f16 v[4:7], v[214:217], v[242:245], v[4:7]
	v_mfma_f32_16x16x32_f16 v[32:35], v[194:197], v[238:241], v[32:35]
	v_mfma_f32_16x16x32_f16 v[28:31], v[194:197], v[246:249], v[28:31]
	v_mfma_f32_16x16x32_f16 v[24:27], v[202:205], v[238:241], v[24:27]
	v_mfma_f32_16x16x32_f16 v[20:23], v[202:205], v[246:249], v[20:23]
	v_mfma_f32_16x16x32_f16 v[16:19], v[210:213], v[238:241], v[16:19]
	v_mfma_f32_16x16x32_f16 v[12:15], v[210:213], v[246:249], v[12:15]
	v_mfma_f32_16x16x32_f16 v[8:11], v[218:221], v[238:241], v[8:11]
	v_mfma_f32_16x16x32_f16 v[4:7], v[218:221], v[246:249], v[4:7]
	s_add_i32 s1, s1, 2
	s_add_u32 s14, s14, 0x100
	s_addc_u32 s15, s15, 0
	s_cmp_lt_u32 s1, 12
	s_cbranch_scc1 .LBB0_242

; #define LDA8(dst, b, h) _Pragma("unroll") for (int m = 0; m < 4; ++m) _Pragma("unroll") for (int k = 0; k < 2; ++k) \
;     dst[m][k] = *(const bf16x8*)((const char*)SA8(b, h) + lds_byte8(wr * 64 + m * 16 + fr, k * 32 + fq * 8))
; #define LDB8(dst, b, h) _Pragma("unroll") for (int n = 0; n < 2; ++n) _Pragma("unroll") for (int k = 0; k < 2; ++k) \
;     dst[n][k] = *(const bf16x8*)((const char*)SB8(b, h) + lds_byte8(wc * 32 + n * 16 + fr, k * 32 + fq * 8))
; #define WAIT_V8(n) asm volatile("s_waitcnt vmcnt(" #n ")" ::: "memory")
; #define WAIT_L8(n) asm volatile("s_waitcnt lgkmcnt(" #n ")" ::: "memory")
; #define BAR8 __builtin_amdgcn_s_barrier()
; #define SCHED8 __builtin_amdgcn_sched_barrier(0)
;     ...
;   if (wr == 1) BAR8;
;   WAIT_V8(4); BAR8;
;   STAGE8(SB8(1, 0), Bt, K, bcol, 1); STAGE8(SA8(1, 0), A, lda, brow, 1); STAGE8(SB8(1, 1), Bt, K, bcol + 128, 1);
;   WAIT_V8(6); BAR8;
;   for (int tt = 0; tt < nt - 2; tt += 2) {
;     LDB8(B0, 0, 0); SCHED8; LDA8(At, 0, 0); STAGE8(SA8(1, 1), A, lda, brow + 128, tt + 1);
;     WAIT_L8(8); BAR8; WAIT_L8(0); MMA8(0, 0, At, B0); BAR8; SCHED8;
;     LDB8(B1, 0, 1); STAGE8(SB8(0, 0), Bt, K, bcol, tt + 2);
;     BAR8; WAIT_L8(0); MMA8(0, 1, At, B1); BAR8;
.LBB0_907:
	s_or_b64 exec, exec, s[12:13]
	s_lshl_b32 s29, s20, 11
	s_waitcnt vmcnt(0)
	s_and_b32 s36, s29, 0x1f80000
	s_mov_b64 s[38:39], 0x80
	v_lshl_add_u64 v[14:15], v[14:15], 0, s[38:39]
	s_or_b32 m0, s100, 0x18000
	s_waitcnt vmcnt(4)
	s_barrier
	global_load_lds_dwordx4 v[14:15], off
	v_lshl_add_u64 v[14:15], v[18:19], 0, s[38:39]
	s_or_b32 m0, s100, 0x1a000
	global_load_lds_dwordx4 v[14:15], off
	v_lshl_add_u64 v[14:15], v[20:21], 0, s[38:39]
	s_or_b32 m0, s100, 0x8000
	global_load_lds_dwordx4 v[14:15], off
	v_lshl_add_u64 v[14:15], v[22:23], 0, s[38:39]
	s_or_b32 m0, s100, 0xa000
	global_load_lds_dwordx4 v[14:15], off
	s_or_b32 m0, s100, 0x1c000
	v_lshl_add_u64 v[14:15], v[26:27], 0, s[38:39]
	global_load_lds_dwordx4 v[14:15], off
	v_lshl_add_u64 v[14:15], v[28:29], 0, s[38:39]
	s_or_b32 m0, s100, 0x1e000
	v_and_b32_e32 v147, 15, v3
	global_load_lds_dwordx4 v[14:15], off
	v_bfe_u32 v148, v3, 4, 2
	v_lshlrev_b32_e32 v14, 4, v148
	v_lshlrev_b32_e32 v15, 6, v147
	v_lshlrev_b32_e32 v18, 2, v3
	v_lshlrev_b64 v[136:137], 10, v[16:17]
	v_or_b32_e32 v17, v14, v15
	v_and_b32_e32 v18, 32, v18
	s_mov_b32 s29, 0x10000
	s_and_b32 s12, s21, 0xffffff00
	v_bitop3_b32 v20, v17, s29, v18 bitop3:0xde
	s_mov_b32 s29, 0x14000
	s_ashr_i32 s13, s12, 31
	v_readlane_b32 s40, v254, 35
	v_bitop3_b32 v19, v14, v18, v15 bitop3:0x36
	v_bitop3_b32 v21, v17, s29, v18 bitop3:0xde
	s_mov_b32 s29, 0x18000
	v_lshlrev_b32_e32 v15, 6, v3
	s_lshl_b64 s[12:13], s[12:13], 11
	s_mov_b32 s37, s40
	v_bitop3_b32 v22, v17, s29, v18 bitop3:0xde
	s_mov_b32 s29, 0x1c000
	v_and_b32_e32 v15, 0x3c0, v15
	v_bitop3_b32 v17, v17, s29, v18 bitop3:0xde
	v_bitop3_b32 v18, v15, v18, v14 bitop3:0x36
	v_lshl_add_u64 v[14:15], s[12:13], 0, v[6:7]
	v_lshl_add_u64 v[6:7], s[36:37], 0, v[6:7]
	v_lshl_add_u64 v[14:15], v[14:15], 0, v[8:9]
	v_lshl_add_u64 v[6:7], v[6:7], 0, v[8:9]
	v_bfe_u32 v146, v3, 6, 2
	s_waitcnt vmcnt(6)
	v_lshlrev_b32_e32 v149, 6, v5
	v_lshlrev_b32_e32 v5, 13, v5
	v_lshl_add_u64 v[138:139], s[4:5], 0, v[14:15]
	v_lshl_add_u64 v[14:15], s[12:13], 0, v[10:11]
	v_lshl_add_u64 v[142:143], s[2:3], 0, v[6:7]
	v_lshl_add_u64 v[6:7], s[36:37], 0, v[10:11]
	v_lshlrev_b64 v[134:135], 10, v[24:25]
	v_readlane_b32 s41, v254, 36
	v_readlane_b32 s42, v254, 37
	v_readlane_b32 s43, v254, 38
	v_lshlrev_b32_e32 v16, 12, v146
	v_or_b32_e32 v23, 0x800, v5
	v_or_b32_e32 v24, 0x1000, v5
	v_or_b32_e32 v25, 0x1800, v5
	v_lshl_add_u64 v[14:15], v[14:15], 0, v[12:13]
	v_lshl_add_u64 v[6:7], v[6:7], 0, v[12:13]
	v_lshl_add_u64 v[140:141], s[4:5], 0, v[14:15]
	v_lshl_add_u64 v[144:145], s[2:3], 0, v[6:7]
	s_mov_b32 s29, -2
	s_mov_b64 s[12:13], 0
	v_add_u32_e32 v171, v20, v16
	v_add_u32_e32 v156, v19, v5
	v_add_u32_e32 v155, v18, v23
	v_add_u32_e32 v154, v18, v24
	v_add_u32_e32 v153, v18, v25
	v_add_u32_e32 v167, v21, v16
	v_add_u32_e32 v160, v22, v16
	v_add_u32_e32 v158, v17, v16
	s_mov_b64 s[36:37], 0x6040080
	s_mov_b64 s[38:39], 0xc4a0100
	s_mov_b64 s[40:41], 0x6000100
	s_mov_b64 s[42:43], 0xc4e0100
	s_mov_b64 s[44:45], 0x6040100
	s_mov_b64 s[46:47], 0xc4a0180
	s_mov_b64 s[48:49], 0x6000180
	s_mov_b64 s[50:51], 0xc4e0180
	s_barrier
	ds_read_b128 v[174:177], v171
	ds_read_b128 v[178:181], v171 offset:1024
	ds_read_b128 v[182:185], v171 offset:2048
	ds_read_b128 v[186:189], v171 offset:3072
	v_lshl_add_u64 v[222:223], v[142:143], 0, s[12:13]
	v_lshl_add_u64 v[226:227], v[222:223], 0, s[36:37]
	s_or_b32 m0, s100, 0xc000
	ds_read_b128 v[190:193], v156
	ds_read_b128 v[194:197], v156 offset:1024
	ds_read_b128 v[198:201], v155
	ds_read_b128 v[202:205], v155 offset:1024
	ds_read_b128 v[206:209], v154
	ds_read_b128 v[210:213], v154 offset:1024
	ds_read_b128 v[214:217], v153
	ds_read_b128 v[218:221], v153 offset:1024
	global_load_lds_dwordx4 v[226:227], off
	v_lshl_add_u64 v[226:227], v[144:145], 0, s[12:13]
	s_or_b32 m0, s100, 0xe000
	v_lshl_add_u64 v[228:229], v[226:227], 0, s[36:37]
	global_load_lds_dwordx4 v[228:229], off
	s_waitcnt lgkmcnt(8)
	s_barrier
	s_waitcnt lgkmcnt(0)
	v_mfma_f32_16x16x32_bf16 v[128:131], v[190:193], v[174:177], 0
	v_mfma_f32_16x16x32_bf16 v[124:127], v[190:193], v[182:185], 0
	v_mfma_f32_16x16x32_bf16 v[120:123], v[198:201], v[174:177], 0
	v_mfma_f32_16x16x32_bf16 v[116:119], v[198:201], v[182:185], 0
	v_mfma_f32_16x16x32_bf16 v[112:115], v[206:209], v[174:177], 0
	v_mfma_f32_16x16x32_bf16 v[108:111], v[206:209], v[182:185], 0
	v_mfma_f32_16x16x32_bf16 v[104:107], v[214:217], v[174:177], 0
	v_mfma_f32_16x16x32_bf16 v[100:103], v[214:217], v[182:185], 0
	v_mfma_f32_16x16x32_bf16 v[128:131], v[194:197], v[178:181], v[128:131]
	v_mfma_f32_16x16x32_bf16 v[124:127], v[194:197], v[186:189], v[124:127]
	v_mfma_f32_16x16x32_bf16 v[120:123], v[202:205], v[178:181], v[120:123]
	v_mfma_f32_16x16x32_bf16 v[116:119], v[202:205], v[186:189], v[116:119]
	v_mfma_f32_16x16x32_bf16 v[112:115], v[210:213], v[178:181], v[112:115]
	v_mfma_f32_16x16x32_bf16 v[108:111], v[210:213], v[186:189], v[108:111]
	v_mfma_f32_16x16x32_bf16 v[104:107], v[218:221], v[178:181], v[104:107]
	v_mfma_f32_16x16x32_bf16 v[100:103], v[218:221], v[186:189], v[100:103]
	s_barrier
	v_lshl_add_u64 v[228:229], v[138:139], 0, s[12:13]
	v_lshl_add_u64 v[236:237], v[228:229], 0, s[38:39]
	s_or_b32 m0, s100, 0x10000
	ds_read_b128 v[230:233], v167
	ds_read_b128 v[238:241], v167 offset:1024
	ds_read_b128 v[242:245], v167 offset:2048
	ds_read_b128 v[246:249], v167 offset:3072
	global_load_lds_dwordx4 v[236:237], off
	v_lshl_add_u64 v[236:237], v[140:141], 0, s[12:13]
	s_or_b32 m0, s100, 0x12000
	v_lshl_add_u64 v[250:251], v[236:237], 0, s[38:39]
	global_load_lds_dwordx4 v[250:251], off
	s_barrier
; #define LDA8(dst, b, h) _Pragma("unroll") for (int m = 0; m < 4; ++m) _Pragma("unroll") for (int k = 0; k < 2; ++k) \
;     dst[m][k] = *(const bf16x8*)((const char*)SA8(b, h) + lds_byte8(wr * 64 + m * 16 + fr, k * 32 + fq * 8))
; #define LDB8(dst, b, h) _Pragma("unroll") for (int n = 0; n < 2; ++n) _Pragma("unroll") for (int k = 0; k < 2; ++k) \
;     dst[n][k] = *(const bf16x8*)((const char*)SB8(b, h) + lds_byte8(wc * 32 + n * 16 + fr, k * 32 + fq * 8))
; #define WAIT_V8(n) asm volatile("s_waitcnt vmcnt(" #n ")" ::: "memory")
; #define WAIT_L8(n) asm volatile("s_waitcnt lgkmcnt(" #n ")" ::: "memory")
; #define BAR8 __builtin_amdgcn_s_barrier()
; #define SCHED8 __builtin_amdgcn_sched_barrier(0)
;     ...
;     BAR8; WAIT_L8(0); MMA8(0, 1, At, B1); BAR8;
;     LDA8(At, 0, 1); STAGE8(SA8(0, 0), A, lda, brow, tt + 2);
;     BAR8; WAIT_L8(0); MMA8(1, 0, At, B0); BAR8; SCHED8;
;     STAGE8(SB8(0, 1), Bt, K, bcol + 128, tt + 2);
;     WAIT_V8(6); BAR8; MMA8(1, 1, At, B1); BAR8;
;     LDB8(B0, 1, 0); SCHED8; LDA8(At, 1, 0); STAGE8(SA8(0, 1), A, lda, brow + 128, tt + 2);
;     WAIT_L8(8); BAR8; WAIT_L8(0); MMA8(0, 0, At, B0); BAR8; SCHED8;
	s_waitcnt lgkmcnt(0)
	v_mfma_f32_16x16x32_bf16 v[96:99], v[190:193], v[230:233], 0
	v_mfma_f32_16x16x32_bf16 v[92:95], v[190:193], v[242:245], 0
	v_mfma_f32_16x16x32_bf16 v[88:91], v[198:201], v[230:233], 0
	v_mfma_f32_16x16x32_bf16 v[84:87], v[198:201], v[242:245], 0
	v_mfma_f32_16x16x32_bf16 v[80:83], v[206:209], v[230:233], 0
	v_mfma_f32_16x16x32_bf16 v[76:79], v[206:209], v[242:245], 0
	v_mfma_f32_16x16x32_bf16 v[72:75], v[214:217], v[230:233], 0
	v_mfma_f32_16x16x32_bf16 v[68:71], v[214:217], v[242:245], 0
	v_mfma_f32_16x16x32_bf16 v[96:99], v[194:197], v[238:241], v[96:99]
	v_mfma_f32_16x16x32_bf16 v[92:95], v[194:197], v[246:249], v[92:95]
	v_mfma_f32_16x16x32_bf16 v[88:91], v[202:205], v[238:241], v[88:91]
	v_mfma_f32_16x16x32_bf16 v[84:87], v[202:205], v[246:249], v[84:87]
	v_mfma_f32_16x16x32_bf16 v[80:83], v[210:213], v[238:241], v[80:83]
	v_mfma_f32_16x16x32_bf16 v[76:79], v[210:213], v[246:249], v[76:79]
	v_mfma_f32_16x16x32_bf16 v[72:75], v[218:221], v[238:241], v[72:75]
	v_mfma_f32_16x16x32_bf16 v[68:71], v[218:221], v[246:249], v[68:71]
	v_lshl_add_u64 v[250:251], v[222:223], 0, s[40:41]
	s_mov_b32 m0, s100
	s_barrier
	ds_read_b128 v[190:193], v156 offset:16384
	ds_read_b128 v[194:197], v156 offset:17408
	ds_read_b128 v[198:201], v155 offset:16384
	ds_read_b128 v[202:205], v155 offset:17408
	ds_read_b128 v[206:209], v154 offset:16384
	ds_read_b128 v[210:213], v154 offset:17408
	ds_read_b128 v[214:217], v153 offset:16384
	ds_read_b128 v[218:221], v153 offset:17408
	global_load_lds_dwordx4 v[250:251], off
	s_or_b32 m0, s100, 0x2000
	v_lshl_add_u64 v[250:251], v[226:227], 0, s[40:41]
	global_load_lds_dwordx4 v[250:251], off
	s_barrier
	s_waitcnt lgkmcnt(0)
	v_mfma_f32_16x16x32_bf16 v[64:67], v[190:193], v[174:177], 0
	v_mfma_f32_16x16x32_bf16 v[60:63], v[190:193], v[182:185], 0
	v_mfma_f32_16x16x32_bf16 v[56:59], v[198:201], v[174:177], 0
	v_mfma_f32_16x16x32_bf16 v[52:55], v[198:201], v[182:185], 0
	v_mfma_f32_16x16x32_bf16 v[48:51], v[206:209], v[174:177], 0
	v_mfma_f32_16x16x32_bf16 v[44:47], v[206:209], v[182:185], 0
	v_mfma_f32_16x16x32_bf16 v[40:43], v[214:217], v[174:177], 0
	v_mfma_f32_16x16x32_bf16 v[36:39], v[214:217], v[182:185], 0
	v_mfma_f32_16x16x32_bf16 v[64:67], v[194:197], v[178:181], v[64:67]
	v_mfma_f32_16x16x32_bf16 v[60:63], v[194:197], v[186:189], v[60:63]
	v_mfma_f32_16x16x32_bf16 v[56:59], v[202:205], v[178:181], v[56:59]
	v_mfma_f32_16x16x32_bf16 v[52:55], v[202:205], v[186:189], v[52:55]
	v_mfma_f32_16x16x32_bf16 v[48:51], v[210:213], v[178:181], v[48:51]
	v_mfma_f32_16x16x32_bf16 v[44:47], v[210:213], v[186:189], v[44:47]
	v_mfma_f32_16x16x32_bf16 v[40:43], v[218:221], v[178:181], v[40:43]
	v_mfma_f32_16x16x32_bf16 v[36:39], v[218:221], v[186:189], v[36:39]
	s_barrier
	s_or_b32 m0, s100, 0x14000
	v_lshl_add_u64 v[174:175], v[228:229], 0, s[42:43]
	global_load_lds_dwordx4 v[174:175], off
	s_or_b32 m0, s100, 0x16000
	v_lshl_add_u64 v[174:175], v[236:237], 0, s[42:43]
	global_load_lds_dwordx4 v[174:175], off
	s_waitcnt vmcnt(6)
	s_barrier
	v_mfma_f32_16x16x32_bf16 v[32:35], v[190:193], v[230:233], 0
	v_mfma_f32_16x16x32_bf16 v[28:31], v[190:193], v[242:245], 0
	v_mfma_f32_16x16x32_bf16 v[24:27], v[198:201], v[230:233], 0
	v_mfma_f32_16x16x32_bf16 v[20:23], v[198:201], v[242:245], 0
	v_mfma_f32_16x16x32_bf16 v[16:19], v[206:209], v[230:233], 0
	v_mfma_f32_16x16x32_bf16 v[12:15], v[206:209], v[242:245], 0
	v_mfma_f32_16x16x32_bf16 v[8:11], v[214:217], v[230:233], 0
	v_mfma_f32_16x16x32_bf16 v[4:7], v[214:217], v[242:245], 0
	v_mfma_f32_16x16x32_bf16 v[32:35], v[194:197], v[238:241], v[32:35]
	v_mfma_f32_16x16x32_bf16 v[28:31], v[194:197], v[246:249], v[28:31]
	v_mfma_f32_16x16x32_bf16 v[24:27], v[202:205], v[238:241], v[24:27]
	v_mfma_f32_16x16x32_bf16 v[20:23], v[202:205], v[246:249], v[20:23]
	v_mfma_f32_16x16x32_bf16 v[16:19], v[210:213], v[238:241], v[16:19]
	v_mfma_f32_16x16x32_bf16 v[12:15], v[210:213], v[246:249], v[12:15]
	v_mfma_f32_16x16x32_bf16 v[8:11], v[218:221], v[238:241], v[8:11]
	v_mfma_f32_16x16x32_bf16 v[4:7], v[218:221], v[246:249], v[4:7]
	s_barrier
	ds_read_b128 v[174:177], v160
	ds_read_b128 v[178:181], v160 offset:1024
	ds_read_b128 v[182:185], v160 offset:2048
	ds_read_b128 v[186:189], v160 offset:3072
	v_lshl_add_u64 v[230:231], v[222:223], 0, s[44:45]
	s_or_b32 m0, s100, 0x4000
	ds_read_b128 v[190:193], v156 offset:32768
	ds_read_b128 v[194:197], v156 offset:33792
	ds_read_b128 v[198:201], v155 offset:32768
	ds_read_b128 v[202:205], v155 offset:33792
	ds_read_b128 v[206:209], v154 offset:32768
	ds_read_b128 v[210:213], v154 offset:33792
	ds_read_b128 v[214:217], v153 offset:32768
	ds_read_b128 v[218:221], v153 offset:33792
	global_load_lds_dwordx4 v[230:231], off
	s_or_b32 m0, s100, 0x6000
	v_lshl_add_u64 v[230:231], v[226:227], 0, s[44:45]
	global_load_lds_dwordx4 v[230:231], off
	s_waitcnt lgkmcnt(8)
	s_barrier
	s_waitcnt lgkmcnt(0)
	v_mfma_f32_16x16x32_bf16 v[128:131], v[190:193], v[174:177], v[128:131]
	v_mfma_f32_16x16x32_bf16 v[124:127], v[190:193], v[182:185], v[124:127]
	v_mfma_f32_16x16x32_bf16 v[120:123], v[198:201], v[174:177], v[120:123]
	v_mfma_f32_16x16x32_bf16 v[116:119], v[198:201], v[182:185], v[116:119]
	v_mfma_f32_16x16x32_bf16 v[112:115], v[206:209], v[174:177], v[112:115]
	v_mfma_f32_16x16x32_bf16 v[108:111], v[206:209], v[182:185], v[108:111]
	v_mfma_f32_16x16x32_bf16 v[104:107], v[214:217], v[174:177], v[104:107]
	v_mfma_f32_16x16x32_bf16 v[100:103], v[214:217], v[182:185], v[100:103]
	v_mfma_f32_16x16x32_bf16 v[128:131], v[194:197], v[178:181], v[128:131]
	v_mfma_f32_16x16x32_bf16 v[124:127], v[194:197], v[186:189], v[124:127]
	v_mfma_f32_16x16x32_bf16 v[120:123], v[202:205], v[178:181], v[120:123]
	v_mfma_f32_16x16x32_bf16 v[116:119], v[202:205], v[186:189], v[116:119]
	v_mfma_f32_16x16x32_bf16 v[112:115], v[210:213], v[178:181], v[112:115]
	v_mfma_f32_16x16x32_bf16 v[108:111], v[210:213], v[186:189], v[108:111]
	v_mfma_f32_16x16x32_bf16 v[104:107], v[218:221], v[178:181], v[104:107]
	v_mfma_f32_16x16x32_bf16 v[100:103], v[218:221], v[186:189], v[100:103]
	s_barrier
; #define LDA8(dst, b, h) _Pragma("unroll") for (int m = 0; m < 4; ++m) _Pragma("unroll") for (int k = 0; k < 2; ++k) \
;     dst[m][k] = *(const bf16x8*)((const char*)SA8(b, h) + lds_byte8(wr * 64 + m * 16 + fr, k * 32 + fq * 8))
; #define LDB8(dst, b, h) _Pragma("unroll") for (int n = 0; n < 2; ++n) _Pragma("unroll") for (int k = 0; k < 2; ++k) \
;     dst[n][k] = *(const bf16x8*)((const char*)SB8(b, h) + lds_byte8(wc * 32 + n * 16 + fr, k * 32 + fq * 8))
; #define WAIT_V8(n) asm volatile("s_waitcnt vmcnt(" #n ")" ::: "memory")
; #define WAIT_L8(n) asm volatile("s_waitcnt lgkmcnt(" #n ")" ::: "memory")
; #define BAR8 __builtin_amdgcn_s_barrier()
; #define SCHED8 __builtin_amdgcn_sched_barrier(0)
;     ...
;   for (int tt = 0; tt < nt - 2; tt += 2) {
;     LDB8(B0, 0, 0); SCHED8; LDA8(At, 0, 0); STAGE8(SA8(1, 1), A, lda, brow + 128, tt + 1);
;     WAIT_L8(8); BAR8; WAIT_L8(0); MMA8(0, 0, At, B0); BAR8; SCHED8;
;     LDB8(B1, 0, 1); STAGE8(SB8(0, 0), Bt, K, bcol, tt + 2);
;     BAR8; WAIT_L8(0); MMA8(0, 1, At, B1); BAR8;
;     LDA8(At, 0, 1); STAGE8(SA8(0, 0), A, lda, brow, tt + 2);
;     BAR8; WAIT_L8(0); MMA8(1, 0, At, B0); BAR8; SCHED8;
;     STAGE8(SB8(0, 1), Bt, K, bcol + 128, tt + 2);
;     WAIT_V8(6); BAR8; MMA8(1, 1, At, B1); BAR8;
;     LDB8(B0, 1, 0); SCHED8; LDA8(At, 1, 0); STAGE8(SA8(0, 1), A, lda, brow + 128, tt + 2);
;     WAIT_L8(8); BAR8; WAIT_L8(0); MMA8(0, 0, At, B0); BAR8; SCHED8;
;     LDB8(B1, 1, 1); STAGE8(SB8(1, 0), Bt, K, bcol, tt + 3);
;     BAR8; WAIT_L8(0); MMA8(0, 1, At, B1); BAR8;
;     LDA8(At, 1, 1); STAGE8(SA8(1, 0), A, lda, brow, tt + 3);
;     BAR8; WAIT_L8(0); MMA8(1, 0, At, B0); BAR8; SCHED8;
;     STAGE8(SB8(1, 1), Bt, K, bcol + 128, tt + 3);
;     WAIT_V8(6); BAR8; MMA8(1, 1, At, B1); BAR8;
;   }
	v_lshl_add_u64 v[250:251], v[228:229], 0, s[46:47]
	s_or_b32 m0, s100, 0x18000
	ds_read_b128 v[230:233], v158
	ds_read_b128 v[238:241], v158 offset:1024
	ds_read_b128 v[242:245], v158 offset:2048
	ds_read_b128 v[246:249], v158 offset:3072
	global_load_lds_dwordx4 v[250:251], off
	s_or_b32 m0, s100, 0x1a000
	v_lshl_add_u64 v[250:251], v[236:237], 0, s[46:47]
	global_load_lds_dwordx4 v[250:251], off
	s_barrier
	s_waitcnt lgkmcnt(0)
	v_mfma_f32_16x16x32_bf16 v[96:99], v[190:193], v[230:233], v[96:99]
	v_mfma_f32_16x16x32_bf16 v[92:95], v[190:193], v[242:245], v[92:95]
	v_mfma_f32_16x16x32_bf16 v[88:91], v[198:201], v[230:233], v[88:91]
	v_mfma_f32_16x16x32_bf16 v[84:87], v[198:201], v[242:245], v[84:87]
	v_mfma_f32_16x16x32_bf16 v[80:83], v[206:209], v[230:233], v[80:83]
	v_mfma_f32_16x16x32_bf16 v[76:79], v[206:209], v[242:245], v[76:79]
	v_mfma_f32_16x16x32_bf16 v[72:75], v[214:217], v[230:233], v[72:75]
	v_mfma_f32_16x16x32_bf16 v[68:71], v[214:217], v[242:245], v[68:71]
	v_mfma_f32_16x16x32_bf16 v[96:99], v[194:197], v[238:241], v[96:99]
	v_mfma_f32_16x16x32_bf16 v[92:95], v[194:197], v[246:249], v[92:95]
	v_mfma_f32_16x16x32_bf16 v[88:91], v[202:205], v[238:241], v[88:91]
	v_mfma_f32_16x16x32_bf16 v[84:87], v[202:205], v[246:249], v[84:87]
	v_mfma_f32_16x16x32_bf16 v[80:83], v[210:213], v[238:241], v[80:83]
	v_mfma_f32_16x16x32_bf16 v[76:79], v[210:213], v[246:249], v[76:79]
	v_mfma_f32_16x16x32_bf16 v[72:75], v[218:221], v[238:241], v[72:75]
	v_mfma_f32_16x16x32_bf16 v[68:71], v[218:221], v[246:249], v[68:71]
	v_lshl_add_u64 v[222:223], v[222:223], 0, s[48:49]
	s_or_b32 m0, s100, 0x8000
	s_barrier
	ds_read_b128 v[190:193], v156 offset:49152
	ds_read_b128 v[194:197], v156 offset:50176
	ds_read_b128 v[198:201], v155 offset:49152
	ds_read_b128 v[202:205], v155 offset:50176
	ds_read_b128 v[206:209], v154 offset:49152
	ds_read_b128 v[210:213], v154 offset:50176
	ds_read_b128 v[214:217], v153 offset:49152
	ds_read_b128 v[218:221], v153 offset:50176
	global_load_lds_dwordx4 v[222:223], off
	s_or_b32 m0, s100, 0xa000
	v_lshl_add_u64 v[222:223], v[226:227], 0, s[48:49]
	global_load_lds_dwordx4 v[222:223], off
	s_barrier
	s_waitcnt lgkmcnt(0)
	v_mfma_f32_16x16x32_bf16 v[64:67], v[190:193], v[174:177], v[64:67]
	v_mfma_f32_16x16x32_bf16 v[60:63], v[190:193], v[182:185], v[60:63]
	v_mfma_f32_16x16x32_bf16 v[56:59], v[198:201], v[174:177], v[56:59]
	v_mfma_f32_16x16x32_bf16 v[52:55], v[198:201], v[182:185], v[52:55]
	v_mfma_f32_16x16x32_bf16 v[48:51], v[206:209], v[174:177], v[48:51]
	v_mfma_f32_16x16x32_bf16 v[44:47], v[206:209], v[182:185], v[44:47]
	v_mfma_f32_16x16x32_bf16 v[40:43], v[214:217], v[174:177], v[40:43]
	v_mfma_f32_16x16x32_bf16 v[36:39], v[214:217], v[182:185], v[36:39]
	v_mfma_f32_16x16x32_bf16 v[64:67], v[194:197], v[178:181], v[64:67]
	v_mfma_f32_16x16x32_bf16 v[60:63], v[194:197], v[186:189], v[60:63]
	v_mfma_f32_16x16x32_bf16 v[56:59], v[202:205], v[178:181], v[56:59]
	v_mfma_f32_16x16x32_bf16 v[52:55], v[202:205], v[186:189], v[52:55]
	v_mfma_f32_16x16x32_bf16 v[48:51], v[210:213], v[178:181], v[48:51]
	v_mfma_f32_16x16x32_bf16 v[44:47], v[210:213], v[186:189], v[44:47]
	v_mfma_f32_16x16x32_bf16 v[40:43], v[218:221], v[178:181], v[40:43]
	v_mfma_f32_16x16x32_bf16 v[36:39], v[218:221], v[186:189], v[36:39]
	s_barrier
	s_or_b32 m0, s100, 0x1c000
	v_lshl_add_u64 v[174:175], v[228:229], 0, s[50:51]
	global_load_lds_dwordx4 v[174:175], off
	s_or_b32 m0, s100, 0x1e000
	v_lshl_add_u64 v[174:175], v[236:237], 0, s[50:51]
	global_load_lds_dwordx4 v[174:175], off
	s_waitcnt vmcnt(6)
	s_barrier
	v_mfma_f32_16x16x32_bf16 v[32:35], v[190:193], v[230:233], v[32:35]
	v_mfma_f32_16x16x32_bf16 v[28:31], v[190:193], v[242:245], v[28:31]
	v_mfma_f32_16x16x32_bf16 v[24:27], v[198:201], v[230:233], v[24:27]
	v_mfma_f32_16x16x32_bf16 v[20:23], v[198:201], v[242:245], v[20:23]
	v_mfma_f32_16x16x32_bf16 v[16:19], v[206:209], v[230:233], v[16:19]
	v_mfma_f32_16x16x32_bf16 v[12:15], v[206:209], v[242:245], v[12:15]
	v_mfma_f32_16x16x32_bf16 v[8:11], v[214:217], v[230:233], v[8:11]
	v_mfma_f32_16x16x32_bf16 v[4:7], v[214:217], v[242:245], v[4:7]
	v_mfma_f32_16x16x32_bf16 v[32:35], v[194:197], v[238:241], v[32:35]
	v_mfma_f32_16x16x32_bf16 v[28:31], v[194:197], v[246:249], v[28:31]
	v_mfma_f32_16x16x32_bf16 v[24:27], v[202:205], v[238:241], v[24:27]
	v_mfma_f32_16x16x32_bf16 v[20:23], v[202:205], v[246:249], v[20:23]
	v_mfma_f32_16x16x32_bf16 v[16:19], v[210:213], v[238:241], v[16:19]
	v_mfma_f32_16x16x32_bf16 v[12:15], v[210:213], v[246:249], v[12:15]
	v_mfma_f32_16x16x32_bf16 v[8:11], v[218:221], v[238:241], v[8:11]
	v_mfma_f32_16x16x32_bf16 v[4:7], v[218:221], v[246:249], v[4:7]
	s_add_i32 s29, s29, 2
	s_add_u32 s12, s12, 0x100
	s_addc_u32 s13, s13, 0
	s_cmp_lt_u32 s29, 12
	s_cbranch_scc0 .Lpk_exitb_2
; #define LDA8(dst, b, h) _Pragma("unroll") for (int m = 0; m < 4; ++m) _Pragma("unroll") for (int k = 0; k < 2; ++k) \
;     dst[m][k] = *(const bf16x8*)((const char*)SA8(b, h) + lds_byte8(wr * 64 + m * 16 + fr, k * 32 + fq * 8))
; #define LDB8(dst, b, h) _Pragma("unroll") for (int n = 0; n < 2; ++n) _Pragma("unroll") for (int k = 0; k < 2; ++k) \
;     dst[n][k] = *(const bf16x8*)((const char*)SB8(b, h) + lds_byte8(wc * 32 + n * 16 + fr, k * 32 + fq * 8))
; #define WAIT_V8(n) asm volatile("s_waitcnt vmcnt(" #n ")" ::: "memory")
; #define WAIT_L8(n) asm volatile("s_waitcnt lgkmcnt(" #n ")" ::: "memory")
; #define BAR8 __builtin_amdgcn_s_barrier()
; #define SCHED8 __builtin_amdgcn_sched_barrier(0)
;     ...
;   for (int tt = 0; tt < nt - 2; tt += 2) {
;     LDB8(B0, 0, 0); SCHED8; LDA8(At, 0, 0); STAGE8(SA8(1, 1), A, lda, brow + 128, tt + 1);
;     WAIT_L8(8); BAR8; WAIT_L8(0); MMA8(0, 0, At, B0); BAR8; SCHED8;
;     LDB8(B1, 0, 1); STAGE8(SB8(0, 0), Bt, K, bcol, tt + 2);
;     BAR8; WAIT_L8(0); MMA8(0, 1, At, B1); BAR8;
;     LDA8(At, 0, 1); STAGE8(SA8(0, 0), A, lda, brow, tt + 2);
;     BAR8; WAIT_L8(0); MMA8(1, 0, At, B0); BAR8; SCHED8;
;     STAGE8(SB8(0, 1), Bt, K, bcol + 128, tt + 2);
;     WAIT_V8(6); BAR8; MMA8(1, 1, At, B1); BAR8;
.LBB0_908:
	s_barrier
	ds_read_b128 v[174:177], v171
	ds_read_b128 v[178:181], v171 offset:1024
	ds_read_b128 v[182:185], v171 offset:2048
	ds_read_b128 v[186:189], v171 offset:3072
	v_lshl_add_u64 v[222:223], v[142:143], 0, s[12:13]
	v_lshl_add_u64 v[226:227], v[222:223], 0, s[36:37]
	s_or_b32 m0, s100, 0xc000
	ds_read_b128 v[190:193], v156
	ds_read_b128 v[194:197], v156 offset:1024
	ds_read_b128 v[198:201], v155
	ds_read_b128 v[202:205], v155 offset:1024
	ds_read_b128 v[206:209], v154
	ds_read_b128 v[210:213], v154 offset:1024
	ds_read_b128 v[214:217], v153
	ds_read_b128 v[218:221], v153 offset:1024
	global_load_lds_dwordx4 v[226:227], off
	v_lshl_add_u64 v[226:227], v[144:145], 0, s[12:13]
	s_or_b32 m0, s100, 0xe000
	v_lshl_add_u64 v[228:229], v[226:227], 0, s[36:37]
	global_load_lds_dwordx4 v[228:229], off
	s_waitcnt lgkmcnt(8)
	s_barrier
	s_waitcnt lgkmcnt(0)
	v_mfma_f32_16x16x32_bf16 v[128:131], v[190:193], v[174:177], v[128:131]
	v_mfma_f32_16x16x32_bf16 v[124:127], v[190:193], v[182:185], v[124:127]
	v_mfma_f32_16x16x32_bf16 v[120:123], v[198:201], v[174:177], v[120:123]
	v_mfma_f32_16x16x32_bf16 v[116:119], v[198:201], v[182:185], v[116:119]
	v_mfma_f32_16x16x32_bf16 v[112:115], v[206:209], v[174:177], v[112:115]
	v_mfma_f32_16x16x32_bf16 v[108:111], v[206:209], v[182:185], v[108:111]
	v_mfma_f32_16x16x32_bf16 v[104:107], v[214:217], v[174:177], v[104:107]
	v_mfma_f32_16x16x32_bf16 v[100:103], v[214:217], v[182:185], v[100:103]
	v_mfma_f32_16x16x32_bf16 v[128:131], v[194:197], v[178:181], v[128:131]
	v_mfma_f32_16x16x32_bf16 v[124:127], v[194:197], v[186:189], v[124:127]
	v_mfma_f32_16x16x32_bf16 v[120:123], v[202:205], v[178:181], v[120:123]
	v_mfma_f32_16x16x32_bf16 v[116:119], v[202:205], v[186:189], v[116:119]
	v_mfma_f32_16x16x32_bf16 v[112:115], v[210:213], v[178:181], v[112:115]
	v_mfma_f32_16x16x32_bf16 v[108:111], v[210:213], v[186:189], v[108:111]
	v_mfma_f32_16x16x32_bf16 v[104:107], v[218:221], v[178:181], v[104:107]
	v_mfma_f32_16x16x32_bf16 v[100:103], v[218:221], v[186:189], v[100:103]
	s_barrier
	v_lshl_add_u64 v[228:229], v[138:139], 0, s[12:13]
	v_lshl_add_u64 v[236:237], v[228:229], 0, s[38:39]
	s_or_b32 m0, s100, 0x10000
	ds_read_b128 v[230:233], v167
	ds_read_b128 v[238:241], v167 offset:1024
	ds_read_b128 v[242:245], v167 offset:2048
	ds_read_b128 v[246:249], v167 offset:3072
	global_load_lds_dwordx4 v[236:237], off
	v_lshl_add_u64 v[236:237], v[140:141], 0, s[12:13]
	s_or_b32 m0, s100, 0x12000
	v_lshl_add_u64 v[250:251], v[236:237], 0, s[38:39]
	global_load_lds_dwordx4 v[250:251], off
	s_barrier
	s_waitcnt lgkmcnt(0)
	v_mfma_f32_16x16x32_bf16 v[96:99], v[190:193], v[230:233], v[96:99]
	v_mfma_f32_16x16x32_bf16 v[92:95], v[190:193], v[242:245], v[92:95]
	v_mfma_f32_16x16x32_bf16 v[88:91], v[198:201], v[230:233], v[88:91]
	v_mfma_f32_16x16x32_bf16 v[84:87], v[198:201], v[242:245], v[84:87]
	v_mfma_f32_16x16x32_bf16 v[80:83], v[206:209], v[230:233], v[80:83]
	v_mfma_f32_16x16x32_bf16 v[76:79], v[206:209], v[242:245], v[76:79]
	v_mfma_f32_16x16x32_bf16 v[72:75], v[214:217], v[230:233], v[72:75]
	v_mfma_f32_16x16x32_bf16 v[68:71], v[214:217], v[242:245], v[68:71]
	v_mfma_f32_16x16x32_bf16 v[96:99], v[194:197], v[238:241], v[96:99]
	v_mfma_f32_16x16x32_bf16 v[92:95], v[194:197], v[246:249], v[92:95]
	v_mfma_f32_16x16x32_bf16 v[88:91], v[202:205], v[238:241], v[88:91]
	v_mfma_f32_16x16x32_bf16 v[84:87], v[202:205], v[246:249], v[84:87]
	v_mfma_f32_16x16x32_bf16 v[80:83], v[210:213], v[238:241], v[80:83]
	v_mfma_f32_16x16x32_bf16 v[76:79], v[210:213], v[246:249], v[76:79]
	v_mfma_f32_16x16x32_bf16 v[72:75], v[218:221], v[238:241], v[72:75]
	v_mfma_f32_16x16x32_bf16 v[68:71], v[218:221], v[246:249], v[68:71]
	v_lshl_add_u64 v[250:251], v[222:223], 0, s[40:41]
	s_mov_b32 m0, s100
	s_barrier
	ds_read_b128 v[190:193], v156 offset:16384
	ds_read_b128 v[194:197], v156 offset:17408
	ds_read_b128 v[198:201], v155 offset:16384
	ds_read_b128 v[202:205], v155 offset:17408
	ds_read_b128 v[206:209], v154 offset:16384
	ds_read_b128 v[210:213], v154 offset:17408
	ds_read_b128 v[214:217], v153 offset:16384
	ds_read_b128 v[218:221], v153 offset:17408
	global_load_lds_dwordx4 v[250:251], off
	s_or_b32 m0, s100, 0x2000
	v_lshl_add_u64 v[250:251], v[226:227], 0, s[40:41]
	global_load_lds_dwordx4 v[250:251], off
	s_barrier
	s_waitcnt lgkmcnt(0)
	v_mfma_f32_16x16x32_bf16 v[64:67], v[190:193], v[174:177], v[64:67]
	v_mfma_f32_16x16x32_bf16 v[60:63], v[190:193], v[182:185], v[60:63]
	v_mfma_f32_16x16x32_bf16 v[56:59], v[198:201], v[174:177], v[56:59]
	v_mfma_f32_16x16x32_bf16 v[52:55], v[198:201], v[182:185], v[52:55]
	v_mfma_f32_16x16x32_bf16 v[48:51], v[206:209], v[174:177], v[48:51]
	v_mfma_f32_16x16x32_bf16 v[44:47], v[206:209], v[182:185], v[44:47]
	v_mfma_f32_16x16x32_bf16 v[40:43], v[214:217], v[174:177], v[40:43]
	v_mfma_f32_16x16x32_bf16 v[36:39], v[214:217], v[182:185], v[36:39]
	v_mfma_f32_16x16x32_bf16 v[64:67], v[194:197], v[178:181], v[64:67]
	v_mfma_f32_16x16x32_bf16 v[60:63], v[194:197], v[186:189], v[60:63]
	v_mfma_f32_16x16x32_bf16 v[56:59], v[202:205], v[178:181], v[56:59]
	v_mfma_f32_16x16x32_bf16 v[52:55], v[202:205], v[186:189], v[52:55]
	v_mfma_f32_16x16x32_bf16 v[48:51], v[210:213], v[178:181], v[48:51]
	v_mfma_f32_16x16x32_bf16 v[44:47], v[210:213], v[186:189], v[44:47]
	v_mfma_f32_16x16x32_bf16 v[40:43], v[218:221], v[178:181], v[40:43]
	v_mfma_f32_16x16x32_bf16 v[36:39], v[218:221], v[186:189], v[36:39]
	s_barrier
	s_or_b32 m0, s100, 0x14000
	v_lshl_add_u64 v[174:175], v[228:229], 0, s[42:43]
	global_load_lds_dwordx4 v[174:175], off
	s_or_b32 m0, s100, 0x16000
	v_lshl_add_u64 v[174:175], v[236:237], 0, s[42:43]
	global_load_lds_dwordx4 v[174:175], off
	s_waitcnt vmcnt(6)
	s_barrier
; #define LDA8(dst, b, h) _Pragma("unroll") for (int m = 0; m < 4; ++m) _Pragma("unroll") for (int k = 0; k < 2; ++k) \
;     dst[m][k] = *(const bf16x8*)((const char*)SA8(b, h) + lds_byte8(wr * 64 + m * 16 + fr, k * 32 + fq * 8))
; #define LDB8(dst, b, h) _Pragma("unroll") for (int n = 0; n < 2; ++n) _Pragma("unroll") for (int k = 0; k < 2; ++k) \
;     dst[n][k] = *(const bf16x8*)((const char*)SB8(b, h) + lds_byte8(wc * 32 + n * 16 + fr, k * 32 + fq * 8))
; #define WAIT_V8(n) asm volatile("s_waitcnt vmcnt(" #n ")" ::: "memory")
; #define WAIT_L8(n) asm volatile("s_waitcnt lgkmcnt(" #n ")" ::: "memory")
; #define BAR8 __builtin_amdgcn_s_barrier()
; #define SCHED8 __builtin_amdgcn_sched_barrier(0)
;     ...
;     WAIT_V8(6); BAR8; MMA8(1, 1, At, B1); BAR8;
;     LDB8(B0, 1, 0); SCHED8; LDA8(At, 1, 0); STAGE8(SA8(0, 1), A, lda, brow + 128, tt + 2);
;     WAIT_L8(8); BAR8; WAIT_L8(0); MMA8(0, 0, At, B0); BAR8; SCHED8;
;     LDB8(B1, 1, 1); STAGE8(SB8(1, 0), Bt, K, bcol, tt + 3);
;     BAR8; WAIT_L8(0); MMA8(0, 1, At, B1); BAR8;
	v_mfma_f32_16x16x32_bf16 v[32:35], v[190:193], v[230:233], v[32:35]
	v_mfma_f32_16x16x32_bf16 v[28:31], v[190:193], v[242:245], v[28:31]
	v_mfma_f32_16x16x32_bf16 v[24:27], v[198:201], v[230:233], v[24:27]
	v_mfma_f32_16x16x32_bf16 v[20:23], v[198:201], v[242:245], v[20:23]
	v_mfma_f32_16x16x32_bf16 v[16:19], v[206:209], v[230:233], v[16:19]
	v_mfma_f32_16x16x32_bf16 v[12:15], v[206:209], v[242:245], v[12:15]
	v_mfma_f32_16x16x32_bf16 v[8:11], v[214:217], v[230:233], v[8:11]
	v_mfma_f32_16x16x32_bf16 v[4:7], v[214:217], v[242:245], v[4:7]
	v_mfma_f32_16x16x32_bf16 v[32:35], v[194:197], v[238:241], v[32:35]
	v_mfma_f32_16x16x32_bf16 v[28:31], v[194:197], v[246:249], v[28:31]
	v_mfma_f32_16x16x32_bf16 v[24:27], v[202:205], v[238:241], v[24:27]
	v_mfma_f32_16x16x32_bf16 v[20:23], v[202:205], v[246:249], v[20:23]
	v_mfma_f32_16x16x32_bf16 v[16:19], v[210:213], v[238:241], v[16:19]
	v_mfma_f32_16x16x32_bf16 v[12:15], v[210:213], v[246:249], v[12:15]
	v_mfma_f32_16x16x32_bf16 v[8:11], v[218:221], v[238:241], v[8:11]
	v_mfma_f32_16x16x32_bf16 v[4:7], v[218:221], v[246:249], v[4:7]
	s_barrier
	ds_read_b128 v[174:177], v160
	ds_read_b128 v[178:181], v160 offset:1024
	ds_read_b128 v[182:185], v160 offset:2048
	ds_read_b128 v[186:189], v160 offset:3072
	v_lshl_add_u64 v[230:231], v[222:223], 0, s[44:45]
	s_or_b32 m0, s100, 0x4000
	ds_read_b128 v[190:193], v156 offset:32768
	ds_read_b128 v[194:197], v156 offset:33792
	ds_read_b128 v[198:201], v155 offset:32768
	ds_read_b128 v[202:205], v155 offset:33792
	ds_read_b128 v[206:209], v154 offset:32768
	ds_read_b128 v[210:213], v154 offset:33792
	ds_read_b128 v[214:217], v153 offset:32768
	ds_read_b128 v[218:221], v153 offset:33792
	global_load_lds_dwordx4 v[230:231], off
	s_or_b32 m0, s100, 0x6000
	v_lshl_add_u64 v[230:231], v[226:227], 0, s[44:45]
	global_load_lds_dwordx4 v[230:231], off
	s_waitcnt lgkmcnt(8)
	s_barrier
	s_waitcnt lgkmcnt(0)
	v_mfma_f32_16x16x32_bf16 v[128:131], v[190:193], v[174:177], v[128:131]
	v_mfma_f32_16x16x32_bf16 v[124:127], v[190:193], v[182:185], v[124:127]
	v_mfma_f32_16x16x32_bf16 v[120:123], v[198:201], v[174:177], v[120:123]
	v_mfma_f32_16x16x32_bf16 v[116:119], v[198:201], v[182:185], v[116:119]
	v_mfma_f32_16x16x32_bf16 v[112:115], v[206:209], v[174:177], v[112:115]
	v_mfma_f32_16x16x32_bf16 v[108:111], v[206:209], v[182:185], v[108:111]
	v_mfma_f32_16x16x32_bf16 v[104:107], v[214:217], v[174:177], v[104:107]
	v_mfma_f32_16x16x32_bf16 v[100:103], v[214:217], v[182:185], v[100:103]
	v_mfma_f32_16x16x32_bf16 v[128:131], v[194:197], v[178:181], v[128:131]
	v_mfma_f32_16x16x32_bf16 v[124:127], v[194:197], v[186:189], v[124:127]
	v_mfma_f32_16x16x32_bf16 v[120:123], v[202:205], v[178:181], v[120:123]
	v_mfma_f32_16x16x32_bf16 v[116:119], v[202:205], v[186:189], v[116:119]
	v_mfma_f32_16x16x32_bf16 v[112:115], v[210:213], v[178:181], v[112:115]
	v_mfma_f32_16x16x32_bf16 v[108:111], v[210:213], v[186:189], v[108:111]
	v_mfma_f32_16x16x32_bf16 v[104:107], v[218:221], v[178:181], v[104:107]
	v_mfma_f32_16x16x32_bf16 v[100:103], v[218:221], v[186:189], v[100:103]
	s_barrier
	v_lshl_add_u64 v[250:251], v[228:229], 0, s[46:47]
	s_or_b32 m0, s100, 0x18000
	ds_read_b128 v[230:233], v158
	ds_read_b128 v[238:241], v158 offset:1024
	ds_read_b128 v[242:245], v158 offset:2048
	ds_read_b128 v[246:249], v158 offset:3072
	global_load_lds_dwordx4 v[250:251], off
	s_or_b32 m0, s100, 0x1a000
	v_lshl_add_u64 v[250:251], v[236:237], 0, s[46:47]
	global_load_lds_dwordx4 v[250:251], off
	s_barrier
; #define LDA8(dst, b, h) _Pragma("unroll") for (int m = 0; m < 4; ++m) _Pragma("unroll") for (int k = 0; k < 2; ++k) \
;     dst[m][k] = *(const bf16x8*)((const char*)SA8(b, h) + lds_byte8(wr * 64 + m * 16 + fr, k * 32 + fq * 8))
; #define WAIT_V8(n) asm volatile("s_waitcnt vmcnt(" #n ")" ::: "memory")
; #define WAIT_L8(n) asm volatile("s_waitcnt lgkmcnt(" #n ")" ::: "memory")
; #define BAR8 __builtin_amdgcn_s_barrier()
; #define SCHED8 __builtin_amdgcn_sched_barrier(0)
;     ...
;     BAR8; WAIT_L8(0); MMA8(0, 1, At, B1); BAR8;
;     LDA8(At, 1, 1); STAGE8(SA8(1, 0), A, lda, brow, tt + 3);
;     BAR8; WAIT_L8(0); MMA8(1, 0, At, B0); BAR8; SCHED8;
;     STAGE8(SB8(1, 1), Bt, K, bcol + 128, tt + 3);
;     WAIT_V8(6); BAR8; MMA8(1, 1, At, B1); BAR8;
;   }
	s_waitcnt lgkmcnt(0)
	v_mfma_f32_16x16x32_bf16 v[96:99], v[190:193], v[230:233], v[96:99]
	v_mfma_f32_16x16x32_bf16 v[92:95], v[190:193], v[242:245], v[92:95]
	v_mfma_f32_16x16x32_bf16 v[88:91], v[198:201], v[230:233], v[88:91]
	v_mfma_f32_16x16x32_bf16 v[84:87], v[198:201], v[242:245], v[84:87]
	v_mfma_f32_16x16x32_bf16 v[80:83], v[206:209], v[230:233], v[80:83]
	v_mfma_f32_16x16x32_bf16 v[76:79], v[206:209], v[242:245], v[76:79]
	v_mfma_f32_16x16x32_bf16 v[72:75], v[214:217], v[230:233], v[72:75]
	v_mfma_f32_16x16x32_bf16 v[68:71], v[214:217], v[242:245], v[68:71]
	v_mfma_f32_16x16x32_bf16 v[96:99], v[194:197], v[238:241], v[96:99]
	v_mfma_f32_16x16x32_bf16 v[92:95], v[194:197], v[246:249], v[92:95]
	v_mfma_f32_16x16x32_bf16 v[88:91], v[202:205], v[238:241], v[88:91]
	v_mfma_f32_16x16x32_bf16 v[84:87], v[202:205], v[246:249], v[84:87]
	v_mfma_f32_16x16x32_bf16 v[80:83], v[210:213], v[238:241], v[80:83]
	v_mfma_f32_16x16x32_bf16 v[76:79], v[210:213], v[246:249], v[76:79]
	v_mfma_f32_16x16x32_bf16 v[72:75], v[218:221], v[238:241], v[72:75]
	v_mfma_f32_16x16x32_bf16 v[68:71], v[218:221], v[246:249], v[68:71]
	v_lshl_add_u64 v[222:223], v[222:223], 0, s[48:49]
	s_or_b32 m0, s100, 0x8000
	s_barrier
	ds_read_b128 v[190:193], v156 offset:49152
	ds_read_b128 v[194:197], v156 offset:50176
	ds_read_b128 v[198:201], v155 offset:49152
	ds_read_b128 v[202:205], v155 offset:50176
	ds_read_b128 v[206:209], v154 offset:49152
	ds_read_b128 v[210:213], v154 offset:50176
	ds_read_b128 v[214:217], v153 offset:49152
	ds_read_b128 v[218:221], v153 offset:50176
	global_load_lds_dwordx4 v[222:223], off
	s_or_b32 m0, s100, 0xa000
	v_lshl_add_u64 v[222:223], v[226:227], 0, s[48:49]
	global_load_lds_dwordx4 v[222:223], off
	s_barrier
	s_waitcnt lgkmcnt(0)
	v_mfma_f32_16x16x32_bf16 v[64:67], v[190:193], v[174:177], v[64:67]
	v_mfma_f32_16x16x32_bf16 v[60:63], v[190:193], v[182:185], v[60:63]
	v_mfma_f32_16x16x32_bf16 v[56:59], v[198:201], v[174:177], v[56:59]
	v_mfma_f32_16x16x32_bf16 v[52:55], v[198:201], v[182:185], v[52:55]
	v_mfma_f32_16x16x32_bf16 v[48:51], v[206:209], v[174:177], v[48:51]
	v_mfma_f32_16x16x32_bf16 v[44:47], v[206:209], v[182:185], v[44:47]
	v_mfma_f32_16x16x32_bf16 v[40:43], v[214:217], v[174:177], v[40:43]
	v_mfma_f32_16x16x32_bf16 v[36:39], v[214:217], v[182:185], v[36:39]
	v_mfma_f32_16x16x32_bf16 v[64:67], v[194:197], v[178:181], v[64:67]
	v_mfma_f32_16x16x32_bf16 v[60:63], v[194:197], v[186:189], v[60:63]
	v_mfma_f32_16x16x32_bf16 v[56:59], v[202:205], v[178:181], v[56:59]
	v_mfma_f32_16x16x32_bf16 v[52:55], v[202:205], v[186:189], v[52:55]
	v_mfma_f32_16x16x32_bf16 v[48:51], v[210:213], v[178:181], v[48:51]
	v_mfma_f32_16x16x32_bf16 v[44:47], v[210:213], v[186:189], v[44:47]
	v_mfma_f32_16x16x32_bf16 v[40:43], v[218:221], v[178:181], v[40:43]
	v_mfma_f32_16x16x32_bf16 v[36:39], v[218:221], v[186:189], v[36:39]
	s_barrier
	s_or_b32 m0, s100, 0x1c000
	v_lshl_add_u64 v[174:175], v[228:229], 0, s[50:51]
	global_load_lds_dwordx4 v[174:175], off
	s_or_b32 m0, s100, 0x1e000
	v_lshl_add_u64 v[174:175], v[236:237], 0, s[50:51]
	global_load_lds_dwordx4 v[174:175], off
	s_waitcnt vmcnt(6)
	s_barrier
	v_mfma_f32_16x16x32_bf16 v[32:35], v[190:193], v[230:233], v[32:35]
	v_mfma_f32_16x16x32_bf16 v[28:31], v[190:193], v[242:245], v[28:31]
	v_mfma_f32_16x16x32_bf16 v[24:27], v[198:201], v[230:233], v[24:27]
	v_mfma_f32_16x16x32_bf16 v[20:23], v[198:201], v[242:245], v[20:23]
	v_mfma_f32_16x16x32_bf16 v[16:19], v[206:209], v[230:233], v[16:19]
	v_mfma_f32_16x16x32_bf16 v[12:15], v[206:209], v[242:245], v[12:15]
	v_mfma_f32_16x16x32_bf16 v[8:11], v[214:217], v[230:233], v[8:11]
	v_mfma_f32_16x16x32_bf16 v[4:7], v[214:217], v[242:245], v[4:7]
	v_mfma_f32_16x16x32_bf16 v[32:35], v[194:197], v[238:241], v[32:35]
	v_mfma_f32_16x16x32_bf16 v[28:31], v[194:197], v[246:249], v[28:31]
	v_mfma_f32_16x16x32_bf16 v[24:27], v[202:205], v[238:241], v[24:27]
	v_mfma_f32_16x16x32_bf16 v[20:23], v[202:205], v[246:249], v[20:23]
	v_mfma_f32_16x16x32_bf16 v[16:19], v[210:213], v[238:241], v[16:19]
	v_mfma_f32_16x16x32_bf16 v[12:15], v[210:213], v[246:249], v[12:15]
	v_mfma_f32_16x16x32_bf16 v[8:11], v[218:221], v[238:241], v[8:11]
	v_mfma_f32_16x16x32_bf16 v[4:7], v[218:221], v[246:249], v[4:7]
	s_add_i32 s29, s29, 2
	s_add_u32 s12, s12, 0x100
	s_addc_u32 s13, s13, 0
	s_cmp_lt_u32 s29, 12
	s_cbranch_scc1 .LBB0_908

; #define LDA8(dst, b, h) _Pragma("unroll") for (int m = 0; m < 4; ++m) _Pragma("unroll") for (int k = 0; k < 2; ++k) \
;     dst[m][k] = *(const bf16x8*)((const char*)SA8(b, h) + lds_byte8(wr * 64 + m * 16 + fr, k * 32 + fq * 8))
; #define LDB8(dst, b, h) _Pragma("unroll") for (int n = 0; n < 2; ++n) _Pragma("unroll") for (int k = 0; k < 2; ++k) \
;     dst[n][k] = *(const bf16x8*)((const char*)SB8(b, h) + lds_byte8(wc * 32 + n * 16 + fr, k * 32 + fq * 8))
; #define WAIT_V8(n) asm volatile("s_waitcnt vmcnt(" #n ")" ::: "memory")
; #define WAIT_L8(n) asm volatile("s_waitcnt lgkmcnt(" #n ")" ::: "memory")
; #define BAR8 __builtin_amdgcn_s_barrier()
; #define SCHED8 __builtin_amdgcn_sched_barrier(0)
;     ...
;   if (wr == 1) BAR8;
;   WAIT_V8(4); BAR8;
;   STAGE8(SB8(1, 0), Bt, K, bcol, 1); STAGE8(SA8(1, 0), A, lda, brow, 1); STAGE8(SB8(1, 1), Bt, K, bcol + 128, 1);
;   WAIT_V8(6); BAR8;
;   for (int tt = 0; tt < nt - 2; tt += 2) {
;     LDB8(B0, 0, 0); SCHED8; LDA8(At, 0, 0); STAGE8(SA8(1, 1), A, lda, brow + 128, tt + 1);
;     WAIT_L8(8); BAR8; WAIT_L8(0); MMA8(0, 0, At, B0); BAR8; SCHED8;
;     LDB8(B1, 0, 1); STAGE8(SB8(0, 0), Bt, K, bcol, tt + 2);
;     BAR8; WAIT_L8(0); MMA8(0, 1, At, B1); BAR8;
.LBB0_1004:
	s_or_b64 exec, exec, s[20:21]
	v_readlane_b32 s40, v254, 35
	s_lshl_b32 s20, s36, 10
	v_readlane_b32 s42, v254, 37
	v_readlane_b32 s43, v254, 38
	s_waitcnt vmcnt(0)
	s_and_b32 s20, s20, 0xfffc0000
	s_mov_b32 s21, s40
	s_mov_b64 s[42:43], 0x80
	s_and_b32 s1, s27, 7
	s_add_i32 s20, s20, 0xffc00000
	v_lshl_add_u64 v[10:11], v[10:11], 0, s[42:43]
	s_or_b32 m0, s100, 0x18000
	s_lshl_b32 s1, s1, 19
	s_lshl_b64 s[20:21], s[20:21], 1
	s_waitcnt vmcnt(4)
	s_barrier
	global_load_lds_dwordx4 v[10:11], off
	v_lshl_add_u64 v[10:11], v[12:13], 0, s[42:43]
	s_or_b32 m0, s100, 0x1a000
	global_load_lds_dwordx4 v[10:11], off
	v_lshl_add_u64 v[10:11], v[16:17], 0, s[42:43]
	s_or_b32 m0, s100, 0x8000
	s_add_u32 s14, s14, 0x40080
	global_load_lds_dwordx4 v[10:11], off
	v_lshl_add_u64 v[10:11], v[14:15], 0, s[42:43]
	s_addc_u32 s15, s15, 0
	s_or_b32 m0, s100, 0xa000
	global_load_lds_dwordx4 v[10:11], off
	v_lshl_add_u64 v[10:11], s[14:15], 0, v[132:133]
	v_lshl_add_u64 v[10:11], v[10:11], 0, v[6:7]
	s_or_b32 m0, s100, 0x1c000
	global_load_lds_dwordx4 v[10:11], off
	v_lshl_add_u64 v[10:11], s[14:15], 0, v[136:137]
	v_lshl_add_u64 v[10:11], v[10:11], 0, v[8:9]
	s_or_b32 m0, s100, 0x1e000
	v_and_b32_e32 v147, 15, v3
	global_load_lds_dwordx4 v[10:11], off
	v_bfe_u32 v148, v3, 4, 2
	v_lshlrev_b32_e32 v11, 4, v148
	v_lshlrev_b32_e32 v12, 6, v147
	v_lshlrev_b32_e32 v14, 2, v3
	v_or_b32_e32 v13, v11, v12
	v_and_b32_e32 v14, 32, v14
	s_mov_b32 s14, 0x10000
	v_bitop3_b32 v15, v13, s14, v14 bitop3:0xde
	s_mov_b32 s14, 0x14000
	s_add_u32 s12, s12, s1
	v_bitop3_b32 v16, v13, s14, v14 bitop3:0xde
	s_mov_b32 s14, 0x18000
	v_lshlrev_b32_e32 v18, 6, v3
	s_addc_u32 s13, s13, 0
	v_lshl_add_u64 v[8:9], v[136:137], 0, v[8:9]
	v_lshl_add_u64 v[6:7], v[132:133], 0, v[6:7]
	v_bfe_u32 v146, v3, 6, 2
	s_waitcnt vmcnt(6)
	v_lshlrev_b32_e32 v149, 6, v5
	v_bitop3_b32 v17, v13, s14, v14 bitop3:0xde
	s_mov_b32 s14, 0x1c000
	v_lshlrev_b32_e32 v5, 13, v5
	v_and_b32_e32 v18, 0x3c0, v18
	v_lshl_add_u64 v[138:139], s[12:13], 0, v[8:9]
	v_lshl_add_u64 v[140:141], s[12:13], 0, v[6:7]
	s_add_u32 s12, s4, s20
	v_readlane_b32 s41, v254, 36
	v_lshlrev_b32_e32 v10, 12, v146
	v_bitop3_b32 v12, v11, v14, v12 bitop3:0x36
	v_bitop3_b32 v13, v13, s14, v14 bitop3:0xde
	v_bitop3_b32 v11, v18, v14, v11 bitop3:0x36
	v_or_b32_e32 v14, 0x800, v5
	v_or_b32_e32 v18, 0x1000, v5
	v_or_b32_e32 v19, 0x1800, v5
	s_addc_u32 s13, s5, s21
	v_lshl_add_u64 v[142:143], s[12:13], 0, v[6:7]
	v_lshl_add_u64 v[144:145], s[12:13], 0, v[8:9]
	s_mov_b32 s1, -2
	s_mov_b64 s[12:13], 0
	v_add_u32_e32 v171, v15, v10
	v_add_u32_e32 v156, v12, v5
	v_add_u32_e32 v155, v11, v14
	v_add_u32_e32 v154, v11, v18
	v_add_u32_e32 v153, v11, v19
	v_add_u32_e32 v168, v16, v10
	v_add_u32_e32 v161, v17, v10
	v_add_u32_e32 v158, v13, v10
	s_mov_b64 s[20:21], 0xb840080
	s_mov_b64 s[40:41], 0xc7a0100
	s_mov_b64 s[42:43], 0xb800100
	s_mov_b64 s[44:45], 0xc7e0100
	s_mov_b64 s[46:47], 0xb840100
	s_mov_b64 s[48:49], 0xc7a0180
	s_mov_b64 s[50:51], 0xb800180
	s_mov_b64 s[52:53], 0xc7e0180
	s_barrier
	ds_read_b128 v[174:177], v171
	ds_read_b128 v[178:181], v171 offset:1024
	ds_read_b128 v[182:185], v171 offset:2048
	ds_read_b128 v[186:189], v171 offset:3072
	v_lshl_add_u64 v[222:223], v[140:141], 0, s[12:13]
	v_lshl_add_u64 v[226:227], v[222:223], 0, s[20:21]
	s_or_b32 m0, s100, 0xc000
	v_lshl_add_u64 v[236:237], v[138:139], 0, s[12:13]
	ds_read_b128 v[190:193], v156
	ds_read_b128 v[194:197], v156 offset:1024
	ds_read_b128 v[198:201], v155
	ds_read_b128 v[202:205], v155 offset:1024
	ds_read_b128 v[206:209], v154
	ds_read_b128 v[210:213], v154 offset:1024
	ds_read_b128 v[214:217], v153
	ds_read_b128 v[218:221], v153 offset:1024
	global_load_lds_dwordx4 v[226:227], off
	s_or_b32 m0, s100, 0xe000
	v_lshl_add_u64 v[226:227], v[236:237], 0, s[20:21]
	global_load_lds_dwordx4 v[226:227], off
	s_waitcnt lgkmcnt(8)
	s_barrier
	s_waitcnt lgkmcnt(0)
	v_mfma_f32_16x16x32_bf16 v[128:131], v[190:193], v[174:177], 0
	v_mfma_f32_16x16x32_bf16 v[124:127], v[190:193], v[182:185], 0
	v_mfma_f32_16x16x32_bf16 v[120:123], v[198:201], v[174:177], 0
	v_mfma_f32_16x16x32_bf16 v[116:119], v[198:201], v[182:185], 0
	v_mfma_f32_16x16x32_bf16 v[112:115], v[206:209], v[174:177], 0
	v_mfma_f32_16x16x32_bf16 v[108:111], v[206:209], v[182:185], 0
	v_mfma_f32_16x16x32_bf16 v[104:107], v[214:217], v[174:177], 0
	v_mfma_f32_16x16x32_bf16 v[100:103], v[214:217], v[182:185], 0
	v_mfma_f32_16x16x32_bf16 v[128:131], v[194:197], v[178:181], v[128:131]
	v_mfma_f32_16x16x32_bf16 v[124:127], v[194:197], v[186:189], v[124:127]
	v_mfma_f32_16x16x32_bf16 v[120:123], v[202:205], v[178:181], v[120:123]
	v_mfma_f32_16x16x32_bf16 v[116:119], v[202:205], v[186:189], v[116:119]
	v_mfma_f32_16x16x32_bf16 v[112:115], v[210:213], v[178:181], v[112:115]
	v_mfma_f32_16x16x32_bf16 v[108:111], v[210:213], v[186:189], v[108:111]
	v_mfma_f32_16x16x32_bf16 v[104:107], v[218:221], v[178:181], v[104:107]
	v_mfma_f32_16x16x32_bf16 v[100:103], v[218:221], v[186:189], v[100:103]
	s_barrier
	v_lshl_add_u64 v[246:247], v[142:143], 0, s[12:13]
	v_lshl_add_u64 v[248:249], v[246:247], 0, s[40:41]
	s_or_b32 m0, s100, 0x10000
	ds_read_b128 v[226:229], v168
	ds_read_b128 v[230:233], v168 offset:1024
	ds_read_b128 v[238:241], v168 offset:2048
	ds_read_b128 v[242:245], v168 offset:3072
	global_load_lds_dwordx4 v[248:249], off
	v_lshl_add_u64 v[248:249], v[144:145], 0, s[12:13]
	s_or_b32 m0, s100, 0x12000
	v_lshl_add_u64 v[250:251], v[248:249], 0, s[40:41]
	global_load_lds_dwordx4 v[250:251], off
	s_barrier
; #define LDA8(dst, b, h) _Pragma("unroll") for (int m = 0; m < 4; ++m) _Pragma("unroll") for (int k = 0; k < 2; ++k) \
;     dst[m][k] = *(const bf16x8*)((const char*)SA8(b, h) + lds_byte8(wr * 64 + m * 16 + fr, k * 32 + fq * 8))
; #define LDB8(dst, b, h) _Pragma("unroll") for (int n = 0; n < 2; ++n) _Pragma("unroll") for (int k = 0; k < 2; ++k) \
;     dst[n][k] = *(const bf16x8*)((const char*)SB8(b, h) + lds_byte8(wc * 32 + n * 16 + fr, k * 32 + fq * 8))
; #define WAIT_V8(n) asm volatile("s_waitcnt vmcnt(" #n ")" ::: "memory")
; #define WAIT_L8(n) asm volatile("s_waitcnt lgkmcnt(" #n ")" ::: "memory")
; #define BAR8 __builtin_amdgcn_s_barrier()
; #define SCHED8 __builtin_amdgcn_sched_barrier(0)
;     ...
;     BAR8; WAIT_L8(0); MMA8(0, 1, At, B1); BAR8;
;     LDA8(At, 0, 1); STAGE8(SA8(0, 0), A, lda, brow, tt + 2);
;     BAR8; WAIT_L8(0); MMA8(1, 0, At, B0); BAR8; SCHED8;
;     STAGE8(SB8(0, 1), Bt, K, bcol + 128, tt + 2);
;     WAIT_V8(6); BAR8; MMA8(1, 1, At, B1); BAR8;
;     LDB8(B0, 1, 0); SCHED8; LDA8(At, 1, 0); STAGE8(SA8(0, 1), A, lda, brow + 128, tt + 2);
;     WAIT_L8(8); BAR8; WAIT_L8(0); MMA8(0, 0, At, B0); BAR8; SCHED8;
	s_waitcnt lgkmcnt(0)
	v_mfma_f32_16x16x32_bf16 v[96:99], v[190:193], v[226:229], 0
	v_mfma_f32_16x16x32_bf16 v[92:95], v[190:193], v[238:241], 0
	v_mfma_f32_16x16x32_bf16 v[88:91], v[198:201], v[226:229], 0
	v_mfma_f32_16x16x32_bf16 v[84:87], v[198:201], v[238:241], 0
	v_mfma_f32_16x16x32_bf16 v[80:83], v[206:209], v[226:229], 0
	v_mfma_f32_16x16x32_bf16 v[76:79], v[206:209], v[238:241], 0
	v_mfma_f32_16x16x32_bf16 v[72:75], v[214:217], v[226:229], 0
	v_mfma_f32_16x16x32_bf16 v[68:71], v[214:217], v[238:241], 0
	v_mfma_f32_16x16x32_bf16 v[96:99], v[194:197], v[230:233], v[96:99]
	v_mfma_f32_16x16x32_bf16 v[92:95], v[194:197], v[242:245], v[92:95]
	v_mfma_f32_16x16x32_bf16 v[88:91], v[202:205], v[230:233], v[88:91]
	v_mfma_f32_16x16x32_bf16 v[84:87], v[202:205], v[242:245], v[84:87]
	v_mfma_f32_16x16x32_bf16 v[80:83], v[210:213], v[230:233], v[80:83]
	v_mfma_f32_16x16x32_bf16 v[76:79], v[210:213], v[242:245], v[76:79]
	v_mfma_f32_16x16x32_bf16 v[72:75], v[218:221], v[230:233], v[72:75]
	v_mfma_f32_16x16x32_bf16 v[68:71], v[218:221], v[242:245], v[68:71]
	v_lshl_add_u64 v[250:251], v[222:223], 0, s[42:43]
	s_mov_b32 m0, s100
	s_barrier
	ds_read_b128 v[190:193], v156 offset:16384
	ds_read_b128 v[194:197], v156 offset:17408
	ds_read_b128 v[198:201], v155 offset:16384
	ds_read_b128 v[202:205], v155 offset:17408
	ds_read_b128 v[206:209], v154 offset:16384
	ds_read_b128 v[210:213], v154 offset:17408
	ds_read_b128 v[214:217], v153 offset:16384
	ds_read_b128 v[218:221], v153 offset:17408
	global_load_lds_dwordx4 v[250:251], off
	s_or_b32 m0, s100, 0x2000
	v_lshl_add_u64 v[250:251], v[236:237], 0, s[42:43]
	global_load_lds_dwordx4 v[250:251], off
	s_barrier
	s_waitcnt lgkmcnt(0)
	v_mfma_f32_16x16x32_bf16 v[64:67], v[190:193], v[174:177], 0
	v_mfma_f32_16x16x32_bf16 v[60:63], v[190:193], v[182:185], 0
	v_mfma_f32_16x16x32_bf16 v[56:59], v[198:201], v[174:177], 0
	v_mfma_f32_16x16x32_bf16 v[52:55], v[198:201], v[182:185], 0
	v_mfma_f32_16x16x32_bf16 v[48:51], v[206:209], v[174:177], 0
	v_mfma_f32_16x16x32_bf16 v[44:47], v[206:209], v[182:185], 0
	v_mfma_f32_16x16x32_bf16 v[40:43], v[214:217], v[174:177], 0
	v_mfma_f32_16x16x32_bf16 v[36:39], v[214:217], v[182:185], 0
	v_mfma_f32_16x16x32_bf16 v[64:67], v[194:197], v[178:181], v[64:67]
	v_mfma_f32_16x16x32_bf16 v[60:63], v[194:197], v[186:189], v[60:63]
	v_mfma_f32_16x16x32_bf16 v[56:59], v[202:205], v[178:181], v[56:59]
	v_mfma_f32_16x16x32_bf16 v[52:55], v[202:205], v[186:189], v[52:55]
	v_mfma_f32_16x16x32_bf16 v[48:51], v[210:213], v[178:181], v[48:51]
	v_mfma_f32_16x16x32_bf16 v[44:47], v[210:213], v[186:189], v[44:47]
	v_mfma_f32_16x16x32_bf16 v[40:43], v[218:221], v[178:181], v[40:43]
	v_mfma_f32_16x16x32_bf16 v[36:39], v[218:221], v[186:189], v[36:39]
	s_barrier
	s_or_b32 m0, s100, 0x14000
	v_lshl_add_u64 v[174:175], v[246:247], 0, s[44:45]
	global_load_lds_dwordx4 v[174:175], off
	s_or_b32 m0, s100, 0x16000
	v_lshl_add_u64 v[174:175], v[248:249], 0, s[44:45]
	global_load_lds_dwordx4 v[174:175], off
	s_waitcnt vmcnt(6)
	s_barrier
	v_mfma_f32_16x16x32_bf16 v[32:35], v[190:193], v[226:229], 0
	v_mfma_f32_16x16x32_bf16 v[28:31], v[190:193], v[238:241], 0
	v_mfma_f32_16x16x32_bf16 v[24:27], v[198:201], v[226:229], 0
	v_mfma_f32_16x16x32_bf16 v[20:23], v[198:201], v[238:241], 0
	v_mfma_f32_16x16x32_bf16 v[16:19], v[206:209], v[226:229], 0
	v_mfma_f32_16x16x32_bf16 v[12:15], v[206:209], v[238:241], 0
	v_mfma_f32_16x16x32_bf16 v[8:11], v[214:217], v[226:229], 0
	v_mfma_f32_16x16x32_bf16 v[4:7], v[214:217], v[238:241], 0
	v_mfma_f32_16x16x32_bf16 v[32:35], v[194:197], v[230:233], v[32:35]
	v_mfma_f32_16x16x32_bf16 v[28:31], v[194:197], v[242:245], v[28:31]
	v_mfma_f32_16x16x32_bf16 v[24:27], v[202:205], v[230:233], v[24:27]
	v_mfma_f32_16x16x32_bf16 v[20:23], v[202:205], v[242:245], v[20:23]
	v_mfma_f32_16x16x32_bf16 v[16:19], v[210:213], v[230:233], v[16:19]
	v_mfma_f32_16x16x32_bf16 v[12:15], v[210:213], v[242:245], v[12:15]
	v_mfma_f32_16x16x32_bf16 v[8:11], v[218:221], v[230:233], v[8:11]
	v_mfma_f32_16x16x32_bf16 v[4:7], v[218:221], v[242:245], v[4:7]
	s_barrier
	ds_read_b128 v[174:177], v161
	ds_read_b128 v[178:181], v161 offset:1024
	ds_read_b128 v[182:185], v161 offset:2048
	ds_read_b128 v[186:189], v161 offset:3072
	v_lshl_add_u64 v[226:227], v[222:223], 0, s[46:47]
	s_or_b32 m0, s100, 0x4000
	ds_read_b128 v[190:193], v156 offset:32768
	ds_read_b128 v[194:197], v156 offset:33792
	ds_read_b128 v[198:201], v155 offset:32768
	ds_read_b128 v[202:205], v155 offset:33792
	ds_read_b128 v[206:209], v154 offset:32768
	ds_read_b128 v[210:213], v154 offset:33792
	ds_read_b128 v[214:217], v153 offset:32768
	ds_read_b128 v[218:221], v153 offset:33792
	global_load_lds_dwordx4 v[226:227], off
	s_or_b32 m0, s100, 0x6000
	v_lshl_add_u64 v[226:227], v[236:237], 0, s[46:47]
	global_load_lds_dwordx4 v[226:227], off
	s_waitcnt lgkmcnt(8)
	s_barrier
	s_waitcnt lgkmcnt(0)
	v_mfma_f32_16x16x32_bf16 v[128:131], v[190:193], v[174:177], v[128:131]
	v_mfma_f32_16x16x32_bf16 v[124:127], v[190:193], v[182:185], v[124:127]
	v_mfma_f32_16x16x32_bf16 v[120:123], v[198:201], v[174:177], v[120:123]
	v_mfma_f32_16x16x32_bf16 v[116:119], v[198:201], v[182:185], v[116:119]
	v_mfma_f32_16x16x32_bf16 v[112:115], v[206:209], v[174:177], v[112:115]
	v_mfma_f32_16x16x32_bf16 v[108:111], v[206:209], v[182:185], v[108:111]
	v_mfma_f32_16x16x32_bf16 v[104:107], v[214:217], v[174:177], v[104:107]
	v_mfma_f32_16x16x32_bf16 v[100:103], v[214:217], v[182:185], v[100:103]
	v_mfma_f32_16x16x32_bf16 v[128:131], v[194:197], v[178:181], v[128:131]
	v_mfma_f32_16x16x32_bf16 v[124:127], v[194:197], v[186:189], v[124:127]
	v_mfma_f32_16x16x32_bf16 v[120:123], v[202:205], v[178:181], v[120:123]
	v_mfma_f32_16x16x32_bf16 v[116:119], v[202:205], v[186:189], v[116:119]
	v_mfma_f32_16x16x32_bf16 v[112:115], v[210:213], v[178:181], v[112:115]
	v_mfma_f32_16x16x32_bf16 v[108:111], v[210:213], v[186:189], v[108:111]
	v_mfma_f32_16x16x32_bf16 v[104:107], v[218:221], v[178:181], v[104:107]
	v_mfma_f32_16x16x32_bf16 v[100:103], v[218:221], v[186:189], v[100:103]
	s_barrier
; #define LDA8(dst, b, h) _Pragma("unroll") for (int m = 0; m < 4; ++m) _Pragma("unroll") for (int k = 0; k < 2; ++k) \
;     dst[m][k] = *(const bf16x8*)((const char*)SA8(b, h) + lds_byte8(wr * 64 + m * 16 + fr, k * 32 + fq * 8))
; #define LDB8(dst, b, h) _Pragma("unroll") for (int n = 0; n < 2; ++n) _Pragma("unroll") for (int k = 0; k < 2; ++k) \
;     dst[n][k] = *(const bf16x8*)((const char*)SB8(b, h) + lds_byte8(wc * 32 + n * 16 + fr, k * 32 + fq * 8))
; #define WAIT_V8(n) asm volatile("s_waitcnt vmcnt(" #n ")" ::: "memory")
; #define WAIT_L8(n) asm volatile("s_waitcnt lgkmcnt(" #n ")" ::: "memory")
; #define BAR8 __builtin_amdgcn_s_barrier()
; #define SCHED8 __builtin_amdgcn_sched_barrier(0)
;     ...
;   for (int tt = 0; tt < nt - 2; tt += 2) {
;     LDB8(B0, 0, 0); SCHED8; LDA8(At, 0, 0); STAGE8(SA8(1, 1), A, lda, brow + 128, tt + 1);
;     WAIT_L8(8); BAR8; WAIT_L8(0); MMA8(0, 0, At, B0); BAR8; SCHED8;
;     LDB8(B1, 0, 1); STAGE8(SB8(0, 0), Bt, K, bcol, tt + 2);
;     BAR8; WAIT_L8(0); MMA8(0, 1, At, B1); BAR8;
;     LDA8(At, 0, 1); STAGE8(SA8(0, 0), A, lda, brow, tt + 2);
;     BAR8; WAIT_L8(0); MMA8(1, 0, At, B0); BAR8; SCHED8;
;     STAGE8(SB8(0, 1), Bt, K, bcol + 128, tt + 2);
;     WAIT_V8(6); BAR8; MMA8(1, 1, At, B1); BAR8;
;     LDB8(B0, 1, 0); SCHED8; LDA8(At, 1, 0); STAGE8(SA8(0, 1), A, lda, brow + 128, tt + 2);
;     WAIT_L8(8); BAR8; WAIT_L8(0); MMA8(0, 0, At, B0); BAR8; SCHED8;
;     LDB8(B1, 1, 1); STAGE8(SB8(1, 0), Bt, K, bcol, tt + 3);
;     BAR8; WAIT_L8(0); MMA8(0, 1, At, B1); BAR8;
;     LDA8(At, 1, 1); STAGE8(SA8(1, 0), A, lda, brow, tt + 3);
;     BAR8; WAIT_L8(0); MMA8(1, 0, At, B0); BAR8; SCHED8;
;     STAGE8(SB8(1, 1), Bt, K, bcol + 128, tt + 3);
;     WAIT_V8(6); BAR8; MMA8(1, 1, At, B1); BAR8;
;   }
	v_lshl_add_u64 v[250:251], v[246:247], 0, s[48:49]
	s_or_b32 m0, s100, 0x18000
	ds_read_b128 v[226:229], v158
	ds_read_b128 v[230:233], v158 offset:1024
	ds_read_b128 v[238:241], v158 offset:2048
	ds_read_b128 v[242:245], v158 offset:3072
	global_load_lds_dwordx4 v[250:251], off
	s_or_b32 m0, s100, 0x1a000
	v_lshl_add_u64 v[250:251], v[248:249], 0, s[48:49]
	global_load_lds_dwordx4 v[250:251], off
	s_barrier
	s_waitcnt lgkmcnt(0)
	v_mfma_f32_16x16x32_bf16 v[96:99], v[190:193], v[226:229], v[96:99]
	v_mfma_f32_16x16x32_bf16 v[92:95], v[190:193], v[238:241], v[92:95]
	v_mfma_f32_16x16x32_bf16 v[88:91], v[198:201], v[226:229], v[88:91]
	v_mfma_f32_16x16x32_bf16 v[84:87], v[198:201], v[238:241], v[84:87]
	v_mfma_f32_16x16x32_bf16 v[80:83], v[206:209], v[226:229], v[80:83]
	v_mfma_f32_16x16x32_bf16 v[76:79], v[206:209], v[238:241], v[76:79]
	v_mfma_f32_16x16x32_bf16 v[72:75], v[214:217], v[226:229], v[72:75]
	v_mfma_f32_16x16x32_bf16 v[68:71], v[214:217], v[238:241], v[68:71]
	v_mfma_f32_16x16x32_bf16 v[96:99], v[194:197], v[230:233], v[96:99]
	v_mfma_f32_16x16x32_bf16 v[92:95], v[194:197], v[242:245], v[92:95]
	v_mfma_f32_16x16x32_bf16 v[88:91], v[202:205], v[230:233], v[88:91]
	v_mfma_f32_16x16x32_bf16 v[84:87], v[202:205], v[242:245], v[84:87]
	v_mfma_f32_16x16x32_bf16 v[80:83], v[210:213], v[230:233], v[80:83]
	v_mfma_f32_16x16x32_bf16 v[76:79], v[210:213], v[242:245], v[76:79]
	v_mfma_f32_16x16x32_bf16 v[72:75], v[218:221], v[230:233], v[72:75]
	v_mfma_f32_16x16x32_bf16 v[68:71], v[218:221], v[242:245], v[68:71]
	v_lshl_add_u64 v[222:223], v[222:223], 0, s[50:51]
	s_or_b32 m0, s100, 0x8000
	s_barrier
	ds_read_b128 v[190:193], v156 offset:49152
	ds_read_b128 v[194:197], v156 offset:50176
	ds_read_b128 v[198:201], v155 offset:49152
	ds_read_b128 v[202:205], v155 offset:50176
	ds_read_b128 v[206:209], v154 offset:49152
	ds_read_b128 v[210:213], v154 offset:50176
	ds_read_b128 v[214:217], v153 offset:49152
	ds_read_b128 v[218:221], v153 offset:50176
	global_load_lds_dwordx4 v[222:223], off
	s_or_b32 m0, s100, 0xa000
	v_lshl_add_u64 v[222:223], v[236:237], 0, s[50:51]
	global_load_lds_dwordx4 v[222:223], off
	s_barrier
	s_waitcnt lgkmcnt(0)
	v_mfma_f32_16x16x32_bf16 v[64:67], v[190:193], v[174:177], v[64:67]
	v_mfma_f32_16x16x32_bf16 v[60:63], v[190:193], v[182:185], v[60:63]
	v_mfma_f32_16x16x32_bf16 v[56:59], v[198:201], v[174:177], v[56:59]
	v_mfma_f32_16x16x32_bf16 v[52:55], v[198:201], v[182:185], v[52:55]
	v_mfma_f32_16x16x32_bf16 v[48:51], v[206:209], v[174:177], v[48:51]
	v_mfma_f32_16x16x32_bf16 v[44:47], v[206:209], v[182:185], v[44:47]
	v_mfma_f32_16x16x32_bf16 v[40:43], v[214:217], v[174:177], v[40:43]
	v_mfma_f32_16x16x32_bf16 v[36:39], v[214:217], v[182:185], v[36:39]
	v_mfma_f32_16x16x32_bf16 v[64:67], v[194:197], v[178:181], v[64:67]
	v_mfma_f32_16x16x32_bf16 v[60:63], v[194:197], v[186:189], v[60:63]
	v_mfma_f32_16x16x32_bf16 v[56:59], v[202:205], v[178:181], v[56:59]
	v_mfma_f32_16x16x32_bf16 v[52:55], v[202:205], v[186:189], v[52:55]
	v_mfma_f32_16x16x32_bf16 v[48:51], v[210:213], v[178:181], v[48:51]
	v_mfma_f32_16x16x32_bf16 v[44:47], v[210:213], v[186:189], v[44:47]
	v_mfma_f32_16x16x32_bf16 v[40:43], v[218:221], v[178:181], v[40:43]
	v_mfma_f32_16x16x32_bf16 v[36:39], v[218:221], v[186:189], v[36:39]
	s_barrier
	s_or_b32 m0, s100, 0x1c000
	v_lshl_add_u64 v[174:175], v[246:247], 0, s[52:53]
	global_load_lds_dwordx4 v[174:175], off
	s_or_b32 m0, s100, 0x1e000
	v_lshl_add_u64 v[174:175], v[248:249], 0, s[52:53]
	global_load_lds_dwordx4 v[174:175], off
	s_waitcnt vmcnt(6)
	s_barrier
	v_mfma_f32_16x16x32_bf16 v[32:35], v[190:193], v[226:229], v[32:35]
	v_mfma_f32_16x16x32_bf16 v[28:31], v[190:193], v[238:241], v[28:31]
	v_mfma_f32_16x16x32_bf16 v[24:27], v[198:201], v[226:229], v[24:27]
	v_mfma_f32_16x16x32_bf16 v[20:23], v[198:201], v[238:241], v[20:23]
	v_mfma_f32_16x16x32_bf16 v[16:19], v[206:209], v[226:229], v[16:19]
	v_mfma_f32_16x16x32_bf16 v[12:15], v[206:209], v[238:241], v[12:15]
	v_mfma_f32_16x16x32_bf16 v[8:11], v[214:217], v[226:229], v[8:11]
	v_mfma_f32_16x16x32_bf16 v[4:7], v[214:217], v[238:241], v[4:7]
	v_mfma_f32_16x16x32_bf16 v[32:35], v[194:197], v[230:233], v[32:35]
	v_mfma_f32_16x16x32_bf16 v[28:31], v[194:197], v[242:245], v[28:31]
	v_mfma_f32_16x16x32_bf16 v[24:27], v[202:205], v[230:233], v[24:27]
	v_mfma_f32_16x16x32_bf16 v[20:23], v[202:205], v[242:245], v[20:23]
	v_mfma_f32_16x16x32_bf16 v[16:19], v[210:213], v[230:233], v[16:19]
	v_mfma_f32_16x16x32_bf16 v[12:15], v[210:213], v[242:245], v[12:15]
	v_mfma_f32_16x16x32_bf16 v[8:11], v[218:221], v[230:233], v[8:11]
	v_mfma_f32_16x16x32_bf16 v[4:7], v[218:221], v[242:245], v[4:7]
	s_add_i32 s1, s1, 2
	s_add_u32 s12, s12, 0x100
	s_addc_u32 s13, s13, 0
	s_cmp_lt_u32 s1, 12
	s_cbranch_scc0 .Lpk_exitb_3
; #define LDA8(dst, b, h) _Pragma("unroll") for (int m = 0; m < 4; ++m) _Pragma("unroll") for (int k = 0; k < 2; ++k) \
;     dst[m][k] = *(const bf16x8*)((const char*)SA8(b, h) + lds_byte8(wr * 64 + m * 16 + fr, k * 32 + fq * 8))
; #define LDB8(dst, b, h) _Pragma("unroll") for (int n = 0; n < 2; ++n) _Pragma("unroll") for (int k = 0; k < 2; ++k) \
;     dst[n][k] = *(const bf16x8*)((const char*)SB8(b, h) + lds_byte8(wc * 32 + n * 16 + fr, k * 32 + fq * 8))
; #define WAIT_V8(n) asm volatile("s_waitcnt vmcnt(" #n ")" ::: "memory")
; #define WAIT_L8(n) asm volatile("s_waitcnt lgkmcnt(" #n ")" ::: "memory")
; #define BAR8 __builtin_amdgcn_s_barrier()
; #define SCHED8 __builtin_amdgcn_sched_barrier(0)
;     ...
;   for (int tt = 0; tt < nt - 2; tt += 2) {
;     LDB8(B0, 0, 0); SCHED8; LDA8(At, 0, 0); STAGE8(SA8(1, 1), A, lda, brow + 128, tt + 1);
;     WAIT_L8(8); BAR8; WAIT_L8(0); MMA8(0, 0, At, B0); BAR8; SCHED8;
;     LDB8(B1, 0, 1); STAGE8(SB8(0, 0), Bt, K, bcol, tt + 2);
;     BAR8; WAIT_L8(0); MMA8(0, 1, At, B1); BAR8;
;     LDA8(At, 0, 1); STAGE8(SA8(0, 0), A, lda, brow, tt + 2);
;     BAR8; WAIT_L8(0); MMA8(1, 0, At, B0); BAR8; SCHED8;
;     STAGE8(SB8(0, 1), Bt, K, bcol + 128, tt + 2);
;     WAIT_V8(6); BAR8; MMA8(1, 1, At, B1); BAR8;
.LBB0_1005:
	s_barrier
	ds_read_b128 v[174:177], v171
	ds_read_b128 v[178:181], v171 offset:1024
	ds_read_b128 v[182:185], v171 offset:2048
	ds_read_b128 v[186:189], v171 offset:3072
	v_lshl_add_u64 v[222:223], v[140:141], 0, s[12:13]
	v_lshl_add_u64 v[226:227], v[222:223], 0, s[20:21]
	s_or_b32 m0, s100, 0xc000
	v_lshl_add_u64 v[236:237], v[138:139], 0, s[12:13]
	ds_read_b128 v[190:193], v156
	ds_read_b128 v[194:197], v156 offset:1024
	ds_read_b128 v[198:201], v155
	ds_read_b128 v[202:205], v155 offset:1024
	ds_read_b128 v[206:209], v154
	ds_read_b128 v[210:213], v154 offset:1024
	ds_read_b128 v[214:217], v153
	ds_read_b128 v[218:221], v153 offset:1024
	global_load_lds_dwordx4 v[226:227], off
	s_or_b32 m0, s100, 0xe000
	v_lshl_add_u64 v[226:227], v[236:237], 0, s[20:21]
	global_load_lds_dwordx4 v[226:227], off
	s_waitcnt lgkmcnt(8)
	s_barrier
	s_waitcnt lgkmcnt(0)
	v_mfma_f32_16x16x32_bf16 v[128:131], v[190:193], v[174:177], v[128:131]
	v_mfma_f32_16x16x32_bf16 v[124:127], v[190:193], v[182:185], v[124:127]
	v_mfma_f32_16x16x32_bf16 v[120:123], v[198:201], v[174:177], v[120:123]
	v_mfma_f32_16x16x32_bf16 v[116:119], v[198:201], v[182:185], v[116:119]
	v_mfma_f32_16x16x32_bf16 v[112:115], v[206:209], v[174:177], v[112:115]
	v_mfma_f32_16x16x32_bf16 v[108:111], v[206:209], v[182:185], v[108:111]
	v_mfma_f32_16x16x32_bf16 v[104:107], v[214:217], v[174:177], v[104:107]
	v_mfma_f32_16x16x32_bf16 v[100:103], v[214:217], v[182:185], v[100:103]
	v_mfma_f32_16x16x32_bf16 v[128:131], v[194:197], v[178:181], v[128:131]
	v_mfma_f32_16x16x32_bf16 v[124:127], v[194:197], v[186:189], v[124:127]
	v_mfma_f32_16x16x32_bf16 v[120:123], v[202:205], v[178:181], v[120:123]
	v_mfma_f32_16x16x32_bf16 v[116:119], v[202:205], v[186:189], v[116:119]
	v_mfma_f32_16x16x32_bf16 v[112:115], v[210:213], v[178:181], v[112:115]
	v_mfma_f32_16x16x32_bf16 v[108:111], v[210:213], v[186:189], v[108:111]
	v_mfma_f32_16x16x32_bf16 v[104:107], v[218:221], v[178:181], v[104:107]
	v_mfma_f32_16x16x32_bf16 v[100:103], v[218:221], v[186:189], v[100:103]
	s_barrier
	v_lshl_add_u64 v[246:247], v[142:143], 0, s[12:13]
	v_lshl_add_u64 v[248:249], v[246:247], 0, s[40:41]
	s_or_b32 m0, s100, 0x10000
	ds_read_b128 v[226:229], v168
	ds_read_b128 v[230:233], v168 offset:1024
	ds_read_b128 v[238:241], v168 offset:2048
	ds_read_b128 v[242:245], v168 offset:3072
	global_load_lds_dwordx4 v[248:249], off
	v_lshl_add_u64 v[248:249], v[144:145], 0, s[12:13]
	s_or_b32 m0, s100, 0x12000
	v_lshl_add_u64 v[250:251], v[248:249], 0, s[40:41]
	global_load_lds_dwordx4 v[250:251], off
	s_barrier
	s_waitcnt lgkmcnt(0)
	v_mfma_f32_16x16x32_bf16 v[96:99], v[190:193], v[226:229], v[96:99]
	v_mfma_f32_16x16x32_bf16 v[92:95], v[190:193], v[238:241], v[92:95]
	v_mfma_f32_16x16x32_bf16 v[88:91], v[198:201], v[226:229], v[88:91]
	v_mfma_f32_16x16x32_bf16 v[84:87], v[198:201], v[238:241], v[84:87]
	v_mfma_f32_16x16x32_bf16 v[80:83], v[206:209], v[226:229], v[80:83]
	v_mfma_f32_16x16x32_bf16 v[76:79], v[206:209], v[238:241], v[76:79]
	v_mfma_f32_16x16x32_bf16 v[72:75], v[214:217], v[226:229], v[72:75]
	v_mfma_f32_16x16x32_bf16 v[68:71], v[214:217], v[238:241], v[68:71]
	v_mfma_f32_16x16x32_bf16 v[96:99], v[194:197], v[230:233], v[96:99]
	v_mfma_f32_16x16x32_bf16 v[92:95], v[194:197], v[242:245], v[92:95]
	v_mfma_f32_16x16x32_bf16 v[88:91], v[202:205], v[230:233], v[88:91]
	v_mfma_f32_16x16x32_bf16 v[84:87], v[202:205], v[242:245], v[84:87]
	v_mfma_f32_16x16x32_bf16 v[80:83], v[210:213], v[230:233], v[80:83]
	v_mfma_f32_16x16x32_bf16 v[76:79], v[210:213], v[242:245], v[76:79]
	v_mfma_f32_16x16x32_bf16 v[72:75], v[218:221], v[230:233], v[72:75]
	v_mfma_f32_16x16x32_bf16 v[68:71], v[218:221], v[242:245], v[68:71]
	v_lshl_add_u64 v[250:251], v[222:223], 0, s[42:43]
	s_mov_b32 m0, s100
	s_barrier
	ds_read_b128 v[190:193], v156 offset:16384
	ds_read_b128 v[194:197], v156 offset:17408
	ds_read_b128 v[198:201], v155 offset:16384
	ds_read_b128 v[202:205], v155 offset:17408
	ds_read_b128 v[206:209], v154 offset:16384
	ds_read_b128 v[210:213], v154 offset:17408
	ds_read_b128 v[214:217], v153 offset:16384
	ds_read_b128 v[218:221], v153 offset:17408
	global_load_lds_dwordx4 v[250:251], off
	s_or_b32 m0, s100, 0x2000
	v_lshl_add_u64 v[250:251], v[236:237], 0, s[42:43]
	global_load_lds_dwordx4 v[250:251], off
	s_barrier
	s_waitcnt lgkmcnt(0)
	v_mfma_f32_16x16x32_bf16 v[64:67], v[190:193], v[174:177], v[64:67]
	v_mfma_f32_16x16x32_bf16 v[60:63], v[190:193], v[182:185], v[60:63]
	v_mfma_f32_16x16x32_bf16 v[56:59], v[198:201], v[174:177], v[56:59]
	v_mfma_f32_16x16x32_bf16 v[52:55], v[198:201], v[182:185], v[52:55]
	v_mfma_f32_16x16x32_bf16 v[48:51], v[206:209], v[174:177], v[48:51]
	v_mfma_f32_16x16x32_bf16 v[44:47], v[206:209], v[182:185], v[44:47]
	v_mfma_f32_16x16x32_bf16 v[40:43], v[214:217], v[174:177], v[40:43]
	v_mfma_f32_16x16x32_bf16 v[36:39], v[214:217], v[182:185], v[36:39]
	v_mfma_f32_16x16x32_bf16 v[64:67], v[194:197], v[178:181], v[64:67]
	v_mfma_f32_16x16x32_bf16 v[60:63], v[194:197], v[186:189], v[60:63]
	v_mfma_f32_16x16x32_bf16 v[56:59], v[202:205], v[178:181], v[56:59]
	v_mfma_f32_16x16x32_bf16 v[52:55], v[202:205], v[186:189], v[52:55]
	v_mfma_f32_16x16x32_bf16 v[48:51], v[210:213], v[178:181], v[48:51]
	v_mfma_f32_16x16x32_bf16 v[44:47], v[210:213], v[186:189], v[44:47]
	v_mfma_f32_16x16x32_bf16 v[40:43], v[218:221], v[178:181], v[40:43]
	v_mfma_f32_16x16x32_bf16 v[36:39], v[218:221], v[186:189], v[36:39]
	s_barrier
	s_or_b32 m0, s100, 0x14000
	v_lshl_add_u64 v[174:175], v[246:247], 0, s[44:45]
	global_load_lds_dwordx4 v[174:175], off
	s_or_b32 m0, s100, 0x16000
	v_lshl_add_u64 v[174:175], v[248:249], 0, s[44:45]
	global_load_lds_dwordx4 v[174:175], off
	s_waitcnt vmcnt(6)
	s_barrier
; #define LDA8(dst, b, h) _Pragma("unroll") for (int m = 0; m < 4; ++m) _Pragma("unroll") for (int k = 0; k < 2; ++k) \
;     dst[m][k] = *(const bf16x8*)((const char*)SA8(b, h) + lds_byte8(wr * 64 + m * 16 + fr, k * 32 + fq * 8))
; #define LDB8(dst, b, h) _Pragma("unroll") for (int n = 0; n < 2; ++n) _Pragma("unroll") for (int k = 0; k < 2; ++k) \
;     dst[n][k] = *(const bf16x8*)((const char*)SB8(b, h) + lds_byte8(wc * 32 + n * 16 + fr, k * 32 + fq * 8))
; #define WAIT_V8(n) asm volatile("s_waitcnt vmcnt(" #n ")" ::: "memory")
; #define WAIT_L8(n) asm volatile("s_waitcnt lgkmcnt(" #n ")" ::: "memory")
; #define BAR8 __builtin_amdgcn_s_barrier()
; #define SCHED8 __builtin_amdgcn_sched_barrier(0)
;     ...
;     WAIT_V8(6); BAR8; MMA8(1, 1, At, B1); BAR8;
;     LDB8(B0, 1, 0); SCHED8; LDA8(At, 1, 0); STAGE8(SA8(0, 1), A, lda, brow + 128, tt + 2);
;     WAIT_L8(8); BAR8; WAIT_L8(0); MMA8(0, 0, At, B0); BAR8; SCHED8;
;     LDB8(B1, 1, 1); STAGE8(SB8(1, 0), Bt, K, bcol, tt + 3);
;     BAR8; WAIT_L8(0); MMA8(0, 1, At, B1); BAR8;
	v_mfma_f32_16x16x32_bf16 v[32:35], v[190:193], v[226:229], v[32:35]
	v_mfma_f32_16x16x32_bf16 v[28:31], v[190:193], v[238:241], v[28:31]
	v_mfma_f32_16x16x32_bf16 v[24:27], v[198:201], v[226:229], v[24:27]
	v_mfma_f32_16x16x32_bf16 v[20:23], v[198:201], v[238:241], v[20:23]
	v_mfma_f32_16x16x32_bf16 v[16:19], v[206:209], v[226:229], v[16:19]
	v_mfma_f32_16x16x32_bf16 v[12:15], v[206:209], v[238:241], v[12:15]
	v_mfma_f32_16x16x32_bf16 v[8:11], v[214:217], v[226:229], v[8:11]
	v_mfma_f32_16x16x32_bf16 v[4:7], v[214:217], v[238:241], v[4:7]
	v_mfma_f32_16x16x32_bf16 v[32:35], v[194:197], v[230:233], v[32:35]
	v_mfma_f32_16x16x32_bf16 v[28:31], v[194:197], v[242:245], v[28:31]
	v_mfma_f32_16x16x32_bf16 v[24:27], v[202:205], v[230:233], v[24:27]
	v_mfma_f32_16x16x32_bf16 v[20:23], v[202:205], v[242:245], v[20:23]
	v_mfma_f32_16x16x32_bf16 v[16:19], v[210:213], v[230:233], v[16:19]
	v_mfma_f32_16x16x32_bf16 v[12:15], v[210:213], v[242:245], v[12:15]
	v_mfma_f32_16x16x32_bf16 v[8:11], v[218:221], v[230:233], v[8:11]
	v_mfma_f32_16x16x32_bf16 v[4:7], v[218:221], v[242:245], v[4:7]
	s_barrier
	ds_read_b128 v[174:177], v161
	ds_read_b128 v[178:181], v161 offset:1024
	ds_read_b128 v[182:185], v161 offset:2048
	ds_read_b128 v[186:189], v161 offset:3072
	v_lshl_add_u64 v[226:227], v[222:223], 0, s[46:47]
	s_or_b32 m0, s100, 0x4000
	ds_read_b128 v[190:193], v156 offset:32768
	ds_read_b128 v[194:197], v156 offset:33792
	ds_read_b128 v[198:201], v155 offset:32768
	ds_read_b128 v[202:205], v155 offset:33792
	ds_read_b128 v[206:209], v154 offset:32768
	ds_read_b128 v[210:213], v154 offset:33792
	ds_read_b128 v[214:217], v153 offset:32768
	ds_read_b128 v[218:221], v153 offset:33792
	global_load_lds_dwordx4 v[226:227], off
	s_or_b32 m0, s100, 0x6000
	v_lshl_add_u64 v[226:227], v[236:237], 0, s[46:47]
	global_load_lds_dwordx4 v[226:227], off
	s_waitcnt lgkmcnt(8)
	s_barrier
	s_waitcnt lgkmcnt(0)
	v_mfma_f32_16x16x32_bf16 v[128:131], v[190:193], v[174:177], v[128:131]
	v_mfma_f32_16x16x32_bf16 v[124:127], v[190:193], v[182:185], v[124:127]
	v_mfma_f32_16x16x32_bf16 v[120:123], v[198:201], v[174:177], v[120:123]
	v_mfma_f32_16x16x32_bf16 v[116:119], v[198:201], v[182:185], v[116:119]
	v_mfma_f32_16x16x32_bf16 v[112:115], v[206:209], v[174:177], v[112:115]
	v_mfma_f32_16x16x32_bf16 v[108:111], v[206:209], v[182:185], v[108:111]
	v_mfma_f32_16x16x32_bf16 v[104:107], v[214:217], v[174:177], v[104:107]
	v_mfma_f32_16x16x32_bf16 v[100:103], v[214:217], v[182:185], v[100:103]
	v_mfma_f32_16x16x32_bf16 v[128:131], v[194:197], v[178:181], v[128:131]
	v_mfma_f32_16x16x32_bf16 v[124:127], v[194:197], v[186:189], v[124:127]
	v_mfma_f32_16x16x32_bf16 v[120:123], v[202:205], v[178:181], v[120:123]
	v_mfma_f32_16x16x32_bf16 v[116:119], v[202:205], v[186:189], v[116:119]
	v_mfma_f32_16x16x32_bf16 v[112:115], v[210:213], v[178:181], v[112:115]
	v_mfma_f32_16x16x32_bf16 v[108:111], v[210:213], v[186:189], v[108:111]
	v_mfma_f32_16x16x32_bf16 v[104:107], v[218:221], v[178:181], v[104:107]
	v_mfma_f32_16x16x32_bf16 v[100:103], v[218:221], v[186:189], v[100:103]
	s_barrier
	v_lshl_add_u64 v[250:251], v[246:247], 0, s[48:49]
	s_or_b32 m0, s100, 0x18000
	ds_read_b128 v[226:229], v158
	ds_read_b128 v[230:233], v158 offset:1024
	ds_read_b128 v[238:241], v158 offset:2048
	ds_read_b128 v[242:245], v158 offset:3072
	global_load_lds_dwordx4 v[250:251], off
	s_or_b32 m0, s100, 0x1a000
	v_lshl_add_u64 v[250:251], v[248:249], 0, s[48:49]
	global_load_lds_dwordx4 v[250:251], off
	s_barrier
; #define LDA8(dst, b, h) _Pragma("unroll") for (int m = 0; m < 4; ++m) _Pragma("unroll") for (int k = 0; k < 2; ++k) \
;     dst[m][k] = *(const bf16x8*)((const char*)SA8(b, h) + lds_byte8(wr * 64 + m * 16 + fr, k * 32 + fq * 8))
; #define WAIT_V8(n) asm volatile("s_waitcnt vmcnt(" #n ")" ::: "memory")
; #define WAIT_L8(n) asm volatile("s_waitcnt lgkmcnt(" #n ")" ::: "memory")
; #define BAR8 __builtin_amdgcn_s_barrier()
; #define SCHED8 __builtin_amdgcn_sched_barrier(0)
;     ...
;     BAR8; WAIT_L8(0); MMA8(0, 1, At, B1); BAR8;
;     LDA8(At, 1, 1); STAGE8(SA8(1, 0), A, lda, brow, tt + 3);
;     BAR8; WAIT_L8(0); MMA8(1, 0, At, B0); BAR8; SCHED8;
;     STAGE8(SB8(1, 1), Bt, K, bcol + 128, tt + 3);
;     WAIT_V8(6); BAR8; MMA8(1, 1, At, B1); BAR8;
;   }
	s_waitcnt lgkmcnt(0)
	v_mfma_f32_16x16x32_bf16 v[96:99], v[190:193], v[226:229], v[96:99]
	v_mfma_f32_16x16x32_bf16 v[92:95], v[190:193], v[238:241], v[92:95]
	v_mfma_f32_16x16x32_bf16 v[88:91], v[198:201], v[226:229], v[88:91]
	v_mfma_f32_16x16x32_bf16 v[84:87], v[198:201], v[238:241], v[84:87]
	v_mfma_f32_16x16x32_bf16 v[80:83], v[206:209], v[226:229], v[80:83]
	v_mfma_f32_16x16x32_bf16 v[76:79], v[206:209], v[238:241], v[76:79]
	v_mfma_f32_16x16x32_bf16 v[72:75], v[214:217], v[226:229], v[72:75]
	v_mfma_f32_16x16x32_bf16 v[68:71], v[214:217], v[238:241], v[68:71]
	v_mfma_f32_16x16x32_bf16 v[96:99], v[194:197], v[230:233], v[96:99]
	v_mfma_f32_16x16x32_bf16 v[92:95], v[194:197], v[242:245], v[92:95]
	v_mfma_f32_16x16x32_bf16 v[88:91], v[202:205], v[230:233], v[88:91]
	v_mfma_f32_16x16x32_bf16 v[84:87], v[202:205], v[242:245], v[84:87]
	v_mfma_f32_16x16x32_bf16 v[80:83], v[210:213], v[230:233], v[80:83]
	v_mfma_f32_16x16x32_bf16 v[76:79], v[210:213], v[242:245], v[76:79]
	v_mfma_f32_16x16x32_bf16 v[72:75], v[218:221], v[230:233], v[72:75]
	v_mfma_f32_16x16x32_bf16 v[68:71], v[218:221], v[242:245], v[68:71]
	v_lshl_add_u64 v[222:223], v[222:223], 0, s[50:51]
	s_or_b32 m0, s100, 0x8000
	s_barrier
	ds_read_b128 v[190:193], v156 offset:49152
	ds_read_b128 v[194:197], v156 offset:50176
	ds_read_b128 v[198:201], v155 offset:49152
	ds_read_b128 v[202:205], v155 offset:50176
	ds_read_b128 v[206:209], v154 offset:49152
	ds_read_b128 v[210:213], v154 offset:50176
	ds_read_b128 v[214:217], v153 offset:49152
	ds_read_b128 v[218:221], v153 offset:50176
	global_load_lds_dwordx4 v[222:223], off
	s_or_b32 m0, s100, 0xa000
	v_lshl_add_u64 v[222:223], v[236:237], 0, s[50:51]
	global_load_lds_dwordx4 v[222:223], off
	s_barrier
	s_waitcnt lgkmcnt(0)
	v_mfma_f32_16x16x32_bf16 v[64:67], v[190:193], v[174:177], v[64:67]
	v_mfma_f32_16x16x32_bf16 v[60:63], v[190:193], v[182:185], v[60:63]
	v_mfma_f32_16x16x32_bf16 v[56:59], v[198:201], v[174:177], v[56:59]
	v_mfma_f32_16x16x32_bf16 v[52:55], v[198:201], v[182:185], v[52:55]
	v_mfma_f32_16x16x32_bf16 v[48:51], v[206:209], v[174:177], v[48:51]
	v_mfma_f32_16x16x32_bf16 v[44:47], v[206:209], v[182:185], v[44:47]
	v_mfma_f32_16x16x32_bf16 v[40:43], v[214:217], v[174:177], v[40:43]
	v_mfma_f32_16x16x32_bf16 v[36:39], v[214:217], v[182:185], v[36:39]
	v_mfma_f32_16x16x32_bf16 v[64:67], v[194:197], v[178:181], v[64:67]
	v_mfma_f32_16x16x32_bf16 v[60:63], v[194:197], v[186:189], v[60:63]
	v_mfma_f32_16x16x32_bf16 v[56:59], v[202:205], v[178:181], v[56:59]
	v_mfma_f32_16x16x32_bf16 v[52:55], v[202:205], v[186:189], v[52:55]
	v_mfma_f32_16x16x32_bf16 v[48:51], v[210:213], v[178:181], v[48:51]
	v_mfma_f32_16x16x32_bf16 v[44:47], v[210:213], v[186:189], v[44:47]
	v_mfma_f32_16x16x32_bf16 v[40:43], v[218:221], v[178:181], v[40:43]
	v_mfma_f32_16x16x32_bf16 v[36:39], v[218:221], v[186:189], v[36:39]
	s_barrier
	s_or_b32 m0, s100, 0x1c000
	v_lshl_add_u64 v[174:175], v[246:247], 0, s[52:53]
	global_load_lds_dwordx4 v[174:175], off
	s_or_b32 m0, s100, 0x1e000
	v_lshl_add_u64 v[174:175], v[248:249], 0, s[52:53]
	global_load_lds_dwordx4 v[174:175], off
	s_waitcnt vmcnt(6)
	s_barrier
	v_mfma_f32_16x16x32_bf16 v[32:35], v[190:193], v[226:229], v[32:35]
	v_mfma_f32_16x16x32_bf16 v[28:31], v[190:193], v[238:241], v[28:31]
	v_mfma_f32_16x16x32_bf16 v[24:27], v[198:201], v[226:229], v[24:27]
	v_mfma_f32_16x16x32_bf16 v[20:23], v[198:201], v[238:241], v[20:23]
	v_mfma_f32_16x16x32_bf16 v[16:19], v[206:209], v[226:229], v[16:19]
	v_mfma_f32_16x16x32_bf16 v[12:15], v[206:209], v[238:241], v[12:15]
	v_mfma_f32_16x16x32_bf16 v[8:11], v[214:217], v[226:229], v[8:11]
	v_mfma_f32_16x16x32_bf16 v[4:7], v[214:217], v[238:241], v[4:7]
	v_mfma_f32_16x16x32_bf16 v[32:35], v[194:197], v[230:233], v[32:35]
	v_mfma_f32_16x16x32_bf16 v[28:31], v[194:197], v[242:245], v[28:31]
	v_mfma_f32_16x16x32_bf16 v[24:27], v[202:205], v[230:233], v[24:27]
	v_mfma_f32_16x16x32_bf16 v[20:23], v[202:205], v[242:245], v[20:23]
	v_mfma_f32_16x16x32_bf16 v[16:19], v[210:213], v[230:233], v[16:19]
	v_mfma_f32_16x16x32_bf16 v[12:15], v[210:213], v[242:245], v[12:15]
	v_mfma_f32_16x16x32_bf16 v[8:11], v[218:221], v[230:233], v[8:11]
	v_mfma_f32_16x16x32_bf16 v[4:7], v[218:221], v[242:245], v[4:7]
	s_add_i32 s1, s1, 2
	s_add_u32 s12, s12, 0x100
	s_addc_u32 s13, s13, 0
	s_cmp_lt_u32 s1, 12
	s_cbranch_scc1 .LBB0_1005

; #define LDA8(dst, b, h) _Pragma("unroll") for (int m = 0; m < 4; ++m) _Pragma("unroll") for (int k = 0; k < 2; ++k) \
;     dst[m][k] = *(const bf16x8*)((const char*)SA8(b, h) + lds_byte8(wr * 64 + m * 16 + fr, k * 32 + fq * 8))
; #define LDB8(dst, b, h) _Pragma("unroll") for (int n = 0; n < 2; ++n) _Pragma("unroll") for (int k = 0; k < 2; ++k) \
;     dst[n][k] = *(const bf16x8*)((const char*)SB8(b, h) + lds_byte8(wc * 32 + n * 16 + fr, k * 32 + fq * 8))
; #define WAIT_V8(n) asm volatile("s_waitcnt vmcnt(" #n ")" ::: "memory")
; #define WAIT_L8(n) asm volatile("s_waitcnt lgkmcnt(" #n ")" ::: "memory")
; #define BAR8 __builtin_amdgcn_s_barrier()
; #define SCHED8 __builtin_amdgcn_sched_barrier(0)
;     ...
;   if (wr == 1) BAR8;
;   WAIT_V8(4); BAR8;
;   STAGE8(SB8(1, 0), Bt, K, bcol, 1); STAGE8(SA8(1, 0), A, lda, brow, 1); STAGE8(SB8(1, 1), Bt, K, bcol + 128, 1);
;   WAIT_V8(6); BAR8;
;   for (int tt = 0; tt < nt - 2; tt += 2) {
;     LDB8(B0, 0, 0); SCHED8; LDA8(At, 0, 0); STAGE8(SA8(1, 1), A, lda, brow + 128, tt + 1);
;     WAIT_L8(8); BAR8; WAIT_L8(0); MMA8(0, 0, At, B0); BAR8; SCHED8;
;     LDB8(B1, 0, 1); STAGE8(SB8(0, 0), Bt, K, bcol, tt + 2);
;     BAR8; WAIT_L8(0); MMA8(0, 1, At, B1); BAR8;
.LBB0_1014:
	s_or_b64 exec, exec, s[14:15]
	v_readlane_b32 s40, v254, 35
	v_readlane_b32 s42, v254, 37
	v_readlane_b32 s43, v254, 38
	s_waitcnt vmcnt(0)
	s_mov_b64 s[42:43], 0x80
	v_lshl_add_u64 v[10:11], v[10:11], 0, s[42:43]
	s_or_b32 m0, s100, 0x18000
	s_waitcnt vmcnt(4)
	s_barrier
	global_load_lds_dwordx4 v[10:11], off
	v_lshl_add_u64 v[10:11], v[12:13], 0, s[42:43]
	s_or_b32 m0, s100, 0x1a000
	global_load_lds_dwordx4 v[10:11], off
	v_lshl_add_u64 v[10:11], v[14:15], 0, s[42:43]
	s_or_b32 m0, s100, 0x8000
	global_load_lds_dwordx4 v[10:11], off
	v_lshl_add_u64 v[10:11], v[16:17], 0, s[42:43]
	s_or_b32 m0, s100, 0xa000
	global_load_lds_dwordx4 v[10:11], off
	s_or_b32 m0, s100, 0x1c000
	v_lshl_add_u64 v[10:11], v[18:19], 0, s[42:43]
	global_load_lds_dwordx4 v[10:11], off
	v_lshl_add_u64 v[10:11], v[20:21], 0, s[42:43]
	s_or_b32 m0, s100, 0x1e000
	v_and_b32_e32 v147, 15, v3
	global_load_lds_dwordx4 v[10:11], off
	v_bfe_u32 v148, v3, 4, 2
	v_lshlrev_b32_e32 v10, 4, v148
	v_lshlrev_b32_e32 v11, 6, v147
	v_lshlrev_b32_e32 v14, 2, v3
	v_or_b32_e32 v13, v10, v11
	v_and_b32_e32 v14, 32, v14
	s_mov_b32 s21, 0x10000
	v_bitop3_b32 v16, v13, s21, v14 bitop3:0xde
	s_mov_b32 s21, 0x14000
	s_and_b32 s14, s27, 63
	v_bitop3_b32 v15, v10, v14, v11 bitop3:0x36
	v_bitop3_b32 v17, v13, s21, v14 bitop3:0xde
	s_mov_b32 s21, 0x18000
	v_lshlrev_b32_e32 v11, 6, v3
	s_lshl_b32 s14, s14, 19
	s_mov_b32 s15, s40
	v_bitop3_b32 v18, v13, s21, v14 bitop3:0xde
	s_mov_b32 s21, 0x1c000
	v_and_b32_e32 v11, 0x3c0, v11
	v_bitop3_b32 v13, v13, s21, v14 bitop3:0xde
	v_bitop3_b32 v14, v11, v14, v10 bitop3:0x36
	v_lshl_add_u64 v[10:11], s[14:15], 0, v[136:137]
	v_readlane_b32 s41, v254, 36
	s_and_b32 s40, s33, 0xffffff00
	v_lshl_add_u64 v[10:11], v[10:11], 0, v[8:9]
	s_ashr_i32 s41, s40, 31
	v_lshl_add_u64 v[138:139], s[12:13], 0, v[10:11]
	v_lshl_add_u64 v[10:11], s[14:15], 0, v[132:133]
	s_lshl_b64 s[40:41], s[40:41], 11
	v_lshl_add_u64 v[10:11], v[10:11], 0, v[6:7]
	v_lshl_add_u64 v[140:141], s[12:13], 0, v[10:11]
	v_lshl_add_u64 v[10:11], s[40:41], 0, v[132:133]
	v_lshl_add_u64 v[6:7], v[10:11], 0, v[6:7]
	v_bfe_u32 v146, v3, 6, 2
	s_waitcnt vmcnt(6)
	v_lshlrev_b32_e32 v149, 6, v5
	v_lshlrev_b32_e32 v5, 13, v5
	v_lshl_add_u64 v[142:143], s[4:5], 0, v[6:7]
	v_lshl_add_u64 v[6:7], s[40:41], 0, v[136:137]
	v_lshlrev_b32_e32 v12, 12, v146
	v_or_b32_e32 v19, 0x800, v5
	v_or_b32_e32 v20, 0x1000, v5
	v_or_b32_e32 v21, 0x1800, v5
	v_lshl_add_u64 v[6:7], v[6:7], 0, v[8:9]
	v_lshl_add_u64 v[144:145], s[4:5], 0, v[6:7]
	s_mov_b32 s14, -2
	s_mov_b64 s[12:13], 0
	v_add_u32_e32 v171, v16, v12
	v_add_u32_e32 v156, v15, v5
	v_add_u32_e32 v155, v14, v19
	v_add_u32_e32 v154, v14, v20
	v_add_u32_e32 v153, v14, v21
	v_add_u32_e32 v168, v17, v12
	v_add_u32_e32 v161, v18, v12
	v_add_u32_e32 v158, v13, v12
	s_mov_b64 s[40:41], 0xc6a0100
	s_mov_b64 s[42:43], 0xc6e0100
	s_mov_b64 s[44:45], 0xc6a0180
	s_mov_b64 s[46:47], 0xc6e0180
	s_barrier
	ds_read_b128 v[174:177], v171
	ds_read_b128 v[178:181], v171 offset:1024
	ds_read_b128 v[182:185], v171 offset:2048
	ds_read_b128 v[186:189], v171 offset:3072
	v_lshl_add_u64 v[222:223], v[140:141], 0, s[12:13]
	v_lshl_add_u64 v[226:227], v[222:223], 0, s[34:35]
	s_or_b32 m0, s100, 0xc000
	v_lshl_add_u64 v[236:237], v[138:139], 0, s[12:13]
	ds_read_b128 v[190:193], v156
	ds_read_b128 v[194:197], v156 offset:1024
	ds_read_b128 v[198:201], v155
	ds_read_b128 v[202:205], v155 offset:1024
	ds_read_b128 v[206:209], v154
	ds_read_b128 v[210:213], v154 offset:1024
	ds_read_b128 v[214:217], v153
	ds_read_b128 v[218:221], v153 offset:1024
	global_load_lds_dwordx4 v[226:227], off
	s_or_b32 m0, s100, 0xe000
	v_lshl_add_u64 v[226:227], v[236:237], 0, s[34:35]
	global_load_lds_dwordx4 v[226:227], off
	s_waitcnt lgkmcnt(8)
	s_barrier
	s_waitcnt lgkmcnt(0)
	v_mfma_f32_16x16x32_f16 v[128:131], v[190:193], v[174:177], 0
	v_mfma_f32_16x16x32_f16 v[124:127], v[190:193], v[182:185], 0
	v_mfma_f32_16x16x32_f16 v[120:123], v[198:201], v[174:177], 0
	v_mfma_f32_16x16x32_f16 v[116:119], v[198:201], v[182:185], 0
	v_mfma_f32_16x16x32_f16 v[112:115], v[206:209], v[174:177], 0
	v_mfma_f32_16x16x32_f16 v[108:111], v[206:209], v[182:185], 0
	v_mfma_f32_16x16x32_f16 v[104:107], v[214:217], v[174:177], 0
	v_mfma_f32_16x16x32_f16 v[100:103], v[214:217], v[182:185], 0
	v_mfma_f32_16x16x32_f16 v[128:131], v[194:197], v[178:181], v[128:131]
	v_mfma_f32_16x16x32_f16 v[124:127], v[194:197], v[186:189], v[124:127]
	v_mfma_f32_16x16x32_f16 v[120:123], v[202:205], v[178:181], v[120:123]
	v_mfma_f32_16x16x32_f16 v[116:119], v[202:205], v[186:189], v[116:119]
	v_mfma_f32_16x16x32_f16 v[112:115], v[210:213], v[178:181], v[112:115]
	v_mfma_f32_16x16x32_f16 v[108:111], v[210:213], v[186:189], v[108:111]
	v_mfma_f32_16x16x32_f16 v[104:107], v[218:221], v[178:181], v[104:107]
	v_mfma_f32_16x16x32_f16 v[100:103], v[218:221], v[186:189], v[100:103]
	s_barrier
	v_lshl_add_u64 v[246:247], v[142:143], 0, s[12:13]
	v_lshl_add_u64 v[248:249], v[246:247], 0, s[40:41]
	s_or_b32 m0, s100, 0x10000
	ds_read_b128 v[226:229], v168
	ds_read_b128 v[230:233], v168 offset:1024
	ds_read_b128 v[238:241], v168 offset:2048
	ds_read_b128 v[242:245], v168 offset:3072
	global_load_lds_dwordx4 v[248:249], off
	v_lshl_add_u64 v[248:249], v[144:145], 0, s[12:13]
	s_or_b32 m0, s100, 0x12000
	v_lshl_add_u64 v[250:251], v[248:249], 0, s[40:41]
	global_load_lds_dwordx4 v[250:251], off
	s_barrier
; #define LDA8(dst, b, h) _Pragma("unroll") for (int m = 0; m < 4; ++m) _Pragma("unroll") for (int k = 0; k < 2; ++k) \
;     dst[m][k] = *(const bf16x8*)((const char*)SA8(b, h) + lds_byte8(wr * 64 + m * 16 + fr, k * 32 + fq * 8))
; #define LDB8(dst, b, h) _Pragma("unroll") for (int n = 0; n < 2; ++n) _Pragma("unroll") for (int k = 0; k < 2; ++k) \
;     dst[n][k] = *(const bf16x8*)((const char*)SB8(b, h) + lds_byte8(wc * 32 + n * 16 + fr, k * 32 + fq * 8))
; #define WAIT_V8(n) asm volatile("s_waitcnt vmcnt(" #n ")" ::: "memory")
; #define WAIT_L8(n) asm volatile("s_waitcnt lgkmcnt(" #n ")" ::: "memory")
; #define BAR8 __builtin_amdgcn_s_barrier()
; #define SCHED8 __builtin_amdgcn_sched_barrier(0)
;     ...
;     BAR8; WAIT_L8(0); MMA8(0, 1, At, B1); BAR8;
;     LDA8(At, 0, 1); STAGE8(SA8(0, 0), A, lda, brow, tt + 2);
;     BAR8; WAIT_L8(0); MMA8(1, 0, At, B0); BAR8; SCHED8;
;     STAGE8(SB8(0, 1), Bt, K, bcol + 128, tt + 2);
;     WAIT_V8(6); BAR8; MMA8(1, 1, At, B1); BAR8;
;     LDB8(B0, 1, 0); SCHED8; LDA8(At, 1, 0); STAGE8(SA8(0, 1), A, lda, brow + 128, tt + 2);
;     WAIT_L8(8); BAR8; WAIT_L8(0); MMA8(0, 0, At, B0); BAR8; SCHED8;
	s_waitcnt lgkmcnt(0)
	v_mfma_f32_16x16x32_f16 v[96:99], v[190:193], v[226:229], 0
	v_mfma_f32_16x16x32_f16 v[92:95], v[190:193], v[238:241], 0
	v_mfma_f32_16x16x32_f16 v[88:91], v[198:201], v[226:229], 0
	v_mfma_f32_16x16x32_f16 v[84:87], v[198:201], v[238:241], 0
	v_mfma_f32_16x16x32_f16 v[80:83], v[206:209], v[226:229], 0
	v_mfma_f32_16x16x32_f16 v[76:79], v[206:209], v[238:241], 0
	v_mfma_f32_16x16x32_f16 v[72:75], v[214:217], v[226:229], 0
	v_mfma_f32_16x16x32_f16 v[68:71], v[214:217], v[238:241], 0
	v_mfma_f32_16x16x32_f16 v[96:99], v[194:197], v[230:233], v[96:99]
	v_mfma_f32_16x16x32_f16 v[92:95], v[194:197], v[242:245], v[92:95]
	v_mfma_f32_16x16x32_f16 v[88:91], v[202:205], v[230:233], v[88:91]
	v_mfma_f32_16x16x32_f16 v[84:87], v[202:205], v[242:245], v[84:87]
	v_mfma_f32_16x16x32_f16 v[80:83], v[210:213], v[230:233], v[80:83]
	v_mfma_f32_16x16x32_f16 v[76:79], v[210:213], v[242:245], v[76:79]
	v_mfma_f32_16x16x32_f16 v[72:75], v[218:221], v[230:233], v[72:75]
	v_mfma_f32_16x16x32_f16 v[68:71], v[218:221], v[242:245], v[68:71]
	v_lshl_add_u64 v[250:251], v[222:223], 0, s[10:11]
	s_mov_b32 m0, s100
	s_barrier
	ds_read_b128 v[190:193], v156 offset:16384
	ds_read_b128 v[194:197], v156 offset:17408
	ds_read_b128 v[198:201], v155 offset:16384
	ds_read_b128 v[202:205], v155 offset:17408
	ds_read_b128 v[206:209], v154 offset:16384
	ds_read_b128 v[210:213], v154 offset:17408
	ds_read_b128 v[214:217], v153 offset:16384
	ds_read_b128 v[218:221], v153 offset:17408
	global_load_lds_dwordx4 v[250:251], off
	s_or_b32 m0, s100, 0x2000
	v_lshl_add_u64 v[250:251], v[236:237], 0, s[10:11]
	global_load_lds_dwordx4 v[250:251], off
	s_barrier
	s_waitcnt lgkmcnt(0)
	v_mfma_f32_16x16x32_f16 v[64:67], v[190:193], v[174:177], 0
	v_mfma_f32_16x16x32_f16 v[60:63], v[190:193], v[182:185], 0
	v_mfma_f32_16x16x32_f16 v[56:59], v[198:201], v[174:177], 0
	v_mfma_f32_16x16x32_f16 v[52:55], v[198:201], v[182:185], 0
	v_mfma_f32_16x16x32_f16 v[48:51], v[206:209], v[174:177], 0
	v_mfma_f32_16x16x32_f16 v[44:47], v[206:209], v[182:185], 0
	v_mfma_f32_16x16x32_f16 v[40:43], v[214:217], v[174:177], 0
	v_mfma_f32_16x16x32_f16 v[36:39], v[214:217], v[182:185], 0
	v_mfma_f32_16x16x32_f16 v[64:67], v[194:197], v[178:181], v[64:67]
	v_mfma_f32_16x16x32_f16 v[60:63], v[194:197], v[186:189], v[60:63]
	v_mfma_f32_16x16x32_f16 v[56:59], v[202:205], v[178:181], v[56:59]
	v_mfma_f32_16x16x32_f16 v[52:55], v[202:205], v[186:189], v[52:55]
	v_mfma_f32_16x16x32_f16 v[48:51], v[210:213], v[178:181], v[48:51]
	v_mfma_f32_16x16x32_f16 v[44:47], v[210:213], v[186:189], v[44:47]
	v_mfma_f32_16x16x32_f16 v[40:43], v[218:221], v[178:181], v[40:43]
	v_mfma_f32_16x16x32_f16 v[36:39], v[218:221], v[186:189], v[36:39]
	s_barrier
	s_or_b32 m0, s100, 0x14000
	v_lshl_add_u64 v[174:175], v[246:247], 0, s[42:43]
	global_load_lds_dwordx4 v[174:175], off
	s_or_b32 m0, s100, 0x16000
	v_lshl_add_u64 v[174:175], v[248:249], 0, s[42:43]
	global_load_lds_dwordx4 v[174:175], off
	s_waitcnt vmcnt(6)
	s_barrier
	v_mfma_f32_16x16x32_f16 v[32:35], v[190:193], v[226:229], 0
	v_mfma_f32_16x16x32_f16 v[28:31], v[190:193], v[238:241], 0
	v_mfma_f32_16x16x32_f16 v[24:27], v[198:201], v[226:229], 0
	v_mfma_f32_16x16x32_f16 v[20:23], v[198:201], v[238:241], 0
	v_mfma_f32_16x16x32_f16 v[16:19], v[206:209], v[226:229], 0
	v_mfma_f32_16x16x32_f16 v[12:15], v[206:209], v[238:241], 0
	v_mfma_f32_16x16x32_f16 v[8:11], v[214:217], v[226:229], 0
	v_mfma_f32_16x16x32_f16 v[4:7], v[214:217], v[238:241], 0
	v_mfma_f32_16x16x32_f16 v[32:35], v[194:197], v[230:233], v[32:35]
	v_mfma_f32_16x16x32_f16 v[28:31], v[194:197], v[242:245], v[28:31]
	v_mfma_f32_16x16x32_f16 v[24:27], v[202:205], v[230:233], v[24:27]
	v_mfma_f32_16x16x32_f16 v[20:23], v[202:205], v[242:245], v[20:23]
	v_mfma_f32_16x16x32_f16 v[16:19], v[210:213], v[230:233], v[16:19]
	v_mfma_f32_16x16x32_f16 v[12:15], v[210:213], v[242:245], v[12:15]
	v_mfma_f32_16x16x32_f16 v[8:11], v[218:221], v[230:233], v[8:11]
	v_mfma_f32_16x16x32_f16 v[4:7], v[218:221], v[242:245], v[4:7]
	s_barrier
	ds_read_b128 v[174:177], v161
	ds_read_b128 v[178:181], v161 offset:1024
	ds_read_b128 v[182:185], v161 offset:2048
	ds_read_b128 v[186:189], v161 offset:3072
	v_lshl_add_u64 v[226:227], v[222:223], 0, s[18:19]
	s_or_b32 m0, s100, 0x4000
	ds_read_b128 v[190:193], v156 offset:32768
	ds_read_b128 v[194:197], v156 offset:33792
	ds_read_b128 v[198:201], v155 offset:32768
	ds_read_b128 v[202:205], v155 offset:33792
	ds_read_b128 v[206:209], v154 offset:32768
	ds_read_b128 v[210:213], v154 offset:33792
	ds_read_b128 v[214:217], v153 offset:32768
	ds_read_b128 v[218:221], v153 offset:33792
	global_load_lds_dwordx4 v[226:227], off
	s_or_b32 m0, s100, 0x6000
	v_lshl_add_u64 v[226:227], v[236:237], 0, s[18:19]
	global_load_lds_dwordx4 v[226:227], off
	s_waitcnt lgkmcnt(8)
	s_barrier
	s_waitcnt lgkmcnt(0)
	v_mfma_f32_16x16x32_f16 v[128:131], v[190:193], v[174:177], v[128:131]
	v_mfma_f32_16x16x32_f16 v[124:127], v[190:193], v[182:185], v[124:127]
	v_mfma_f32_16x16x32_f16 v[120:123], v[198:201], v[174:177], v[120:123]
	v_mfma_f32_16x16x32_f16 v[116:119], v[198:201], v[182:185], v[116:119]
	v_mfma_f32_16x16x32_f16 v[112:115], v[206:209], v[174:177], v[112:115]
	v_mfma_f32_16x16x32_f16 v[108:111], v[206:209], v[182:185], v[108:111]
	v_mfma_f32_16x16x32_f16 v[104:107], v[214:217], v[174:177], v[104:107]
	v_mfma_f32_16x16x32_f16 v[100:103], v[214:217], v[182:185], v[100:103]
	v_mfma_f32_16x16x32_f16 v[128:131], v[194:197], v[178:181], v[128:131]
	v_mfma_f32_16x16x32_f16 v[124:127], v[194:197], v[186:189], v[124:127]
	v_mfma_f32_16x16x32_f16 v[120:123], v[202:205], v[178:181], v[120:123]
	v_mfma_f32_16x16x32_f16 v[116:119], v[202:205], v[186:189], v[116:119]
	v_mfma_f32_16x16x32_f16 v[112:115], v[210:213], v[178:181], v[112:115]
	v_mfma_f32_16x16x32_f16 v[108:111], v[210:213], v[186:189], v[108:111]
	v_mfma_f32_16x16x32_f16 v[104:107], v[218:221], v[178:181], v[104:107]
	v_mfma_f32_16x16x32_f16 v[100:103], v[218:221], v[186:189], v[100:103]
	s_barrier
; #define LDA8(dst, b, h) _Pragma("unroll") for (int m = 0; m < 4; ++m) _Pragma("unroll") for (int k = 0; k < 2; ++k) \
;     dst[m][k] = *(const bf16x8*)((const char*)SA8(b, h) + lds_byte8(wr * 64 + m * 16 + fr, k * 32 + fq * 8))
; #define LDB8(dst, b, h) _Pragma("unroll") for (int n = 0; n < 2; ++n) _Pragma("unroll") for (int k = 0; k < 2; ++k) \
;     dst[n][k] = *(const bf16x8*)((const char*)SB8(b, h) + lds_byte8(wc * 32 + n * 16 + fr, k * 32 + fq * 8))
; #define WAIT_V8(n) asm volatile("s_waitcnt vmcnt(" #n ")" ::: "memory")
; #define WAIT_L8(n) asm volatile("s_waitcnt lgkmcnt(" #n ")" ::: "memory")
; #define BAR8 __builtin_amdgcn_s_barrier()
; #define SCHED8 __builtin_amdgcn_sched_barrier(0)
;     ...
;   for (int tt = 0; tt < nt - 2; tt += 2) {
;     LDB8(B0, 0, 0); SCHED8; LDA8(At, 0, 0); STAGE8(SA8(1, 1), A, lda, brow + 128, tt + 1);
;     WAIT_L8(8); BAR8; WAIT_L8(0); MMA8(0, 0, At, B0); BAR8; SCHED8;
;     LDB8(B1, 0, 1); STAGE8(SB8(0, 0), Bt, K, bcol, tt + 2);
;     BAR8; WAIT_L8(0); MMA8(0, 1, At, B1); BAR8;
;     LDA8(At, 0, 1); STAGE8(SA8(0, 0), A, lda, brow, tt + 2);
;     BAR8; WAIT_L8(0); MMA8(1, 0, At, B0); BAR8; SCHED8;
;     STAGE8(SB8(0, 1), Bt, K, bcol + 128, tt + 2);
;     WAIT_V8(6); BAR8; MMA8(1, 1, At, B1); BAR8;
;     LDB8(B0, 1, 0); SCHED8; LDA8(At, 1, 0); STAGE8(SA8(0, 1), A, lda, brow + 128, tt + 2);
;     WAIT_L8(8); BAR8; WAIT_L8(0); MMA8(0, 0, At, B0); BAR8; SCHED8;
;     LDB8(B1, 1, 1); STAGE8(SB8(1, 0), Bt, K, bcol, tt + 3);
;     BAR8; WAIT_L8(0); MMA8(0, 1, At, B1); BAR8;
;     LDA8(At, 1, 1); STAGE8(SA8(1, 0), A, lda, brow, tt + 3);
;     BAR8; WAIT_L8(0); MMA8(1, 0, At, B0); BAR8; SCHED8;
;     STAGE8(SB8(1, 1), Bt, K, bcol + 128, tt + 3);
;     WAIT_V8(6); BAR8; MMA8(1, 1, At, B1); BAR8;
;   }
	v_lshl_add_u64 v[250:251], v[246:247], 0, s[44:45]
	s_or_b32 m0, s100, 0x18000
	ds_read_b128 v[226:229], v158
	ds_read_b128 v[230:233], v158 offset:1024
	ds_read_b128 v[238:241], v158 offset:2048
	ds_read_b128 v[242:245], v158 offset:3072
	global_load_lds_dwordx4 v[250:251], off
	s_or_b32 m0, s100, 0x1a000
	v_lshl_add_u64 v[250:251], v[248:249], 0, s[44:45]
	global_load_lds_dwordx4 v[250:251], off
	s_barrier
	s_waitcnt lgkmcnt(0)
	v_mfma_f32_16x16x32_f16 v[96:99], v[190:193], v[226:229], v[96:99]
	v_mfma_f32_16x16x32_f16 v[92:95], v[190:193], v[238:241], v[92:95]
	v_mfma_f32_16x16x32_f16 v[88:91], v[198:201], v[226:229], v[88:91]
	v_mfma_f32_16x16x32_f16 v[84:87], v[198:201], v[238:241], v[84:87]
	v_mfma_f32_16x16x32_f16 v[80:83], v[206:209], v[226:229], v[80:83]
	v_mfma_f32_16x16x32_f16 v[76:79], v[206:209], v[238:241], v[76:79]
	v_mfma_f32_16x16x32_f16 v[72:75], v[214:217], v[226:229], v[72:75]
	v_mfma_f32_16x16x32_f16 v[68:71], v[214:217], v[238:241], v[68:71]
	v_mfma_f32_16x16x32_f16 v[96:99], v[194:197], v[230:233], v[96:99]
	v_mfma_f32_16x16x32_f16 v[92:95], v[194:197], v[242:245], v[92:95]
	v_mfma_f32_16x16x32_f16 v[88:91], v[202:205], v[230:233], v[88:91]
	v_mfma_f32_16x16x32_f16 v[84:87], v[202:205], v[242:245], v[84:87]
	v_mfma_f32_16x16x32_f16 v[80:83], v[210:213], v[230:233], v[80:83]
	v_mfma_f32_16x16x32_f16 v[76:79], v[210:213], v[242:245], v[76:79]
	v_mfma_f32_16x16x32_f16 v[72:75], v[218:221], v[230:233], v[72:75]
	v_mfma_f32_16x16x32_f16 v[68:71], v[218:221], v[242:245], v[68:71]
	v_lshl_add_u64 v[222:223], v[222:223], 0, s[22:23]
	s_or_b32 m0, s100, 0x8000
	s_barrier
	ds_read_b128 v[190:193], v156 offset:49152
	ds_read_b128 v[194:197], v156 offset:50176
	ds_read_b128 v[198:201], v155 offset:49152
	ds_read_b128 v[202:205], v155 offset:50176
	ds_read_b128 v[206:209], v154 offset:49152
	ds_read_b128 v[210:213], v154 offset:50176
	ds_read_b128 v[214:217], v153 offset:49152
	ds_read_b128 v[218:221], v153 offset:50176
	global_load_lds_dwordx4 v[222:223], off
	s_or_b32 m0, s100, 0xa000
	v_lshl_add_u64 v[222:223], v[236:237], 0, s[22:23]
	global_load_lds_dwordx4 v[222:223], off
	s_barrier
	s_waitcnt lgkmcnt(0)
	v_mfma_f32_16x16x32_f16 v[64:67], v[190:193], v[174:177], v[64:67]
	v_mfma_f32_16x16x32_f16 v[60:63], v[190:193], v[182:185], v[60:63]
	v_mfma_f32_16x16x32_f16 v[56:59], v[198:201], v[174:177], v[56:59]
	v_mfma_f32_16x16x32_f16 v[52:55], v[198:201], v[182:185], v[52:55]
	v_mfma_f32_16x16x32_f16 v[48:51], v[206:209], v[174:177], v[48:51]
	v_mfma_f32_16x16x32_f16 v[44:47], v[206:209], v[182:185], v[44:47]
	v_mfma_f32_16x16x32_f16 v[40:43], v[214:217], v[174:177], v[40:43]
	v_mfma_f32_16x16x32_f16 v[36:39], v[214:217], v[182:185], v[36:39]
	v_mfma_f32_16x16x32_f16 v[64:67], v[194:197], v[178:181], v[64:67]
	v_mfma_f32_16x16x32_f16 v[60:63], v[194:197], v[186:189], v[60:63]
	v_mfma_f32_16x16x32_f16 v[56:59], v[202:205], v[178:181], v[56:59]
	v_mfma_f32_16x16x32_f16 v[52:55], v[202:205], v[186:189], v[52:55]
	v_mfma_f32_16x16x32_f16 v[48:51], v[210:213], v[178:181], v[48:51]
	v_mfma_f32_16x16x32_f16 v[44:47], v[210:213], v[186:189], v[44:47]
	v_mfma_f32_16x16x32_f16 v[40:43], v[218:221], v[178:181], v[40:43]
	v_mfma_f32_16x16x32_f16 v[36:39], v[218:221], v[186:189], v[36:39]
	s_barrier
	s_or_b32 m0, s100, 0x1c000
	v_lshl_add_u64 v[174:175], v[246:247], 0, s[46:47]
	global_load_lds_dwordx4 v[174:175], off
	s_or_b32 m0, s100, 0x1e000
	v_lshl_add_u64 v[174:175], v[248:249], 0, s[46:47]
	global_load_lds_dwordx4 v[174:175], off
	s_waitcnt vmcnt(6)
	s_barrier
	v_mfma_f32_16x16x32_f16 v[32:35], v[190:193], v[226:229], v[32:35]
	v_mfma_f32_16x16x32_f16 v[28:31], v[190:193], v[238:241], v[28:31]
	v_mfma_f32_16x16x32_f16 v[24:27], v[198:201], v[226:229], v[24:27]
	v_mfma_f32_16x16x32_f16 v[20:23], v[198:201], v[238:241], v[20:23]
	v_mfma_f32_16x16x32_f16 v[16:19], v[206:209], v[226:229], v[16:19]
	v_mfma_f32_16x16x32_f16 v[12:15], v[206:209], v[238:241], v[12:15]
	v_mfma_f32_16x16x32_f16 v[8:11], v[214:217], v[226:229], v[8:11]
	v_mfma_f32_16x16x32_f16 v[4:7], v[214:217], v[238:241], v[4:7]
	v_mfma_f32_16x16x32_f16 v[32:35], v[194:197], v[230:233], v[32:35]
	v_mfma_f32_16x16x32_f16 v[28:31], v[194:197], v[242:245], v[28:31]
	v_mfma_f32_16x16x32_f16 v[24:27], v[202:205], v[230:233], v[24:27]
	v_mfma_f32_16x16x32_f16 v[20:23], v[202:205], v[242:245], v[20:23]
	v_mfma_f32_16x16x32_f16 v[16:19], v[210:213], v[230:233], v[16:19]
	v_mfma_f32_16x16x32_f16 v[12:15], v[210:213], v[242:245], v[12:15]
	v_mfma_f32_16x16x32_f16 v[8:11], v[218:221], v[230:233], v[8:11]
	v_mfma_f32_16x16x32_f16 v[4:7], v[218:221], v[242:245], v[4:7]
	s_add_i32 s14, s14, 2
	s_add_u32 s12, s12, 0x100
	s_addc_u32 s13, s13, 0
	s_cmp_lt_u32 s14, 12
	s_cbranch_scc0 .Lpk_exitb_4
; #define LDA8(dst, b, h) _Pragma("unroll") for (int m = 0; m < 4; ++m) _Pragma("unroll") for (int k = 0; k < 2; ++k) \
;     dst[m][k] = *(const bf16x8*)((const char*)SA8(b, h) + lds_byte8(wr * 64 + m * 16 + fr, k * 32 + fq * 8))
; #define LDB8(dst, b, h) _Pragma("unroll") for (int n = 0; n < 2; ++n) _Pragma("unroll") for (int k = 0; k < 2; ++k) \
;     dst[n][k] = *(const bf16x8*)((const char*)SB8(b, h) + lds_byte8(wc * 32 + n * 16 + fr, k * 32 + fq * 8))
; #define WAIT_V8(n) asm volatile("s_waitcnt vmcnt(" #n ")" ::: "memory")
; #define WAIT_L8(n) asm volatile("s_waitcnt lgkmcnt(" #n ")" ::: "memory")
; #define BAR8 __builtin_amdgcn_s_barrier()
; #define SCHED8 __builtin_amdgcn_sched_barrier(0)
;     ...
;   for (int tt = 0; tt < nt - 2; tt += 2) {
;     LDB8(B0, 0, 0); SCHED8; LDA8(At, 0, 0); STAGE8(SA8(1, 1), A, lda, brow + 128, tt + 1);
;     WAIT_L8(8); BAR8; WAIT_L8(0); MMA8(0, 0, At, B0); BAR8; SCHED8;
;     LDB8(B1, 0, 1); STAGE8(SB8(0, 0), Bt, K, bcol, tt + 2);
;     BAR8; WAIT_L8(0); MMA8(0, 1, At, B1); BAR8;
;     LDA8(At, 0, 1); STAGE8(SA8(0, 0), A, lda, brow, tt + 2);
;     BAR8; WAIT_L8(0); MMA8(1, 0, At, B0); BAR8; SCHED8;
;     STAGE8(SB8(0, 1), Bt, K, bcol + 128, tt + 2);
;     WAIT_V8(6); BAR8; MMA8(1, 1, At, B1); BAR8;
.LBB0_1015:
	s_barrier
	ds_read_b128 v[174:177], v171
	ds_read_b128 v[178:181], v171 offset:1024
	ds_read_b128 v[182:185], v171 offset:2048
	ds_read_b128 v[186:189], v171 offset:3072
	v_lshl_add_u64 v[222:223], v[140:141], 0, s[12:13]
	v_lshl_add_u64 v[226:227], v[222:223], 0, s[34:35]
	s_or_b32 m0, s100, 0xc000
	v_lshl_add_u64 v[236:237], v[138:139], 0, s[12:13]
	ds_read_b128 v[190:193], v156
	ds_read_b128 v[194:197], v156 offset:1024
	ds_read_b128 v[198:201], v155
	ds_read_b128 v[202:205], v155 offset:1024
	ds_read_b128 v[206:209], v154
	ds_read_b128 v[210:213], v154 offset:1024
	ds_read_b128 v[214:217], v153
	ds_read_b128 v[218:221], v153 offset:1024
	global_load_lds_dwordx4 v[226:227], off
	s_or_b32 m0, s100, 0xe000
	v_lshl_add_u64 v[226:227], v[236:237], 0, s[34:35]
	global_load_lds_dwordx4 v[226:227], off
	s_waitcnt lgkmcnt(8)
	s_barrier
	s_waitcnt lgkmcnt(0)
	v_mfma_f32_16x16x32_f16 v[128:131], v[190:193], v[174:177], v[128:131]
	v_mfma_f32_16x16x32_f16 v[124:127], v[190:193], v[182:185], v[124:127]
	v_mfma_f32_16x16x32_f16 v[120:123], v[198:201], v[174:177], v[120:123]
	v_mfma_f32_16x16x32_f16 v[116:119], v[198:201], v[182:185], v[116:119]
	v_mfma_f32_16x16x32_f16 v[112:115], v[206:209], v[174:177], v[112:115]
	v_mfma_f32_16x16x32_f16 v[108:111], v[206:209], v[182:185], v[108:111]
	v_mfma_f32_16x16x32_f16 v[104:107], v[214:217], v[174:177], v[104:107]
	v_mfma_f32_16x16x32_f16 v[100:103], v[214:217], v[182:185], v[100:103]
	v_mfma_f32_16x16x32_f16 v[128:131], v[194:197], v[178:181], v[128:131]
	v_mfma_f32_16x16x32_f16 v[124:127], v[194:197], v[186:189], v[124:127]
	v_mfma_f32_16x16x32_f16 v[120:123], v[202:205], v[178:181], v[120:123]
	v_mfma_f32_16x16x32_f16 v[116:119], v[202:205], v[186:189], v[116:119]
	v_mfma_f32_16x16x32_f16 v[112:115], v[210:213], v[178:181], v[112:115]
	v_mfma_f32_16x16x32_f16 v[108:111], v[210:213], v[186:189], v[108:111]
	v_mfma_f32_16x16x32_f16 v[104:107], v[218:221], v[178:181], v[104:107]
	v_mfma_f32_16x16x32_f16 v[100:103], v[218:221], v[186:189], v[100:103]
	s_barrier
	v_lshl_add_u64 v[246:247], v[142:143], 0, s[12:13]
	v_lshl_add_u64 v[248:249], v[246:247], 0, s[40:41]
	s_or_b32 m0, s100, 0x10000
	ds_read_b128 v[226:229], v168
	ds_read_b128 v[230:233], v168 offset:1024
	ds_read_b128 v[238:241], v168 offset:2048
	ds_read_b128 v[242:245], v168 offset:3072
	global_load_lds_dwordx4 v[248:249], off
	v_lshl_add_u64 v[248:249], v[144:145], 0, s[12:13]
	s_or_b32 m0, s100, 0x12000
	v_lshl_add_u64 v[250:251], v[248:249], 0, s[40:41]
	global_load_lds_dwordx4 v[250:251], off
	s_barrier
	s_waitcnt lgkmcnt(0)
	v_mfma_f32_16x16x32_f16 v[96:99], v[190:193], v[226:229], v[96:99]
	v_mfma_f32_16x16x32_f16 v[92:95], v[190:193], v[238:241], v[92:95]
	v_mfma_f32_16x16x32_f16 v[88:91], v[198:201], v[226:229], v[88:91]
	v_mfma_f32_16x16x32_f16 v[84:87], v[198:201], v[238:241], v[84:87]
	v_mfma_f32_16x16x32_f16 v[80:83], v[206:209], v[226:229], v[80:83]
	v_mfma_f32_16x16x32_f16 v[76:79], v[206:209], v[238:241], v[76:79]
	v_mfma_f32_16x16x32_f16 v[72:75], v[214:217], v[226:229], v[72:75]
	v_mfma_f32_16x16x32_f16 v[68:71], v[214:217], v[238:241], v[68:71]
	v_mfma_f32_16x16x32_f16 v[96:99], v[194:197], v[230:233], v[96:99]
	v_mfma_f32_16x16x32_f16 v[92:95], v[194:197], v[242:245], v[92:95]
	v_mfma_f32_16x16x32_f16 v[88:91], v[202:205], v[230:233], v[88:91]
	v_mfma_f32_16x16x32_f16 v[84:87], v[202:205], v[242:245], v[84:87]
	v_mfma_f32_16x16x32_f16 v[80:83], v[210:213], v[230:233], v[80:83]
	v_mfma_f32_16x16x32_f16 v[76:79], v[210:213], v[242:245], v[76:79]
	v_mfma_f32_16x16x32_f16 v[72:75], v[218:221], v[230:233], v[72:75]
	v_mfma_f32_16x16x32_f16 v[68:71], v[218:221], v[242:245], v[68:71]
	v_lshl_add_u64 v[250:251], v[222:223], 0, s[10:11]
	s_mov_b32 m0, s100
	s_barrier
	ds_read_b128 v[190:193], v156 offset:16384
	ds_read_b128 v[194:197], v156 offset:17408
	ds_read_b128 v[198:201], v155 offset:16384
	ds_read_b128 v[202:205], v155 offset:17408
	ds_read_b128 v[206:209], v154 offset:16384
	ds_read_b128 v[210:213], v154 offset:17408
	ds_read_b128 v[214:217], v153 offset:16384
	ds_read_b128 v[218:221], v153 offset:17408
	global_load_lds_dwordx4 v[250:251], off
	s_or_b32 m0, s100, 0x2000
	v_lshl_add_u64 v[250:251], v[236:237], 0, s[10:11]
	global_load_lds_dwordx4 v[250:251], off
	s_barrier
	s_waitcnt lgkmcnt(0)
	v_mfma_f32_16x16x32_f16 v[64:67], v[190:193], v[174:177], v[64:67]
	v_mfma_f32_16x16x32_f16 v[60:63], v[190:193], v[182:185], v[60:63]
	v_mfma_f32_16x16x32_f16 v[56:59], v[198:201], v[174:177], v[56:59]
	v_mfma_f32_16x16x32_f16 v[52:55], v[198:201], v[182:185], v[52:55]
	v_mfma_f32_16x16x32_f16 v[48:51], v[206:209], v[174:177], v[48:51]
	v_mfma_f32_16x16x32_f16 v[44:47], v[206:209], v[182:185], v[44:47]
	v_mfma_f32_16x16x32_f16 v[40:43], v[214:217], v[174:177], v[40:43]
	v_mfma_f32_16x16x32_f16 v[36:39], v[214:217], v[182:185], v[36:39]
	v_mfma_f32_16x16x32_f16 v[64:67], v[194:197], v[178:181], v[64:67]
	v_mfma_f32_16x16x32_f16 v[60:63], v[194:197], v[186:189], v[60:63]
	v_mfma_f32_16x16x32_f16 v[56:59], v[202:205], v[178:181], v[56:59]
	v_mfma_f32_16x16x32_f16 v[52:55], v[202:205], v[186:189], v[52:55]
	v_mfma_f32_16x16x32_f16 v[48:51], v[210:213], v[178:181], v[48:51]
	v_mfma_f32_16x16x32_f16 v[44:47], v[210:213], v[186:189], v[44:47]
	v_mfma_f32_16x16x32_f16 v[40:43], v[218:221], v[178:181], v[40:43]
	v_mfma_f32_16x16x32_f16 v[36:39], v[218:221], v[186:189], v[36:39]
	s_barrier
	s_or_b32 m0, s100, 0x14000
	v_lshl_add_u64 v[174:175], v[246:247], 0, s[42:43]
	global_load_lds_dwordx4 v[174:175], off
	s_or_b32 m0, s100, 0x16000
	v_lshl_add_u64 v[174:175], v[248:249], 0, s[42:43]
	global_load_lds_dwordx4 v[174:175], off
	s_waitcnt vmcnt(6)
	s_barrier
; #define LDA8(dst, b, h) _Pragma("unroll") for (int m = 0; m < 4; ++m) _Pragma("unroll") for (int k = 0; k < 2; ++k) \
;     dst[m][k] = *(const bf16x8*)((const char*)SA8(b, h) + lds_byte8(wr * 64 + m * 16 + fr, k * 32 + fq * 8))
; #define LDB8(dst, b, h) _Pragma("unroll") for (int n = 0; n < 2; ++n) _Pragma("unroll") for (int k = 0; k < 2; ++k) \
;     dst[n][k] = *(const bf16x8*)((const char*)SB8(b, h) + lds_byte8(wc * 32 + n * 16 + fr, k * 32 + fq * 8))
; #define WAIT_V8(n) asm volatile("s_waitcnt vmcnt(" #n ")" ::: "memory")
; #define WAIT_L8(n) asm volatile("s_waitcnt lgkmcnt(" #n ")" ::: "memory")
; #define BAR8 __builtin_amdgcn_s_barrier()
; #define SCHED8 __builtin_amdgcn_sched_barrier(0)
;     ...
;     WAIT_V8(6); BAR8; MMA8(1, 1, At, B1); BAR8;
;     LDB8(B0, 1, 0); SCHED8; LDA8(At, 1, 0); STAGE8(SA8(0, 1), A, lda, brow + 128, tt + 2);
;     WAIT_L8(8); BAR8; WAIT_L8(0); MMA8(0, 0, At, B0); BAR8; SCHED8;
;     LDB8(B1, 1, 1); STAGE8(SB8(1, 0), Bt, K, bcol, tt + 3);
;     BAR8; WAIT_L8(0); MMA8(0, 1, At, B1); BAR8;
	v_mfma_f32_16x16x32_f16 v[32:35], v[190:193], v[226:229], v[32:35]
	v_mfma_f32_16x16x32_f16 v[28:31], v[190:193], v[238:241], v[28:31]
	v_mfma_f32_16x16x32_f16 v[24:27], v[198:201], v[226:229], v[24:27]
	v_mfma_f32_16x16x32_f16 v[20:23], v[198:201], v[238:241], v[20:23]
	v_mfma_f32_16x16x32_f16 v[16:19], v[206:209], v[226:229], v[16:19]
	v_mfma_f32_16x16x32_f16 v[12:15], v[206:209], v[238:241], v[12:15]
	v_mfma_f32_16x16x32_f16 v[8:11], v[214:217], v[226:229], v[8:11]
	v_mfma_f32_16x16x32_f16 v[4:7], v[214:217], v[238:241], v[4:7]
	v_mfma_f32_16x16x32_f16 v[32:35], v[194:197], v[230:233], v[32:35]
	v_mfma_f32_16x16x32_f16 v[28:31], v[194:197], v[242:245], v[28:31]
	v_mfma_f32_16x16x32_f16 v[24:27], v[202:205], v[230:233], v[24:27]
	v_mfma_f32_16x16x32_f16 v[20:23], v[202:205], v[242:245], v[20:23]
	v_mfma_f32_16x16x32_f16 v[16:19], v[210:213], v[230:233], v[16:19]
	v_mfma_f32_16x16x32_f16 v[12:15], v[210:213], v[242:245], v[12:15]
	v_mfma_f32_16x16x32_f16 v[8:11], v[218:221], v[230:233], v[8:11]
	v_mfma_f32_16x16x32_f16 v[4:7], v[218:221], v[242:245], v[4:7]
	s_barrier
	ds_read_b128 v[174:177], v161
	ds_read_b128 v[178:181], v161 offset:1024
	ds_read_b128 v[182:185], v161 offset:2048
	ds_read_b128 v[186:189], v161 offset:3072
	v_lshl_add_u64 v[226:227], v[222:223], 0, s[18:19]
	s_or_b32 m0, s100, 0x4000
	ds_read_b128 v[190:193], v156 offset:32768
	ds_read_b128 v[194:197], v156 offset:33792
	ds_read_b128 v[198:201], v155 offset:32768
	ds_read_b128 v[202:205], v155 offset:33792
	ds_read_b128 v[206:209], v154 offset:32768
	ds_read_b128 v[210:213], v154 offset:33792
	ds_read_b128 v[214:217], v153 offset:32768
	ds_read_b128 v[218:221], v153 offset:33792
	global_load_lds_dwordx4 v[226:227], off
	s_or_b32 m0, s100, 0x6000
	v_lshl_add_u64 v[226:227], v[236:237], 0, s[18:19]
	global_load_lds_dwordx4 v[226:227], off
	s_waitcnt lgkmcnt(8)
	s_barrier
	s_waitcnt lgkmcnt(0)
	v_mfma_f32_16x16x32_f16 v[128:131], v[190:193], v[174:177], v[128:131]
	v_mfma_f32_16x16x32_f16 v[124:127], v[190:193], v[182:185], v[124:127]
	v_mfma_f32_16x16x32_f16 v[120:123], v[198:201], v[174:177], v[120:123]
	v_mfma_f32_16x16x32_f16 v[116:119], v[198:201], v[182:185], v[116:119]
	v_mfma_f32_16x16x32_f16 v[112:115], v[206:209], v[174:177], v[112:115]
	v_mfma_f32_16x16x32_f16 v[108:111], v[206:209], v[182:185], v[108:111]
	v_mfma_f32_16x16x32_f16 v[104:107], v[214:217], v[174:177], v[104:107]
	v_mfma_f32_16x16x32_f16 v[100:103], v[214:217], v[182:185], v[100:103]
	v_mfma_f32_16x16x32_f16 v[128:131], v[194:197], v[178:181], v[128:131]
	v_mfma_f32_16x16x32_f16 v[124:127], v[194:197], v[186:189], v[124:127]
	v_mfma_f32_16x16x32_f16 v[120:123], v[202:205], v[178:181], v[120:123]
	v_mfma_f32_16x16x32_f16 v[116:119], v[202:205], v[186:189], v[116:119]
	v_mfma_f32_16x16x32_f16 v[112:115], v[210:213], v[178:181], v[112:115]
	v_mfma_f32_16x16x32_f16 v[108:111], v[210:213], v[186:189], v[108:111]
	v_mfma_f32_16x16x32_f16 v[104:107], v[218:221], v[178:181], v[104:107]
	v_mfma_f32_16x16x32_f16 v[100:103], v[218:221], v[186:189], v[100:103]
	s_barrier
	v_lshl_add_u64 v[250:251], v[246:247], 0, s[44:45]
	s_or_b32 m0, s100, 0x18000
	ds_read_b128 v[226:229], v158
	ds_read_b128 v[230:233], v158 offset:1024
	ds_read_b128 v[238:241], v158 offset:2048
	ds_read_b128 v[242:245], v158 offset:3072
	global_load_lds_dwordx4 v[250:251], off
	s_or_b32 m0, s100, 0x1a000
	v_lshl_add_u64 v[250:251], v[248:249], 0, s[44:45]
	global_load_lds_dwordx4 v[250:251], off
	s_barrier
; #define LDA8(dst, b, h) _Pragma("unroll") for (int m = 0; m < 4; ++m) _Pragma("unroll") for (int k = 0; k < 2; ++k) \
;     dst[m][k] = *(const bf16x8*)((const char*)SA8(b, h) + lds_byte8(wr * 64 + m * 16 + fr, k * 32 + fq * 8))
; #define WAIT_V8(n) asm volatile("s_waitcnt vmcnt(" #n ")" ::: "memory")
; #define WAIT_L8(n) asm volatile("s_waitcnt lgkmcnt(" #n ")" ::: "memory")
; #define BAR8 __builtin_amdgcn_s_barrier()
; #define SCHED8 __builtin_amdgcn_sched_barrier(0)
;     ...
;     BAR8; WAIT_L8(0); MMA8(0, 1, At, B1); BAR8;
;     LDA8(At, 1, 1); STAGE8(SA8(1, 0), A, lda, brow, tt + 3);
;     BAR8; WAIT_L8(0); MMA8(1, 0, At, B0); BAR8; SCHED8;
;     STAGE8(SB8(1, 1), Bt, K, bcol + 128, tt + 3);
;     WAIT_V8(6); BAR8; MMA8(1, 1, At, B1); BAR8;
;   }
	s_waitcnt lgkmcnt(0)
	v_mfma_f32_16x16x32_f16 v[96:99], v[190:193], v[226:229], v[96:99]
	v_mfma_f32_16x16x32_f16 v[92:95], v[190:193], v[238:241], v[92:95]
	v_mfma_f32_16x16x32_f16 v[88:91], v[198:201], v[226:229], v[88:91]
	v_mfma_f32_16x16x32_f16 v[84:87], v[198:201], v[238:241], v[84:87]
	v_mfma_f32_16x16x32_f16 v[80:83], v[206:209], v[226:229], v[80:83]
	v_mfma_f32_16x16x32_f16 v[76:79], v[206:209], v[238:241], v[76:79]
	v_mfma_f32_16x16x32_f16 v[72:75], v[214:217], v[226:229], v[72:75]
	v_mfma_f32_16x16x32_f16 v[68:71], v[214:217], v[238:241], v[68:71]
	v_mfma_f32_16x16x32_f16 v[96:99], v[194:197], v[230:233], v[96:99]
	v_mfma_f32_16x16x32_f16 v[92:95], v[194:197], v[242:245], v[92:95]
	v_mfma_f32_16x16x32_f16 v[88:91], v[202:205], v[230:233], v[88:91]
	v_mfma_f32_16x16x32_f16 v[84:87], v[202:205], v[242:245], v[84:87]
	v_mfma_f32_16x16x32_f16 v[80:83], v[210:213], v[230:233], v[80:83]
	v_mfma_f32_16x16x32_f16 v[76:79], v[210:213], v[242:245], v[76:79]
	v_mfma_f32_16x16x32_f16 v[72:75], v[218:221], v[230:233], v[72:75]
	v_mfma_f32_16x16x32_f16 v[68:71], v[218:221], v[242:245], v[68:71]
	v_lshl_add_u64 v[222:223], v[222:223], 0, s[22:23]
	s_or_b32 m0, s100, 0x8000
	s_barrier
	ds_read_b128 v[190:193], v156 offset:49152
	ds_read_b128 v[194:197], v156 offset:50176
	ds_read_b128 v[198:201], v155 offset:49152
	ds_read_b128 v[202:205], v155 offset:50176
	ds_read_b128 v[206:209], v154 offset:49152
	ds_read_b128 v[210:213], v154 offset:50176
	ds_read_b128 v[214:217], v153 offset:49152
	ds_read_b128 v[218:221], v153 offset:50176
	global_load_lds_dwordx4 v[222:223], off
	s_or_b32 m0, s100, 0xa000
	v_lshl_add_u64 v[222:223], v[236:237], 0, s[22:23]
	global_load_lds_dwordx4 v[222:223], off
	s_barrier
	s_waitcnt lgkmcnt(0)
	v_mfma_f32_16x16x32_f16 v[64:67], v[190:193], v[174:177], v[64:67]
	v_mfma_f32_16x16x32_f16 v[60:63], v[190:193], v[182:185], v[60:63]
	v_mfma_f32_16x16x32_f16 v[56:59], v[198:201], v[174:177], v[56:59]
	v_mfma_f32_16x16x32_f16 v[52:55], v[198:201], v[182:185], v[52:55]
	v_mfma_f32_16x16x32_f16 v[48:51], v[206:209], v[174:177], v[48:51]
	v_mfma_f32_16x16x32_f16 v[44:47], v[206:209], v[182:185], v[44:47]
	v_mfma_f32_16x16x32_f16 v[40:43], v[214:217], v[174:177], v[40:43]
	v_mfma_f32_16x16x32_f16 v[36:39], v[214:217], v[182:185], v[36:39]
	v_mfma_f32_16x16x32_f16 v[64:67], v[194:197], v[178:181], v[64:67]
	v_mfma_f32_16x16x32_f16 v[60:63], v[194:197], v[186:189], v[60:63]
	v_mfma_f32_16x16x32_f16 v[56:59], v[202:205], v[178:181], v[56:59]
	v_mfma_f32_16x16x32_f16 v[52:55], v[202:205], v[186:189], v[52:55]
	v_mfma_f32_16x16x32_f16 v[48:51], v[210:213], v[178:181], v[48:51]
	v_mfma_f32_16x16x32_f16 v[44:47], v[210:213], v[186:189], v[44:47]
	v_mfma_f32_16x16x32_f16 v[40:43], v[218:221], v[178:181], v[40:43]
	v_mfma_f32_16x16x32_f16 v[36:39], v[218:221], v[186:189], v[36:39]
	s_barrier
	s_or_b32 m0, s100, 0x1c000
	v_lshl_add_u64 v[174:175], v[246:247], 0, s[46:47]
	global_load_lds_dwordx4 v[174:175], off
	s_or_b32 m0, s100, 0x1e000
	v_lshl_add_u64 v[174:175], v[248:249], 0, s[46:47]
	global_load_lds_dwordx4 v[174:175], off
	s_waitcnt vmcnt(6)
	s_barrier
	v_mfma_f32_16x16x32_f16 v[32:35], v[190:193], v[226:229], v[32:35]
	v_mfma_f32_16x16x32_f16 v[28:31], v[190:193], v[238:241], v[28:31]
	v_mfma_f32_16x16x32_f16 v[24:27], v[198:201], v[226:229], v[24:27]
	v_mfma_f32_16x16x32_f16 v[20:23], v[198:201], v[238:241], v[20:23]
	v_mfma_f32_16x16x32_f16 v[16:19], v[206:209], v[226:229], v[16:19]
	v_mfma_f32_16x16x32_f16 v[12:15], v[206:209], v[238:241], v[12:15]
	v_mfma_f32_16x16x32_f16 v[8:11], v[214:217], v[226:229], v[8:11]
	v_mfma_f32_16x16x32_f16 v[4:7], v[214:217], v[238:241], v[4:7]
	v_mfma_f32_16x16x32_f16 v[32:35], v[194:197], v[230:233], v[32:35]
	v_mfma_f32_16x16x32_f16 v[28:31], v[194:197], v[242:245], v[28:31]
	v_mfma_f32_16x16x32_f16 v[24:27], v[202:205], v[230:233], v[24:27]
	v_mfma_f32_16x16x32_f16 v[20:23], v[202:205], v[242:245], v[20:23]
	v_mfma_f32_16x16x32_f16 v[16:19], v[210:213], v[230:233], v[16:19]
	v_mfma_f32_16x16x32_f16 v[12:15], v[210:213], v[242:245], v[12:15]
	v_mfma_f32_16x16x32_f16 v[8:11], v[218:221], v[230:233], v[8:11]
	v_mfma_f32_16x16x32_f16 v[4:7], v[218:221], v[242:245], v[4:7]
	s_add_i32 s14, s14, 2
	s_add_u32 s12, s12, 0x100
	s_addc_u32 s13, s13, 0
	s_cmp_lt_u32 s14, 12
	s_cbranch_scc1 .LBB0_1015

; #define LDA8(dst, b, h) _Pragma("unroll") for (int m = 0; m < 4; ++m) _Pragma("unroll") for (int k = 0; k < 2; ++k) \
;     dst[m][k] = *(const bf16x8*)((const char*)SA8(b, h) + lds_byte8(wr * 64 + m * 16 + fr, k * 32 + fq * 8))
; #define LDB8(dst, b, h) _Pragma("unroll") for (int n = 0; n < 2; ++n) _Pragma("unroll") for (int k = 0; k < 2; ++k) \
;     dst[n][k] = *(const bf16x8*)((const char*)SB8(b, h) + lds_byte8(wc * 32 + n * 16 + fr, k * 32 + fq * 8))
; #define WAIT_V8(n) asm volatile("s_waitcnt vmcnt(" #n ")" ::: "memory")
; #define WAIT_L8(n) asm volatile("s_waitcnt lgkmcnt(" #n ")" ::: "memory")
; #define BAR8 __builtin_amdgcn_s_barrier()
; #define SCHED8 __builtin_amdgcn_sched_barrier(0)
;     ...
;   if (wr == 1) BAR8;
;   WAIT_V8(4); BAR8;
;   STAGE8(SB8(1, 0), Bt, K, bcol, 1); STAGE8(SA8(1, 0), A, lda, brow, 1); STAGE8(SB8(1, 1), Bt, K, bcol + 128, 1);
;   WAIT_V8(6); BAR8;
;   for (int tt = 0; tt < nt - 2; tt += 2) {
;     LDB8(B0, 0, 0); SCHED8; LDA8(At, 0, 0); STAGE8(SA8(1, 1), A, lda, brow + 128, tt + 1);
;     WAIT_L8(8); BAR8; WAIT_L8(0); MMA8(0, 0, At, B0); BAR8; SCHED8;
;     LDB8(B1, 0, 1); STAGE8(SB8(0, 0), Bt, K, bcol, tt + 2);
;     BAR8; WAIT_L8(0); MMA8(0, 1, At, B1); BAR8;
.LBB0_1151:
	s_or_b64 exec, exec, s[12:13]
	s_lshl_b32 s29, s20, 10
	s_and_b32 s36, s29, 0xfc0000
	s_mov_b64 s[38:39], 0x80
	v_lshl_add_u64 v[14:15], v[14:15], 0, s[38:39]
	s_or_b32 m0, s100, 0x18000
	s_waitcnt vmcnt(4)
	s_barrier
	global_load_lds_dwordx4 v[14:15], off
	v_lshl_add_u64 v[14:15], v[18:19], 0, s[38:39]
	s_or_b32 m0, s100, 0x1a000
	global_load_lds_dwordx4 v[14:15], off
	v_lshl_add_u64 v[14:15], v[20:21], 0, s[38:39]
	s_or_b32 m0, s100, 0x8000
	global_load_lds_dwordx4 v[14:15], off
	v_lshl_add_u64 v[14:15], v[22:23], 0, s[38:39]
	s_or_b32 m0, s100, 0xa000
	global_load_lds_dwordx4 v[14:15], off
	s_or_b32 m0, s100, 0x1c000
	v_lshl_add_u64 v[14:15], v[26:27], 0, s[38:39]
	global_load_lds_dwordx4 v[14:15], off
	v_lshl_add_u64 v[14:15], v[28:29], 0, s[38:39]
	s_or_b32 m0, s100, 0x1e000
	v_and_b32_e32 v147, 15, v3
	global_load_lds_dwordx4 v[14:15], off
	v_bfe_u32 v148, v3, 4, 2
	v_lshlrev_b32_e32 v14, 4, v148
	v_lshlrev_b32_e32 v15, 6, v147
	v_lshlrev_b32_e32 v18, 2, v3
	v_lshlrev_b64 v[136:137], 9, v[16:17]
	v_or_b32_e32 v17, v14, v15
	v_and_b32_e32 v18, 32, v18
	s_mov_b32 s29, 0x10000
	s_and_b32 s12, s21, 0xffffff00
	v_bitop3_b32 v20, v17, s29, v18 bitop3:0xde
	s_mov_b32 s29, 0x14000
	s_ashr_i32 s13, s12, 31
	v_readlane_b32 s40, v254, 35
	v_bitop3_b32 v19, v14, v18, v15 bitop3:0x36
	v_bitop3_b32 v21, v17, s29, v18 bitop3:0xde
	s_mov_b32 s29, 0x18000
	v_lshlrev_b32_e32 v15, 6, v3
	s_lshl_b64 s[12:13], s[12:13], 10
	s_mov_b32 s37, s40
	v_bitop3_b32 v22, v17, s29, v18 bitop3:0xde
	s_mov_b32 s29, 0x1c000
	v_and_b32_e32 v15, 0x3c0, v15
	v_bitop3_b32 v17, v17, s29, v18 bitop3:0xde
	v_bitop3_b32 v18, v15, v18, v14 bitop3:0x36
	v_lshl_add_u64 v[14:15], s[12:13], 0, v[6:7]
	v_lshl_add_u64 v[6:7], s[36:37], 0, v[6:7]
	v_lshl_add_u64 v[14:15], v[14:15], 0, v[8:9]
	v_lshl_add_u64 v[6:7], v[6:7], 0, v[8:9]
	v_bfe_u32 v146, v3, 6, 2
	s_waitcnt vmcnt(6)
	v_lshlrev_b32_e32 v149, 6, v5
	v_lshlrev_b32_e32 v5, 13, v5
	v_lshl_add_u64 v[138:139], s[4:5], 0, v[14:15]
	v_lshl_add_u64 v[14:15], s[12:13], 0, v[10:11]
	v_lshl_add_u64 v[142:143], s[2:3], 0, v[6:7]
	v_lshl_add_u64 v[6:7], s[36:37], 0, v[10:11]
	v_lshlrev_b64 v[134:135], 9, v[24:25]
	v_readlane_b32 s41, v254, 36
	v_readlane_b32 s42, v254, 37
	v_readlane_b32 s43, v254, 38
	v_lshlrev_b32_e32 v16, 12, v146
	v_or_b32_e32 v23, 0x800, v5
	v_or_b32_e32 v24, 0x1000, v5
	v_or_b32_e32 v25, 0x1800, v5
	v_lshl_add_u64 v[14:15], v[14:15], 0, v[12:13]
	v_lshl_add_u64 v[6:7], v[6:7], 0, v[12:13]
	v_lshl_add_u64 v[140:141], s[4:5], 0, v[14:15]
	v_lshl_add_u64 v[144:145], s[2:3], 0, v[6:7]
	s_mov_b32 s29, -2
	s_mov_b64 s[12:13], 0
	v_add_u32_e32 v171, v20, v16
	v_add_u32_e32 v156, v19, v5
	v_add_u32_e32 v155, v18, v23
	v_add_u32_e32 v154, v18, v24
	v_add_u32_e32 v153, v18, v25
	v_add_u32_e32 v167, v21, v16
	v_add_u32_e32 v160, v22, v16
	v_add_u32_e32 v158, v17, v16
	s_mov_b64 s[36:37], 0x3020080
	s_mov_b64 s[38:39], 0xc9a0100
	s_mov_b64 s[40:41], 0x3000100
	s_mov_b64 s[42:43], 0xc9c0100
	s_mov_b64 s[44:45], 0x3020100
	s_mov_b64 s[46:47], 0xc9a0180
	s_mov_b64 s[48:49], 0x3000180
	s_mov_b64 s[50:51], 0xc9c0180
	s_barrier
	ds_read_b128 v[174:177], v171
	ds_read_b128 v[178:181], v171 offset:1024
	ds_read_b128 v[182:185], v171 offset:2048
	ds_read_b128 v[186:189], v171 offset:3072
	v_lshl_add_u64 v[222:223], v[142:143], 0, s[12:13]
	v_lshl_add_u64 v[226:227], v[222:223], 0, s[36:37]
	s_or_b32 m0, s100, 0xc000
	v_lshl_add_u64 v[236:237], v[144:145], 0, s[12:13]
	ds_read_b128 v[190:193], v156
	ds_read_b128 v[194:197], v156 offset:1024
	ds_read_b128 v[198:201], v155
	ds_read_b128 v[202:205], v155 offset:1024
	ds_read_b128 v[206:209], v154
	ds_read_b128 v[210:213], v154 offset:1024
	ds_read_b128 v[214:217], v153
	ds_read_b128 v[218:221], v153 offset:1024
	global_load_lds_dwordx4 v[226:227], off
	s_or_b32 m0, s100, 0xe000
	v_lshl_add_u64 v[226:227], v[236:237], 0, s[36:37]
	global_load_lds_dwordx4 v[226:227], off
	s_waitcnt lgkmcnt(8)
	s_barrier
	s_waitcnt lgkmcnt(0)
	v_mfma_f32_16x16x32_bf16 v[128:131], v[190:193], v[174:177], 0
	v_mfma_f32_16x16x32_bf16 v[124:127], v[190:193], v[182:185], 0
	v_mfma_f32_16x16x32_bf16 v[120:123], v[198:201], v[174:177], 0
	v_mfma_f32_16x16x32_bf16 v[116:119], v[198:201], v[182:185], 0
	v_mfma_f32_16x16x32_bf16 v[112:115], v[206:209], v[174:177], 0
	v_mfma_f32_16x16x32_bf16 v[108:111], v[206:209], v[182:185], 0
	v_mfma_f32_16x16x32_bf16 v[104:107], v[214:217], v[174:177], 0
	v_mfma_f32_16x16x32_bf16 v[100:103], v[214:217], v[182:185], 0
	v_mfma_f32_16x16x32_bf16 v[128:131], v[194:197], v[178:181], v[128:131]
	v_mfma_f32_16x16x32_bf16 v[124:127], v[194:197], v[186:189], v[124:127]
	v_mfma_f32_16x16x32_bf16 v[120:123], v[202:205], v[178:181], v[120:123]
	v_mfma_f32_16x16x32_bf16 v[116:119], v[202:205], v[186:189], v[116:119]
	v_mfma_f32_16x16x32_bf16 v[112:115], v[210:213], v[178:181], v[112:115]
	v_mfma_f32_16x16x32_bf16 v[108:111], v[210:213], v[186:189], v[108:111]
	v_mfma_f32_16x16x32_bf16 v[104:107], v[218:221], v[178:181], v[104:107]
	v_mfma_f32_16x16x32_bf16 v[100:103], v[218:221], v[186:189], v[100:103]
	s_barrier
	v_lshl_add_u64 v[246:247], v[138:139], 0, s[12:13]
	v_lshl_add_u64 v[248:249], v[246:247], 0, s[38:39]
	s_or_b32 m0, s100, 0x10000
	ds_read_b128 v[226:229], v167
	ds_read_b128 v[230:233], v167 offset:1024
	ds_read_b128 v[238:241], v167 offset:2048
	ds_read_b128 v[242:245], v167 offset:3072
	global_load_lds_dwordx4 v[248:249], off
	v_lshl_add_u64 v[248:249], v[140:141], 0, s[12:13]
	s_or_b32 m0, s100, 0x12000
	v_lshl_add_u64 v[250:251], v[248:249], 0, s[38:39]
	global_load_lds_dwordx4 v[250:251], off
	s_barrier
; #define LDA8(dst, b, h) _Pragma("unroll") for (int m = 0; m < 4; ++m) _Pragma("unroll") for (int k = 0; k < 2; ++k) \
;     dst[m][k] = *(const bf16x8*)((const char*)SA8(b, h) + lds_byte8(wr * 64 + m * 16 + fr, k * 32 + fq * 8))
; #define LDB8(dst, b, h) _Pragma("unroll") for (int n = 0; n < 2; ++n) _Pragma("unroll") for (int k = 0; k < 2; ++k) \
;     dst[n][k] = *(const bf16x8*)((const char*)SB8(b, h) + lds_byte8(wc * 32 + n * 16 + fr, k * 32 + fq * 8))
; #define WAIT_V8(n) asm volatile("s_waitcnt vmcnt(" #n ")" ::: "memory")
; #define WAIT_L8(n) asm volatile("s_waitcnt lgkmcnt(" #n ")" ::: "memory")
; #define BAR8 __builtin_amdgcn_s_barrier()
; #define SCHED8 __builtin_amdgcn_sched_barrier(0)
;     ...
;   for (int tt = 0; tt < nt - 2; tt += 2) {
;     LDB8(B0, 0, 0); SCHED8; LDA8(At, 0, 0); STAGE8(SA8(1, 1), A, lda, brow + 128, tt + 1);
;     WAIT_L8(8); BAR8; WAIT_L8(0); MMA8(0, 0, At, B0); BAR8; SCHED8;
;     LDB8(B1, 0, 1); STAGE8(SB8(0, 0), Bt, K, bcol, tt + 2);
;     BAR8; WAIT_L8(0); MMA8(0, 1, At, B1); BAR8;
;     LDA8(At, 0, 1); STAGE8(SA8(0, 0), A, lda, brow, tt + 2);
;     BAR8; WAIT_L8(0); MMA8(1, 0, At, B0); BAR8; SCHED8;
;     STAGE8(SB8(0, 1), Bt, K, bcol + 128, tt + 2);
;     WAIT_V8(6); BAR8; MMA8(1, 1, At, B1); BAR8;
;     LDB8(B0, 1, 0); SCHED8; LDA8(At, 1, 0); STAGE8(SA8(0, 1), A, lda, brow + 128, tt + 2);
;     WAIT_L8(8); BAR8; WAIT_L8(0); MMA8(0, 0, At, B0); BAR8; SCHED8;
;     LDB8(B1, 1, 1); STAGE8(SB8(1, 0), Bt, K, bcol, tt + 3);
;     BAR8; WAIT_L8(0); MMA8(0, 1, At, B1); BAR8;
;     LDA8(At, 1, 1); STAGE8(SA8(1, 0), A, lda, brow, tt + 3);
;     BAR8; WAIT_L8(0); MMA8(1, 0, At, B0); BAR8; SCHED8;
;     STAGE8(SB8(1, 1), Bt, K, bcol + 128, tt + 3);
;     WAIT_V8(6); BAR8; MMA8(1, 1, At, B1); BAR8;
	s_waitcnt lgkmcnt(0)
	v_mfma_f32_16x16x32_bf16 v[96:99], v[190:193], v[226:229], 0
	v_mfma_f32_16x16x32_bf16 v[92:95], v[190:193], v[238:241], 0
	v_mfma_f32_16x16x32_bf16 v[88:91], v[198:201], v[226:229], 0
	v_mfma_f32_16x16x32_bf16 v[84:87], v[198:201], v[238:241], 0
	v_mfma_f32_16x16x32_bf16 v[80:83], v[206:209], v[226:229], 0
	v_mfma_f32_16x16x32_bf16 v[76:79], v[206:209], v[238:241], 0
	v_mfma_f32_16x16x32_bf16 v[72:75], v[214:217], v[226:229], 0
	v_mfma_f32_16x16x32_bf16 v[68:71], v[214:217], v[238:241], 0
	v_mfma_f32_16x16x32_bf16 v[96:99], v[194:197], v[230:233], v[96:99]
	v_mfma_f32_16x16x32_bf16 v[92:95], v[194:197], v[242:245], v[92:95]
	v_mfma_f32_16x16x32_bf16 v[88:91], v[202:205], v[230:233], v[88:91]
	v_mfma_f32_16x16x32_bf16 v[84:87], v[202:205], v[242:245], v[84:87]
	v_mfma_f32_16x16x32_bf16 v[80:83], v[210:213], v[230:233], v[80:83]
	v_mfma_f32_16x16x32_bf16 v[76:79], v[210:213], v[242:245], v[76:79]
	v_mfma_f32_16x16x32_bf16 v[72:75], v[218:221], v[230:233], v[72:75]
	v_mfma_f32_16x16x32_bf16 v[68:71], v[218:221], v[242:245], v[68:71]
	v_lshl_add_u64 v[250:251], v[222:223], 0, s[40:41]
	s_mov_b32 m0, s100
	s_barrier
	ds_read_b128 v[190:193], v156 offset:16384
	ds_read_b128 v[194:197], v156 offset:17408
	ds_read_b128 v[198:201], v155 offset:16384
	ds_read_b128 v[202:205], v155 offset:17408
	ds_read_b128 v[206:209], v154 offset:16384
	ds_read_b128 v[210:213], v154 offset:17408
	ds_read_b128 v[214:217], v153 offset:16384
	ds_read_b128 v[218:221], v153 offset:17408
	global_load_lds_dwordx4 v[250:251], off
	s_or_b32 m0, s100, 0x2000
	v_lshl_add_u64 v[250:251], v[236:237], 0, s[40:41]
	global_load_lds_dwordx4 v[250:251], off
	s_barrier
	s_waitcnt lgkmcnt(0)
	v_mfma_f32_16x16x32_bf16 v[64:67], v[190:193], v[174:177], 0
	v_mfma_f32_16x16x32_bf16 v[60:63], v[190:193], v[182:185], 0
	v_mfma_f32_16x16x32_bf16 v[56:59], v[198:201], v[174:177], 0
	v_mfma_f32_16x16x32_bf16 v[52:55], v[198:201], v[182:185], 0
	v_mfma_f32_16x16x32_bf16 v[48:51], v[206:209], v[174:177], 0
	v_mfma_f32_16x16x32_bf16 v[44:47], v[206:209], v[182:185], 0
	v_mfma_f32_16x16x32_bf16 v[40:43], v[214:217], v[174:177], 0
	v_mfma_f32_16x16x32_bf16 v[36:39], v[214:217], v[182:185], 0
	v_mfma_f32_16x16x32_bf16 v[64:67], v[194:197], v[178:181], v[64:67]
	v_mfma_f32_16x16x32_bf16 v[60:63], v[194:197], v[186:189], v[60:63]
	v_mfma_f32_16x16x32_bf16 v[56:59], v[202:205], v[178:181], v[56:59]
	v_mfma_f32_16x16x32_bf16 v[52:55], v[202:205], v[186:189], v[52:55]
	v_mfma_f32_16x16x32_bf16 v[48:51], v[210:213], v[178:181], v[48:51]
	v_mfma_f32_16x16x32_bf16 v[44:47], v[210:213], v[186:189], v[44:47]
	v_mfma_f32_16x16x32_bf16 v[40:43], v[218:221], v[178:181], v[40:43]
	v_mfma_f32_16x16x32_bf16 v[36:39], v[218:221], v[186:189], v[36:39]
	s_barrier
	s_or_b32 m0, s100, 0x14000
	v_lshl_add_u64 v[174:175], v[246:247], 0, s[42:43]
	global_load_lds_dwordx4 v[174:175], off
	s_or_b32 m0, s100, 0x16000
	v_lshl_add_u64 v[174:175], v[248:249], 0, s[42:43]
	global_load_lds_dwordx4 v[174:175], off
	s_waitcnt vmcnt(6)
	s_barrier
	v_mfma_f32_16x16x32_bf16 v[32:35], v[190:193], v[226:229], 0
	v_mfma_f32_16x16x32_bf16 v[28:31], v[190:193], v[238:241], 0
	v_mfma_f32_16x16x32_bf16 v[24:27], v[198:201], v[226:229], 0
	v_mfma_f32_16x16x32_bf16 v[20:23], v[198:201], v[238:241], 0
	v_mfma_f32_16x16x32_bf16 v[16:19], v[206:209], v[226:229], 0
	v_mfma_f32_16x16x32_bf16 v[12:15], v[206:209], v[238:241], 0
	v_mfma_f32_16x16x32_bf16 v[8:11], v[214:217], v[226:229], 0
	v_mfma_f32_16x16x32_bf16 v[4:7], v[214:217], v[238:241], 0
	v_mfma_f32_16x16x32_bf16 v[32:35], v[194:197], v[230:233], v[32:35]
	v_mfma_f32_16x16x32_bf16 v[28:31], v[194:197], v[242:245], v[28:31]
	v_mfma_f32_16x16x32_bf16 v[24:27], v[202:205], v[230:233], v[24:27]
	v_mfma_f32_16x16x32_bf16 v[20:23], v[202:205], v[242:245], v[20:23]
	v_mfma_f32_16x16x32_bf16 v[16:19], v[210:213], v[230:233], v[16:19]
	v_mfma_f32_16x16x32_bf16 v[12:15], v[210:213], v[242:245], v[12:15]
	v_mfma_f32_16x16x32_bf16 v[8:11], v[218:221], v[230:233], v[8:11]
	v_mfma_f32_16x16x32_bf16 v[4:7], v[218:221], v[242:245], v[4:7]
	s_barrier
	ds_read_b128 v[174:177], v160
	ds_read_b128 v[178:181], v160 offset:1024
	ds_read_b128 v[182:185], v160 offset:2048
	ds_read_b128 v[186:189], v160 offset:3072
	v_lshl_add_u64 v[226:227], v[222:223], 0, s[44:45]
	s_or_b32 m0, s100, 0x4000
	ds_read_b128 v[190:193], v156 offset:32768
	ds_read_b128 v[194:197], v156 offset:33792
	ds_read_b128 v[198:201], v155 offset:32768
	ds_read_b128 v[202:205], v155 offset:33792
	ds_read_b128 v[206:209], v154 offset:32768
	ds_read_b128 v[210:213], v154 offset:33792
	ds_read_b128 v[214:217], v153 offset:32768
	ds_read_b128 v[218:221], v153 offset:33792
	global_load_lds_dwordx4 v[226:227], off
	s_or_b32 m0, s100, 0x6000
	v_lshl_add_u64 v[226:227], v[236:237], 0, s[44:45]
	global_load_lds_dwordx4 v[226:227], off
	s_waitcnt lgkmcnt(8)
	s_barrier
	s_waitcnt lgkmcnt(0)
	v_mfma_f32_16x16x32_bf16 v[128:131], v[190:193], v[174:177], v[128:131]
	v_mfma_f32_16x16x32_bf16 v[124:127], v[190:193], v[182:185], v[124:127]
	v_mfma_f32_16x16x32_bf16 v[120:123], v[198:201], v[174:177], v[120:123]
	v_mfma_f32_16x16x32_bf16 v[116:119], v[198:201], v[182:185], v[116:119]
	v_mfma_f32_16x16x32_bf16 v[112:115], v[206:209], v[174:177], v[112:115]
	v_mfma_f32_16x16x32_bf16 v[108:111], v[206:209], v[182:185], v[108:111]
	v_mfma_f32_16x16x32_bf16 v[104:107], v[214:217], v[174:177], v[104:107]
	v_mfma_f32_16x16x32_bf16 v[100:103], v[214:217], v[182:185], v[100:103]
	v_mfma_f32_16x16x32_bf16 v[128:131], v[194:197], v[178:181], v[128:131]
	v_mfma_f32_16x16x32_bf16 v[124:127], v[194:197], v[186:189], v[124:127]
	v_mfma_f32_16x16x32_bf16 v[120:123], v[202:205], v[178:181], v[120:123]
	v_mfma_f32_16x16x32_bf16 v[116:119], v[202:205], v[186:189], v[116:119]
	v_mfma_f32_16x16x32_bf16 v[112:115], v[210:213], v[178:181], v[112:115]
	v_mfma_f32_16x16x32_bf16 v[108:111], v[210:213], v[186:189], v[108:111]
	v_mfma_f32_16x16x32_bf16 v[104:107], v[218:221], v[178:181], v[104:107]
	v_mfma_f32_16x16x32_bf16 v[100:103], v[218:221], v[186:189], v[100:103]
	s_barrier
; #define LDA8(dst, b, h) _Pragma("unroll") for (int m = 0; m < 4; ++m) _Pragma("unroll") for (int k = 0; k < 2; ++k) \
;     dst[m][k] = *(const bf16x8*)((const char*)SA8(b, h) + lds_byte8(wr * 64 + m * 16 + fr, k * 32 + fq * 8))
; #define LDB8(dst, b, h) _Pragma("unroll") for (int n = 0; n < 2; ++n) _Pragma("unroll") for (int k = 0; k < 2; ++k) \
;     dst[n][k] = *(const bf16x8*)((const char*)SB8(b, h) + lds_byte8(wc * 32 + n * 16 + fr, k * 32 + fq * 8))
; #define WAIT_V8(n) asm volatile("s_waitcnt vmcnt(" #n ")" ::: "memory")
; #define WAIT_L8(n) asm volatile("s_waitcnt lgkmcnt(" #n ")" ::: "memory")
; #define BAR8 __builtin_amdgcn_s_barrier()
; #define SCHED8 __builtin_amdgcn_sched_barrier(0)
;     ...
;     BAR8; WAIT_L8(0); MMA8(1, 0, At, B0); BAR8; SCHED8;
;     STAGE8(SB8(0, 1), Bt, K, bcol + 128, tt + 2);
;     WAIT_V8(6); BAR8; MMA8(1, 1, At, B1); BAR8;
;     LDB8(B0, 1, 0); SCHED8; LDA8(At, 1, 0); STAGE8(SA8(0, 1), A, lda, brow + 128, tt + 2);
;     WAIT_L8(8); BAR8; WAIT_L8(0); MMA8(0, 0, At, B0); BAR8; SCHED8;
;     LDB8(B1, 1, 1); STAGE8(SB8(1, 0), Bt, K, bcol, tt + 3);
;     BAR8; WAIT_L8(0); MMA8(0, 1, At, B1); BAR8;
;     LDA8(At, 1, 1); STAGE8(SA8(1, 0), A, lda, brow, tt + 3);
;     BAR8; WAIT_L8(0); MMA8(1, 0, At, B0); BAR8; SCHED8;
;     STAGE8(SB8(1, 1), Bt, K, bcol + 128, tt + 3);
;     WAIT_V8(6); BAR8; MMA8(1, 1, At, B1); BAR8;
	v_lshl_add_u64 v[250:251], v[246:247], 0, s[46:47]
	s_or_b32 m0, s100, 0x18000
	ds_read_b128 v[226:229], v158
	ds_read_b128 v[230:233], v158 offset:1024
	ds_read_b128 v[238:241], v158 offset:2048
	ds_read_b128 v[242:245], v158 offset:3072
	global_load_lds_dwordx4 v[250:251], off
	s_or_b32 m0, s100, 0x1a000
	v_lshl_add_u64 v[250:251], v[248:249], 0, s[46:47]
	global_load_lds_dwordx4 v[250:251], off
	s_barrier
	s_waitcnt lgkmcnt(0)
	v_mfma_f32_16x16x32_bf16 v[96:99], v[190:193], v[226:229], v[96:99]
	v_mfma_f32_16x16x32_bf16 v[92:95], v[190:193], v[238:241], v[92:95]
	v_mfma_f32_16x16x32_bf16 v[88:91], v[198:201], v[226:229], v[88:91]
	v_mfma_f32_16x16x32_bf16 v[84:87], v[198:201], v[238:241], v[84:87]
	v_mfma_f32_16x16x32_bf16 v[80:83], v[206:209], v[226:229], v[80:83]
	v_mfma_f32_16x16x32_bf16 v[76:79], v[206:209], v[238:241], v[76:79]
	v_mfma_f32_16x16x32_bf16 v[72:75], v[214:217], v[226:229], v[72:75]
	v_mfma_f32_16x16x32_bf16 v[68:71], v[214:217], v[238:241], v[68:71]
	v_mfma_f32_16x16x32_bf16 v[96:99], v[194:197], v[230:233], v[96:99]
	v_mfma_f32_16x16x32_bf16 v[92:95], v[194:197], v[242:245], v[92:95]
	v_mfma_f32_16x16x32_bf16 v[88:91], v[202:205], v[230:233], v[88:91]
	v_mfma_f32_16x16x32_bf16 v[84:87], v[202:205], v[242:245], v[84:87]
	v_mfma_f32_16x16x32_bf16 v[80:83], v[210:213], v[230:233], v[80:83]
	v_mfma_f32_16x16x32_bf16 v[76:79], v[210:213], v[242:245], v[76:79]
	v_mfma_f32_16x16x32_bf16 v[72:75], v[218:221], v[230:233], v[72:75]
	v_mfma_f32_16x16x32_bf16 v[68:71], v[218:221], v[242:245], v[68:71]
	v_lshl_add_u64 v[222:223], v[222:223], 0, s[48:49]
	s_or_b32 m0, s100, 0x8000
	s_barrier
	ds_read_b128 v[190:193], v156 offset:49152
	ds_read_b128 v[194:197], v156 offset:50176
	ds_read_b128 v[198:201], v155 offset:49152
	ds_read_b128 v[202:205], v155 offset:50176
	ds_read_b128 v[206:209], v154 offset:49152
	ds_read_b128 v[210:213], v154 offset:50176
	ds_read_b128 v[214:217], v153 offset:49152
	ds_read_b128 v[218:221], v153 offset:50176
	global_load_lds_dwordx4 v[222:223], off
	s_or_b32 m0, s100, 0xa000
	v_lshl_add_u64 v[222:223], v[236:237], 0, s[48:49]
	global_load_lds_dwordx4 v[222:223], off
	s_barrier
	s_waitcnt lgkmcnt(0)
	v_mfma_f32_16x16x32_bf16 v[64:67], v[190:193], v[174:177], v[64:67]
	v_mfma_f32_16x16x32_bf16 v[60:63], v[190:193], v[182:185], v[60:63]
	v_mfma_f32_16x16x32_bf16 v[56:59], v[198:201], v[174:177], v[56:59]
	v_mfma_f32_16x16x32_bf16 v[52:55], v[198:201], v[182:185], v[52:55]
	v_mfma_f32_16x16x32_bf16 v[48:51], v[206:209], v[174:177], v[48:51]
	v_mfma_f32_16x16x32_bf16 v[44:47], v[206:209], v[182:185], v[44:47]
	v_mfma_f32_16x16x32_bf16 v[40:43], v[214:217], v[174:177], v[40:43]
	v_mfma_f32_16x16x32_bf16 v[36:39], v[214:217], v[182:185], v[36:39]
	v_mfma_f32_16x16x32_bf16 v[64:67], v[194:197], v[178:181], v[64:67]
	v_mfma_f32_16x16x32_bf16 v[60:63], v[194:197], v[186:189], v[60:63]
	v_mfma_f32_16x16x32_bf16 v[56:59], v[202:205], v[178:181], v[56:59]
	v_mfma_f32_16x16x32_bf16 v[52:55], v[202:205], v[186:189], v[52:55]
	v_mfma_f32_16x16x32_bf16 v[48:51], v[210:213], v[178:181], v[48:51]
	v_mfma_f32_16x16x32_bf16 v[44:47], v[210:213], v[186:189], v[44:47]
	v_mfma_f32_16x16x32_bf16 v[40:43], v[218:221], v[178:181], v[40:43]
	v_mfma_f32_16x16x32_bf16 v[36:39], v[218:221], v[186:189], v[36:39]
	s_barrier
	s_or_b32 m0, s100, 0x1c000
	v_lshl_add_u64 v[174:175], v[246:247], 0, s[50:51]
	global_load_lds_dwordx4 v[174:175], off
	s_or_b32 m0, s100, 0x1e000
	v_lshl_add_u64 v[174:175], v[248:249], 0, s[50:51]
	global_load_lds_dwordx4 v[174:175], off
	s_waitcnt vmcnt(6)
	s_barrier
	v_mfma_f32_16x16x32_bf16 v[32:35], v[190:193], v[226:229], v[32:35]
	v_mfma_f32_16x16x32_bf16 v[28:31], v[190:193], v[238:241], v[28:31]
	v_mfma_f32_16x16x32_bf16 v[24:27], v[198:201], v[226:229], v[24:27]
	v_mfma_f32_16x16x32_bf16 v[20:23], v[198:201], v[238:241], v[20:23]
	v_mfma_f32_16x16x32_bf16 v[16:19], v[206:209], v[226:229], v[16:19]
	v_mfma_f32_16x16x32_bf16 v[12:15], v[206:209], v[238:241], v[12:15]
	v_mfma_f32_16x16x32_bf16 v[8:11], v[214:217], v[226:229], v[8:11]
	v_mfma_f32_16x16x32_bf16 v[4:7], v[214:217], v[238:241], v[4:7]
	v_mfma_f32_16x16x32_bf16 v[32:35], v[194:197], v[230:233], v[32:35]
	v_mfma_f32_16x16x32_bf16 v[28:31], v[194:197], v[242:245], v[28:31]
	v_mfma_f32_16x16x32_bf16 v[24:27], v[202:205], v[230:233], v[24:27]
	v_mfma_f32_16x16x32_bf16 v[20:23], v[202:205], v[242:245], v[20:23]
	v_mfma_f32_16x16x32_bf16 v[16:19], v[210:213], v[230:233], v[16:19]
	v_mfma_f32_16x16x32_bf16 v[12:15], v[210:213], v[242:245], v[12:15]
	v_mfma_f32_16x16x32_bf16 v[8:11], v[218:221], v[230:233], v[8:11]
	v_mfma_f32_16x16x32_bf16 v[4:7], v[218:221], v[242:245], v[4:7]
	s_add_i32 s29, s29, 2
	s_add_u32 s12, s12, 0x100
	s_addc_u32 s13, s13, 0
	s_cmp_lt_u32 s29, 4
	s_cbranch_scc0 .Lpk_exitb_5
; #define LDA8(dst, b, h) _Pragma("unroll") for (int m = 0; m < 4; ++m) _Pragma("unroll") for (int k = 0; k < 2; ++k) \
;     dst[m][k] = *(const bf16x8*)((const char*)SA8(b, h) + lds_byte8(wr * 64 + m * 16 + fr, k * 32 + fq * 8))
; #define LDB8(dst, b, h) _Pragma("unroll") for (int n = 0; n < 2; ++n) _Pragma("unroll") for (int k = 0; k < 2; ++k) \
;     dst[n][k] = *(const bf16x8*)((const char*)SB8(b, h) + lds_byte8(wc * 32 + n * 16 + fr, k * 32 + fq * 8))
; #define WAIT_V8(n) asm volatile("s_waitcnt vmcnt(" #n ")" ::: "memory")
; #define WAIT_L8(n) asm volatile("s_waitcnt lgkmcnt(" #n ")" ::: "memory")
; #define BAR8 __builtin_amdgcn_s_barrier()
; #define SCHED8 __builtin_amdgcn_sched_barrier(0)
;     ...
;   for (int tt = 0; tt < nt - 2; tt += 2) {
;     LDB8(B0, 0, 0); SCHED8; LDA8(At, 0, 0); STAGE8(SA8(1, 1), A, lda, brow + 128, tt + 1);
;     WAIT_L8(8); BAR8; WAIT_L8(0); MMA8(0, 0, At, B0); BAR8; SCHED8;
;     LDB8(B1, 0, 1); STAGE8(SB8(0, 0), Bt, K, bcol, tt + 2);
;     BAR8; WAIT_L8(0); MMA8(0, 1, At, B1); BAR8;
;     LDA8(At, 0, 1); STAGE8(SA8(0, 0), A, lda, brow, tt + 2);
;     BAR8; WAIT_L8(0); MMA8(1, 0, At, B0); BAR8; SCHED8;
;     STAGE8(SB8(0, 1), Bt, K, bcol + 128, tt + 2);
;     WAIT_V8(6); BAR8; MMA8(1, 1, At, B1); BAR8;
;     LDB8(B0, 1, 0); SCHED8; LDA8(At, 1, 0); STAGE8(SA8(0, 1), A, lda, brow + 128, tt + 2);
;     WAIT_L8(8); BAR8; WAIT_L8(0); MMA8(0, 0, At, B0); BAR8; SCHED8;
.LBB0_1152:
	s_barrier
	ds_read_b128 v[174:177], v171
	ds_read_b128 v[178:181], v171 offset:1024
	ds_read_b128 v[182:185], v171 offset:2048
	ds_read_b128 v[186:189], v171 offset:3072
	v_lshl_add_u64 v[222:223], v[142:143], 0, s[12:13]
	v_lshl_add_u64 v[226:227], v[222:223], 0, s[36:37]
	s_or_b32 m0, s100, 0xc000
	v_lshl_add_u64 v[236:237], v[144:145], 0, s[12:13]
	ds_read_b128 v[190:193], v156
	ds_read_b128 v[194:197], v156 offset:1024
	ds_read_b128 v[198:201], v155
	ds_read_b128 v[202:205], v155 offset:1024
	ds_read_b128 v[206:209], v154
	ds_read_b128 v[210:213], v154 offset:1024
	ds_read_b128 v[214:217], v153
	ds_read_b128 v[218:221], v153 offset:1024
	global_load_lds_dwordx4 v[226:227], off
	s_or_b32 m0, s100, 0xe000
	v_lshl_add_u64 v[226:227], v[236:237], 0, s[36:37]
	global_load_lds_dwordx4 v[226:227], off
	s_waitcnt lgkmcnt(8)
	s_barrier
	s_waitcnt lgkmcnt(0)
	v_mfma_f32_16x16x32_bf16 v[128:131], v[190:193], v[174:177], v[128:131]
	v_mfma_f32_16x16x32_bf16 v[124:127], v[190:193], v[182:185], v[124:127]
	v_mfma_f32_16x16x32_bf16 v[120:123], v[198:201], v[174:177], v[120:123]
	v_mfma_f32_16x16x32_bf16 v[116:119], v[198:201], v[182:185], v[116:119]
	v_mfma_f32_16x16x32_bf16 v[112:115], v[206:209], v[174:177], v[112:115]
	v_mfma_f32_16x16x32_bf16 v[108:111], v[206:209], v[182:185], v[108:111]
	v_mfma_f32_16x16x32_bf16 v[104:107], v[214:217], v[174:177], v[104:107]
	v_mfma_f32_16x16x32_bf16 v[100:103], v[214:217], v[182:185], v[100:103]
	v_mfma_f32_16x16x32_bf16 v[128:131], v[194:197], v[178:181], v[128:131]
	v_mfma_f32_16x16x32_bf16 v[124:127], v[194:197], v[186:189], v[124:127]
	v_mfma_f32_16x16x32_bf16 v[120:123], v[202:205], v[178:181], v[120:123]
	v_mfma_f32_16x16x32_bf16 v[116:119], v[202:205], v[186:189], v[116:119]
	v_mfma_f32_16x16x32_bf16 v[112:115], v[210:213], v[178:181], v[112:115]
	v_mfma_f32_16x16x32_bf16 v[108:111], v[210:213], v[186:189], v[108:111]
	v_mfma_f32_16x16x32_bf16 v[104:107], v[218:221], v[178:181], v[104:107]
	v_mfma_f32_16x16x32_bf16 v[100:103], v[218:221], v[186:189], v[100:103]
	s_barrier
	v_lshl_add_u64 v[246:247], v[138:139], 0, s[12:13]
	v_lshl_add_u64 v[248:249], v[246:247], 0, s[38:39]
	s_or_b32 m0, s100, 0x10000
	ds_read_b128 v[226:229], v167
	ds_read_b128 v[230:233], v167 offset:1024
	ds_read_b128 v[238:241], v167 offset:2048
	ds_read_b128 v[242:245], v167 offset:3072
	global_load_lds_dwordx4 v[248:249], off
	v_lshl_add_u64 v[248:249], v[140:141], 0, s[12:13]
	s_or_b32 m0, s100, 0x12000
	v_lshl_add_u64 v[250:251], v[248:249], 0, s[38:39]
	global_load_lds_dwordx4 v[250:251], off
	s_barrier
	s_waitcnt lgkmcnt(0)
	v_mfma_f32_16x16x32_bf16 v[96:99], v[190:193], v[226:229], v[96:99]
	v_mfma_f32_16x16x32_bf16 v[92:95], v[190:193], v[238:241], v[92:95]
	v_mfma_f32_16x16x32_bf16 v[88:91], v[198:201], v[226:229], v[88:91]
	v_mfma_f32_16x16x32_bf16 v[84:87], v[198:201], v[238:241], v[84:87]
	v_mfma_f32_16x16x32_bf16 v[80:83], v[206:209], v[226:229], v[80:83]
	v_mfma_f32_16x16x32_bf16 v[76:79], v[206:209], v[238:241], v[76:79]
	v_mfma_f32_16x16x32_bf16 v[72:75], v[214:217], v[226:229], v[72:75]
	v_mfma_f32_16x16x32_bf16 v[68:71], v[214:217], v[238:241], v[68:71]
	v_mfma_f32_16x16x32_bf16 v[96:99], v[194:197], v[230:233], v[96:99]
	v_mfma_f32_16x16x32_bf16 v[92:95], v[194:197], v[242:245], v[92:95]
	v_mfma_f32_16x16x32_bf16 v[88:91], v[202:205], v[230:233], v[88:91]
	v_mfma_f32_16x16x32_bf16 v[84:87], v[202:205], v[242:245], v[84:87]
	v_mfma_f32_16x16x32_bf16 v[80:83], v[210:213], v[230:233], v[80:83]
	v_mfma_f32_16x16x32_bf16 v[76:79], v[210:213], v[242:245], v[76:79]
	v_mfma_f32_16x16x32_bf16 v[72:75], v[218:221], v[230:233], v[72:75]
	v_mfma_f32_16x16x32_bf16 v[68:71], v[218:221], v[242:245], v[68:71]
	v_lshl_add_u64 v[250:251], v[222:223], 0, s[40:41]
	s_mov_b32 m0, s100
	s_barrier
	ds_read_b128 v[190:193], v156 offset:16384
	ds_read_b128 v[194:197], v156 offset:17408
	ds_read_b128 v[198:201], v155 offset:16384
	ds_read_b128 v[202:205], v155 offset:17408
	ds_read_b128 v[206:209], v154 offset:16384
	ds_read_b128 v[210:213], v154 offset:17408
	ds_read_b128 v[214:217], v153 offset:16384
	ds_read_b128 v[218:221], v153 offset:17408
	global_load_lds_dwordx4 v[250:251], off
	s_or_b32 m0, s100, 0x2000
	v_lshl_add_u64 v[250:251], v[236:237], 0, s[40:41]
	global_load_lds_dwordx4 v[250:251], off
	s_barrier
	s_waitcnt lgkmcnt(0)
	v_mfma_f32_16x16x32_bf16 v[64:67], v[190:193], v[174:177], v[64:67]
	v_mfma_f32_16x16x32_bf16 v[60:63], v[190:193], v[182:185], v[60:63]
	v_mfma_f32_16x16x32_bf16 v[56:59], v[198:201], v[174:177], v[56:59]
	v_mfma_f32_16x16x32_bf16 v[52:55], v[198:201], v[182:185], v[52:55]
	v_mfma_f32_16x16x32_bf16 v[48:51], v[206:209], v[174:177], v[48:51]
	v_mfma_f32_16x16x32_bf16 v[44:47], v[206:209], v[182:185], v[44:47]
	v_mfma_f32_16x16x32_bf16 v[40:43], v[214:217], v[174:177], v[40:43]
	v_mfma_f32_16x16x32_bf16 v[36:39], v[214:217], v[182:185], v[36:39]
	v_mfma_f32_16x16x32_bf16 v[64:67], v[194:197], v[178:181], v[64:67]
	v_mfma_f32_16x16x32_bf16 v[60:63], v[194:197], v[186:189], v[60:63]
	v_mfma_f32_16x16x32_bf16 v[56:59], v[202:205], v[178:181], v[56:59]
	v_mfma_f32_16x16x32_bf16 v[52:55], v[202:205], v[186:189], v[52:55]
	v_mfma_f32_16x16x32_bf16 v[48:51], v[210:213], v[178:181], v[48:51]
	v_mfma_f32_16x16x32_bf16 v[44:47], v[210:213], v[186:189], v[44:47]
	v_mfma_f32_16x16x32_bf16 v[40:43], v[218:221], v[178:181], v[40:43]
	v_mfma_f32_16x16x32_bf16 v[36:39], v[218:221], v[186:189], v[36:39]
	s_barrier
	s_or_b32 m0, s100, 0x14000
	v_lshl_add_u64 v[174:175], v[246:247], 0, s[42:43]
	global_load_lds_dwordx4 v[174:175], off
	s_or_b32 m0, s100, 0x16000
	v_lshl_add_u64 v[174:175], v[248:249], 0, s[42:43]
	global_load_lds_dwordx4 v[174:175], off
	s_waitcnt vmcnt(6)
	s_barrier
; #define LDA8(dst, b, h) _Pragma("unroll") for (int m = 0; m < 4; ++m) _Pragma("unroll") for (int k = 0; k < 2; ++k) \
;     dst[m][k] = *(const bf16x8*)((const char*)SA8(b, h) + lds_byte8(wr * 64 + m * 16 + fr, k * 32 + fq * 8))
; #define LDB8(dst, b, h) _Pragma("unroll") for (int n = 0; n < 2; ++n) _Pragma("unroll") for (int k = 0; k < 2; ++k) \
;     dst[n][k] = *(const bf16x8*)((const char*)SB8(b, h) + lds_byte8(wc * 32 + n * 16 + fr, k * 32 + fq * 8))
; #define WAIT_V8(n) asm volatile("s_waitcnt vmcnt(" #n ")" ::: "memory")
; #define WAIT_L8(n) asm volatile("s_waitcnt lgkmcnt(" #n ")" ::: "memory")
; #define BAR8 __builtin_amdgcn_s_barrier()
; #define SCHED8 __builtin_amdgcn_sched_barrier(0)
;     ...
;     WAIT_V8(6); BAR8; MMA8(1, 1, At, B1); BAR8;
;     LDB8(B0, 1, 0); SCHED8; LDA8(At, 1, 0); STAGE8(SA8(0, 1), A, lda, brow + 128, tt + 2);
;     WAIT_L8(8); BAR8; WAIT_L8(0); MMA8(0, 0, At, B0); BAR8; SCHED8;
;     LDB8(B1, 1, 1); STAGE8(SB8(1, 0), Bt, K, bcol, tt + 3);
;     BAR8; WAIT_L8(0); MMA8(0, 1, At, B1); BAR8;
;     LDA8(At, 1, 1); STAGE8(SA8(1, 0), A, lda, brow, tt + 3);
;     BAR8; WAIT_L8(0); MMA8(1, 0, At, B0); BAR8; SCHED8;
	v_mfma_f32_16x16x32_bf16 v[32:35], v[190:193], v[226:229], v[32:35]
	v_mfma_f32_16x16x32_bf16 v[28:31], v[190:193], v[238:241], v[28:31]
	v_mfma_f32_16x16x32_bf16 v[24:27], v[198:201], v[226:229], v[24:27]
	v_mfma_f32_16x16x32_bf16 v[20:23], v[198:201], v[238:241], v[20:23]
	v_mfma_f32_16x16x32_bf16 v[16:19], v[206:209], v[226:229], v[16:19]
	v_mfma_f32_16x16x32_bf16 v[12:15], v[206:209], v[238:241], v[12:15]
	v_mfma_f32_16x16x32_bf16 v[8:11], v[214:217], v[226:229], v[8:11]
	v_mfma_f32_16x16x32_bf16 v[4:7], v[214:217], v[238:241], v[4:7]
	v_mfma_f32_16x16x32_bf16 v[32:35], v[194:197], v[230:233], v[32:35]
	v_mfma_f32_16x16x32_bf16 v[28:31], v[194:197], v[242:245], v[28:31]
	v_mfma_f32_16x16x32_bf16 v[24:27], v[202:205], v[230:233], v[24:27]
	v_mfma_f32_16x16x32_bf16 v[20:23], v[202:205], v[242:245], v[20:23]
	v_mfma_f32_16x16x32_bf16 v[16:19], v[210:213], v[230:233], v[16:19]
	v_mfma_f32_16x16x32_bf16 v[12:15], v[210:213], v[242:245], v[12:15]
	v_mfma_f32_16x16x32_bf16 v[8:11], v[218:221], v[230:233], v[8:11]
	v_mfma_f32_16x16x32_bf16 v[4:7], v[218:221], v[242:245], v[4:7]
	s_barrier
	ds_read_b128 v[174:177], v160
	ds_read_b128 v[178:181], v160 offset:1024
	ds_read_b128 v[182:185], v160 offset:2048
	ds_read_b128 v[186:189], v160 offset:3072
	v_lshl_add_u64 v[226:227], v[222:223], 0, s[44:45]
	s_or_b32 m0, s100, 0x4000
	ds_read_b128 v[190:193], v156 offset:32768
	ds_read_b128 v[194:197], v156 offset:33792
	ds_read_b128 v[198:201], v155 offset:32768
	ds_read_b128 v[202:205], v155 offset:33792
	ds_read_b128 v[206:209], v154 offset:32768
	ds_read_b128 v[210:213], v154 offset:33792
	ds_read_b128 v[214:217], v153 offset:32768
	ds_read_b128 v[218:221], v153 offset:33792
	global_load_lds_dwordx4 v[226:227], off
	s_or_b32 m0, s100, 0x6000
	v_lshl_add_u64 v[226:227], v[236:237], 0, s[44:45]
	global_load_lds_dwordx4 v[226:227], off
	s_waitcnt lgkmcnt(8)
	s_barrier
	s_waitcnt lgkmcnt(0)
	v_mfma_f32_16x16x32_bf16 v[128:131], v[190:193], v[174:177], v[128:131]
	v_mfma_f32_16x16x32_bf16 v[124:127], v[190:193], v[182:185], v[124:127]
	v_mfma_f32_16x16x32_bf16 v[120:123], v[198:201], v[174:177], v[120:123]
	v_mfma_f32_16x16x32_bf16 v[116:119], v[198:201], v[182:185], v[116:119]
	v_mfma_f32_16x16x32_bf16 v[112:115], v[206:209], v[174:177], v[112:115]
	v_mfma_f32_16x16x32_bf16 v[108:111], v[206:209], v[182:185], v[108:111]
	v_mfma_f32_16x16x32_bf16 v[104:107], v[214:217], v[174:177], v[104:107]
	v_mfma_f32_16x16x32_bf16 v[100:103], v[214:217], v[182:185], v[100:103]
	v_mfma_f32_16x16x32_bf16 v[128:131], v[194:197], v[178:181], v[128:131]
	v_mfma_f32_16x16x32_bf16 v[124:127], v[194:197], v[186:189], v[124:127]
	v_mfma_f32_16x16x32_bf16 v[120:123], v[202:205], v[178:181], v[120:123]
	v_mfma_f32_16x16x32_bf16 v[116:119], v[202:205], v[186:189], v[116:119]
	v_mfma_f32_16x16x32_bf16 v[112:115], v[210:213], v[178:181], v[112:115]
	v_mfma_f32_16x16x32_bf16 v[108:111], v[210:213], v[186:189], v[108:111]
	v_mfma_f32_16x16x32_bf16 v[104:107], v[218:221], v[178:181], v[104:107]
	v_mfma_f32_16x16x32_bf16 v[100:103], v[218:221], v[186:189], v[100:103]
	s_barrier
	v_lshl_add_u64 v[250:251], v[246:247], 0, s[46:47]
	s_or_b32 m0, s100, 0x18000
	ds_read_b128 v[226:229], v158
	ds_read_b128 v[230:233], v158 offset:1024
	ds_read_b128 v[238:241], v158 offset:2048
	ds_read_b128 v[242:245], v158 offset:3072
	global_load_lds_dwordx4 v[250:251], off
	s_or_b32 m0, s100, 0x1a000
	v_lshl_add_u64 v[250:251], v[248:249], 0, s[46:47]
	global_load_lds_dwordx4 v[250:251], off
	s_barrier
; #define LDA8(dst, b, h) _Pragma("unroll") for (int m = 0; m < 4; ++m) _Pragma("unroll") for (int k = 0; k < 2; ++k) \
;     dst[m][k] = *(const bf16x8*)((const char*)SA8(b, h) + lds_byte8(wr * 64 + m * 16 + fr, k * 32 + fq * 8))
; #define LDB8(dst, b, h) _Pragma("unroll") for (int n = 0; n < 2; ++n) _Pragma("unroll") for (int k = 0; k < 2; ++k) \
;     dst[n][k] = *(const bf16x8*)((const char*)SB8(b, h) + lds_byte8(wc * 32 + n * 16 + fr, k * 32 + fq * 8))
; #define WAIT_V8(n) asm volatile("s_waitcnt vmcnt(" #n ")" ::: "memory")
; #define WAIT_L8(n) asm volatile("s_waitcnt lgkmcnt(" #n ")" ::: "memory")
; #define BAR8 __builtin_amdgcn_s_barrier()
; #define SCHED8 __builtin_amdgcn_sched_barrier(0)
;     ...
;     WAIT_L8(8); BAR8; WAIT_L8(0); MMA8(0, 0, At, B0); BAR8; SCHED8;
;     LDB8(B1, 1, 1); STAGE8(SB8(1, 0), Bt, K, bcol, tt + 3);
;     BAR8; WAIT_L8(0); MMA8(0, 1, At, B1); BAR8;
;     LDA8(At, 1, 1); STAGE8(SA8(1, 0), A, lda, brow, tt + 3);
;     BAR8; WAIT_L8(0); MMA8(1, 0, At, B0); BAR8; SCHED8;
;     STAGE8(SB8(1, 1), Bt, K, bcol + 128, tt + 3);
;     WAIT_V8(6); BAR8; MMA8(1, 1, At, B1); BAR8;
;   }
	s_waitcnt lgkmcnt(0)
	v_mfma_f32_16x16x32_bf16 v[96:99], v[190:193], v[226:229], v[96:99]
	v_mfma_f32_16x16x32_bf16 v[92:95], v[190:193], v[238:241], v[92:95]
	v_mfma_f32_16x16x32_bf16 v[88:91], v[198:201], v[226:229], v[88:91]
	v_mfma_f32_16x16x32_bf16 v[84:87], v[198:201], v[238:241], v[84:87]
	v_mfma_f32_16x16x32_bf16 v[80:83], v[206:209], v[226:229], v[80:83]
	v_mfma_f32_16x16x32_bf16 v[76:79], v[206:209], v[238:241], v[76:79]
	v_mfma_f32_16x16x32_bf16 v[72:75], v[214:217], v[226:229], v[72:75]
	v_mfma_f32_16x16x32_bf16 v[68:71], v[214:217], v[238:241], v[68:71]
	v_mfma_f32_16x16x32_bf16 v[96:99], v[194:197], v[230:233], v[96:99]
	v_mfma_f32_16x16x32_bf16 v[92:95], v[194:197], v[242:245], v[92:95]
	v_mfma_f32_16x16x32_bf16 v[88:91], v[202:205], v[230:233], v[88:91]
	v_mfma_f32_16x16x32_bf16 v[84:87], v[202:205], v[242:245], v[84:87]
	v_mfma_f32_16x16x32_bf16 v[80:83], v[210:213], v[230:233], v[80:83]
	v_mfma_f32_16x16x32_bf16 v[76:79], v[210:213], v[242:245], v[76:79]
	v_mfma_f32_16x16x32_bf16 v[72:75], v[218:221], v[230:233], v[72:75]
	v_mfma_f32_16x16x32_bf16 v[68:71], v[218:221], v[242:245], v[68:71]
	v_lshl_add_u64 v[222:223], v[222:223], 0, s[48:49]
	s_or_b32 m0, s100, 0x8000
	s_barrier
	ds_read_b128 v[190:193], v156 offset:49152
	ds_read_b128 v[194:197], v156 offset:50176
	ds_read_b128 v[198:201], v155 offset:49152
	ds_read_b128 v[202:205], v155 offset:50176
	ds_read_b128 v[206:209], v154 offset:49152
	ds_read_b128 v[210:213], v154 offset:50176
	ds_read_b128 v[214:217], v153 offset:49152
	ds_read_b128 v[218:221], v153 offset:50176
	global_load_lds_dwordx4 v[222:223], off
	s_or_b32 m0, s100, 0xa000
	v_lshl_add_u64 v[222:223], v[236:237], 0, s[48:49]
	global_load_lds_dwordx4 v[222:223], off
	s_barrier
	s_waitcnt lgkmcnt(0)
	v_mfma_f32_16x16x32_bf16 v[64:67], v[190:193], v[174:177], v[64:67]
	v_mfma_f32_16x16x32_bf16 v[60:63], v[190:193], v[182:185], v[60:63]
	v_mfma_f32_16x16x32_bf16 v[56:59], v[198:201], v[174:177], v[56:59]
	v_mfma_f32_16x16x32_bf16 v[52:55], v[198:201], v[182:185], v[52:55]
	v_mfma_f32_16x16x32_bf16 v[48:51], v[206:209], v[174:177], v[48:51]
	v_mfma_f32_16x16x32_bf16 v[44:47], v[206:209], v[182:185], v[44:47]
	v_mfma_f32_16x16x32_bf16 v[40:43], v[214:217], v[174:177], v[40:43]
	v_mfma_f32_16x16x32_bf16 v[36:39], v[214:217], v[182:185], v[36:39]
	v_mfma_f32_16x16x32_bf16 v[64:67], v[194:197], v[178:181], v[64:67]
	v_mfma_f32_16x16x32_bf16 v[60:63], v[194:197], v[186:189], v[60:63]
	v_mfma_f32_16x16x32_bf16 v[56:59], v[202:205], v[178:181], v[56:59]
	v_mfma_f32_16x16x32_bf16 v[52:55], v[202:205], v[186:189], v[52:55]
	v_mfma_f32_16x16x32_bf16 v[48:51], v[210:213], v[178:181], v[48:51]
	v_mfma_f32_16x16x32_bf16 v[44:47], v[210:213], v[186:189], v[44:47]
	v_mfma_f32_16x16x32_bf16 v[40:43], v[218:221], v[178:181], v[40:43]
	v_mfma_f32_16x16x32_bf16 v[36:39], v[218:221], v[186:189], v[36:39]
	s_barrier
	s_or_b32 m0, s100, 0x1c000
	v_lshl_add_u64 v[174:175], v[246:247], 0, s[50:51]
	global_load_lds_dwordx4 v[174:175], off
	s_or_b32 m0, s100, 0x1e000
	v_lshl_add_u64 v[174:175], v[248:249], 0, s[50:51]
	global_load_lds_dwordx4 v[174:175], off
	s_waitcnt vmcnt(6)
	s_barrier
	v_mfma_f32_16x16x32_bf16 v[32:35], v[190:193], v[226:229], v[32:35]
	v_mfma_f32_16x16x32_bf16 v[28:31], v[190:193], v[238:241], v[28:31]
	v_mfma_f32_16x16x32_bf16 v[24:27], v[198:201], v[226:229], v[24:27]
	v_mfma_f32_16x16x32_bf16 v[20:23], v[198:201], v[238:241], v[20:23]
	v_mfma_f32_16x16x32_bf16 v[16:19], v[206:209], v[226:229], v[16:19]
	v_mfma_f32_16x16x32_bf16 v[12:15], v[206:209], v[238:241], v[12:15]
	v_mfma_f32_16x16x32_bf16 v[8:11], v[214:217], v[226:229], v[8:11]
	v_mfma_f32_16x16x32_bf16 v[4:7], v[214:217], v[238:241], v[4:7]
	v_mfma_f32_16x16x32_bf16 v[32:35], v[194:197], v[230:233], v[32:35]
	v_mfma_f32_16x16x32_bf16 v[28:31], v[194:197], v[242:245], v[28:31]
	v_mfma_f32_16x16x32_bf16 v[24:27], v[202:205], v[230:233], v[24:27]
	v_mfma_f32_16x16x32_bf16 v[20:23], v[202:205], v[242:245], v[20:23]
	v_mfma_f32_16x16x32_bf16 v[16:19], v[210:213], v[230:233], v[16:19]
	v_mfma_f32_16x16x32_bf16 v[12:15], v[210:213], v[242:245], v[12:15]
	v_mfma_f32_16x16x32_bf16 v[8:11], v[218:221], v[230:233], v[8:11]
	v_mfma_f32_16x16x32_bf16 v[4:7], v[218:221], v[242:245], v[4:7]
	s_add_i32 s29, s29, 2
	s_add_u32 s12, s12, 0x100
	s_addc_u32 s13, s13, 0
	s_cmp_lt_u32 s29, 4
	s_cbranch_scc1 .LBB0_1152

; #define LDA8(dst, b, h) _Pragma("unroll") for (int m = 0; m < 4; ++m) _Pragma("unroll") for (int k = 0; k < 2; ++k) \
;     dst[m][k] = *(const bf16x8*)((const char*)SA8(b, h) + lds_byte8(wr * 64 + m * 16 + fr, k * 32 + fq * 8))
; #define LDB8(dst, b, h) _Pragma("unroll") for (int n = 0; n < 2; ++n) _Pragma("unroll") for (int k = 0; k < 2; ++k) \
;     dst[n][k] = *(const bf16x8*)((const char*)SB8(b, h) + lds_byte8(wc * 32 + n * 16 + fr, k * 32 + fq * 8))
; #define WAIT_V8(n) asm volatile("s_waitcnt vmcnt(" #n ")" ::: "memory")
; #define BAR8 __builtin_amdgcn_s_barrier()
; #define SCHED8 __builtin_amdgcn_sched_barrier(0)
;     ...
;   if (!pre) {
;     STAGE8(SB8(0, 0), Bt, K, bcol, 0); STAGE8(SA8(0, 0), A, lda, brow, 0);
;     STAGE8(SB8(0, 1), Bt, K, bcol + 128, 0); STAGE8(SA8(0, 1), A, lda, brow + 128, 0);
;   }
;   if (wr == 1) BAR8;
;   WAIT_V8(4); BAR8;
;   STAGE8(SB8(1, 0), Bt, K, bcol, 1); STAGE8(SA8(1, 0), A, lda, brow, 1); STAGE8(SB8(1, 1), Bt, K, bcol + 128, 1);
;   WAIT_V8(6); BAR8;
;   for (int tt = 0; tt < nt - 2; tt += 2) {
;     LDB8(B0, 0, 0); SCHED8; LDA8(At, 0, 0); STAGE8(SA8(1, 1), A, lda, brow + 128, tt + 1);
.LBB0_1258:
	s_or_b64 exec, exec, s[8:9]
	v_add_u32_e32 v0, v150, v0
	v_and_b32_e32 v0, 0xfffffc00, v0
	v_sub_u32_e32 v0, v150, v0
	v_lshrrev_b32_e32 v6, 4, v0
	v_add_u32_e32 v1, v3, v1
	v_bitop3_b32 v7, v6, v0, 32 bitop3:0x6c
	v_ashrrev_i32_e32 v0, 31, v0
	v_ashrrev_i32_e32 v1, 6, v1
	v_lshrrev_b32_e32 v0, 26, v0
	v_lshlrev_b32_e32 v6, 3, v1
	v_add_u32_e32 v0, v7, v0
	v_and_b32_e32 v6, -16, v6
	v_ashrrev_i32_e32 v0, 6, v0
	s_and_b32 s1, s12, 63
	s_and_b32 s8, s20, 0xffffff00
	v_add_u32_e32 v6, v0, v6
	v_mul_i32_i24_e32 v0, 64, v0
	s_lshl_b32 s12, s1, 19
	s_ashr_i32 s9, s8, 31
	s_ashr_i32 s1, s0, 31
	v_lshlrev_b32_e32 v1, 5, v1
	v_sub_u32_e32 v0, v7, v0
	v_mov_b32_e32 v13, 1
	s_lshl_b64 s[14:15], s[8:9], 11
	s_lshl_b64 s[8:9], s[0:1], 11
	v_and_b32_e32 v1, 32, v1
	v_ashrrev_i16_sdwa v0, v13, sext(v0) dst_sel:DWORD dst_unused:UNUSED_PAD src0_sel:DWORD src1_sel:BYTE_0
	s_add_u32 s8, s4, s8
	v_add_u32_sdwa v0, v1, sext(v0) dst_sel:DWORD dst_unused:UNUSED_PAD src0_sel:DWORD src1_sel:WORD_0
	v_ashrrev_i32_e32 v7, 31, v6
	v_readlane_b32 s40, v254, 35
	s_addc_u32 s9, s5, s9
	v_lshlrev_b64 v[132:133], 11, v[6:7]
	v_ashrrev_i32_e32 v1, 31, v0
	v_readlane_b32 s41, v254, 36
	v_lshl_add_u64 v[6:7], s[8:9], 0, v[132:133]
	v_lshlrev_b64 v[8:9], 1, v[0:1]
	s_mov_b32 s13, s40
	v_lshl_add_u64 v[6:7], v[6:7], 0, v[8:9]
	s_mov_b64 s[40:41], 0x80
	v_lshl_add_u64 v[6:7], v[6:7], 0, s[40:41]
	s_or_b32 m0, s100, 0x18000
	s_waitcnt vmcnt(4)
	s_barrier
	global_load_lds_dwordx4 v[6:7], off
	v_ashrrev_i32_e32 v6, 31, v152
	v_lshrrev_b32_e32 v6, 22, v6
	v_add_u32_e32 v6, v152, v6
	v_ashrrev_i32_e32 v7, 10, v6
	v_mul_i32_i24_e32 v6, 0x400, v7
	v_sub_u32_e32 v6, v152, v6
	v_lshrrev_b32_e32 v10, 4, v6
	v_bitop3_b32 v10, v10, v6, 32 bitop3:0x6c
	v_ashrrev_i32_e32 v11, 31, v10
	v_lshrrev_b32_e32 v11, 26, v11
	v_add_u32_e32 v11, v10, v11
	v_lshlrev_b32_e32 v6, 3, v7
	v_ashrrev_i32_e32 v12, 6, v11
	v_and_b32_e32 v11, 0xc0, v11
	v_and_b32_e32 v6, -16, v6
	v_lshlrev_b32_e32 v7, 5, v7
	v_sub_u32_e32 v10, v10, v11
	v_add_u32_e32 v6, v12, v6
	v_and_b32_e32 v7, 32, v7
	v_ashrrev_i16_sdwa v10, v13, sext(v10) dst_sel:DWORD dst_unused:UNUSED_PAD src0_sel:DWORD src1_sel:BYTE_0
	v_add_u32_sdwa v134, v7, sext(v10) dst_sel:DWORD dst_unused:UNUSED_PAD src0_sel:DWORD src1_sel:WORD_0
	v_ashrrev_i32_e32 v7, 31, v6
	v_lshlrev_b64 v[136:137], 11, v[6:7]
	v_ashrrev_i32_e32 v135, 31, v134
	v_lshl_add_u64 v[6:7], s[8:9], 0, v[136:137]
	v_lshlrev_b64 v[10:11], 1, v[134:135]
	s_or_b32 m0, s100, 0x1a000
	s_lshl_b32 s1, s27, 11
	v_lshl_add_u64 v[6:7], v[6:7], 0, v[10:11]
	s_waitcnt lgkmcnt(0)
	s_add_u32 s8, s2, s1
	v_lshl_add_u64 v[6:7], v[6:7], 0, s[40:41]
	s_addc_u32 s9, s3, 0
	global_load_lds_dwordx4 v[6:7], off
	v_lshl_add_u64 v[6:7], s[8:9], 0, v[132:133]
	v_lshl_add_u64 v[6:7], v[6:7], 0, v[8:9]
	s_or_b32 s36, s0, 0x80
	v_lshl_add_u64 v[6:7], v[6:7], 0, s[40:41]
	s_or_b32 m0, s100, 0x8000
	s_ashr_i32 s37, s36, 31
	global_load_lds_dwordx4 v[6:7], off
	v_lshl_add_u64 v[6:7], s[8:9], 0, v[136:137]
	s_lshl_b64 s[36:37], s[36:37], 11
	v_lshl_add_u64 v[6:7], v[6:7], 0, v[10:11]
	s_add_u32 s36, s4, s36
	v_lshl_add_u64 v[6:7], v[6:7], 0, s[40:41]
	s_addc_u32 s37, s5, s37
	s_or_b32 m0, s100, 0xa000
	global_load_lds_dwordx4 v[6:7], off
	v_lshl_add_u64 v[6:7], s[36:37], 0, v[132:133]
	v_lshl_add_u64 v[6:7], v[6:7], 0, v[8:9]
	v_lshl_add_u64 v[6:7], v[6:7], 0, s[40:41]
	s_or_b32 m0, s100, 0x1c000
	global_load_lds_dwordx4 v[6:7], off
	v_lshl_add_u64 v[6:7], s[36:37], 0, v[136:137]
	v_lshl_add_u64 v[6:7], v[6:7], 0, v[10:11]
	v_lshl_add_u64 v[6:7], v[6:7], 0, s[40:41]
	s_or_b32 m0, s100, 0x1e000
	v_and_b32_e32 v147, 15, v3
	global_load_lds_dwordx4 v[6:7], off
	v_bfe_u32 v148, v3, 4, 2
	v_lshlrev_b32_e32 v6, 4, v148
	v_lshlrev_b32_e32 v7, 6, v147
	v_lshlrev_b32_e32 v14, 2, v3
	v_or_b32_e32 v13, v6, v7
	v_and_b32_e32 v14, 32, v14
	s_mov_b32 s1, 0x10000
	v_bitop3_b32 v16, v13, s1, v14 bitop3:0xde
	s_mov_b32 s1, 0x14000
	v_bitop3_b32 v15, v6, v14, v7 bitop3:0x36
	v_bitop3_b32 v17, v13, s1, v14 bitop3:0xde
	s_mov_b32 s1, 0x18000
	v_lshlrev_b32_e32 v7, 6, v3
	v_bitop3_b32 v18, v13, s1, v14 bitop3:0xde
	s_mov_b32 s1, 0x1c000
	v_and_b32_e32 v7, 0x3c0, v7
	v_bitop3_b32 v13, v13, s1, v14 bitop3:0xde
	v_bitop3_b32 v14, v7, v14, v6 bitop3:0x36
	v_lshl_add_u64 v[6:7], s[12:13], 0, v[132:133]
	v_lshl_add_u64 v[6:7], v[6:7], 0, v[8:9]
	v_lshl_add_u64 v[138:139], s[2:3], 0, v[6:7]
	v_lshl_add_u64 v[6:7], s[12:13], 0, v[136:137]
	v_lshl_add_u64 v[6:7], v[6:7], 0, v[10:11]
	v_lshl_add_u64 v[140:141], s[2:3], 0, v[6:7]
	v_lshl_add_u64 v[6:7], s[14:15], 0, v[132:133]
	v_lshl_add_u64 v[6:7], v[6:7], 0, v[8:9]
	v_bfe_u32 v146, v3, 6, 2
	s_waitcnt vmcnt(6)
	v_lshlrev_b32_e32 v149, 6, v5
	v_lshlrev_b32_e32 v5, 13, v5
	v_lshl_add_u64 v[142:143], s[6:7], 0, v[6:7]
	v_lshl_add_u64 v[6:7], s[14:15], 0, v[136:137]
	v_readlane_b32 s42, v254, 37
	v_readlane_b32 s43, v254, 38
	v_lshlrev_b32_e32 v12, 12, v146
	v_or_b32_e32 v19, 0x800, v5
	v_or_b32_e32 v20, 0x1000, v5
	v_or_b32_e32 v21, 0x1800, v5
	v_lshl_add_u64 v[6:7], v[6:7], 0, v[10:11]
	v_lshl_add_u64 v[144:145], s[6:7], 0, v[6:7]
	s_mov_b32 s1, -2
	s_mov_b64 s[12:13], 0
	v_add_u32_e32 v171, v16, v12
	v_add_u32_e32 v161, v15, v5
	v_add_u32_e32 v160, v14, v19
	v_add_u32_e32 v159, v14, v20
	v_add_u32_e32 v158, v14, v21
	v_add_u32_e32 v169, v17, v12
	v_add_u32_e32 v163, v18, v12
	v_add_u32_e32 v162, v13, v12
	s_mov_b64 s[36:37], 0xcaa0100
	s_mov_b64 s[40:41], 0xcae0100
	s_mov_b64 s[42:43], 0xcaa0180
	s_mov_b64 s[44:45], 0xcae0180
	s_barrier
; #define LDA8(dst, b, h) _Pragma("unroll") for (int m = 0; m < 4; ++m) _Pragma("unroll") for (int k = 0; k < 2; ++k) \
;     dst[m][k] = *(const bf16x8*)((const char*)SA8(b, h) + lds_byte8(wr * 64 + m * 16 + fr, k * 32 + fq * 8))
; #define LDB8(dst, b, h) _Pragma("unroll") for (int n = 0; n < 2; ++n) _Pragma("unroll") for (int k = 0; k < 2; ++k) \
;     dst[n][k] = *(const bf16x8*)((const char*)SB8(b, h) + lds_byte8(wc * 32 + n * 16 + fr, k * 32 + fq * 8))
; #define WAIT_V8(n) asm volatile("s_waitcnt vmcnt(" #n ")" ::: "memory")
; #define WAIT_L8(n) asm volatile("s_waitcnt lgkmcnt(" #n ")" ::: "memory")
; #define BAR8 __builtin_amdgcn_s_barrier()
; #define SCHED8 __builtin_amdgcn_sched_barrier(0)
;     ...
;   for (int tt = 0; tt < nt - 2; tt += 2) {
;     LDB8(B0, 0, 0); SCHED8; LDA8(At, 0, 0); STAGE8(SA8(1, 1), A, lda, brow + 128, tt + 1);
;     WAIT_L8(8); BAR8; WAIT_L8(0); MMA8(0, 0, At, B0); BAR8; SCHED8;
;     LDB8(B1, 0, 1); STAGE8(SB8(0, 0), Bt, K, bcol, tt + 2);
;     BAR8; WAIT_L8(0); MMA8(0, 1, At, B1); BAR8;
;     LDA8(At, 0, 1); STAGE8(SA8(0, 0), A, lda, brow, tt + 2);
;     BAR8; WAIT_L8(0); MMA8(1, 0, At, B0); BAR8; SCHED8;
;     STAGE8(SB8(0, 1), Bt, K, bcol + 128, tt + 2);
;     WAIT_V8(6); BAR8; MMA8(1, 1, At, B1); BAR8;
	ds_read_b128 v[174:177], v171
	ds_read_b128 v[178:181], v171 offset:1024
	ds_read_b128 v[182:185], v171 offset:2048
	ds_read_b128 v[186:189], v171 offset:3072
	v_lshl_add_u64 v[222:223], v[138:139], 0, s[12:13]
	v_lshl_add_u64 v[226:227], v[222:223], 0, s[34:35]
	s_or_b32 m0, s100, 0xc000
	v_lshl_add_u64 v[236:237], v[140:141], 0, s[12:13]
	ds_read_b128 v[190:193], v161
	ds_read_b128 v[194:197], v161 offset:1024
	ds_read_b128 v[198:201], v160
	ds_read_b128 v[202:205], v160 offset:1024
	ds_read_b128 v[206:209], v159
	ds_read_b128 v[210:213], v159 offset:1024
	ds_read_b128 v[214:217], v158
	ds_read_b128 v[218:221], v158 offset:1024
	global_load_lds_dwordx4 v[226:227], off
	s_or_b32 m0, s100, 0xe000
	v_lshl_add_u64 v[226:227], v[236:237], 0, s[34:35]
	global_load_lds_dwordx4 v[226:227], off
	s_waitcnt lgkmcnt(8)
	s_barrier
	s_waitcnt lgkmcnt(0)
	v_mfma_f32_16x16x32_f16 v[128:131], v[190:193], v[174:177], 0
	v_mfma_f32_16x16x32_f16 v[124:127], v[190:193], v[182:185], 0
	v_mfma_f32_16x16x32_f16 v[120:123], v[198:201], v[174:177], 0
	v_mfma_f32_16x16x32_f16 v[116:119], v[198:201], v[182:185], 0
	v_mfma_f32_16x16x32_f16 v[112:115], v[206:209], v[174:177], 0
	v_mfma_f32_16x16x32_f16 v[108:111], v[206:209], v[182:185], 0
	v_mfma_f32_16x16x32_f16 v[104:107], v[214:217], v[174:177], 0
	v_mfma_f32_16x16x32_f16 v[100:103], v[214:217], v[182:185], 0
	v_mfma_f32_16x16x32_f16 v[128:131], v[194:197], v[178:181], v[128:131]
	v_mfma_f32_16x16x32_f16 v[124:127], v[194:197], v[186:189], v[124:127]
	v_mfma_f32_16x16x32_f16 v[120:123], v[202:205], v[178:181], v[120:123]
	v_mfma_f32_16x16x32_f16 v[116:119], v[202:205], v[186:189], v[116:119]
	v_mfma_f32_16x16x32_f16 v[112:115], v[210:213], v[178:181], v[112:115]
	v_mfma_f32_16x16x32_f16 v[108:111], v[210:213], v[186:189], v[108:111]
	v_mfma_f32_16x16x32_f16 v[104:107], v[218:221], v[178:181], v[104:107]
	v_mfma_f32_16x16x32_f16 v[100:103], v[218:221], v[186:189], v[100:103]
	s_barrier
	v_lshl_add_u64 v[246:247], v[142:143], 0, s[12:13]
	v_lshl_add_u64 v[248:249], v[246:247], 0, s[36:37]
	s_or_b32 m0, s100, 0x10000
	ds_read_b128 v[226:229], v169
	ds_read_b128 v[230:233], v169 offset:1024
	ds_read_b128 v[238:241], v169 offset:2048
	ds_read_b128 v[242:245], v169 offset:3072
	global_load_lds_dwordx4 v[248:249], off
	v_lshl_add_u64 v[248:249], v[144:145], 0, s[12:13]
	s_or_b32 m0, s100, 0x12000
	v_lshl_add_u64 v[250:251], v[248:249], 0, s[36:37]
	global_load_lds_dwordx4 v[250:251], off
	s_barrier
	s_waitcnt lgkmcnt(0)
	v_mfma_f32_16x16x32_f16 v[96:99], v[190:193], v[226:229], 0
	v_mfma_f32_16x16x32_f16 v[92:95], v[190:193], v[238:241], 0
	v_mfma_f32_16x16x32_f16 v[88:91], v[198:201], v[226:229], 0
	v_mfma_f32_16x16x32_f16 v[84:87], v[198:201], v[238:241], 0
	v_mfma_f32_16x16x32_f16 v[80:83], v[206:209], v[226:229], 0
	v_mfma_f32_16x16x32_f16 v[76:79], v[206:209], v[238:241], 0
	v_mfma_f32_16x16x32_f16 v[72:75], v[214:217], v[226:229], 0
	v_mfma_f32_16x16x32_f16 v[68:71], v[214:217], v[238:241], 0
	v_mfma_f32_16x16x32_f16 v[96:99], v[194:197], v[230:233], v[96:99]
	v_mfma_f32_16x16x32_f16 v[92:95], v[194:197], v[242:245], v[92:95]
	v_mfma_f32_16x16x32_f16 v[88:91], v[202:205], v[230:233], v[88:91]
	v_mfma_f32_16x16x32_f16 v[84:87], v[202:205], v[242:245], v[84:87]
	v_mfma_f32_16x16x32_f16 v[80:83], v[210:213], v[230:233], v[80:83]
	v_mfma_f32_16x16x32_f16 v[76:79], v[210:213], v[242:245], v[76:79]
	v_mfma_f32_16x16x32_f16 v[72:75], v[218:221], v[230:233], v[72:75]
	v_mfma_f32_16x16x32_f16 v[68:71], v[218:221], v[242:245], v[68:71]
	v_lshl_add_u64 v[250:251], v[222:223], 0, s[10:11]
	s_mov_b32 m0, s100
	s_barrier
	ds_read_b128 v[190:193], v161 offset:16384
	ds_read_b128 v[194:197], v161 offset:17408
	ds_read_b128 v[198:201], v160 offset:16384
	ds_read_b128 v[202:205], v160 offset:17408
	ds_read_b128 v[206:209], v159 offset:16384
	ds_read_b128 v[210:213], v159 offset:17408
	ds_read_b128 v[214:217], v158 offset:16384
	ds_read_b128 v[218:221], v158 offset:17408
	global_load_lds_dwordx4 v[250:251], off
	s_or_b32 m0, s100, 0x2000
	v_lshl_add_u64 v[250:251], v[236:237], 0, s[10:11]
	global_load_lds_dwordx4 v[250:251], off
	s_barrier
	s_waitcnt lgkmcnt(0)
	v_mfma_f32_16x16x32_f16 v[64:67], v[190:193], v[174:177], 0
	v_mfma_f32_16x16x32_f16 v[60:63], v[190:193], v[182:185], 0
	v_mfma_f32_16x16x32_f16 v[56:59], v[198:201], v[174:177], 0
	v_mfma_f32_16x16x32_f16 v[52:55], v[198:201], v[182:185], 0
	v_mfma_f32_16x16x32_f16 v[48:51], v[206:209], v[174:177], 0
	v_mfma_f32_16x16x32_f16 v[44:47], v[206:209], v[182:185], 0
	v_mfma_f32_16x16x32_f16 v[40:43], v[214:217], v[174:177], 0
	v_mfma_f32_16x16x32_f16 v[36:39], v[214:217], v[182:185], 0
	v_mfma_f32_16x16x32_f16 v[64:67], v[194:197], v[178:181], v[64:67]
	v_mfma_f32_16x16x32_f16 v[60:63], v[194:197], v[186:189], v[60:63]
	v_mfma_f32_16x16x32_f16 v[56:59], v[202:205], v[178:181], v[56:59]
	v_mfma_f32_16x16x32_f16 v[52:55], v[202:205], v[186:189], v[52:55]
	v_mfma_f32_16x16x32_f16 v[48:51], v[210:213], v[178:181], v[48:51]
	v_mfma_f32_16x16x32_f16 v[44:47], v[210:213], v[186:189], v[44:47]
	v_mfma_f32_16x16x32_f16 v[40:43], v[218:221], v[178:181], v[40:43]
	v_mfma_f32_16x16x32_f16 v[36:39], v[218:221], v[186:189], v[36:39]
	s_barrier
	s_or_b32 m0, s100, 0x14000
	v_lshl_add_u64 v[174:175], v[246:247], 0, s[40:41]
	global_load_lds_dwordx4 v[174:175], off
	s_or_b32 m0, s100, 0x16000
	v_lshl_add_u64 v[174:175], v[248:249], 0, s[40:41]
	global_load_lds_dwordx4 v[174:175], off
	s_waitcnt vmcnt(6)
	s_barrier
; #define LDA8(dst, b, h) _Pragma("unroll") for (int m = 0; m < 4; ++m) _Pragma("unroll") for (int k = 0; k < 2; ++k) \
;     dst[m][k] = *(const bf16x8*)((const char*)SA8(b, h) + lds_byte8(wr * 64 + m * 16 + fr, k * 32 + fq * 8))
; #define LDB8(dst, b, h) _Pragma("unroll") for (int n = 0; n < 2; ++n) _Pragma("unroll") for (int k = 0; k < 2; ++k) \
;     dst[n][k] = *(const bf16x8*)((const char*)SB8(b, h) + lds_byte8(wc * 32 + n * 16 + fr, k * 32 + fq * 8))
; #define WAIT_V8(n) asm volatile("s_waitcnt vmcnt(" #n ")" ::: "memory")
; #define WAIT_L8(n) asm volatile("s_waitcnt lgkmcnt(" #n ")" ::: "memory")
; #define BAR8 __builtin_amdgcn_s_barrier()
; #define SCHED8 __builtin_amdgcn_sched_barrier(0)
;     ...
;     WAIT_V8(6); BAR8; MMA8(1, 1, At, B1); BAR8;
;     LDB8(B0, 1, 0); SCHED8; LDA8(At, 1, 0); STAGE8(SA8(0, 1), A, lda, brow + 128, tt + 2);
;     WAIT_L8(8); BAR8; WAIT_L8(0); MMA8(0, 0, At, B0); BAR8; SCHED8;
;     LDB8(B1, 1, 1); STAGE8(SB8(1, 0), Bt, K, bcol, tt + 3);
;     BAR8; WAIT_L8(0); MMA8(0, 1, At, B1); BAR8;
;     LDA8(At, 1, 1); STAGE8(SA8(1, 0), A, lda, brow, tt + 3);
;     BAR8; WAIT_L8(0); MMA8(1, 0, At, B0); BAR8; SCHED8;
	v_mfma_f32_16x16x32_f16 v[32:35], v[190:193], v[226:229], 0
	v_mfma_f32_16x16x32_f16 v[28:31], v[190:193], v[238:241], 0
	v_mfma_f32_16x16x32_f16 v[24:27], v[198:201], v[226:229], 0
	v_mfma_f32_16x16x32_f16 v[20:23], v[198:201], v[238:241], 0
	v_mfma_f32_16x16x32_f16 v[16:19], v[206:209], v[226:229], 0
	v_mfma_f32_16x16x32_f16 v[12:15], v[206:209], v[238:241], 0
	v_mfma_f32_16x16x32_f16 v[8:11], v[214:217], v[226:229], 0
	v_mfma_f32_16x16x32_f16 v[4:7], v[214:217], v[238:241], 0
	v_mfma_f32_16x16x32_f16 v[32:35], v[194:197], v[230:233], v[32:35]
	v_mfma_f32_16x16x32_f16 v[28:31], v[194:197], v[242:245], v[28:31]
	v_mfma_f32_16x16x32_f16 v[24:27], v[202:205], v[230:233], v[24:27]
	v_mfma_f32_16x16x32_f16 v[20:23], v[202:205], v[242:245], v[20:23]
	v_mfma_f32_16x16x32_f16 v[16:19], v[210:213], v[230:233], v[16:19]
	v_mfma_f32_16x16x32_f16 v[12:15], v[210:213], v[242:245], v[12:15]
	v_mfma_f32_16x16x32_f16 v[8:11], v[218:221], v[230:233], v[8:11]
	v_mfma_f32_16x16x32_f16 v[4:7], v[218:221], v[242:245], v[4:7]
	s_barrier
	ds_read_b128 v[174:177], v163
	ds_read_b128 v[178:181], v163 offset:1024
	ds_read_b128 v[182:185], v163 offset:2048
	ds_read_b128 v[186:189], v163 offset:3072
	v_lshl_add_u64 v[226:227], v[222:223], 0, s[18:19]
	s_or_b32 m0, s100, 0x4000
	ds_read_b128 v[190:193], v161 offset:32768
	ds_read_b128 v[194:197], v161 offset:33792
	ds_read_b128 v[198:201], v160 offset:32768
	ds_read_b128 v[202:205], v160 offset:33792
	ds_read_b128 v[206:209], v159 offset:32768
	ds_read_b128 v[210:213], v159 offset:33792
	ds_read_b128 v[214:217], v158 offset:32768
	ds_read_b128 v[218:221], v158 offset:33792
	global_load_lds_dwordx4 v[226:227], off
	s_or_b32 m0, s100, 0x6000
	v_lshl_add_u64 v[226:227], v[236:237], 0, s[18:19]
	global_load_lds_dwordx4 v[226:227], off
	s_waitcnt lgkmcnt(8)
	s_barrier
	s_waitcnt lgkmcnt(0)
	v_mfma_f32_16x16x32_f16 v[128:131], v[190:193], v[174:177], v[128:131]
	v_mfma_f32_16x16x32_f16 v[124:127], v[190:193], v[182:185], v[124:127]
	v_mfma_f32_16x16x32_f16 v[120:123], v[198:201], v[174:177], v[120:123]
	v_mfma_f32_16x16x32_f16 v[116:119], v[198:201], v[182:185], v[116:119]
	v_mfma_f32_16x16x32_f16 v[112:115], v[206:209], v[174:177], v[112:115]
	v_mfma_f32_16x16x32_f16 v[108:111], v[206:209], v[182:185], v[108:111]
	v_mfma_f32_16x16x32_f16 v[104:107], v[214:217], v[174:177], v[104:107]
	v_mfma_f32_16x16x32_f16 v[100:103], v[214:217], v[182:185], v[100:103]
	v_mfma_f32_16x16x32_f16 v[128:131], v[194:197], v[178:181], v[128:131]
	v_mfma_f32_16x16x32_f16 v[124:127], v[194:197], v[186:189], v[124:127]
	v_mfma_f32_16x16x32_f16 v[120:123], v[202:205], v[178:181], v[120:123]
	v_mfma_f32_16x16x32_f16 v[116:119], v[202:205], v[186:189], v[116:119]
	v_mfma_f32_16x16x32_f16 v[112:115], v[210:213], v[178:181], v[112:115]
	v_mfma_f32_16x16x32_f16 v[108:111], v[210:213], v[186:189], v[108:111]
	v_mfma_f32_16x16x32_f16 v[104:107], v[218:221], v[178:181], v[104:107]
	v_mfma_f32_16x16x32_f16 v[100:103], v[218:221], v[186:189], v[100:103]
	s_barrier
	v_lshl_add_u64 v[250:251], v[246:247], 0, s[42:43]
	s_or_b32 m0, s100, 0x18000
	ds_read_b128 v[226:229], v162
	ds_read_b128 v[230:233], v162 offset:1024
	ds_read_b128 v[238:241], v162 offset:2048
	ds_read_b128 v[242:245], v162 offset:3072
	global_load_lds_dwordx4 v[250:251], off
	s_or_b32 m0, s100, 0x1a000
	v_lshl_add_u64 v[250:251], v[248:249], 0, s[42:43]
	global_load_lds_dwordx4 v[250:251], off
	s_barrier
	s_waitcnt lgkmcnt(0)
	v_mfma_f32_16x16x32_f16 v[96:99], v[190:193], v[226:229], v[96:99]
	v_mfma_f32_16x16x32_f16 v[92:95], v[190:193], v[238:241], v[92:95]
	v_mfma_f32_16x16x32_f16 v[88:91], v[198:201], v[226:229], v[88:91]
	v_mfma_f32_16x16x32_f16 v[84:87], v[198:201], v[238:241], v[84:87]
	v_mfma_f32_16x16x32_f16 v[80:83], v[206:209], v[226:229], v[80:83]
	v_mfma_f32_16x16x32_f16 v[76:79], v[206:209], v[238:241], v[76:79]
	v_mfma_f32_16x16x32_f16 v[72:75], v[214:217], v[226:229], v[72:75]
	v_mfma_f32_16x16x32_f16 v[68:71], v[214:217], v[238:241], v[68:71]
	v_mfma_f32_16x16x32_f16 v[96:99], v[194:197], v[230:233], v[96:99]
	v_mfma_f32_16x16x32_f16 v[92:95], v[194:197], v[242:245], v[92:95]
	v_mfma_f32_16x16x32_f16 v[88:91], v[202:205], v[230:233], v[88:91]
	v_mfma_f32_16x16x32_f16 v[84:87], v[202:205], v[242:245], v[84:87]
	v_mfma_f32_16x16x32_f16 v[80:83], v[210:213], v[230:233], v[80:83]
	v_mfma_f32_16x16x32_f16 v[76:79], v[210:213], v[242:245], v[76:79]
	v_mfma_f32_16x16x32_f16 v[72:75], v[218:221], v[230:233], v[72:75]
	v_mfma_f32_16x16x32_f16 v[68:71], v[218:221], v[242:245], v[68:71]
	v_lshl_add_u64 v[222:223], v[222:223], 0, s[22:23]
	s_or_b32 m0, s100, 0x8000
	s_barrier
	ds_read_b128 v[190:193], v161 offset:49152
	ds_read_b128 v[194:197], v161 offset:50176
	ds_read_b128 v[198:201], v160 offset:49152
	ds_read_b128 v[202:205], v160 offset:50176
	ds_read_b128 v[206:209], v159 offset:49152
	ds_read_b128 v[210:213], v159 offset:50176
	ds_read_b128 v[214:217], v158 offset:49152
	ds_read_b128 v[218:221], v158 offset:50176
	global_load_lds_dwordx4 v[222:223], off
	s_or_b32 m0, s100, 0xa000
	v_lshl_add_u64 v[222:223], v[236:237], 0, s[22:23]
	global_load_lds_dwordx4 v[222:223], off
	s_barrier
; #define LDA8(dst, b, h) _Pragma("unroll") for (int m = 0; m < 4; ++m) _Pragma("unroll") for (int k = 0; k < 2; ++k) \
;     dst[m][k] = *(const bf16x8*)((const char*)SA8(b, h) + lds_byte8(wr * 64 + m * 16 + fr, k * 32 + fq * 8))
; #define LDB8(dst, b, h) _Pragma("unroll") for (int n = 0; n < 2; ++n) _Pragma("unroll") for (int k = 0; k < 2; ++k) \
;     dst[n][k] = *(const bf16x8*)((const char*)SB8(b, h) + lds_byte8(wc * 32 + n * 16 + fr, k * 32 + fq * 8))
; #define WAIT_V8(n) asm volatile("s_waitcnt vmcnt(" #n ")" ::: "memory")
; #define WAIT_L8(n) asm volatile("s_waitcnt lgkmcnt(" #n ")" ::: "memory")
; #define BAR8 __builtin_amdgcn_s_barrier()
; #define SCHED8 __builtin_amdgcn_sched_barrier(0)
;     ...
;   for (int tt = 0; tt < nt - 2; tt += 2) {
;     LDB8(B0, 0, 0); SCHED8; LDA8(At, 0, 0); STAGE8(SA8(1, 1), A, lda, brow + 128, tt + 1);
;     WAIT_L8(8); BAR8; WAIT_L8(0); MMA8(0, 0, At, B0); BAR8; SCHED8;
;     LDB8(B1, 0, 1); STAGE8(SB8(0, 0), Bt, K, bcol, tt + 2);
;     BAR8; WAIT_L8(0); MMA8(0, 1, At, B1); BAR8;
;     LDA8(At, 0, 1); STAGE8(SA8(0, 0), A, lda, brow, tt + 2);
;     BAR8; WAIT_L8(0); MMA8(1, 0, At, B0); BAR8; SCHED8;
;     STAGE8(SB8(0, 1), Bt, K, bcol + 128, tt + 2);
;     WAIT_V8(6); BAR8; MMA8(1, 1, At, B1); BAR8;
;     LDB8(B0, 1, 0); SCHED8; LDA8(At, 1, 0); STAGE8(SA8(0, 1), A, lda, brow + 128, tt + 2);
;     WAIT_L8(8); BAR8; WAIT_L8(0); MMA8(0, 0, At, B0); BAR8; SCHED8;
;     LDB8(B1, 1, 1); STAGE8(SB8(1, 0), Bt, K, bcol, tt + 3);
;     BAR8; WAIT_L8(0); MMA8(0, 1, At, B1); BAR8;
;     LDA8(At, 1, 1); STAGE8(SA8(1, 0), A, lda, brow, tt + 3);
;     BAR8; WAIT_L8(0); MMA8(1, 0, At, B0); BAR8; SCHED8;
;     STAGE8(SB8(1, 1), Bt, K, bcol + 128, tt + 3);
;     WAIT_V8(6); BAR8; MMA8(1, 1, At, B1); BAR8;
	s_waitcnt lgkmcnt(0)
	v_mfma_f32_16x16x32_f16 v[64:67], v[190:193], v[174:177], v[64:67]
	v_mfma_f32_16x16x32_f16 v[60:63], v[190:193], v[182:185], v[60:63]
	v_mfma_f32_16x16x32_f16 v[56:59], v[198:201], v[174:177], v[56:59]
	v_mfma_f32_16x16x32_f16 v[52:55], v[198:201], v[182:185], v[52:55]
	v_mfma_f32_16x16x32_f16 v[48:51], v[206:209], v[174:177], v[48:51]
	v_mfma_f32_16x16x32_f16 v[44:47], v[206:209], v[182:185], v[44:47]
	v_mfma_f32_16x16x32_f16 v[40:43], v[214:217], v[174:177], v[40:43]
	v_mfma_f32_16x16x32_f16 v[36:39], v[214:217], v[182:185], v[36:39]
	v_mfma_f32_16x16x32_f16 v[64:67], v[194:197], v[178:181], v[64:67]
	v_mfma_f32_16x16x32_f16 v[60:63], v[194:197], v[186:189], v[60:63]
	v_mfma_f32_16x16x32_f16 v[56:59], v[202:205], v[178:181], v[56:59]
	v_mfma_f32_16x16x32_f16 v[52:55], v[202:205], v[186:189], v[52:55]
	v_mfma_f32_16x16x32_f16 v[48:51], v[210:213], v[178:181], v[48:51]
	v_mfma_f32_16x16x32_f16 v[44:47], v[210:213], v[186:189], v[44:47]
	v_mfma_f32_16x16x32_f16 v[40:43], v[218:221], v[178:181], v[40:43]
	v_mfma_f32_16x16x32_f16 v[36:39], v[218:221], v[186:189], v[36:39]
	s_barrier
	s_or_b32 m0, s100, 0x1c000
	v_lshl_add_u64 v[174:175], v[246:247], 0, s[44:45]
	global_load_lds_dwordx4 v[174:175], off
	s_or_b32 m0, s100, 0x1e000
	v_lshl_add_u64 v[174:175], v[248:249], 0, s[44:45]
	global_load_lds_dwordx4 v[174:175], off
	s_waitcnt vmcnt(6)
	s_barrier
	v_mfma_f32_16x16x32_f16 v[32:35], v[190:193], v[226:229], v[32:35]
	v_mfma_f32_16x16x32_f16 v[28:31], v[190:193], v[238:241], v[28:31]
	v_mfma_f32_16x16x32_f16 v[24:27], v[198:201], v[226:229], v[24:27]
	v_mfma_f32_16x16x32_f16 v[20:23], v[198:201], v[238:241], v[20:23]
	v_mfma_f32_16x16x32_f16 v[16:19], v[206:209], v[226:229], v[16:19]
	v_mfma_f32_16x16x32_f16 v[12:15], v[206:209], v[238:241], v[12:15]
	v_mfma_f32_16x16x32_f16 v[8:11], v[214:217], v[226:229], v[8:11]
	v_mfma_f32_16x16x32_f16 v[4:7], v[214:217], v[238:241], v[4:7]
	v_mfma_f32_16x16x32_f16 v[32:35], v[194:197], v[230:233], v[32:35]
	v_mfma_f32_16x16x32_f16 v[28:31], v[194:197], v[242:245], v[28:31]
	v_mfma_f32_16x16x32_f16 v[24:27], v[202:205], v[230:233], v[24:27]
	v_mfma_f32_16x16x32_f16 v[20:23], v[202:205], v[242:245], v[20:23]
	v_mfma_f32_16x16x32_f16 v[16:19], v[210:213], v[230:233], v[16:19]
	v_mfma_f32_16x16x32_f16 v[12:15], v[210:213], v[242:245], v[12:15]
	v_mfma_f32_16x16x32_f16 v[8:11], v[218:221], v[230:233], v[8:11]
	v_mfma_f32_16x16x32_f16 v[4:7], v[218:221], v[242:245], v[4:7]
	s_add_i32 s1, s1, 2
	s_add_u32 s12, s12, 0x100
	s_addc_u32 s13, s13, 0
	s_cmp_lt_u32 s1, 12
	s_cbranch_scc0 .Lpk_exitb_6
.LBB0_1259:
	s_barrier
	ds_read_b128 v[174:177], v171
	ds_read_b128 v[178:181], v171 offset:1024
	ds_read_b128 v[182:185], v171 offset:2048
	ds_read_b128 v[186:189], v171 offset:3072
	v_lshl_add_u64 v[222:223], v[138:139], 0, s[12:13]
	v_lshl_add_u64 v[226:227], v[222:223], 0, s[34:35]
	s_or_b32 m0, s100, 0xc000
	v_lshl_add_u64 v[236:237], v[140:141], 0, s[12:13]
	ds_read_b128 v[190:193], v161
	ds_read_b128 v[194:197], v161 offset:1024
	ds_read_b128 v[198:201], v160
	ds_read_b128 v[202:205], v160 offset:1024
	ds_read_b128 v[206:209], v159
	ds_read_b128 v[210:213], v159 offset:1024
	ds_read_b128 v[214:217], v158
	ds_read_b128 v[218:221], v158 offset:1024
	global_load_lds_dwordx4 v[226:227], off
	s_or_b32 m0, s100, 0xe000
	v_lshl_add_u64 v[226:227], v[236:237], 0, s[34:35]
	global_load_lds_dwordx4 v[226:227], off
	s_waitcnt lgkmcnt(8)
	s_barrier
	s_waitcnt lgkmcnt(0)
	v_mfma_f32_16x16x32_f16 v[128:131], v[190:193], v[174:177], v[128:131]
	v_mfma_f32_16x16x32_f16 v[124:127], v[190:193], v[182:185], v[124:127]
	v_mfma_f32_16x16x32_f16 v[120:123], v[198:201], v[174:177], v[120:123]
	v_mfma_f32_16x16x32_f16 v[116:119], v[198:201], v[182:185], v[116:119]
	v_mfma_f32_16x16x32_f16 v[112:115], v[206:209], v[174:177], v[112:115]
	v_mfma_f32_16x16x32_f16 v[108:111], v[206:209], v[182:185], v[108:111]
	v_mfma_f32_16x16x32_f16 v[104:107], v[214:217], v[174:177], v[104:107]
	v_mfma_f32_16x16x32_f16 v[100:103], v[214:217], v[182:185], v[100:103]
	v_mfma_f32_16x16x32_f16 v[128:131], v[194:197], v[178:181], v[128:131]
	v_mfma_f32_16x16x32_f16 v[124:127], v[194:197], v[186:189], v[124:127]
	v_mfma_f32_16x16x32_f16 v[120:123], v[202:205], v[178:181], v[120:123]
	v_mfma_f32_16x16x32_f16 v[116:119], v[202:205], v[186:189], v[116:119]
	v_mfma_f32_16x16x32_f16 v[112:115], v[210:213], v[178:181], v[112:115]
	v_mfma_f32_16x16x32_f16 v[108:111], v[210:213], v[186:189], v[108:111]
	v_mfma_f32_16x16x32_f16 v[104:107], v[218:221], v[178:181], v[104:107]
	v_mfma_f32_16x16x32_f16 v[100:103], v[218:221], v[186:189], v[100:103]
	s_barrier
	v_lshl_add_u64 v[246:247], v[142:143], 0, s[12:13]
	v_lshl_add_u64 v[248:249], v[246:247], 0, s[36:37]
	s_or_b32 m0, s100, 0x10000
	ds_read_b128 v[226:229], v169
	ds_read_b128 v[230:233], v169 offset:1024
	ds_read_b128 v[238:241], v169 offset:2048
	ds_read_b128 v[242:245], v169 offset:3072
	global_load_lds_dwordx4 v[248:249], off
	v_lshl_add_u64 v[248:249], v[144:145], 0, s[12:13]
	s_or_b32 m0, s100, 0x12000
	v_lshl_add_u64 v[250:251], v[248:249], 0, s[36:37]
	global_load_lds_dwordx4 v[250:251], off
	s_barrier
; #define LDA8(dst, b, h) _Pragma("unroll") for (int m = 0; m < 4; ++m) _Pragma("unroll") for (int k = 0; k < 2; ++k) \
;     dst[m][k] = *(const bf16x8*)((const char*)SA8(b, h) + lds_byte8(wr * 64 + m * 16 + fr, k * 32 + fq * 8))
; #define LDB8(dst, b, h) _Pragma("unroll") for (int n = 0; n < 2; ++n) _Pragma("unroll") for (int k = 0; k < 2; ++k) \
;     dst[n][k] = *(const bf16x8*)((const char*)SB8(b, h) + lds_byte8(wc * 32 + n * 16 + fr, k * 32 + fq * 8))
; #define WAIT_V8(n) asm volatile("s_waitcnt vmcnt(" #n ")" ::: "memory")
; #define WAIT_L8(n) asm volatile("s_waitcnt lgkmcnt(" #n ")" ::: "memory")
; #define BAR8 __builtin_amdgcn_s_barrier()
; #define SCHED8 __builtin_amdgcn_sched_barrier(0)
;     ...
;     BAR8; WAIT_L8(0); MMA8(0, 1, At, B1); BAR8;
;     LDA8(At, 0, 1); STAGE8(SA8(0, 0), A, lda, brow, tt + 2);
;     BAR8; WAIT_L8(0); MMA8(1, 0, At, B0); BAR8; SCHED8;
;     STAGE8(SB8(0, 1), Bt, K, bcol + 128, tt + 2);
;     WAIT_V8(6); BAR8; MMA8(1, 1, At, B1); BAR8;
;     LDB8(B0, 1, 0); SCHED8; LDA8(At, 1, 0); STAGE8(SA8(0, 1), A, lda, brow + 128, tt + 2);
;     WAIT_L8(8); BAR8; WAIT_L8(0); MMA8(0, 0, At, B0); BAR8; SCHED8;
;     LDB8(B1, 1, 1); STAGE8(SB8(1, 0), Bt, K, bcol, tt + 3);
;     BAR8; WAIT_L8(0); MMA8(0, 1, At, B1); BAR8;
	s_waitcnt lgkmcnt(0)
	v_mfma_f32_16x16x32_f16 v[96:99], v[190:193], v[226:229], v[96:99]
	v_mfma_f32_16x16x32_f16 v[92:95], v[190:193], v[238:241], v[92:95]
	v_mfma_f32_16x16x32_f16 v[88:91], v[198:201], v[226:229], v[88:91]
	v_mfma_f32_16x16x32_f16 v[84:87], v[198:201], v[238:241], v[84:87]
	v_mfma_f32_16x16x32_f16 v[80:83], v[206:209], v[226:229], v[80:83]
	v_mfma_f32_16x16x32_f16 v[76:79], v[206:209], v[238:241], v[76:79]
	v_mfma_f32_16x16x32_f16 v[72:75], v[214:217], v[226:229], v[72:75]
	v_mfma_f32_16x16x32_f16 v[68:71], v[214:217], v[238:241], v[68:71]
	v_mfma_f32_16x16x32_f16 v[96:99], v[194:197], v[230:233], v[96:99]
	v_mfma_f32_16x16x32_f16 v[92:95], v[194:197], v[242:245], v[92:95]
	v_mfma_f32_16x16x32_f16 v[88:91], v[202:205], v[230:233], v[88:91]
	v_mfma_f32_16x16x32_f16 v[84:87], v[202:205], v[242:245], v[84:87]
	v_mfma_f32_16x16x32_f16 v[80:83], v[210:213], v[230:233], v[80:83]
	v_mfma_f32_16x16x32_f16 v[76:79], v[210:213], v[242:245], v[76:79]
	v_mfma_f32_16x16x32_f16 v[72:75], v[218:221], v[230:233], v[72:75]
	v_mfma_f32_16x16x32_f16 v[68:71], v[218:221], v[242:245], v[68:71]
	v_lshl_add_u64 v[250:251], v[222:223], 0, s[10:11]
	s_mov_b32 m0, s100
	s_barrier
	ds_read_b128 v[190:193], v161 offset:16384
	ds_read_b128 v[194:197], v161 offset:17408
	ds_read_b128 v[198:201], v160 offset:16384
	ds_read_b128 v[202:205], v160 offset:17408
	ds_read_b128 v[206:209], v159 offset:16384
	ds_read_b128 v[210:213], v159 offset:17408
	ds_read_b128 v[214:217], v158 offset:16384
	ds_read_b128 v[218:221], v158 offset:17408
	global_load_lds_dwordx4 v[250:251], off
	s_or_b32 m0, s100, 0x2000
	v_lshl_add_u64 v[250:251], v[236:237], 0, s[10:11]
	global_load_lds_dwordx4 v[250:251], off
	s_barrier
	s_waitcnt lgkmcnt(0)
	v_mfma_f32_16x16x32_f16 v[64:67], v[190:193], v[174:177], v[64:67]
	v_mfma_f32_16x16x32_f16 v[60:63], v[190:193], v[182:185], v[60:63]
	v_mfma_f32_16x16x32_f16 v[56:59], v[198:201], v[174:177], v[56:59]
	v_mfma_f32_16x16x32_f16 v[52:55], v[198:201], v[182:185], v[52:55]
	v_mfma_f32_16x16x32_f16 v[48:51], v[206:209], v[174:177], v[48:51]
	v_mfma_f32_16x16x32_f16 v[44:47], v[206:209], v[182:185], v[44:47]
	v_mfma_f32_16x16x32_f16 v[40:43], v[214:217], v[174:177], v[40:43]
	v_mfma_f32_16x16x32_f16 v[36:39], v[214:217], v[182:185], v[36:39]
	v_mfma_f32_16x16x32_f16 v[64:67], v[194:197], v[178:181], v[64:67]
	v_mfma_f32_16x16x32_f16 v[60:63], v[194:197], v[186:189], v[60:63]
	v_mfma_f32_16x16x32_f16 v[56:59], v[202:205], v[178:181], v[56:59]
	v_mfma_f32_16x16x32_f16 v[52:55], v[202:205], v[186:189], v[52:55]
	v_mfma_f32_16x16x32_f16 v[48:51], v[210:213], v[178:181], v[48:51]
	v_mfma_f32_16x16x32_f16 v[44:47], v[210:213], v[186:189], v[44:47]
	v_mfma_f32_16x16x32_f16 v[40:43], v[218:221], v[178:181], v[40:43]
	v_mfma_f32_16x16x32_f16 v[36:39], v[218:221], v[186:189], v[36:39]
	s_barrier
	s_or_b32 m0, s100, 0x14000
	v_lshl_add_u64 v[174:175], v[246:247], 0, s[40:41]
	global_load_lds_dwordx4 v[174:175], off
	s_or_b32 m0, s100, 0x16000
	v_lshl_add_u64 v[174:175], v[248:249], 0, s[40:41]
	global_load_lds_dwordx4 v[174:175], off
	s_waitcnt vmcnt(6)
	s_barrier
	v_mfma_f32_16x16x32_f16 v[32:35], v[190:193], v[226:229], v[32:35]
	v_mfma_f32_16x16x32_f16 v[28:31], v[190:193], v[238:241], v[28:31]
	v_mfma_f32_16x16x32_f16 v[24:27], v[198:201], v[226:229], v[24:27]
	v_mfma_f32_16x16x32_f16 v[20:23], v[198:201], v[238:241], v[20:23]
	v_mfma_f32_16x16x32_f16 v[16:19], v[206:209], v[226:229], v[16:19]
	v_mfma_f32_16x16x32_f16 v[12:15], v[206:209], v[238:241], v[12:15]
	v_mfma_f32_16x16x32_f16 v[8:11], v[214:217], v[226:229], v[8:11]
	v_mfma_f32_16x16x32_f16 v[4:7], v[214:217], v[238:241], v[4:7]
	v_mfma_f32_16x16x32_f16 v[32:35], v[194:197], v[230:233], v[32:35]
	v_mfma_f32_16x16x32_f16 v[28:31], v[194:197], v[242:245], v[28:31]
	v_mfma_f32_16x16x32_f16 v[24:27], v[202:205], v[230:233], v[24:27]
	v_mfma_f32_16x16x32_f16 v[20:23], v[202:205], v[242:245], v[20:23]
	v_mfma_f32_16x16x32_f16 v[16:19], v[210:213], v[230:233], v[16:19]
	v_mfma_f32_16x16x32_f16 v[12:15], v[210:213], v[242:245], v[12:15]
	v_mfma_f32_16x16x32_f16 v[8:11], v[218:221], v[230:233], v[8:11]
	v_mfma_f32_16x16x32_f16 v[4:7], v[218:221], v[242:245], v[4:7]
	s_barrier
	ds_read_b128 v[174:177], v163
	ds_read_b128 v[178:181], v163 offset:1024
	ds_read_b128 v[182:185], v163 offset:2048
	ds_read_b128 v[186:189], v163 offset:3072
	v_lshl_add_u64 v[226:227], v[222:223], 0, s[18:19]
	s_or_b32 m0, s100, 0x4000
	ds_read_b128 v[190:193], v161 offset:32768
	ds_read_b128 v[194:197], v161 offset:33792
	ds_read_b128 v[198:201], v160 offset:32768
	ds_read_b128 v[202:205], v160 offset:33792
	ds_read_b128 v[206:209], v159 offset:32768
	ds_read_b128 v[210:213], v159 offset:33792
	ds_read_b128 v[214:217], v158 offset:32768
	ds_read_b128 v[218:221], v158 offset:33792
	global_load_lds_dwordx4 v[226:227], off
	s_or_b32 m0, s100, 0x6000
	v_lshl_add_u64 v[226:227], v[236:237], 0, s[18:19]
	global_load_lds_dwordx4 v[226:227], off
	s_waitcnt lgkmcnt(8)
	s_barrier
; #define LDA8(dst, b, h) _Pragma("unroll") for (int m = 0; m < 4; ++m) _Pragma("unroll") for (int k = 0; k < 2; ++k) \
;     dst[m][k] = *(const bf16x8*)((const char*)SA8(b, h) + lds_byte8(wr * 64 + m * 16 + fr, k * 32 + fq * 8))
; #define LDB8(dst, b, h) _Pragma("unroll") for (int n = 0; n < 2; ++n) _Pragma("unroll") for (int k = 0; k < 2; ++k) \
;     dst[n][k] = *(const bf16x8*)((const char*)SB8(b, h) + lds_byte8(wc * 32 + n * 16 + fr, k * 32 + fq * 8))
; #define WAIT_V8(n) asm volatile("s_waitcnt vmcnt(" #n ")" ::: "memory")
; #define WAIT_L8(n) asm volatile("s_waitcnt lgkmcnt(" #n ")" ::: "memory")
; #define BAR8 __builtin_amdgcn_s_barrier()
; #define SCHED8 __builtin_amdgcn_sched_barrier(0)
;     ...
;     WAIT_L8(8); BAR8; WAIT_L8(0); MMA8(0, 0, At, B0); BAR8; SCHED8;
;     LDB8(B1, 1, 1); STAGE8(SB8(1, 0), Bt, K, bcol, tt + 3);
;     BAR8; WAIT_L8(0); MMA8(0, 1, At, B1); BAR8;
;     LDA8(At, 1, 1); STAGE8(SA8(1, 0), A, lda, brow, tt + 3);
;     BAR8; WAIT_L8(0); MMA8(1, 0, At, B0); BAR8; SCHED8;
;     STAGE8(SB8(1, 1), Bt, K, bcol + 128, tt + 3);
;     WAIT_V8(6); BAR8; MMA8(1, 1, At, B1); BAR8;
;   }
	s_waitcnt lgkmcnt(0)
	v_mfma_f32_16x16x32_f16 v[128:131], v[190:193], v[174:177], v[128:131]
	v_mfma_f32_16x16x32_f16 v[124:127], v[190:193], v[182:185], v[124:127]
	v_mfma_f32_16x16x32_f16 v[120:123], v[198:201], v[174:177], v[120:123]
	v_mfma_f32_16x16x32_f16 v[116:119], v[198:201], v[182:185], v[116:119]
	v_mfma_f32_16x16x32_f16 v[112:115], v[206:209], v[174:177], v[112:115]
	v_mfma_f32_16x16x32_f16 v[108:111], v[206:209], v[182:185], v[108:111]
	v_mfma_f32_16x16x32_f16 v[104:107], v[214:217], v[174:177], v[104:107]
	v_mfma_f32_16x16x32_f16 v[100:103], v[214:217], v[182:185], v[100:103]
	v_mfma_f32_16x16x32_f16 v[128:131], v[194:197], v[178:181], v[128:131]
	v_mfma_f32_16x16x32_f16 v[124:127], v[194:197], v[186:189], v[124:127]
	v_mfma_f32_16x16x32_f16 v[120:123], v[202:205], v[178:181], v[120:123]
	v_mfma_f32_16x16x32_f16 v[116:119], v[202:205], v[186:189], v[116:119]
	v_mfma_f32_16x16x32_f16 v[112:115], v[210:213], v[178:181], v[112:115]
	v_mfma_f32_16x16x32_f16 v[108:111], v[210:213], v[186:189], v[108:111]
	v_mfma_f32_16x16x32_f16 v[104:107], v[218:221], v[178:181], v[104:107]
	v_mfma_f32_16x16x32_f16 v[100:103], v[218:221], v[186:189], v[100:103]
	s_barrier
	v_lshl_add_u64 v[250:251], v[246:247], 0, s[42:43]
	s_or_b32 m0, s100, 0x18000
	ds_read_b128 v[226:229], v162
	ds_read_b128 v[230:233], v162 offset:1024
	ds_read_b128 v[238:241], v162 offset:2048
	ds_read_b128 v[242:245], v162 offset:3072
	global_load_lds_dwordx4 v[250:251], off
	s_or_b32 m0, s100, 0x1a000
	v_lshl_add_u64 v[250:251], v[248:249], 0, s[42:43]
	global_load_lds_dwordx4 v[250:251], off
	s_barrier
	s_waitcnt lgkmcnt(0)
	v_mfma_f32_16x16x32_f16 v[96:99], v[190:193], v[226:229], v[96:99]
	v_mfma_f32_16x16x32_f16 v[92:95], v[190:193], v[238:241], v[92:95]
	v_mfma_f32_16x16x32_f16 v[88:91], v[198:201], v[226:229], v[88:91]
	v_mfma_f32_16x16x32_f16 v[84:87], v[198:201], v[238:241], v[84:87]
	v_mfma_f32_16x16x32_f16 v[80:83], v[206:209], v[226:229], v[80:83]
	v_mfma_f32_16x16x32_f16 v[76:79], v[206:209], v[238:241], v[76:79]
	v_mfma_f32_16x16x32_f16 v[72:75], v[214:217], v[226:229], v[72:75]
	v_mfma_f32_16x16x32_f16 v[68:71], v[214:217], v[238:241], v[68:71]
	v_mfma_f32_16x16x32_f16 v[96:99], v[194:197], v[230:233], v[96:99]
	v_mfma_f32_16x16x32_f16 v[92:95], v[194:197], v[242:245], v[92:95]
	v_mfma_f32_16x16x32_f16 v[88:91], v[202:205], v[230:233], v[88:91]
	v_mfma_f32_16x16x32_f16 v[84:87], v[202:205], v[242:245], v[84:87]
	v_mfma_f32_16x16x32_f16 v[80:83], v[210:213], v[230:233], v[80:83]
	v_mfma_f32_16x16x32_f16 v[76:79], v[210:213], v[242:245], v[76:79]
	v_mfma_f32_16x16x32_f16 v[72:75], v[218:221], v[230:233], v[72:75]
	v_mfma_f32_16x16x32_f16 v[68:71], v[218:221], v[242:245], v[68:71]
	v_lshl_add_u64 v[222:223], v[222:223], 0, s[22:23]
	s_or_b32 m0, s100, 0x8000
	s_barrier
	ds_read_b128 v[190:193], v161 offset:49152
	ds_read_b128 v[194:197], v161 offset:50176
	ds_read_b128 v[198:201], v160 offset:49152
	ds_read_b128 v[202:205], v160 offset:50176
	ds_read_b128 v[206:209], v159 offset:49152
	ds_read_b128 v[210:213], v159 offset:50176
	ds_read_b128 v[214:217], v158 offset:49152
	ds_read_b128 v[218:221], v158 offset:50176
	global_load_lds_dwordx4 v[222:223], off
	s_or_b32 m0, s100, 0xa000
	v_lshl_add_u64 v[222:223], v[236:237], 0, s[22:23]
	global_load_lds_dwordx4 v[222:223], off
	s_barrier
	s_waitcnt lgkmcnt(0)
	v_mfma_f32_16x16x32_f16 v[64:67], v[190:193], v[174:177], v[64:67]
	v_mfma_f32_16x16x32_f16 v[60:63], v[190:193], v[182:185], v[60:63]
	v_mfma_f32_16x16x32_f16 v[56:59], v[198:201], v[174:177], v[56:59]
	v_mfma_f32_16x16x32_f16 v[52:55], v[198:201], v[182:185], v[52:55]
	v_mfma_f32_16x16x32_f16 v[48:51], v[206:209], v[174:177], v[48:51]
	v_mfma_f32_16x16x32_f16 v[44:47], v[206:209], v[182:185], v[44:47]
	v_mfma_f32_16x16x32_f16 v[40:43], v[214:217], v[174:177], v[40:43]
	v_mfma_f32_16x16x32_f16 v[36:39], v[214:217], v[182:185], v[36:39]
	v_mfma_f32_16x16x32_f16 v[64:67], v[194:197], v[178:181], v[64:67]
	v_mfma_f32_16x16x32_f16 v[60:63], v[194:197], v[186:189], v[60:63]
	v_mfma_f32_16x16x32_f16 v[56:59], v[202:205], v[178:181], v[56:59]
	v_mfma_f32_16x16x32_f16 v[52:55], v[202:205], v[186:189], v[52:55]
	v_mfma_f32_16x16x32_f16 v[48:51], v[210:213], v[178:181], v[48:51]
	v_mfma_f32_16x16x32_f16 v[44:47], v[210:213], v[186:189], v[44:47]
	v_mfma_f32_16x16x32_f16 v[40:43], v[218:221], v[178:181], v[40:43]
	v_mfma_f32_16x16x32_f16 v[36:39], v[218:221], v[186:189], v[36:39]
	s_barrier
	s_or_b32 m0, s100, 0x1c000
	v_lshl_add_u64 v[174:175], v[246:247], 0, s[44:45]
	global_load_lds_dwordx4 v[174:175], off
	s_or_b32 m0, s100, 0x1e000
	v_lshl_add_u64 v[174:175], v[248:249], 0, s[44:45]
	global_load_lds_dwordx4 v[174:175], off
	s_waitcnt vmcnt(6)
	s_barrier
	v_mfma_f32_16x16x32_f16 v[32:35], v[190:193], v[226:229], v[32:35]
	v_mfma_f32_16x16x32_f16 v[28:31], v[190:193], v[238:241], v[28:31]
	v_mfma_f32_16x16x32_f16 v[24:27], v[198:201], v[226:229], v[24:27]
	v_mfma_f32_16x16x32_f16 v[20:23], v[198:201], v[238:241], v[20:23]
	v_mfma_f32_16x16x32_f16 v[16:19], v[206:209], v[226:229], v[16:19]
	v_mfma_f32_16x16x32_f16 v[12:15], v[206:209], v[238:241], v[12:15]
	v_mfma_f32_16x16x32_f16 v[8:11], v[214:217], v[226:229], v[8:11]
	v_mfma_f32_16x16x32_f16 v[4:7], v[214:217], v[238:241], v[4:7]
	v_mfma_f32_16x16x32_f16 v[32:35], v[194:197], v[230:233], v[32:35]
	v_mfma_f32_16x16x32_f16 v[28:31], v[194:197], v[242:245], v[28:31]
	v_mfma_f32_16x16x32_f16 v[24:27], v[202:205], v[230:233], v[24:27]
	v_mfma_f32_16x16x32_f16 v[20:23], v[202:205], v[242:245], v[20:23]
	v_mfma_f32_16x16x32_f16 v[16:19], v[210:213], v[230:233], v[16:19]
	v_mfma_f32_16x16x32_f16 v[12:15], v[210:213], v[242:245], v[12:15]
	v_mfma_f32_16x16x32_f16 v[8:11], v[218:221], v[230:233], v[8:11]
	v_mfma_f32_16x16x32_f16 v[4:7], v[218:221], v[242:245], v[4:7]
	s_add_i32 s1, s1, 2
	s_add_u32 s12, s12, 0x100
	s_addc_u32 s13, s13, 0
	s_cmp_lt_u32 s1, 12
	s_cbranch_scc1 .LBB0_1259

; #define LDA8(dst, b, h) _Pragma("unroll") for (int m = 0; m < 4; ++m) _Pragma("unroll") for (int k = 0; k < 2; ++k) \
;     dst[m][k] = *(const bf16x8*)((const char*)SA8(b, h) + lds_byte8(wr * 64 + m * 16 + fr, k * 32 + fq * 8))
; #define LDB8(dst, b, h) _Pragma("unroll") for (int n = 0; n < 2; ++n) _Pragma("unroll") for (int k = 0; k < 2; ++k) \
;     dst[n][k] = *(const bf16x8*)((const char*)SB8(b, h) + lds_byte8(wc * 32 + n * 16 + fr, k * 32 + fq * 8))
; #define WAIT_V8(n) asm volatile("s_waitcnt vmcnt(" #n ")" ::: "memory")
; #define WAIT_L8(n) asm volatile("s_waitcnt lgkmcnt(" #n ")" ::: "memory")
; #define BAR8 __builtin_amdgcn_s_barrier()
; #define SCHED8 __builtin_amdgcn_sched_barrier(0)
;     ...
;   if (!pre) {
;     STAGE8(SB8(0, 0), Bt, K, bcol, 0); STAGE8(SA8(0, 0), A, lda, brow, 0);
;     STAGE8(SB8(0, 1), Bt, K, bcol + 128, 0); STAGE8(SA8(0, 1), A, lda, brow + 128, 0);
;   }
;   if (wr == 1) BAR8;
;   WAIT_V8(4); BAR8;
;   STAGE8(SB8(1, 0), Bt, K, bcol, 1); STAGE8(SA8(1, 0), A, lda, brow, 1); STAGE8(SB8(1, 1), Bt, K, bcol + 128, 1);
;   WAIT_V8(6); BAR8;
;   for (int tt = 0; tt < nt - 2; tt += 2) {
;     LDB8(B0, 0, 0); SCHED8; LDA8(At, 0, 0); STAGE8(SA8(1, 1), A, lda, brow + 128, tt + 1);
;     WAIT_L8(8); BAR8; WAIT_L8(0); MMA8(0, 0, At, B0); BAR8; SCHED8;
;     LDB8(B1, 0, 1); STAGE8(SB8(0, 0), Bt, K, bcol, tt + 2);
;     BAR8; WAIT_L8(0); MMA8(0, 1, At, B1); BAR8;
.LBB0_1324:
	s_or_b64 exec, exec, s[12:13]
	s_mov_b64 s[36:37], 0x80
	v_lshl_add_u64 v[10:11], v[10:11], 0, s[36:37]
	s_or_b32 m0, s100, 0x18000
	s_waitcnt vmcnt(4)
	s_barrier
	global_load_lds_dwordx4 v[10:11], off
	v_lshl_add_u64 v[10:11], v[12:13], 0, s[36:37]
	s_or_b32 m0, s100, 0x1a000
	global_load_lds_dwordx4 v[10:11], off
	v_lshl_add_u64 v[10:11], v[14:15], 0, s[36:37]
	s_or_b32 m0, s100, 0x8000
	global_load_lds_dwordx4 v[10:11], off
	v_lshl_add_u64 v[10:11], v[16:17], 0, s[36:37]
	s_or_b32 m0, s100, 0xa000
	global_load_lds_dwordx4 v[10:11], off
	s_or_b32 m0, s100, 0x1c000
	v_lshl_add_u64 v[10:11], v[18:19], 0, s[36:37]
	global_load_lds_dwordx4 v[10:11], off
	v_lshl_add_u64 v[10:11], v[20:21], 0, s[36:37]
	s_or_b32 m0, s100, 0x1e000
	v_and_b32_e32 v147, 15, v3
	global_load_lds_dwordx4 v[10:11], off
	v_bfe_u32 v148, v3, 4, 2
	v_lshlrev_b32_e32 v10, 4, v148
	v_lshlrev_b32_e32 v11, 6, v147
	v_lshlrev_b32_e32 v13, 2, v3
	v_or_b32_e32 v12, v10, v11
	v_and_b32_e32 v13, 32, v13
	s_mov_b32 s12, 0x10000
	v_bitop3_b32 v18, v12, s12, v13 bitop3:0xde
	s_mov_b32 s12, 0x14000
	v_bitop3_b32 v17, v10, v13, v11 bitop3:0x36
	v_bitop3_b32 v19, v12, s12, v13 bitop3:0xde
	s_mov_b32 s12, 0x18000
	v_lshlrev_b32_e32 v11, 6, v3
	v_bitop3_b32 v20, v12, s12, v13 bitop3:0xde
	s_mov_b32 s12, 0x1c000
	v_and_b32_e32 v11, 0x3c0, v11
	s_movk_i32 s31, 0x1600
	s_and_b32 s29, s21, 0xffffff00
	v_bitop3_b32 v21, v12, s12, v13 bitop3:0xde
	v_bitop3_b32 v24, v11, v13, v10 bitop3:0x36
	v_mad_i64_i32 v[10:11], s[12:13], v5, s31, 0
	v_mov_b32_e32 v5, 0x1600
	v_mad_i64_i32 v[12:13], s[12:13], s29, v5, v[10:11]
	v_lshl_add_u64 v[12:13], v[12:13], 0, v[6:7]
	v_lshl_add_u64 v[138:139], s[4:5], 0, v[12:13]
	v_mad_i64_i32 v[12:13], s[12:13], v22, s31, 0
	v_mad_i64_i32 v[14:15], s[12:13], s29, v5, v[12:13]
	s_bfe_u32 s29, s20, 0x60008
	v_mov_b32_e32 v5, 0x160000
	v_mad_u64_u32 v[10:11], s[12:13], s29, v5, v[10:11]
	v_lshl_add_u64 v[6:7], v[10:11], 0, v[6:7]
	v_bfe_u32 v146, v3, 6, 2
	s_waitcnt vmcnt(6)
	v_lshlrev_b32_e32 v149, 6, v23
	v_lshlrev_b32_e32 v23, 13, v23
	v_lshl_add_u64 v[142:143], s[2:3], 0, v[6:7]
	v_mad_u64_u32 v[6:7], s[12:13], s29, v5, v[12:13]
	v_lshlrev_b32_e32 v16, 12, v146
	v_or_b32_e32 v25, 0x800, v23
	v_or_b32_e32 v26, 0x1000, v23
	v_or_b32_e32 v27, 0x1800, v23
	v_lshl_add_u64 v[14:15], v[14:15], 0, v[8:9]
	v_lshl_add_u64 v[6:7], v[6:7], 0, v[8:9]
	s_ashr_i32 s9, s8, 31
	v_lshl_add_u64 v[140:141], s[4:5], 0, v[14:15]
	v_lshl_add_u64 v[144:145], s[2:3], 0, v[6:7]
	s_mov_b32 s29, -2
	s_mov_b64 s[12:13], 0
	v_add_u32_e32 v171, v18, v16
	v_add_u32_e32 v156, v17, v23
	v_add_u32_e32 v155, v24, v25
	v_add_u32_e32 v154, v24, v26
	v_add_u32_e32 v153, v24, v27
	v_add_u32_e32 v169, v19, v16
	v_add_u32_e32 v159, v20, v16
	v_add_u32_e32 v158, v21, v16
	s_mov_b64 s[36:37], 0x20b0080
	s_mov_b64 s[38:39], 0xd5a0100
	s_mov_b64 s[40:41], 0x2000100
	s_mov_b64 s[42:43], 0xd650100
	s_mov_b64 s[44:45], 0x20b0100
	s_mov_b64 s[46:47], 0xd5a0180
	s_mov_b64 s[48:49], 0x2000180
	s_mov_b64 s[50:51], 0xd650180
	s_barrier
	ds_read_b128 v[174:177], v171
	ds_read_b128 v[178:181], v171 offset:1024
	ds_read_b128 v[182:185], v171 offset:2048
	ds_read_b128 v[186:189], v171 offset:3072
	v_lshl_add_u64 v[222:223], v[142:143], 0, s[12:13]
	v_lshl_add_u64 v[226:227], v[222:223], 0, s[36:37]
	s_or_b32 m0, s100, 0xc000
	v_lshl_add_u64 v[236:237], v[144:145], 0, s[12:13]
	ds_read_b128 v[190:193], v156
	ds_read_b128 v[194:197], v156 offset:1024
	ds_read_b128 v[198:201], v155
	ds_read_b128 v[202:205], v155 offset:1024
	ds_read_b128 v[206:209], v154
	ds_read_b128 v[210:213], v154 offset:1024
	ds_read_b128 v[214:217], v153
	ds_read_b128 v[218:221], v153 offset:1024
	global_load_lds_dwordx4 v[226:227], off
	s_or_b32 m0, s100, 0xe000
	v_lshl_add_u64 v[226:227], v[236:237], 0, s[36:37]
	global_load_lds_dwordx4 v[226:227], off
	s_waitcnt lgkmcnt(8)
	s_barrier
	s_waitcnt lgkmcnt(0)
	v_mfma_f32_16x16x32_bf16 v[128:131], v[190:193], v[174:177], 0
	v_mfma_f32_16x16x32_bf16 v[124:127], v[190:193], v[182:185], 0
	v_mfma_f32_16x16x32_bf16 v[120:123], v[198:201], v[174:177], 0
	v_mfma_f32_16x16x32_bf16 v[116:119], v[198:201], v[182:185], 0
	v_mfma_f32_16x16x32_bf16 v[112:115], v[206:209], v[174:177], 0
	v_mfma_f32_16x16x32_bf16 v[108:111], v[206:209], v[182:185], 0
	v_mfma_f32_16x16x32_bf16 v[104:107], v[214:217], v[174:177], 0
	v_mfma_f32_16x16x32_bf16 v[100:103], v[214:217], v[182:185], 0
	v_mfma_f32_16x16x32_bf16 v[128:131], v[194:197], v[178:181], v[128:131]
	v_mfma_f32_16x16x32_bf16 v[124:127], v[194:197], v[186:189], v[124:127]
	v_mfma_f32_16x16x32_bf16 v[120:123], v[202:205], v[178:181], v[120:123]
	v_mfma_f32_16x16x32_bf16 v[116:119], v[202:205], v[186:189], v[116:119]
	v_mfma_f32_16x16x32_bf16 v[112:115], v[210:213], v[178:181], v[112:115]
	v_mfma_f32_16x16x32_bf16 v[108:111], v[210:213], v[186:189], v[108:111]
	v_mfma_f32_16x16x32_bf16 v[104:107], v[218:221], v[178:181], v[104:107]
	v_mfma_f32_16x16x32_bf16 v[100:103], v[218:221], v[186:189], v[100:103]
	s_barrier
	v_lshl_add_u64 v[246:247], v[138:139], 0, s[12:13]
	v_lshl_add_u64 v[248:249], v[246:247], 0, s[38:39]
	s_or_b32 m0, s100, 0x10000
	ds_read_b128 v[226:229], v169
	ds_read_b128 v[230:233], v169 offset:1024
	ds_read_b128 v[238:241], v169 offset:2048
	ds_read_b128 v[242:245], v169 offset:3072
	global_load_lds_dwordx4 v[248:249], off
	v_lshl_add_u64 v[248:249], v[140:141], 0, s[12:13]
	s_or_b32 m0, s100, 0x12000
	v_lshl_add_u64 v[250:251], v[248:249], 0, s[38:39]
	global_load_lds_dwordx4 v[250:251], off
	s_barrier
; #define LDA8(dst, b, h) _Pragma("unroll") for (int m = 0; m < 4; ++m) _Pragma("unroll") for (int k = 0; k < 2; ++k) \
;     dst[m][k] = *(const bf16x8*)((const char*)SA8(b, h) + lds_byte8(wr * 64 + m * 16 + fr, k * 32 + fq * 8))
; #define LDB8(dst, b, h) _Pragma("unroll") for (int n = 0; n < 2; ++n) _Pragma("unroll") for (int k = 0; k < 2; ++k) \
;     dst[n][k] = *(const bf16x8*)((const char*)SB8(b, h) + lds_byte8(wc * 32 + n * 16 + fr, k * 32 + fq * 8))
; #define WAIT_V8(n) asm volatile("s_waitcnt vmcnt(" #n ")" ::: "memory")
; #define WAIT_L8(n) asm volatile("s_waitcnt lgkmcnt(" #n ")" ::: "memory")
; #define BAR8 __builtin_amdgcn_s_barrier()
; #define SCHED8 __builtin_amdgcn_sched_barrier(0)
;     ...
;     BAR8; WAIT_L8(0); MMA8(0, 1, At, B1); BAR8;
;     LDA8(At, 0, 1); STAGE8(SA8(0, 0), A, lda, brow, tt + 2);
;     BAR8; WAIT_L8(0); MMA8(1, 0, At, B0); BAR8; SCHED8;
;     STAGE8(SB8(0, 1), Bt, K, bcol + 128, tt + 2);
;     WAIT_V8(6); BAR8; MMA8(1, 1, At, B1); BAR8;
;     LDB8(B0, 1, 0); SCHED8; LDA8(At, 1, 0); STAGE8(SA8(0, 1), A, lda, brow + 128, tt + 2);
;     WAIT_L8(8); BAR8; WAIT_L8(0); MMA8(0, 0, At, B0); BAR8; SCHED8;
;     LDB8(B1, 1, 1); STAGE8(SB8(1, 0), Bt, K, bcol, tt + 3);
;     BAR8; WAIT_L8(0); MMA8(0, 1, At, B1); BAR8;
;     LDA8(At, 1, 1); STAGE8(SA8(1, 0), A, lda, brow, tt + 3);
;     BAR8; WAIT_L8(0); MMA8(1, 0, At, B0); BAR8; SCHED8;
	s_waitcnt lgkmcnt(0)
	v_mfma_f32_16x16x32_bf16 v[96:99], v[190:193], v[226:229], 0
	v_mfma_f32_16x16x32_bf16 v[92:95], v[190:193], v[238:241], 0
	v_mfma_f32_16x16x32_bf16 v[88:91], v[198:201], v[226:229], 0
	v_mfma_f32_16x16x32_bf16 v[84:87], v[198:201], v[238:241], 0
	v_mfma_f32_16x16x32_bf16 v[80:83], v[206:209], v[226:229], 0
	v_mfma_f32_16x16x32_bf16 v[76:79], v[206:209], v[238:241], 0
	v_mfma_f32_16x16x32_bf16 v[72:75], v[214:217], v[226:229], 0
	v_mfma_f32_16x16x32_bf16 v[68:71], v[214:217], v[238:241], 0
	v_mfma_f32_16x16x32_bf16 v[96:99], v[194:197], v[230:233], v[96:99]
	v_mfma_f32_16x16x32_bf16 v[92:95], v[194:197], v[242:245], v[92:95]
	v_mfma_f32_16x16x32_bf16 v[88:91], v[202:205], v[230:233], v[88:91]
	v_mfma_f32_16x16x32_bf16 v[84:87], v[202:205], v[242:245], v[84:87]
	v_mfma_f32_16x16x32_bf16 v[80:83], v[210:213], v[230:233], v[80:83]
	v_mfma_f32_16x16x32_bf16 v[76:79], v[210:213], v[242:245], v[76:79]
	v_mfma_f32_16x16x32_bf16 v[72:75], v[218:221], v[230:233], v[72:75]
	v_mfma_f32_16x16x32_bf16 v[68:71], v[218:221], v[242:245], v[68:71]
	v_lshl_add_u64 v[250:251], v[222:223], 0, s[40:41]
	s_mov_b32 m0, s100
	s_barrier
	ds_read_b128 v[190:193], v156 offset:16384
	ds_read_b128 v[194:197], v156 offset:17408
	ds_read_b128 v[198:201], v155 offset:16384
	ds_read_b128 v[202:205], v155 offset:17408
	ds_read_b128 v[206:209], v154 offset:16384
	ds_read_b128 v[210:213], v154 offset:17408
	ds_read_b128 v[214:217], v153 offset:16384
	ds_read_b128 v[218:221], v153 offset:17408
	global_load_lds_dwordx4 v[250:251], off
	s_or_b32 m0, s100, 0x2000
	v_lshl_add_u64 v[250:251], v[236:237], 0, s[40:41]
	global_load_lds_dwordx4 v[250:251], off
	s_barrier
	s_waitcnt lgkmcnt(0)
	v_mfma_f32_16x16x32_bf16 v[64:67], v[190:193], v[174:177], 0
	v_mfma_f32_16x16x32_bf16 v[60:63], v[190:193], v[182:185], 0
	v_mfma_f32_16x16x32_bf16 v[56:59], v[198:201], v[174:177], 0
	v_mfma_f32_16x16x32_bf16 v[52:55], v[198:201], v[182:185], 0
	v_mfma_f32_16x16x32_bf16 v[48:51], v[206:209], v[174:177], 0
	v_mfma_f32_16x16x32_bf16 v[44:47], v[206:209], v[182:185], 0
	v_mfma_f32_16x16x32_bf16 v[40:43], v[214:217], v[174:177], 0
	v_mfma_f32_16x16x32_bf16 v[36:39], v[214:217], v[182:185], 0
	v_mfma_f32_16x16x32_bf16 v[64:67], v[194:197], v[178:181], v[64:67]
	v_mfma_f32_16x16x32_bf16 v[60:63], v[194:197], v[186:189], v[60:63]
	v_mfma_f32_16x16x32_bf16 v[56:59], v[202:205], v[178:181], v[56:59]
	v_mfma_f32_16x16x32_bf16 v[52:55], v[202:205], v[186:189], v[52:55]
	v_mfma_f32_16x16x32_bf16 v[48:51], v[210:213], v[178:181], v[48:51]
	v_mfma_f32_16x16x32_bf16 v[44:47], v[210:213], v[186:189], v[44:47]
	v_mfma_f32_16x16x32_bf16 v[40:43], v[218:221], v[178:181], v[40:43]
	v_mfma_f32_16x16x32_bf16 v[36:39], v[218:221], v[186:189], v[36:39]
	s_barrier
	s_or_b32 m0, s100, 0x14000
	v_lshl_add_u64 v[174:175], v[246:247], 0, s[42:43]
	global_load_lds_dwordx4 v[174:175], off
	s_or_b32 m0, s100, 0x16000
	v_lshl_add_u64 v[174:175], v[248:249], 0, s[42:43]
	global_load_lds_dwordx4 v[174:175], off
	s_waitcnt vmcnt(6)
	s_barrier
	v_mfma_f32_16x16x32_bf16 v[32:35], v[190:193], v[226:229], 0
	v_mfma_f32_16x16x32_bf16 v[28:31], v[190:193], v[238:241], 0
	v_mfma_f32_16x16x32_bf16 v[24:27], v[198:201], v[226:229], 0
	v_mfma_f32_16x16x32_bf16 v[20:23], v[198:201], v[238:241], 0
	v_mfma_f32_16x16x32_bf16 v[16:19], v[206:209], v[226:229], 0
	v_mfma_f32_16x16x32_bf16 v[12:15], v[206:209], v[238:241], 0
	v_mfma_f32_16x16x32_bf16 v[8:11], v[214:217], v[226:229], 0
	v_mfma_f32_16x16x32_bf16 v[4:7], v[214:217], v[238:241], 0
	v_mfma_f32_16x16x32_bf16 v[32:35], v[194:197], v[230:233], v[32:35]
	v_mfma_f32_16x16x32_bf16 v[28:31], v[194:197], v[242:245], v[28:31]
	v_mfma_f32_16x16x32_bf16 v[24:27], v[202:205], v[230:233], v[24:27]
	v_mfma_f32_16x16x32_bf16 v[20:23], v[202:205], v[242:245], v[20:23]
	v_mfma_f32_16x16x32_bf16 v[16:19], v[210:213], v[230:233], v[16:19]
	v_mfma_f32_16x16x32_bf16 v[12:15], v[210:213], v[242:245], v[12:15]
	v_mfma_f32_16x16x32_bf16 v[8:11], v[218:221], v[230:233], v[8:11]
	v_mfma_f32_16x16x32_bf16 v[4:7], v[218:221], v[242:245], v[4:7]
	s_barrier
	ds_read_b128 v[174:177], v159
	ds_read_b128 v[178:181], v159 offset:1024
	ds_read_b128 v[182:185], v159 offset:2048
	ds_read_b128 v[186:189], v159 offset:3072
	v_lshl_add_u64 v[226:227], v[222:223], 0, s[44:45]
	s_or_b32 m0, s100, 0x4000
	ds_read_b128 v[190:193], v156 offset:32768
	ds_read_b128 v[194:197], v156 offset:33792
	ds_read_b128 v[198:201], v155 offset:32768
	ds_read_b128 v[202:205], v155 offset:33792
	ds_read_b128 v[206:209], v154 offset:32768
	ds_read_b128 v[210:213], v154 offset:33792
	ds_read_b128 v[214:217], v153 offset:32768
	ds_read_b128 v[218:221], v153 offset:33792
	global_load_lds_dwordx4 v[226:227], off
	s_or_b32 m0, s100, 0x6000
	v_lshl_add_u64 v[226:227], v[236:237], 0, s[44:45]
	global_load_lds_dwordx4 v[226:227], off
	s_waitcnt lgkmcnt(8)
	s_barrier
	s_waitcnt lgkmcnt(0)
	v_mfma_f32_16x16x32_bf16 v[128:131], v[190:193], v[174:177], v[128:131]
	v_mfma_f32_16x16x32_bf16 v[124:127], v[190:193], v[182:185], v[124:127]
	v_mfma_f32_16x16x32_bf16 v[120:123], v[198:201], v[174:177], v[120:123]
	v_mfma_f32_16x16x32_bf16 v[116:119], v[198:201], v[182:185], v[116:119]
	v_mfma_f32_16x16x32_bf16 v[112:115], v[206:209], v[174:177], v[112:115]
	v_mfma_f32_16x16x32_bf16 v[108:111], v[206:209], v[182:185], v[108:111]
	v_mfma_f32_16x16x32_bf16 v[104:107], v[214:217], v[174:177], v[104:107]
	v_mfma_f32_16x16x32_bf16 v[100:103], v[214:217], v[182:185], v[100:103]
	v_mfma_f32_16x16x32_bf16 v[128:131], v[194:197], v[178:181], v[128:131]
	v_mfma_f32_16x16x32_bf16 v[124:127], v[194:197], v[186:189], v[124:127]
	v_mfma_f32_16x16x32_bf16 v[120:123], v[202:205], v[178:181], v[120:123]
	v_mfma_f32_16x16x32_bf16 v[116:119], v[202:205], v[186:189], v[116:119]
	v_mfma_f32_16x16x32_bf16 v[112:115], v[210:213], v[178:181], v[112:115]
	v_mfma_f32_16x16x32_bf16 v[108:111], v[210:213], v[186:189], v[108:111]
	v_mfma_f32_16x16x32_bf16 v[104:107], v[218:221], v[178:181], v[104:107]
	v_mfma_f32_16x16x32_bf16 v[100:103], v[218:221], v[186:189], v[100:103]
	s_barrier
; #define LDA8(dst, b, h) _Pragma("unroll") for (int m = 0; m < 4; ++m) _Pragma("unroll") for (int k = 0; k < 2; ++k) \
;     dst[m][k] = *(const bf16x8*)((const char*)SA8(b, h) + lds_byte8(wr * 64 + m * 16 + fr, k * 32 + fq * 8))
; #define LDB8(dst, b, h) _Pragma("unroll") for (int n = 0; n < 2; ++n) _Pragma("unroll") for (int k = 0; k < 2; ++k) \
;     dst[n][k] = *(const bf16x8*)((const char*)SB8(b, h) + lds_byte8(wc * 32 + n * 16 + fr, k * 32 + fq * 8))
; #define WAIT_V8(n) asm volatile("s_waitcnt vmcnt(" #n ")" ::: "memory")
; #define WAIT_L8(n) asm volatile("s_waitcnt lgkmcnt(" #n ")" ::: "memory")
; #define BAR8 __builtin_amdgcn_s_barrier()
; #define SCHED8 __builtin_amdgcn_sched_barrier(0)
;     ...
;     WAIT_L8(8); BAR8; WAIT_L8(0); MMA8(0, 0, At, B0); BAR8; SCHED8;
;     LDB8(B1, 1, 1); STAGE8(SB8(1, 0), Bt, K, bcol, tt + 3);
;     BAR8; WAIT_L8(0); MMA8(0, 1, At, B1); BAR8;
;     LDA8(At, 1, 1); STAGE8(SA8(1, 0), A, lda, brow, tt + 3);
;     BAR8; WAIT_L8(0); MMA8(1, 0, At, B0); BAR8; SCHED8;
;     STAGE8(SB8(1, 1), Bt, K, bcol + 128, tt + 3);
;     WAIT_V8(6); BAR8; MMA8(1, 1, At, B1); BAR8;
;   }
	v_lshl_add_u64 v[250:251], v[246:247], 0, s[46:47]
	s_or_b32 m0, s100, 0x18000
	ds_read_b128 v[226:229], v158
	ds_read_b128 v[230:233], v158 offset:1024
	ds_read_b128 v[238:241], v158 offset:2048
	ds_read_b128 v[242:245], v158 offset:3072
	global_load_lds_dwordx4 v[250:251], off
	s_or_b32 m0, s100, 0x1a000
	v_lshl_add_u64 v[250:251], v[248:249], 0, s[46:47]
	global_load_lds_dwordx4 v[250:251], off
	s_barrier
	s_waitcnt lgkmcnt(0)
	v_mfma_f32_16x16x32_bf16 v[96:99], v[190:193], v[226:229], v[96:99]
	v_mfma_f32_16x16x32_bf16 v[92:95], v[190:193], v[238:241], v[92:95]
	v_mfma_f32_16x16x32_bf16 v[88:91], v[198:201], v[226:229], v[88:91]
	v_mfma_f32_16x16x32_bf16 v[84:87], v[198:201], v[238:241], v[84:87]
	v_mfma_f32_16x16x32_bf16 v[80:83], v[206:209], v[226:229], v[80:83]
	v_mfma_f32_16x16x32_bf16 v[76:79], v[206:209], v[238:241], v[76:79]
	v_mfma_f32_16x16x32_bf16 v[72:75], v[214:217], v[226:229], v[72:75]
	v_mfma_f32_16x16x32_bf16 v[68:71], v[214:217], v[238:241], v[68:71]
	v_mfma_f32_16x16x32_bf16 v[96:99], v[194:197], v[230:233], v[96:99]
	v_mfma_f32_16x16x32_bf16 v[92:95], v[194:197], v[242:245], v[92:95]
	v_mfma_f32_16x16x32_bf16 v[88:91], v[202:205], v[230:233], v[88:91]
	v_mfma_f32_16x16x32_bf16 v[84:87], v[202:205], v[242:245], v[84:87]
	v_mfma_f32_16x16x32_bf16 v[80:83], v[210:213], v[230:233], v[80:83]
	v_mfma_f32_16x16x32_bf16 v[76:79], v[210:213], v[242:245], v[76:79]
	v_mfma_f32_16x16x32_bf16 v[72:75], v[218:221], v[230:233], v[72:75]
	v_mfma_f32_16x16x32_bf16 v[68:71], v[218:221], v[242:245], v[68:71]
	v_lshl_add_u64 v[222:223], v[222:223], 0, s[48:49]
	s_or_b32 m0, s100, 0x8000
	s_barrier
	ds_read_b128 v[190:193], v156 offset:49152
	ds_read_b128 v[194:197], v156 offset:50176
	ds_read_b128 v[198:201], v155 offset:49152
	ds_read_b128 v[202:205], v155 offset:50176
	ds_read_b128 v[206:209], v154 offset:49152
	ds_read_b128 v[210:213], v154 offset:50176
	ds_read_b128 v[214:217], v153 offset:49152
	ds_read_b128 v[218:221], v153 offset:50176
	global_load_lds_dwordx4 v[222:223], off
	s_or_b32 m0, s100, 0xa000
	v_lshl_add_u64 v[222:223], v[236:237], 0, s[48:49]
	global_load_lds_dwordx4 v[222:223], off
	s_barrier
	s_waitcnt lgkmcnt(0)
	v_mfma_f32_16x16x32_bf16 v[64:67], v[190:193], v[174:177], v[64:67]
	v_mfma_f32_16x16x32_bf16 v[60:63], v[190:193], v[182:185], v[60:63]
	v_mfma_f32_16x16x32_bf16 v[56:59], v[198:201], v[174:177], v[56:59]
	v_mfma_f32_16x16x32_bf16 v[52:55], v[198:201], v[182:185], v[52:55]
	v_mfma_f32_16x16x32_bf16 v[48:51], v[206:209], v[174:177], v[48:51]
	v_mfma_f32_16x16x32_bf16 v[44:47], v[206:209], v[182:185], v[44:47]
	v_mfma_f32_16x16x32_bf16 v[40:43], v[214:217], v[174:177], v[40:43]
	v_mfma_f32_16x16x32_bf16 v[36:39], v[214:217], v[182:185], v[36:39]
	v_mfma_f32_16x16x32_bf16 v[64:67], v[194:197], v[178:181], v[64:67]
	v_mfma_f32_16x16x32_bf16 v[60:63], v[194:197], v[186:189], v[60:63]
	v_mfma_f32_16x16x32_bf16 v[56:59], v[202:205], v[178:181], v[56:59]
	v_mfma_f32_16x16x32_bf16 v[52:55], v[202:205], v[186:189], v[52:55]
	v_mfma_f32_16x16x32_bf16 v[48:51], v[210:213], v[178:181], v[48:51]
	v_mfma_f32_16x16x32_bf16 v[44:47], v[210:213], v[186:189], v[44:47]
	v_mfma_f32_16x16x32_bf16 v[40:43], v[218:221], v[178:181], v[40:43]
	v_mfma_f32_16x16x32_bf16 v[36:39], v[218:221], v[186:189], v[36:39]
	s_barrier
	s_or_b32 m0, s100, 0x1c000
	v_lshl_add_u64 v[174:175], v[246:247], 0, s[50:51]
	global_load_lds_dwordx4 v[174:175], off
	s_or_b32 m0, s100, 0x1e000
	v_lshl_add_u64 v[174:175], v[248:249], 0, s[50:51]
	global_load_lds_dwordx4 v[174:175], off
	s_waitcnt vmcnt(6)
	s_barrier
	v_mfma_f32_16x16x32_bf16 v[32:35], v[190:193], v[226:229], v[32:35]
	v_mfma_f32_16x16x32_bf16 v[28:31], v[190:193], v[238:241], v[28:31]
	v_mfma_f32_16x16x32_bf16 v[24:27], v[198:201], v[226:229], v[24:27]
	v_mfma_f32_16x16x32_bf16 v[20:23], v[198:201], v[238:241], v[20:23]
	v_mfma_f32_16x16x32_bf16 v[16:19], v[206:209], v[226:229], v[16:19]
	v_mfma_f32_16x16x32_bf16 v[12:15], v[206:209], v[238:241], v[12:15]
	v_mfma_f32_16x16x32_bf16 v[8:11], v[214:217], v[226:229], v[8:11]
	v_mfma_f32_16x16x32_bf16 v[4:7], v[214:217], v[238:241], v[4:7]
	v_mfma_f32_16x16x32_bf16 v[32:35], v[194:197], v[230:233], v[32:35]
	v_mfma_f32_16x16x32_bf16 v[28:31], v[194:197], v[242:245], v[28:31]
	v_mfma_f32_16x16x32_bf16 v[24:27], v[202:205], v[230:233], v[24:27]
	v_mfma_f32_16x16x32_bf16 v[20:23], v[202:205], v[242:245], v[20:23]
	v_mfma_f32_16x16x32_bf16 v[16:19], v[210:213], v[230:233], v[16:19]
	v_mfma_f32_16x16x32_bf16 v[12:15], v[210:213], v[242:245], v[12:15]
	v_mfma_f32_16x16x32_bf16 v[8:11], v[218:221], v[230:233], v[8:11]
	v_mfma_f32_16x16x32_bf16 v[4:7], v[218:221], v[242:245], v[4:7]
	s_add_i32 s29, s29, 2
	s_add_u32 s12, s12, 0x100
	s_addc_u32 s13, s13, 0
	s_cmp_lt_u32 s29, 40
	s_cbranch_scc0 .Lpk_exitb_7
; #define LDA8(dst, b, h) _Pragma("unroll") for (int m = 0; m < 4; ++m) _Pragma("unroll") for (int k = 0; k < 2; ++k) \
;     dst[m][k] = *(const bf16x8*)((const char*)SA8(b, h) + lds_byte8(wr * 64 + m * 16 + fr, k * 32 + fq * 8))
; #define LDB8(dst, b, h) _Pragma("unroll") for (int n = 0; n < 2; ++n) _Pragma("unroll") for (int k = 0; k < 2; ++k) \
;     dst[n][k] = *(const bf16x8*)((const char*)SB8(b, h) + lds_byte8(wc * 32 + n * 16 + fr, k * 32 + fq * 8))
; #define WAIT_V8(n) asm volatile("s_waitcnt vmcnt(" #n ")" ::: "memory")
; #define WAIT_L8(n) asm volatile("s_waitcnt lgkmcnt(" #n ")" ::: "memory")
; #define BAR8 __builtin_amdgcn_s_barrier()
; #define SCHED8 __builtin_amdgcn_sched_barrier(0)
;     ...
;   for (int tt = 0; tt < nt - 2; tt += 2) {
;     LDB8(B0, 0, 0); SCHED8; LDA8(At, 0, 0); STAGE8(SA8(1, 1), A, lda, brow + 128, tt + 1);
;     WAIT_L8(8); BAR8; WAIT_L8(0); MMA8(0, 0, At, B0); BAR8; SCHED8;
;     LDB8(B1, 0, 1); STAGE8(SB8(0, 0), Bt, K, bcol, tt + 2);
;     BAR8; WAIT_L8(0); MMA8(0, 1, At, B1); BAR8;
;     LDA8(At, 0, 1); STAGE8(SA8(0, 0), A, lda, brow, tt + 2);
;     BAR8; WAIT_L8(0); MMA8(1, 0, At, B0); BAR8; SCHED8;
;     STAGE8(SB8(0, 1), Bt, K, bcol + 128, tt + 2);
;     WAIT_V8(6); BAR8; MMA8(1, 1, At, B1); BAR8;
;     LDB8(B0, 1, 0); SCHED8; LDA8(At, 1, 0); STAGE8(SA8(0, 1), A, lda, brow + 128, tt + 2);
;     WAIT_L8(8); BAR8; WAIT_L8(0); MMA8(0, 0, At, B0); BAR8; SCHED8;
.LBB0_1325:
	s_barrier
	ds_read_b128 v[174:177], v171
	ds_read_b128 v[178:181], v171 offset:1024
	ds_read_b128 v[182:185], v171 offset:2048
	ds_read_b128 v[186:189], v171 offset:3072
	v_lshl_add_u64 v[222:223], v[142:143], 0, s[12:13]
	v_lshl_add_u64 v[226:227], v[222:223], 0, s[36:37]
	s_or_b32 m0, s100, 0xc000
	v_lshl_add_u64 v[236:237], v[144:145], 0, s[12:13]
	ds_read_b128 v[190:193], v156
	ds_read_b128 v[194:197], v156 offset:1024
	ds_read_b128 v[198:201], v155
	ds_read_b128 v[202:205], v155 offset:1024
	ds_read_b128 v[206:209], v154
	ds_read_b128 v[210:213], v154 offset:1024
	ds_read_b128 v[214:217], v153
	ds_read_b128 v[218:221], v153 offset:1024
	global_load_lds_dwordx4 v[226:227], off
	s_or_b32 m0, s100, 0xe000
	v_lshl_add_u64 v[226:227], v[236:237], 0, s[36:37]
	global_load_lds_dwordx4 v[226:227], off
	s_waitcnt lgkmcnt(8)
	s_barrier
	s_waitcnt lgkmcnt(0)
	v_mfma_f32_16x16x32_bf16 v[128:131], v[190:193], v[174:177], v[128:131]
	v_mfma_f32_16x16x32_bf16 v[124:127], v[190:193], v[182:185], v[124:127]
	v_mfma_f32_16x16x32_bf16 v[120:123], v[198:201], v[174:177], v[120:123]
	v_mfma_f32_16x16x32_bf16 v[116:119], v[198:201], v[182:185], v[116:119]
	v_mfma_f32_16x16x32_bf16 v[112:115], v[206:209], v[174:177], v[112:115]
	v_mfma_f32_16x16x32_bf16 v[108:111], v[206:209], v[182:185], v[108:111]
	v_mfma_f32_16x16x32_bf16 v[104:107], v[214:217], v[174:177], v[104:107]
	v_mfma_f32_16x16x32_bf16 v[100:103], v[214:217], v[182:185], v[100:103]
	v_mfma_f32_16x16x32_bf16 v[128:131], v[194:197], v[178:181], v[128:131]
	v_mfma_f32_16x16x32_bf16 v[124:127], v[194:197], v[186:189], v[124:127]
	v_mfma_f32_16x16x32_bf16 v[120:123], v[202:205], v[178:181], v[120:123]
	v_mfma_f32_16x16x32_bf16 v[116:119], v[202:205], v[186:189], v[116:119]
	v_mfma_f32_16x16x32_bf16 v[112:115], v[210:213], v[178:181], v[112:115]
	v_mfma_f32_16x16x32_bf16 v[108:111], v[210:213], v[186:189], v[108:111]
	v_mfma_f32_16x16x32_bf16 v[104:107], v[218:221], v[178:181], v[104:107]
	v_mfma_f32_16x16x32_bf16 v[100:103], v[218:221], v[186:189], v[100:103]
	s_barrier
	v_lshl_add_u64 v[246:247], v[138:139], 0, s[12:13]
	v_lshl_add_u64 v[248:249], v[246:247], 0, s[38:39]
	s_or_b32 m0, s100, 0x10000
	ds_read_b128 v[226:229], v169
	ds_read_b128 v[230:233], v169 offset:1024
	ds_read_b128 v[238:241], v169 offset:2048
	ds_read_b128 v[242:245], v169 offset:3072
	global_load_lds_dwordx4 v[248:249], off
	v_lshl_add_u64 v[248:249], v[140:141], 0, s[12:13]
	s_or_b32 m0, s100, 0x12000
	v_lshl_add_u64 v[250:251], v[248:249], 0, s[38:39]
	global_load_lds_dwordx4 v[250:251], off
	s_barrier
	s_waitcnt lgkmcnt(0)
	v_mfma_f32_16x16x32_bf16 v[96:99], v[190:193], v[226:229], v[96:99]
	v_mfma_f32_16x16x32_bf16 v[92:95], v[190:193], v[238:241], v[92:95]
	v_mfma_f32_16x16x32_bf16 v[88:91], v[198:201], v[226:229], v[88:91]
	v_mfma_f32_16x16x32_bf16 v[84:87], v[198:201], v[238:241], v[84:87]
	v_mfma_f32_16x16x32_bf16 v[80:83], v[206:209], v[226:229], v[80:83]
	v_mfma_f32_16x16x32_bf16 v[76:79], v[206:209], v[238:241], v[76:79]
	v_mfma_f32_16x16x32_bf16 v[72:75], v[214:217], v[226:229], v[72:75]
	v_mfma_f32_16x16x32_bf16 v[68:71], v[214:217], v[238:241], v[68:71]
	v_mfma_f32_16x16x32_bf16 v[96:99], v[194:197], v[230:233], v[96:99]
	v_mfma_f32_16x16x32_bf16 v[92:95], v[194:197], v[242:245], v[92:95]
	v_mfma_f32_16x16x32_bf16 v[88:91], v[202:205], v[230:233], v[88:91]
	v_mfma_f32_16x16x32_bf16 v[84:87], v[202:205], v[242:245], v[84:87]
	v_mfma_f32_16x16x32_bf16 v[80:83], v[210:213], v[230:233], v[80:83]
	v_mfma_f32_16x16x32_bf16 v[76:79], v[210:213], v[242:245], v[76:79]
	v_mfma_f32_16x16x32_bf16 v[72:75], v[218:221], v[230:233], v[72:75]
	v_mfma_f32_16x16x32_bf16 v[68:71], v[218:221], v[242:245], v[68:71]
	v_lshl_add_u64 v[250:251], v[222:223], 0, s[40:41]
	s_mov_b32 m0, s100
	s_barrier
	ds_read_b128 v[190:193], v156 offset:16384
	ds_read_b128 v[194:197], v156 offset:17408
	ds_read_b128 v[198:201], v155 offset:16384
	ds_read_b128 v[202:205], v155 offset:17408
	ds_read_b128 v[206:209], v154 offset:16384
	ds_read_b128 v[210:213], v154 offset:17408
	ds_read_b128 v[214:217], v153 offset:16384
	ds_read_b128 v[218:221], v153 offset:17408
	global_load_lds_dwordx4 v[250:251], off
	s_or_b32 m0, s100, 0x2000
	v_lshl_add_u64 v[250:251], v[236:237], 0, s[40:41]
	global_load_lds_dwordx4 v[250:251], off
	s_barrier
	s_waitcnt lgkmcnt(0)
	v_mfma_f32_16x16x32_bf16 v[64:67], v[190:193], v[174:177], v[64:67]
	v_mfma_f32_16x16x32_bf16 v[60:63], v[190:193], v[182:185], v[60:63]
	v_mfma_f32_16x16x32_bf16 v[56:59], v[198:201], v[174:177], v[56:59]
	v_mfma_f32_16x16x32_bf16 v[52:55], v[198:201], v[182:185], v[52:55]
	v_mfma_f32_16x16x32_bf16 v[48:51], v[206:209], v[174:177], v[48:51]
	v_mfma_f32_16x16x32_bf16 v[44:47], v[206:209], v[182:185], v[44:47]
	v_mfma_f32_16x16x32_bf16 v[40:43], v[214:217], v[174:177], v[40:43]
	v_mfma_f32_16x16x32_bf16 v[36:39], v[214:217], v[182:185], v[36:39]
	v_mfma_f32_16x16x32_bf16 v[64:67], v[194:197], v[178:181], v[64:67]
	v_mfma_f32_16x16x32_bf16 v[60:63], v[194:197], v[186:189], v[60:63]
	v_mfma_f32_16x16x32_bf16 v[56:59], v[202:205], v[178:181], v[56:59]
	v_mfma_f32_16x16x32_bf16 v[52:55], v[202:205], v[186:189], v[52:55]
	v_mfma_f32_16x16x32_bf16 v[48:51], v[210:213], v[178:181], v[48:51]
	v_mfma_f32_16x16x32_bf16 v[44:47], v[210:213], v[186:189], v[44:47]
	v_mfma_f32_16x16x32_bf16 v[40:43], v[218:221], v[178:181], v[40:43]
	v_mfma_f32_16x16x32_bf16 v[36:39], v[218:221], v[186:189], v[36:39]
	s_barrier
	s_or_b32 m0, s100, 0x14000
	v_lshl_add_u64 v[174:175], v[246:247], 0, s[42:43]
	global_load_lds_dwordx4 v[174:175], off
	s_or_b32 m0, s100, 0x16000
	v_lshl_add_u64 v[174:175], v[248:249], 0, s[42:43]
	global_load_lds_dwordx4 v[174:175], off
	s_waitcnt vmcnt(6)
	s_barrier
; #define LDA8(dst, b, h) _Pragma("unroll") for (int m = 0; m < 4; ++m) _Pragma("unroll") for (int k = 0; k < 2; ++k) \
;     dst[m][k] = *(const bf16x8*)((const char*)SA8(b, h) + lds_byte8(wr * 64 + m * 16 + fr, k * 32 + fq * 8))
; #define LDB8(dst, b, h) _Pragma("unroll") for (int n = 0; n < 2; ++n) _Pragma("unroll") for (int k = 0; k < 2; ++k) \
;     dst[n][k] = *(const bf16x8*)((const char*)SB8(b, h) + lds_byte8(wc * 32 + n * 16 + fr, k * 32 + fq * 8))
; #define WAIT_V8(n) asm volatile("s_waitcnt vmcnt(" #n ")" ::: "memory")
; #define WAIT_L8(n) asm volatile("s_waitcnt lgkmcnt(" #n ")" ::: "memory")
; #define BAR8 __builtin_amdgcn_s_barrier()
; #define SCHED8 __builtin_amdgcn_sched_barrier(0)
;     ...
;     WAIT_V8(6); BAR8; MMA8(1, 1, At, B1); BAR8;
;     LDB8(B0, 1, 0); SCHED8; LDA8(At, 1, 0); STAGE8(SA8(0, 1), A, lda, brow + 128, tt + 2);
;     WAIT_L8(8); BAR8; WAIT_L8(0); MMA8(0, 0, At, B0); BAR8; SCHED8;
;     LDB8(B1, 1, 1); STAGE8(SB8(1, 0), Bt, K, bcol, tt + 3);
;     BAR8; WAIT_L8(0); MMA8(0, 1, At, B1); BAR8;
;     LDA8(At, 1, 1); STAGE8(SA8(1, 0), A, lda, brow, tt + 3);
;     BAR8; WAIT_L8(0); MMA8(1, 0, At, B0); BAR8; SCHED8;
	v_mfma_f32_16x16x32_bf16 v[32:35], v[190:193], v[226:229], v[32:35]
	v_mfma_f32_16x16x32_bf16 v[28:31], v[190:193], v[238:241], v[28:31]
	v_mfma_f32_16x16x32_bf16 v[24:27], v[198:201], v[226:229], v[24:27]
	v_mfma_f32_16x16x32_bf16 v[20:23], v[198:201], v[238:241], v[20:23]
	v_mfma_f32_16x16x32_bf16 v[16:19], v[206:209], v[226:229], v[16:19]
	v_mfma_f32_16x16x32_bf16 v[12:15], v[206:209], v[238:241], v[12:15]
	v_mfma_f32_16x16x32_bf16 v[8:11], v[214:217], v[226:229], v[8:11]
	v_mfma_f32_16x16x32_bf16 v[4:7], v[214:217], v[238:241], v[4:7]
	v_mfma_f32_16x16x32_bf16 v[32:35], v[194:197], v[230:233], v[32:35]
	v_mfma_f32_16x16x32_bf16 v[28:31], v[194:197], v[242:245], v[28:31]
	v_mfma_f32_16x16x32_bf16 v[24:27], v[202:205], v[230:233], v[24:27]
	v_mfma_f32_16x16x32_bf16 v[20:23], v[202:205], v[242:245], v[20:23]
	v_mfma_f32_16x16x32_bf16 v[16:19], v[210:213], v[230:233], v[16:19]
	v_mfma_f32_16x16x32_bf16 v[12:15], v[210:213], v[242:245], v[12:15]
	v_mfma_f32_16x16x32_bf16 v[8:11], v[218:221], v[230:233], v[8:11]
	v_mfma_f32_16x16x32_bf16 v[4:7], v[218:221], v[242:245], v[4:7]
	s_barrier
	ds_read_b128 v[174:177], v159
	ds_read_b128 v[178:181], v159 offset:1024
	ds_read_b128 v[182:185], v159 offset:2048
	ds_read_b128 v[186:189], v159 offset:3072
	v_lshl_add_u64 v[226:227], v[222:223], 0, s[44:45]
	s_or_b32 m0, s100, 0x4000
	ds_read_b128 v[190:193], v156 offset:32768
	ds_read_b128 v[194:197], v156 offset:33792
	ds_read_b128 v[198:201], v155 offset:32768
	ds_read_b128 v[202:205], v155 offset:33792
	ds_read_b128 v[206:209], v154 offset:32768
	ds_read_b128 v[210:213], v154 offset:33792
	ds_read_b128 v[214:217], v153 offset:32768
	ds_read_b128 v[218:221], v153 offset:33792
	global_load_lds_dwordx4 v[226:227], off
	s_or_b32 m0, s100, 0x6000
	v_lshl_add_u64 v[226:227], v[236:237], 0, s[44:45]
	global_load_lds_dwordx4 v[226:227], off
	s_waitcnt lgkmcnt(8)
	s_barrier
	s_waitcnt lgkmcnt(0)
	v_mfma_f32_16x16x32_bf16 v[128:131], v[190:193], v[174:177], v[128:131]
	v_mfma_f32_16x16x32_bf16 v[124:127], v[190:193], v[182:185], v[124:127]
	v_mfma_f32_16x16x32_bf16 v[120:123], v[198:201], v[174:177], v[120:123]
	v_mfma_f32_16x16x32_bf16 v[116:119], v[198:201], v[182:185], v[116:119]
	v_mfma_f32_16x16x32_bf16 v[112:115], v[206:209], v[174:177], v[112:115]
	v_mfma_f32_16x16x32_bf16 v[108:111], v[206:209], v[182:185], v[108:111]
	v_mfma_f32_16x16x32_bf16 v[104:107], v[214:217], v[174:177], v[104:107]
	v_mfma_f32_16x16x32_bf16 v[100:103], v[214:217], v[182:185], v[100:103]
	v_mfma_f32_16x16x32_bf16 v[128:131], v[194:197], v[178:181], v[128:131]
	v_mfma_f32_16x16x32_bf16 v[124:127], v[194:197], v[186:189], v[124:127]
	v_mfma_f32_16x16x32_bf16 v[120:123], v[202:205], v[178:181], v[120:123]
	v_mfma_f32_16x16x32_bf16 v[116:119], v[202:205], v[186:189], v[116:119]
	v_mfma_f32_16x16x32_bf16 v[112:115], v[210:213], v[178:181], v[112:115]
	v_mfma_f32_16x16x32_bf16 v[108:111], v[210:213], v[186:189], v[108:111]
	v_mfma_f32_16x16x32_bf16 v[104:107], v[218:221], v[178:181], v[104:107]
	v_mfma_f32_16x16x32_bf16 v[100:103], v[218:221], v[186:189], v[100:103]
	s_barrier
	v_lshl_add_u64 v[250:251], v[246:247], 0, s[46:47]
	s_or_b32 m0, s100, 0x18000
	ds_read_b128 v[226:229], v158
	ds_read_b128 v[230:233], v158 offset:1024
	ds_read_b128 v[238:241], v158 offset:2048
	ds_read_b128 v[242:245], v158 offset:3072
	global_load_lds_dwordx4 v[250:251], off
	s_or_b32 m0, s100, 0x1a000
	v_lshl_add_u64 v[250:251], v[248:249], 0, s[46:47]
	global_load_lds_dwordx4 v[250:251], off
	s_barrier
; #define LDA8(dst, b, h) _Pragma("unroll") for (int m = 0; m < 4; ++m) _Pragma("unroll") for (int k = 0; k < 2; ++k) \
;     dst[m][k] = *(const bf16x8*)((const char*)SA8(b, h) + lds_byte8(wr * 64 + m * 16 + fr, k * 32 + fq * 8))
; #define LDB8(dst, b, h) _Pragma("unroll") for (int n = 0; n < 2; ++n) _Pragma("unroll") for (int k = 0; k < 2; ++k) \
;     dst[n][k] = *(const bf16x8*)((const char*)SB8(b, h) + lds_byte8(wc * 32 + n * 16 + fr, k * 32 + fq * 8))
; #define WAIT_V8(n) asm volatile("s_waitcnt vmcnt(" #n ")" ::: "memory")
; #define WAIT_L8(n) asm volatile("s_waitcnt lgkmcnt(" #n ")" ::: "memory")
; #define BAR8 __builtin_amdgcn_s_barrier()
; #define SCHED8 __builtin_amdgcn_sched_barrier(0)
;     ...
;     WAIT_L8(8); BAR8; WAIT_L8(0); MMA8(0, 0, At, B0); BAR8; SCHED8;
;     LDB8(B1, 1, 1); STAGE8(SB8(1, 0), Bt, K, bcol, tt + 3);
;     BAR8; WAIT_L8(0); MMA8(0, 1, At, B1); BAR8;
;     LDA8(At, 1, 1); STAGE8(SA8(1, 0), A, lda, brow, tt + 3);
;     BAR8; WAIT_L8(0); MMA8(1, 0, At, B0); BAR8; SCHED8;
;     STAGE8(SB8(1, 1), Bt, K, bcol + 128, tt + 3);
;     WAIT_V8(6); BAR8; MMA8(1, 1, At, B1); BAR8;
;   }
	s_waitcnt lgkmcnt(0)
	v_mfma_f32_16x16x32_bf16 v[96:99], v[190:193], v[226:229], v[96:99]
	v_mfma_f32_16x16x32_bf16 v[92:95], v[190:193], v[238:241], v[92:95]
	v_mfma_f32_16x16x32_bf16 v[88:91], v[198:201], v[226:229], v[88:91]
	v_mfma_f32_16x16x32_bf16 v[84:87], v[198:201], v[238:241], v[84:87]
	v_mfma_f32_16x16x32_bf16 v[80:83], v[206:209], v[226:229], v[80:83]
	v_mfma_f32_16x16x32_bf16 v[76:79], v[206:209], v[238:241], v[76:79]
	v_mfma_f32_16x16x32_bf16 v[72:75], v[214:217], v[226:229], v[72:75]
	v_mfma_f32_16x16x32_bf16 v[68:71], v[214:217], v[238:241], v[68:71]
	v_mfma_f32_16x16x32_bf16 v[96:99], v[194:197], v[230:233], v[96:99]
	v_mfma_f32_16x16x32_bf16 v[92:95], v[194:197], v[242:245], v[92:95]
	v_mfma_f32_16x16x32_bf16 v[88:91], v[202:205], v[230:233], v[88:91]
	v_mfma_f32_16x16x32_bf16 v[84:87], v[202:205], v[242:245], v[84:87]
	v_mfma_f32_16x16x32_bf16 v[80:83], v[210:213], v[230:233], v[80:83]
	v_mfma_f32_16x16x32_bf16 v[76:79], v[210:213], v[242:245], v[76:79]
	v_mfma_f32_16x16x32_bf16 v[72:75], v[218:221], v[230:233], v[72:75]
	v_mfma_f32_16x16x32_bf16 v[68:71], v[218:221], v[242:245], v[68:71]
	v_lshl_add_u64 v[222:223], v[222:223], 0, s[48:49]
	s_or_b32 m0, s100, 0x8000
	s_barrier
	ds_read_b128 v[190:193], v156 offset:49152
	ds_read_b128 v[194:197], v156 offset:50176
	ds_read_b128 v[198:201], v155 offset:49152
	ds_read_b128 v[202:205], v155 offset:50176
	ds_read_b128 v[206:209], v154 offset:49152
	ds_read_b128 v[210:213], v154 offset:50176
	ds_read_b128 v[214:217], v153 offset:49152
	ds_read_b128 v[218:221], v153 offset:50176
	global_load_lds_dwordx4 v[222:223], off
	s_or_b32 m0, s100, 0xa000
	v_lshl_add_u64 v[222:223], v[236:237], 0, s[48:49]
	global_load_lds_dwordx4 v[222:223], off
	s_barrier
	s_waitcnt lgkmcnt(0)
	v_mfma_f32_16x16x32_bf16 v[64:67], v[190:193], v[174:177], v[64:67]
	v_mfma_f32_16x16x32_bf16 v[60:63], v[190:193], v[182:185], v[60:63]
	v_mfma_f32_16x16x32_bf16 v[56:59], v[198:201], v[174:177], v[56:59]
	v_mfma_f32_16x16x32_bf16 v[52:55], v[198:201], v[182:185], v[52:55]
	v_mfma_f32_16x16x32_bf16 v[48:51], v[206:209], v[174:177], v[48:51]
	v_mfma_f32_16x16x32_bf16 v[44:47], v[206:209], v[182:185], v[44:47]
	v_mfma_f32_16x16x32_bf16 v[40:43], v[214:217], v[174:177], v[40:43]
	v_mfma_f32_16x16x32_bf16 v[36:39], v[214:217], v[182:185], v[36:39]
	v_mfma_f32_16x16x32_bf16 v[64:67], v[194:197], v[178:181], v[64:67]
	v_mfma_f32_16x16x32_bf16 v[60:63], v[194:197], v[186:189], v[60:63]
	v_mfma_f32_16x16x32_bf16 v[56:59], v[202:205], v[178:181], v[56:59]
	v_mfma_f32_16x16x32_bf16 v[52:55], v[202:205], v[186:189], v[52:55]
	v_mfma_f32_16x16x32_bf16 v[48:51], v[210:213], v[178:181], v[48:51]
	v_mfma_f32_16x16x32_bf16 v[44:47], v[210:213], v[186:189], v[44:47]
	v_mfma_f32_16x16x32_bf16 v[40:43], v[218:221], v[178:181], v[40:43]
	v_mfma_f32_16x16x32_bf16 v[36:39], v[218:221], v[186:189], v[36:39]
	s_barrier
	s_or_b32 m0, s100, 0x1c000
	v_lshl_add_u64 v[174:175], v[246:247], 0, s[50:51]
	global_load_lds_dwordx4 v[174:175], off
	s_or_b32 m0, s100, 0x1e000
	v_lshl_add_u64 v[174:175], v[248:249], 0, s[50:51]
	global_load_lds_dwordx4 v[174:175], off
	s_waitcnt vmcnt(6)
	s_barrier
	v_mfma_f32_16x16x32_bf16 v[32:35], v[190:193], v[226:229], v[32:35]
	v_mfma_f32_16x16x32_bf16 v[28:31], v[190:193], v[238:241], v[28:31]
	v_mfma_f32_16x16x32_bf16 v[24:27], v[198:201], v[226:229], v[24:27]
	v_mfma_f32_16x16x32_bf16 v[20:23], v[198:201], v[238:241], v[20:23]
	v_mfma_f32_16x16x32_bf16 v[16:19], v[206:209], v[226:229], v[16:19]
	v_mfma_f32_16x16x32_bf16 v[12:15], v[206:209], v[238:241], v[12:15]
	v_mfma_f32_16x16x32_bf16 v[8:11], v[214:217], v[226:229], v[8:11]
	v_mfma_f32_16x16x32_bf16 v[4:7], v[214:217], v[238:241], v[4:7]
	v_mfma_f32_16x16x32_bf16 v[32:35], v[194:197], v[230:233], v[32:35]
	v_mfma_f32_16x16x32_bf16 v[28:31], v[194:197], v[242:245], v[28:31]
	v_mfma_f32_16x16x32_bf16 v[24:27], v[202:205], v[230:233], v[24:27]
	v_mfma_f32_16x16x32_bf16 v[20:23], v[202:205], v[242:245], v[20:23]
	v_mfma_f32_16x16x32_bf16 v[16:19], v[210:213], v[230:233], v[16:19]
	v_mfma_f32_16x16x32_bf16 v[12:15], v[210:213], v[242:245], v[12:15]
	v_mfma_f32_16x16x32_bf16 v[8:11], v[218:221], v[230:233], v[8:11]
	v_mfma_f32_16x16x32_bf16 v[4:7], v[218:221], v[242:245], v[4:7]
	s_add_i32 s29, s29, 2
	s_add_u32 s12, s12, 0x100
	s_addc_u32 s13, s13, 0
	s_cmp_lt_u32 s29, 40
	s_cbranch_scc1 .LBB0_1325
